# E1 (redundant setprio/waitcnt removed in GEMM K-loops) + nt stores for FFN hidden output
# speedup vs baseline: 1.0019x; 1.0019x over previous
.LBB0_287:
	ds_read_b128 v[160:163], v156
	ds_read_b128 v[164:167], v156 offset:1024
	ds_read_b128 v[168:171], v156 offset:2048
	ds_read_b128 v[172:175], v156 offset:3072
	ds_read_b128 v[176:179], v157
	ds_read_b128 v[180:183], v157 offset:1024
	ds_read_b128 v[184:187], v157 offset:2048
	ds_read_b128 v[188:191], v157 offset:3072
	s_add_u32 s28, s26, 0xfff00080
	s_addc_u32 s29, s27, -1
	s_cmp_eq_u32 s58, 60
	s_cselect_b32 s31, s21, s29
	s_cselect_b32 s30, s54, s28
	s_cselect_b32 s29, s19, s57
	s_cselect_b32 s28, s55, s56
	v_lshl_add_u64 v[192:193], s[26:27], 0, v[138:139]
	s_add_i32 m0, s17, 0xc000
	ds_read_b128 v[196:199], v158
	ds_read_b128 v[200:203], v158 offset:1024
	ds_read_b128 v[204:207], v158 offset:2048
	ds_read_b128 v[208:211], v158 offset:3072
	ds_read_b128 v[212:215], v158 offset:4096
	ds_read_b128 v[216:219], v158 offset:5120
	ds_read_b128 v[220:223], v158 offset:6144
	ds_read_b128 v[224:227], v158 offset:7168
	global_load_lds_dwordx4 v[192:193], off
	v_lshl_add_u64 v[192:193], s[26:27], 0, v[140:141]
	s_add_i32 m0, s17, 0xe000
	s_nop 0
	global_load_lds_dwordx4 v[192:193], off
	s_waitcnt vmcnt(8)
	s_waitcnt lgkmcnt(0)
	s_barrier
	s_setprio 1
	v_mfma_f32_16x16x32_bf16 v[126:129], v[160:163], v[196:199], v[126:129]
	v_mfma_f32_16x16x32_bf16 v[122:125], v[168:171], v[196:199], v[122:125]
	v_mfma_f32_16x16x32_bf16 v[118:121], v[160:163], v[204:207], v[118:121]
	v_mfma_f32_16x16x32_bf16 v[114:117], v[168:171], v[204:207], v[114:117]
	v_mfma_f32_16x16x32_bf16 v[102:105], v[160:163], v[212:215], v[102:105]
	v_mfma_f32_16x16x32_bf16 v[98:101], v[168:171], v[212:215], v[98:101]
	v_mfma_f32_16x16x32_bf16 v[86:89], v[160:163], v[220:223], v[86:89]
	v_mfma_f32_16x16x32_bf16 v[82:85], v[168:171], v[220:223], v[82:85]
	v_mfma_f32_16x16x32_bf16 v[126:129], v[164:167], v[200:203], v[126:129]
	v_mfma_f32_16x16x32_bf16 v[122:125], v[172:175], v[200:203], v[122:125]
	v_mfma_f32_16x16x32_bf16 v[118:121], v[164:167], v[208:211], v[118:121]
	v_mfma_f32_16x16x32_bf16 v[114:117], v[172:175], v[208:211], v[114:117]
	v_mfma_f32_16x16x32_bf16 v[102:105], v[164:167], v[216:219], v[102:105]
	v_mfma_f32_16x16x32_bf16 v[98:101], v[172:175], v[216:219], v[98:101]
	v_mfma_f32_16x16x32_bf16 v[86:89], v[164:167], v[224:227], v[86:89]
	v_mfma_f32_16x16x32_bf16 v[82:85], v[172:175], v[224:227], v[82:85]
	v_mfma_f32_16x16x32_bf16 v[110:113], v[176:179], v[196:199], v[110:113]
	v_mfma_f32_16x16x32_bf16 v[106:109], v[184:187], v[196:199], v[106:109]
	v_mfma_f32_16x16x32_bf16 v[94:97], v[176:179], v[204:207], v[94:97]
	v_mfma_f32_16x16x32_bf16 v[90:93], v[184:187], v[204:207], v[90:93]
	v_mfma_f32_16x16x32_bf16 v[78:81], v[176:179], v[212:215], v[78:81]
	v_mfma_f32_16x16x32_bf16 v[74:77], v[184:187], v[212:215], v[74:77]
	v_mfma_f32_16x16x32_bf16 v[70:73], v[176:179], v[220:223], v[70:73]
	v_mfma_f32_16x16x32_bf16 v[66:69], v[184:187], v[220:223], v[66:69]
	v_mfma_f32_16x16x32_bf16 v[110:113], v[180:183], v[200:203], v[110:113]
	v_mfma_f32_16x16x32_bf16 v[106:109], v[188:191], v[200:203], v[106:109]
	v_mfma_f32_16x16x32_bf16 v[94:97], v[180:183], v[208:211], v[94:97]
	v_mfma_f32_16x16x32_bf16 v[90:93], v[188:191], v[208:211], v[90:93]
	v_mfma_f32_16x16x32_bf16 v[78:81], v[180:183], v[216:219], v[78:81]
	v_mfma_f32_16x16x32_bf16 v[74:77], v[188:191], v[216:219], v[74:77]
	v_mfma_f32_16x16x32_bf16 v[70:73], v[180:183], v[224:227], v[70:73]
	v_mfma_f32_16x16x32_bf16 v[66:69], v[188:191], v[224:227], v[66:69]
	s_setprio 0
	s_barrier
	s_add_i32 s59, s50, s41
	v_lshl_add_u64 v[192:193], s[28:29], 0, v[134:135]
	s_mov_b32 m0, s59
	ds_read_b128 v[196:199], v158 offset:16384
	ds_read_b128 v[200:203], v158 offset:17408
	ds_read_b128 v[204:207], v158 offset:18432
	ds_read_b128 v[208:211], v158 offset:19456
	ds_read_b128 v[212:215], v158 offset:20480
	ds_read_b128 v[216:219], v158 offset:21504
	ds_read_b128 v[220:223], v158 offset:22528
	ds_read_b128 v[224:227], v158 offset:23552
	global_load_lds_dwordx4 v[192:193], off
	s_add_i32 m0, s59, 0x2000
	s_add_u32 s60, s28, 0x100000
	v_lshl_add_u64 v[228:229], s[28:29], 0, v[136:137]
	s_addc_u32 s61, s29, 0
	s_add_i32 s59, s51, s41
	global_load_lds_dwordx4 v[228:229], off
	v_lshl_add_u64 v[230:231], s[60:61], 0, v[134:135]
	s_mov_b32 m0, s59
	v_lshl_add_u64 v[232:233], s[30:31], 0, v[132:133]
	global_load_lds_dwordx4 v[230:231], off
	v_lshl_add_u64 v[230:231], s[60:61], 0, v[136:137]
	s_add_i32 m0, s59, 0x2000
	s_nop 0
	global_load_lds_dwordx4 v[230:231], off
	v_lshl_add_u64 v[230:231], s[30:31], 0, v[130:131]
	s_mov_b32 m0, s17
	s_nop 0
	global_load_lds_dwordx4 v[230:231], off
	s_mov_b32 m0, s42
	s_nop 0
	global_load_lds_dwordx4 v[232:233], off
	s_waitcnt vmcnt(8)
	s_waitcnt lgkmcnt(0)
	s_barrier
	s_setprio 1
	v_mfma_f32_16x16x32_bf16 v[62:65], v[160:163], v[196:199], v[62:65]
	v_mfma_f32_16x16x32_bf16 v[58:61], v[168:171], v[196:199], v[58:61]
	v_mfma_f32_16x16x32_bf16 v[54:57], v[160:163], v[204:207], v[54:57]
	v_mfma_f32_16x16x32_bf16 v[50:53], v[168:171], v[204:207], v[50:53]
	v_mfma_f32_16x16x32_bf16 v[38:41], v[160:163], v[212:215], v[38:41]
	v_mfma_f32_16x16x32_bf16 v[34:37], v[168:171], v[212:215], v[34:37]
	v_mfma_f32_16x16x32_bf16 v[22:25], v[160:163], v[220:223], v[22:25]
	v_mfma_f32_16x16x32_bf16 v[18:21], v[168:171], v[220:223], v[18:21]
	v_mfma_f32_16x16x32_bf16 v[62:65], v[164:167], v[200:203], v[62:65]
	v_mfma_f32_16x16x32_bf16 v[58:61], v[172:175], v[200:203], v[58:61]
	v_mfma_f32_16x16x32_bf16 v[54:57], v[164:167], v[208:211], v[54:57]
	v_mfma_f32_16x16x32_bf16 v[50:53], v[172:175], v[208:211], v[50:53]
	v_mfma_f32_16x16x32_bf16 v[38:41], v[164:167], v[216:219], v[38:41]
	v_mfma_f32_16x16x32_bf16 v[34:37], v[172:175], v[216:219], v[34:37]
	v_mfma_f32_16x16x32_bf16 v[22:25], v[164:167], v[224:227], v[22:25]
	v_mfma_f32_16x16x32_bf16 v[18:21], v[172:175], v[224:227], v[18:21]
	v_mfma_f32_16x16x32_bf16 v[46:49], v[176:179], v[196:199], v[46:49]
	v_mfma_f32_16x16x32_bf16 v[42:45], v[184:187], v[196:199], v[42:45]
	v_mfma_f32_16x16x32_bf16 v[30:33], v[176:179], v[204:207], v[30:33]
	v_mfma_f32_16x16x32_bf16 v[26:29], v[184:187], v[204:207], v[26:29]
	v_mfma_f32_16x16x32_bf16 v[14:17], v[176:179], v[212:215], v[14:17]
	v_mfma_f32_16x16x32_bf16 v[10:13], v[184:187], v[212:215], v[10:13]
	v_mfma_f32_16x16x32_bf16 v[6:9], v[176:179], v[220:223], v[6:9]
	v_mfma_f32_16x16x32_bf16 v[2:5], v[184:187], v[220:223], v[2:5]
	v_mfma_f32_16x16x32_bf16 v[46:49], v[180:183], v[200:203], v[46:49]
	v_mfma_f32_16x16x32_bf16 v[42:45], v[188:191], v[200:203], v[42:45]
	v_mfma_f32_16x16x32_bf16 v[30:33], v[180:183], v[208:211], v[30:33]
	v_mfma_f32_16x16x32_bf16 v[26:29], v[188:191], v[208:211], v[26:29]
	v_mfma_f32_16x16x32_bf16 v[14:17], v[180:183], v[216:219], v[14:17]
	v_mfma_f32_16x16x32_bf16 v[10:13], v[188:191], v[216:219], v[10:13]
	v_mfma_f32_16x16x32_bf16 v[6:9], v[180:183], v[224:227], v[6:9]
	v_mfma_f32_16x16x32_bf16 v[2:5], v[188:191], v[224:227], v[2:5]
	s_setprio 0
	s_barrier
	s_add_i32 s59, 0, 0x18000
	v_add_u32_e32 v159, s59, v154
	s_add_i32 s60, 0, 0x1c000
	ds_read_b128 v[160:163], v159
	ds_read_b128 v[164:167], v159 offset:1024
	ds_read_b128 v[168:171], v159 offset:2048
	ds_read_b128 v[172:175], v159 offset:3072
	v_add_u32_e32 v159, s60, v154
	ds_read_b128 v[176:179], v159
	ds_read_b128 v[180:183], v159 offset:1024
	ds_read_b128 v[184:187], v159 offset:2048
	ds_read_b128 v[188:191], v159 offset:3072
	s_add_u32 s30, s30, 0x100000
	s_addc_u32 s31, s31, 0
	s_mov_b32 m0, s43
	v_lshl_add_u64 v[234:235], s[30:31], 0, v[130:131]
	ds_read_b128 v[196:199], v158 offset:32768
	ds_read_b128 v[200:203], v158 offset:33792
	ds_read_b128 v[204:207], v158 offset:34816
	ds_read_b128 v[208:211], v158 offset:35840
	ds_read_b128 v[212:215], v158 offset:36864
	ds_read_b128 v[216:219], v158 offset:37888
	ds_read_b128 v[220:223], v158 offset:38912
	ds_read_b128 v[224:227], v158 offset:39936
	global_load_lds_dwordx4 v[234:235], off
	v_lshl_add_u64 v[234:235], s[30:31], 0, v[132:133]
	s_mov_b32 m0, s45
	s_nop 0
	global_load_lds_dwordx4 v[234:235], off
	s_waitcnt vmcnt(8)
	s_waitcnt lgkmcnt(0)
	s_barrier
	s_setprio 1
	v_mfma_f32_16x16x32_bf16 v[126:129], v[160:163], v[196:199], v[126:129]
	v_mfma_f32_16x16x32_bf16 v[122:125], v[168:171], v[196:199], v[122:125]
	v_mfma_f32_16x16x32_bf16 v[118:121], v[160:163], v[204:207], v[118:121]
	v_mfma_f32_16x16x32_bf16 v[114:117], v[168:171], v[204:207], v[114:117]
	v_mfma_f32_16x16x32_bf16 v[102:105], v[160:163], v[212:215], v[102:105]
	v_mfma_f32_16x16x32_bf16 v[98:101], v[168:171], v[212:215], v[98:101]
	v_mfma_f32_16x16x32_bf16 v[86:89], v[160:163], v[220:223], v[86:89]
	v_mfma_f32_16x16x32_bf16 v[82:85], v[168:171], v[220:223], v[82:85]
	v_mfma_f32_16x16x32_bf16 v[126:129], v[164:167], v[200:203], v[126:129]
	v_mfma_f32_16x16x32_bf16 v[122:125], v[172:175], v[200:203], v[122:125]
	v_mfma_f32_16x16x32_bf16 v[118:121], v[164:167], v[208:211], v[118:121]
	v_mfma_f32_16x16x32_bf16 v[114:117], v[172:175], v[208:211], v[114:117]
	v_mfma_f32_16x16x32_bf16 v[102:105], v[164:167], v[216:219], v[102:105]
	v_mfma_f32_16x16x32_bf16 v[98:101], v[172:175], v[216:219], v[98:101]
	v_mfma_f32_16x16x32_bf16 v[86:89], v[164:167], v[224:227], v[86:89]
	v_mfma_f32_16x16x32_bf16 v[82:85], v[172:175], v[224:227], v[82:85]
	v_mfma_f32_16x16x32_bf16 v[110:113], v[176:179], v[196:199], v[110:113]
	v_mfma_f32_16x16x32_bf16 v[106:109], v[184:187], v[196:199], v[106:109]
	v_mfma_f32_16x16x32_bf16 v[94:97], v[176:179], v[204:207], v[94:97]
	v_mfma_f32_16x16x32_bf16 v[90:93], v[184:187], v[204:207], v[90:93]
	v_mfma_f32_16x16x32_bf16 v[78:81], v[176:179], v[212:215], v[78:81]
	v_mfma_f32_16x16x32_bf16 v[74:77], v[184:187], v[212:215], v[74:77]
	v_mfma_f32_16x16x32_bf16 v[70:73], v[176:179], v[220:223], v[70:73]
	v_mfma_f32_16x16x32_bf16 v[66:69], v[184:187], v[220:223], v[66:69]
	v_mfma_f32_16x16x32_bf16 v[110:113], v[180:183], v[200:203], v[110:113]
	v_mfma_f32_16x16x32_bf16 v[106:109], v[188:191], v[200:203], v[106:109]
	v_mfma_f32_16x16x32_bf16 v[94:97], v[180:183], v[208:211], v[94:97]
	v_mfma_f32_16x16x32_bf16 v[90:93], v[188:191], v[208:211], v[90:93]
	v_mfma_f32_16x16x32_bf16 v[78:81], v[180:183], v[216:219], v[78:81]
	v_mfma_f32_16x16x32_bf16 v[74:77], v[188:191], v[216:219], v[74:77]
	v_mfma_f32_16x16x32_bf16 v[70:73], v[180:183], v[224:227], v[70:73]
	v_mfma_f32_16x16x32_bf16 v[66:69], v[188:191], v[224:227], v[66:69]
	s_setprio 0
	s_barrier
	s_add_i32 s30, s59, s41
	v_lshl_add_u64 v[192:193], v[192:193], 0, s[12:13]
	s_mov_b32 m0, s30
	ds_read_b128 v[196:199], v158 offset:49152
	ds_read_b128 v[200:203], v158 offset:50176
	ds_read_b128 v[204:207], v158 offset:51200
	ds_read_b128 v[208:211], v158 offset:52224
	ds_read_b128 v[212:215], v158 offset:53248
	ds_read_b128 v[216:219], v158 offset:54272
	ds_read_b128 v[220:223], v158 offset:55296
	ds_read_b128 v[224:227], v158 offset:56320
	global_load_lds_dwordx4 v[192:193], off
	s_add_i32 m0, s30, 0x2000
	s_add_u32 s28, s28, 0x100080
	v_lshl_add_u64 v[192:193], v[228:229], 0, s[12:13]
	s_addc_u32 s29, s29, 0
	s_add_i32 s30, s60, s41
	global_load_lds_dwordx4 v[192:193], off
	v_lshl_add_u64 v[192:193], s[28:29], 0, v[134:135]
	s_mov_b32 m0, s30
	s_nop 0
	global_load_lds_dwordx4 v[192:193], off
	v_lshl_add_u64 v[192:193], s[28:29], 0, v[136:137]
	s_add_i32 m0, s30, 0x2000
	s_nop 0
	global_load_lds_dwordx4 v[192:193], off
	v_lshl_add_u64 v[192:193], v[230:231], 0, s[12:13]
	s_mov_b32 m0, s47
	s_nop 0
	global_load_lds_dwordx4 v[192:193], off
	v_lshl_add_u64 v[192:193], v[232:233], 0, s[12:13]
	s_mov_b32 m0, s48
	s_nop 0
	global_load_lds_dwordx4 v[192:193], off
	s_waitcnt vmcnt(8)
	s_waitcnt lgkmcnt(0)
	s_barrier
	s_setprio 1
	v_mfma_f32_16x16x32_bf16 v[62:65], v[160:163], v[196:199], v[62:65]
	v_mfma_f32_16x16x32_bf16 v[58:61], v[168:171], v[196:199], v[58:61]
	v_mfma_f32_16x16x32_bf16 v[54:57], v[160:163], v[204:207], v[54:57]
	v_mfma_f32_16x16x32_bf16 v[50:53], v[168:171], v[204:207], v[50:53]
	v_mfma_f32_16x16x32_bf16 v[38:41], v[160:163], v[212:215], v[38:41]
	v_mfma_f32_16x16x32_bf16 v[34:37], v[168:171], v[212:215], v[34:37]
	v_mfma_f32_16x16x32_bf16 v[22:25], v[160:163], v[220:223], v[22:25]
	v_mfma_f32_16x16x32_bf16 v[18:21], v[168:171], v[220:223], v[18:21]
	v_mfma_f32_16x16x32_bf16 v[62:65], v[164:167], v[200:203], v[62:65]
	v_mfma_f32_16x16x32_bf16 v[58:61], v[172:175], v[200:203], v[58:61]
	v_mfma_f32_16x16x32_bf16 v[54:57], v[164:167], v[208:211], v[54:57]
	v_mfma_f32_16x16x32_bf16 v[50:53], v[172:175], v[208:211], v[50:53]
	v_mfma_f32_16x16x32_bf16 v[38:41], v[164:167], v[216:219], v[38:41]
	v_mfma_f32_16x16x32_bf16 v[34:37], v[172:175], v[216:219], v[34:37]
	v_mfma_f32_16x16x32_bf16 v[22:25], v[164:167], v[224:227], v[22:25]
	v_mfma_f32_16x16x32_bf16 v[18:21], v[172:175], v[224:227], v[18:21]
	v_mfma_f32_16x16x32_bf16 v[46:49], v[176:179], v[196:199], v[46:49]
	v_mfma_f32_16x16x32_bf16 v[42:45], v[184:187], v[196:199], v[42:45]
	v_mfma_f32_16x16x32_bf16 v[30:33], v[176:179], v[204:207], v[30:33]
	v_mfma_f32_16x16x32_bf16 v[26:29], v[184:187], v[204:207], v[26:29]
	v_mfma_f32_16x16x32_bf16 v[14:17], v[176:179], v[212:215], v[14:17]
	v_mfma_f32_16x16x32_bf16 v[10:13], v[184:187], v[212:215], v[10:13]
	v_mfma_f32_16x16x32_bf16 v[6:9], v[176:179], v[220:223], v[6:9]
	v_mfma_f32_16x16x32_bf16 v[2:5], v[184:187], v[220:223], v[2:5]
	v_mfma_f32_16x16x32_bf16 v[46:49], v[180:183], v[200:203], v[46:49]
	v_mfma_f32_16x16x32_bf16 v[42:45], v[188:191], v[200:203], v[42:45]
	v_mfma_f32_16x16x32_bf16 v[30:33], v[180:183], v[208:211], v[30:33]
	v_mfma_f32_16x16x32_bf16 v[26:29], v[188:191], v[208:211], v[26:29]
	v_mfma_f32_16x16x32_bf16 v[14:17], v[180:183], v[216:219], v[14:17]
	v_mfma_f32_16x16x32_bf16 v[10:13], v[188:191], v[216:219], v[10:13]
	v_mfma_f32_16x16x32_bf16 v[6:9], v[180:183], v[224:227], v[6:9]
	v_mfma_f32_16x16x32_bf16 v[2:5], v[188:191], v[224:227], v[2:5]
	s_setprio 0
	s_barrier
	s_add_i32 s58, s58, 2
	s_add_u32 s26, s26, 0x100
	s_addc_u32 s27, s27, 0
	s_add_u32 s56, s56, 0x100
	s_addc_u32 s57, s57, 0
	s_cmp_gt_u32 s58, 61
	s_cbranch_scc0 .LBB0_287
	s_and_b64 vcc, exec, s[14:15]
	s_cbranch_vccz .LBB0_290
	s_barrier

.LBB0_311:
	ds_read_b128 v[152:155], v144
	ds_read_b128 v[156:159], v144 offset:1024
	ds_read_b128 v[160:163], v144 offset:2048
	ds_read_b128 v[164:167], v144 offset:3072
	ds_read_b128 v[168:171], v145
	ds_read_b128 v[172:175], v145 offset:1024
	ds_read_b128 v[176:179], v145 offset:2048
	ds_read_b128 v[180:183], v145 offset:3072
	s_add_u32 s42, s40, 0xfff00080
	s_addc_u32 s43, s41, -1
	s_cmp_eq_u32 s70, 60
	s_cselect_b32 s47, s27, s43
	s_cselect_b32 s46, s66, s42
	s_cselect_b32 s43, s25, s69
	s_cselect_b32 s42, s67, s68
	v_lshl_add_u64 v[192:193], s[40:41], 0, v[134:135]
	s_add_i32 m0, s29, 0xc000
	ds_read_b128 v[184:187], v151
	ds_read_b128 v[188:191], v151 offset:1024
	ds_read_b128 v[196:199], v151 offset:2048
	ds_read_b128 v[200:203], v151 offset:3072
	ds_read_b128 v[204:207], v151 offset:4096
	ds_read_b128 v[208:211], v151 offset:5120
	ds_read_b128 v[212:215], v151 offset:6144
	ds_read_b128 v[216:219], v151 offset:7168
	global_load_lds_dwordx4 v[192:193], off
	v_lshl_add_u64 v[192:193], s[40:41], 0, v[136:137]
	s_add_i32 m0, s29, 0xe000
	s_nop 0
	global_load_lds_dwordx4 v[192:193], off
	s_waitcnt vmcnt(8)
	s_waitcnt lgkmcnt(0)
	s_barrier
	s_setprio 1
	v_mfma_f32_16x16x32_bf16 v[126:129], v[152:155], v[184:187], v[126:129]
	v_mfma_f32_16x16x32_bf16 v[122:125], v[160:163], v[184:187], v[122:125]
	v_mfma_f32_16x16x32_bf16 v[118:121], v[152:155], v[196:199], v[118:121]
	v_mfma_f32_16x16x32_bf16 v[110:113], v[160:163], v[196:199], v[110:113]
	v_mfma_f32_16x16x32_bf16 v[102:105], v[152:155], v[204:207], v[102:105]
	v_mfma_f32_16x16x32_bf16 v[94:97], v[160:163], v[204:207], v[94:97]
	v_mfma_f32_16x16x32_bf16 v[86:89], v[152:155], v[212:215], v[86:89]
	v_mfma_f32_16x16x32_bf16 v[78:81], v[160:163], v[212:215], v[78:81]
	v_mfma_f32_16x16x32_bf16 v[126:129], v[156:159], v[188:191], v[126:129]
	v_mfma_f32_16x16x32_bf16 v[122:125], v[164:167], v[188:191], v[122:125]
	v_mfma_f32_16x16x32_bf16 v[118:121], v[156:159], v[200:203], v[118:121]
	v_mfma_f32_16x16x32_bf16 v[110:113], v[164:167], v[200:203], v[110:113]
	v_mfma_f32_16x16x32_bf16 v[102:105], v[156:159], v[208:211], v[102:105]
	v_mfma_f32_16x16x32_bf16 v[94:97], v[164:167], v[208:211], v[94:97]
	v_mfma_f32_16x16x32_bf16 v[86:89], v[156:159], v[216:219], v[86:89]
	v_mfma_f32_16x16x32_bf16 v[78:81], v[164:167], v[216:219], v[78:81]
	v_mfma_f32_16x16x32_bf16 v[114:117], v[168:171], v[184:187], v[114:117]
	v_mfma_f32_16x16x32_bf16 v[106:109], v[176:179], v[184:187], v[106:109]
	v_mfma_f32_16x16x32_bf16 v[98:101], v[168:171], v[196:199], v[98:101]
	v_mfma_f32_16x16x32_bf16 v[90:93], v[176:179], v[196:199], v[90:93]
	v_mfma_f32_16x16x32_bf16 v[82:85], v[168:171], v[204:207], v[82:85]
	v_mfma_f32_16x16x32_bf16 v[74:77], v[176:179], v[204:207], v[74:77]
	v_mfma_f32_16x16x32_bf16 v[70:73], v[168:171], v[212:215], v[70:73]
	v_mfma_f32_16x16x32_bf16 v[66:69], v[176:179], v[212:215], v[66:69]
	v_mfma_f32_16x16x32_bf16 v[114:117], v[172:175], v[188:191], v[114:117]
	v_mfma_f32_16x16x32_bf16 v[106:109], v[180:183], v[188:191], v[106:109]
	v_mfma_f32_16x16x32_bf16 v[98:101], v[172:175], v[200:203], v[98:101]
	v_mfma_f32_16x16x32_bf16 v[90:93], v[180:183], v[200:203], v[90:93]
	v_mfma_f32_16x16x32_bf16 v[82:85], v[172:175], v[208:211], v[82:85]
	v_mfma_f32_16x16x32_bf16 v[74:77], v[180:183], v[208:211], v[74:77]
	v_mfma_f32_16x16x32_bf16 v[70:73], v[172:175], v[216:219], v[70:73]
	v_mfma_f32_16x16x32_bf16 v[66:69], v[180:183], v[216:219], v[66:69]
	s_setprio 0
	s_barrier
	s_add_i32 s71, s62, s54
	v_lshl_add_u64 v[192:193], s[42:43], 0, v[130:131]
	s_mov_b32 m0, s71
	ds_read_b128 v[184:187], v151 offset:16384
	ds_read_b128 v[188:191], v151 offset:17408
	ds_read_b128 v[196:199], v151 offset:18432
	ds_read_b128 v[200:203], v151 offset:19456
	ds_read_b128 v[204:207], v151 offset:20480
	ds_read_b128 v[208:211], v151 offset:21504
	ds_read_b128 v[212:215], v151 offset:22528
	ds_read_b128 v[216:219], v151 offset:23552
	global_load_lds_dwordx4 v[192:193], off
	s_add_i32 m0, s71, 0x2000
	s_add_u32 s72, s42, 0x100000
	v_lshl_add_u64 v[220:221], s[42:43], 0, v[132:133]
	s_addc_u32 s73, s43, 0
	s_add_i32 s71, s63, s54
	global_load_lds_dwordx4 v[220:221], off
	v_lshl_add_u64 v[222:223], s[72:73], 0, v[130:131]
	s_mov_b32 m0, s71
	v_lshl_add_u64 v[224:225], s[46:47], 0, v[132:133]
	global_load_lds_dwordx4 v[222:223], off
	v_lshl_add_u64 v[222:223], s[72:73], 0, v[132:133]
	s_add_i32 m0, s71, 0x2000
	s_nop 0
	global_load_lds_dwordx4 v[222:223], off
	v_lshl_add_u64 v[222:223], s[46:47], 0, v[130:131]
	s_mov_b32 m0, s29
	s_nop 0
	global_load_lds_dwordx4 v[222:223], off
	s_mov_b32 m0, s55
	s_nop 0
	global_load_lds_dwordx4 v[224:225], off
	s_waitcnt vmcnt(8)
	s_waitcnt lgkmcnt(0)
	s_barrier
	s_setprio 1
	v_mfma_f32_16x16x32_bf16 v[62:65], v[152:155], v[184:187], v[62:65]
	v_mfma_f32_16x16x32_bf16 v[58:61], v[160:163], v[184:187], v[58:61]
	v_mfma_f32_16x16x32_bf16 v[54:57], v[152:155], v[196:199], v[54:57]
	v_mfma_f32_16x16x32_bf16 v[46:49], v[160:163], v[196:199], v[46:49]
	v_mfma_f32_16x16x32_bf16 v[38:41], v[152:155], v[204:207], v[38:41]
	v_mfma_f32_16x16x32_bf16 v[30:33], v[160:163], v[204:207], v[30:33]
	v_mfma_f32_16x16x32_bf16 v[22:25], v[152:155], v[212:215], v[22:25]
	v_mfma_f32_16x16x32_bf16 v[14:17], v[160:163], v[212:215], v[14:17]
	v_mfma_f32_16x16x32_bf16 v[62:65], v[156:159], v[188:191], v[62:65]
	v_mfma_f32_16x16x32_bf16 v[58:61], v[164:167], v[188:191], v[58:61]
	v_mfma_f32_16x16x32_bf16 v[54:57], v[156:159], v[200:203], v[54:57]
	v_mfma_f32_16x16x32_bf16 v[46:49], v[164:167], v[200:203], v[46:49]
	v_mfma_f32_16x16x32_bf16 v[38:41], v[156:159], v[208:211], v[38:41]
	v_mfma_f32_16x16x32_bf16 v[30:33], v[164:167], v[208:211], v[30:33]
	v_mfma_f32_16x16x32_bf16 v[22:25], v[156:159], v[216:219], v[22:25]
	v_mfma_f32_16x16x32_bf16 v[14:17], v[164:167], v[216:219], v[14:17]
	v_mfma_f32_16x16x32_bf16 v[50:53], v[168:171], v[184:187], v[50:53]
	v_mfma_f32_16x16x32_bf16 v[42:45], v[176:179], v[184:187], v[42:45]
	v_mfma_f32_16x16x32_bf16 v[34:37], v[168:171], v[196:199], v[34:37]
	v_mfma_f32_16x16x32_bf16 v[26:29], v[176:179], v[196:199], v[26:29]
	v_mfma_f32_16x16x32_bf16 v[18:21], v[168:171], v[204:207], v[18:21]
	v_mfma_f32_16x16x32_bf16 v[10:13], v[176:179], v[204:207], v[10:13]
	v_mfma_f32_16x16x32_bf16 v[6:9], v[168:171], v[212:215], v[6:9]
	v_mfma_f32_16x16x32_bf16 v[2:5], v[176:179], v[212:215], v[2:5]
	v_mfma_f32_16x16x32_bf16 v[50:53], v[172:175], v[188:191], v[50:53]
	v_mfma_f32_16x16x32_bf16 v[42:45], v[180:183], v[188:191], v[42:45]
	v_mfma_f32_16x16x32_bf16 v[34:37], v[172:175], v[200:203], v[34:37]
	v_mfma_f32_16x16x32_bf16 v[26:29], v[180:183], v[200:203], v[26:29]
	v_mfma_f32_16x16x32_bf16 v[18:21], v[172:175], v[208:211], v[18:21]
	v_mfma_f32_16x16x32_bf16 v[10:13], v[180:183], v[208:211], v[10:13]
	v_mfma_f32_16x16x32_bf16 v[6:9], v[172:175], v[216:219], v[6:9]
	v_mfma_f32_16x16x32_bf16 v[2:5], v[180:183], v[216:219], v[2:5]
	s_setprio 0
	s_barrier
	s_add_i32 s71, 0, 0x18000
	s_add_i32 s72, 0, 0x1c000
	v_add_u32_e32 v164, s71, v142
	v_add_u32_e32 v180, s72, v142
	ds_read_b128 v[152:155], v164
	ds_read_b128 v[156:159], v164 offset:1024
	ds_read_b128 v[160:163], v164 offset:2048
	ds_read_b128 v[164:167], v164 offset:3072
	ds_read_b128 v[168:171], v180
	ds_read_b128 v[172:175], v180 offset:1024
	ds_read_b128 v[176:179], v180 offset:2048
	ds_read_b128 v[180:183], v180 offset:3072
	s_add_u32 s46, s46, 0x100000
	s_addc_u32 s47, s47, 0
	s_mov_b32 m0, s56
	v_lshl_add_u64 v[226:227], s[46:47], 0, v[130:131]
	ds_read_b128 v[184:187], v151 offset:32768
	ds_read_b128 v[188:191], v151 offset:33792
	ds_read_b128 v[196:199], v151 offset:34816
	ds_read_b128 v[200:203], v151 offset:35840
	ds_read_b128 v[204:207], v151 offset:36864
	ds_read_b128 v[208:211], v151 offset:37888
	ds_read_b128 v[212:215], v151 offset:38912
	ds_read_b128 v[216:219], v151 offset:39936
	global_load_lds_dwordx4 v[226:227], off
	v_lshl_add_u64 v[226:227], s[46:47], 0, v[132:133]
	s_mov_b32 m0, s57
	s_nop 0
	global_load_lds_dwordx4 v[226:227], off
	s_waitcnt vmcnt(8)
	s_waitcnt lgkmcnt(0)
	s_barrier
	s_setprio 1
	v_mfma_f32_16x16x32_bf16 v[126:129], v[152:155], v[184:187], v[126:129]
	v_mfma_f32_16x16x32_bf16 v[122:125], v[160:163], v[184:187], v[122:125]
	v_mfma_f32_16x16x32_bf16 v[118:121], v[152:155], v[196:199], v[118:121]
	v_mfma_f32_16x16x32_bf16 v[110:113], v[160:163], v[196:199], v[110:113]
	v_mfma_f32_16x16x32_bf16 v[102:105], v[152:155], v[204:207], v[102:105]
	v_mfma_f32_16x16x32_bf16 v[94:97], v[160:163], v[204:207], v[94:97]
	v_mfma_f32_16x16x32_bf16 v[86:89], v[152:155], v[212:215], v[86:89]
	v_mfma_f32_16x16x32_bf16 v[78:81], v[160:163], v[212:215], v[78:81]
	v_mfma_f32_16x16x32_bf16 v[126:129], v[156:159], v[188:191], v[126:129]
	v_mfma_f32_16x16x32_bf16 v[122:125], v[164:167], v[188:191], v[122:125]
	v_mfma_f32_16x16x32_bf16 v[118:121], v[156:159], v[200:203], v[118:121]
	v_mfma_f32_16x16x32_bf16 v[110:113], v[164:167], v[200:203], v[110:113]
	v_mfma_f32_16x16x32_bf16 v[102:105], v[156:159], v[208:211], v[102:105]
	v_mfma_f32_16x16x32_bf16 v[94:97], v[164:167], v[208:211], v[94:97]
	v_mfma_f32_16x16x32_bf16 v[86:89], v[156:159], v[216:219], v[86:89]
	v_mfma_f32_16x16x32_bf16 v[78:81], v[164:167], v[216:219], v[78:81]
	v_mfma_f32_16x16x32_bf16 v[114:117], v[168:171], v[184:187], v[114:117]
	v_mfma_f32_16x16x32_bf16 v[106:109], v[176:179], v[184:187], v[106:109]
	v_mfma_f32_16x16x32_bf16 v[98:101], v[168:171], v[196:199], v[98:101]
	v_mfma_f32_16x16x32_bf16 v[90:93], v[176:179], v[196:199], v[90:93]
	v_mfma_f32_16x16x32_bf16 v[82:85], v[168:171], v[204:207], v[82:85]
	v_mfma_f32_16x16x32_bf16 v[74:77], v[176:179], v[204:207], v[74:77]
	v_mfma_f32_16x16x32_bf16 v[70:73], v[168:171], v[212:215], v[70:73]
	v_mfma_f32_16x16x32_bf16 v[66:69], v[176:179], v[212:215], v[66:69]
	v_mfma_f32_16x16x32_bf16 v[114:117], v[172:175], v[188:191], v[114:117]
	v_mfma_f32_16x16x32_bf16 v[106:109], v[180:183], v[188:191], v[106:109]
	v_mfma_f32_16x16x32_bf16 v[98:101], v[172:175], v[200:203], v[98:101]
	v_mfma_f32_16x16x32_bf16 v[90:93], v[180:183], v[200:203], v[90:93]
	v_mfma_f32_16x16x32_bf16 v[82:85], v[172:175], v[208:211], v[82:85]
	v_mfma_f32_16x16x32_bf16 v[74:77], v[180:183], v[208:211], v[74:77]
	v_mfma_f32_16x16x32_bf16 v[70:73], v[172:175], v[216:219], v[70:73]
	v_mfma_f32_16x16x32_bf16 v[66:69], v[180:183], v[216:219], v[66:69]
	s_setprio 0
	s_barrier
	s_add_i32 s46, s71, s54
	v_lshl_add_u64 v[192:193], v[192:193], 0, s[10:11]
	s_mov_b32 m0, s46
	ds_read_b128 v[184:187], v151 offset:49152
	ds_read_b128 v[188:191], v151 offset:50176
	ds_read_b128 v[196:199], v151 offset:51200
	ds_read_b128 v[200:203], v151 offset:52224
	ds_read_b128 v[204:207], v151 offset:53248
	ds_read_b128 v[208:211], v151 offset:54272
	ds_read_b128 v[212:215], v151 offset:55296
	ds_read_b128 v[216:219], v151 offset:56320
	global_load_lds_dwordx4 v[192:193], off
	s_add_i32 m0, s46, 0x2000
	s_add_u32 s42, s42, 0x100080
	v_lshl_add_u64 v[192:193], v[220:221], 0, s[10:11]
	s_addc_u32 s43, s43, 0
	s_add_i32 s46, s72, s54
	global_load_lds_dwordx4 v[192:193], off
	v_lshl_add_u64 v[192:193], s[42:43], 0, v[130:131]
	s_mov_b32 m0, s46
	s_nop 0
	global_load_lds_dwordx4 v[192:193], off
	v_lshl_add_u64 v[192:193], s[42:43], 0, v[132:133]
	s_add_i32 m0, s46, 0x2000
	s_nop 0
	global_load_lds_dwordx4 v[192:193], off
	v_lshl_add_u64 v[192:193], v[222:223], 0, s[10:11]
	s_mov_b32 m0, s59
	s_nop 0
	global_load_lds_dwordx4 v[192:193], off
	v_lshl_add_u64 v[192:193], v[224:225], 0, s[10:11]
	s_mov_b32 m0, s60
	s_nop 0
	global_load_lds_dwordx4 v[192:193], off
	s_waitcnt vmcnt(8)
	s_waitcnt lgkmcnt(0)
	s_barrier
	s_setprio 1
	v_mfma_f32_16x16x32_bf16 v[62:65], v[152:155], v[184:187], v[62:65]
	v_mfma_f32_16x16x32_bf16 v[58:61], v[160:163], v[184:187], v[58:61]
	v_mfma_f32_16x16x32_bf16 v[54:57], v[152:155], v[196:199], v[54:57]
	v_mfma_f32_16x16x32_bf16 v[46:49], v[160:163], v[196:199], v[46:49]
	v_mfma_f32_16x16x32_bf16 v[38:41], v[152:155], v[204:207], v[38:41]
	v_mfma_f32_16x16x32_bf16 v[30:33], v[160:163], v[204:207], v[30:33]
	v_mfma_f32_16x16x32_bf16 v[22:25], v[152:155], v[212:215], v[22:25]
	v_mfma_f32_16x16x32_bf16 v[14:17], v[160:163], v[212:215], v[14:17]
	v_mfma_f32_16x16x32_bf16 v[62:65], v[156:159], v[188:191], v[62:65]
	v_mfma_f32_16x16x32_bf16 v[58:61], v[164:167], v[188:191], v[58:61]
	v_mfma_f32_16x16x32_bf16 v[54:57], v[156:159], v[200:203], v[54:57]
	v_mfma_f32_16x16x32_bf16 v[46:49], v[164:167], v[200:203], v[46:49]
	v_mfma_f32_16x16x32_bf16 v[38:41], v[156:159], v[208:211], v[38:41]
	v_mfma_f32_16x16x32_bf16 v[30:33], v[164:167], v[208:211], v[30:33]
	v_mfma_f32_16x16x32_bf16 v[22:25], v[156:159], v[216:219], v[22:25]
	v_mfma_f32_16x16x32_bf16 v[14:17], v[164:167], v[216:219], v[14:17]
	v_mfma_f32_16x16x32_bf16 v[50:53], v[168:171], v[184:187], v[50:53]
	v_mfma_f32_16x16x32_bf16 v[42:45], v[176:179], v[184:187], v[42:45]
	v_mfma_f32_16x16x32_bf16 v[34:37], v[168:171], v[196:199], v[34:37]
	v_mfma_f32_16x16x32_bf16 v[26:29], v[176:179], v[196:199], v[26:29]
	v_mfma_f32_16x16x32_bf16 v[18:21], v[168:171], v[204:207], v[18:21]
	v_mfma_f32_16x16x32_bf16 v[10:13], v[176:179], v[204:207], v[10:13]
	v_mfma_f32_16x16x32_bf16 v[6:9], v[168:171], v[212:215], v[6:9]
	v_mfma_f32_16x16x32_bf16 v[2:5], v[176:179], v[212:215], v[2:5]
	v_mfma_f32_16x16x32_bf16 v[50:53], v[172:175], v[188:191], v[50:53]
	v_mfma_f32_16x16x32_bf16 v[42:45], v[180:183], v[188:191], v[42:45]
	v_mfma_f32_16x16x32_bf16 v[34:37], v[172:175], v[200:203], v[34:37]
	v_mfma_f32_16x16x32_bf16 v[26:29], v[180:183], v[200:203], v[26:29]
	v_mfma_f32_16x16x32_bf16 v[18:21], v[172:175], v[208:211], v[18:21]
	v_mfma_f32_16x16x32_bf16 v[10:13], v[180:183], v[208:211], v[10:13]
	v_mfma_f32_16x16x32_bf16 v[6:9], v[172:175], v[216:219], v[6:9]
	v_mfma_f32_16x16x32_bf16 v[2:5], v[180:183], v[216:219], v[2:5]
	s_setprio 0
	s_barrier
	s_add_i32 s70, s70, 2
	s_add_u32 s40, s40, 0x100
	s_addc_u32 s41, s41, 0
	s_add_u32 s68, s68, 0x100
	s_addc_u32 s69, s69, 0
	s_cmp_gt_u32 s70, 61
	s_cbranch_scc0 .LBB0_311
	s_and_b64 vcc, exec, s[12:13]
	s_cbranch_vccz .LBB0_314
	s_barrier

.LBB0_335:
	ds_read_b128 v[144:147], v140
	ds_read_b128 v[148:151], v140 offset:1024
	ds_read_b128 v[152:155], v140 offset:2048
	ds_read_b128 v[156:159], v140 offset:3072
	ds_read_b128 v[160:163], v142
	ds_read_b128 v[164:167], v142 offset:1024
	ds_read_b128 v[168:171], v142 offset:2048
	ds_read_b128 v[172:175], v142 offset:3072
	s_add_u32 s42, s40, 0xfff00080
	s_addc_u32 s43, s41, -1
	s_cmp_eq_u32 s67, 60
	s_cselect_b32 s47, s27, s43
	s_cselect_b32 s46, s63, s42
	s_cselect_b32 s43, s25, s66
	s_cselect_b32 s42, s64, s65
	v_lshl_add_u64 v[192:193], s[40:41], 0, v[134:135]
	s_add_i32 m0, s29, 0xc000
	ds_read_b128 v[176:179], v143
	ds_read_b128 v[180:183], v143 offset:1024
	ds_read_b128 v[184:187], v143 offset:2048
	ds_read_b128 v[188:191], v143 offset:3072
	ds_read_b128 v[196:199], v143 offset:4096
	ds_read_b128 v[200:203], v143 offset:5120
	ds_read_b128 v[204:207], v143 offset:6144
	ds_read_b128 v[208:211], v143 offset:7168
	global_load_lds_dwordx4 v[192:193], off
	v_lshl_add_u64 v[192:193], s[40:41], 0, v[136:137]
	s_add_i32 m0, s29, 0xe000
	s_nop 0
	global_load_lds_dwordx4 v[192:193], off
	s_waitcnt vmcnt(8)
	s_waitcnt lgkmcnt(0)
	s_barrier
	s_setprio 1
	v_mfma_f32_16x16x32_bf16 v[126:129], v[144:147], v[176:179], v[126:129]
	v_mfma_f32_16x16x32_bf16 v[122:125], v[152:155], v[176:179], v[122:125]
	v_mfma_f32_16x16x32_bf16 v[118:121], v[144:147], v[184:187], v[118:121]
	v_mfma_f32_16x16x32_bf16 v[110:113], v[152:155], v[184:187], v[110:113]
	v_mfma_f32_16x16x32_bf16 v[102:105], v[144:147], v[196:199], v[102:105]
	v_mfma_f32_16x16x32_bf16 v[94:97], v[152:155], v[196:199], v[94:97]
	v_mfma_f32_16x16x32_bf16 v[86:89], v[144:147], v[204:207], v[86:89]
	v_mfma_f32_16x16x32_bf16 v[78:81], v[152:155], v[204:207], v[78:81]
	v_mfma_f32_16x16x32_bf16 v[126:129], v[148:151], v[180:183], v[126:129]
	v_mfma_f32_16x16x32_bf16 v[122:125], v[156:159], v[180:183], v[122:125]
	v_mfma_f32_16x16x32_bf16 v[118:121], v[148:151], v[188:191], v[118:121]
	v_mfma_f32_16x16x32_bf16 v[110:113], v[156:159], v[188:191], v[110:113]
	v_mfma_f32_16x16x32_bf16 v[102:105], v[148:151], v[200:203], v[102:105]
	v_mfma_f32_16x16x32_bf16 v[94:97], v[156:159], v[200:203], v[94:97]
	v_mfma_f32_16x16x32_bf16 v[86:89], v[148:151], v[208:211], v[86:89]
	v_mfma_f32_16x16x32_bf16 v[78:81], v[156:159], v[208:211], v[78:81]
	v_mfma_f32_16x16x32_bf16 v[114:117], v[160:163], v[176:179], v[114:117]
	v_mfma_f32_16x16x32_bf16 v[106:109], v[168:171], v[176:179], v[106:109]
	v_mfma_f32_16x16x32_bf16 v[98:101], v[160:163], v[184:187], v[98:101]
	v_mfma_f32_16x16x32_bf16 v[90:93], v[168:171], v[184:187], v[90:93]
	v_mfma_f32_16x16x32_bf16 v[82:85], v[160:163], v[196:199], v[82:85]
	v_mfma_f32_16x16x32_bf16 v[74:77], v[168:171], v[196:199], v[74:77]
	v_mfma_f32_16x16x32_bf16 v[70:73], v[160:163], v[204:207], v[70:73]
	v_mfma_f32_16x16x32_bf16 v[66:69], v[168:171], v[204:207], v[66:69]
	v_mfma_f32_16x16x32_bf16 v[114:117], v[164:167], v[180:183], v[114:117]
	v_mfma_f32_16x16x32_bf16 v[106:109], v[172:175], v[180:183], v[106:109]
	v_mfma_f32_16x16x32_bf16 v[98:101], v[164:167], v[188:191], v[98:101]
	v_mfma_f32_16x16x32_bf16 v[90:93], v[172:175], v[188:191], v[90:93]
	v_mfma_f32_16x16x32_bf16 v[82:85], v[164:167], v[200:203], v[82:85]
	v_mfma_f32_16x16x32_bf16 v[74:77], v[172:175], v[200:203], v[74:77]
	v_mfma_f32_16x16x32_bf16 v[70:73], v[164:167], v[208:211], v[70:73]
	v_mfma_f32_16x16x32_bf16 v[66:69], v[172:175], v[208:211], v[66:69]
	s_setprio 0
	s_barrier
	s_add_i32 s68, s59, s51
	v_lshl_add_u64 v[192:193], s[42:43], 0, v[130:131]
	s_mov_b32 m0, s68
	ds_read_b128 v[176:179], v143 offset:16384
	ds_read_b128 v[180:183], v143 offset:17408
	ds_read_b128 v[184:187], v143 offset:18432
	ds_read_b128 v[188:191], v143 offset:19456
	ds_read_b128 v[196:199], v143 offset:20480
	ds_read_b128 v[200:203], v143 offset:21504
	ds_read_b128 v[204:207], v143 offset:22528
	ds_read_b128 v[208:211], v143 offset:23552
	global_load_lds_dwordx4 v[192:193], off
	s_add_i32 m0, s68, 0x2000
	s_add_u32 s68, s42, 0x100000
	v_lshl_add_u64 v[212:213], s[42:43], 0, v[132:133]
	s_addc_u32 s69, s43, 0
	s_add_i32 s70, s60, s51
	global_load_lds_dwordx4 v[212:213], off
	v_lshl_add_u64 v[214:215], s[68:69], 0, v[130:131]
	s_mov_b32 m0, s70
	v_lshl_add_u64 v[216:217], s[46:47], 0, v[132:133]
	global_load_lds_dwordx4 v[214:215], off
	v_lshl_add_u64 v[214:215], s[68:69], 0, v[132:133]
	s_add_i32 m0, s70, 0x2000
	s_nop 0
	global_load_lds_dwordx4 v[214:215], off
	v_lshl_add_u64 v[214:215], s[46:47], 0, v[130:131]
	s_mov_b32 m0, s29
	s_nop 0
	global_load_lds_dwordx4 v[214:215], off
	s_mov_b32 m0, s52
	s_nop 0
	global_load_lds_dwordx4 v[216:217], off
	s_waitcnt vmcnt(8)
	s_waitcnt lgkmcnt(0)
	s_barrier
	s_setprio 1
	v_mfma_f32_16x16x32_bf16 v[62:65], v[144:147], v[176:179], v[62:65]
	v_mfma_f32_16x16x32_bf16 v[58:61], v[152:155], v[176:179], v[58:61]
	v_mfma_f32_16x16x32_bf16 v[54:57], v[144:147], v[184:187], v[54:57]
	v_mfma_f32_16x16x32_bf16 v[46:49], v[152:155], v[184:187], v[46:49]
	v_mfma_f32_16x16x32_bf16 v[38:41], v[144:147], v[196:199], v[38:41]
	v_mfma_f32_16x16x32_bf16 v[30:33], v[152:155], v[196:199], v[30:33]
	v_mfma_f32_16x16x32_bf16 v[22:25], v[144:147], v[204:207], v[22:25]
	v_mfma_f32_16x16x32_bf16 v[14:17], v[152:155], v[204:207], v[14:17]
	v_mfma_f32_16x16x32_bf16 v[62:65], v[148:151], v[180:183], v[62:65]
	v_mfma_f32_16x16x32_bf16 v[58:61], v[156:159], v[180:183], v[58:61]
	v_mfma_f32_16x16x32_bf16 v[54:57], v[148:151], v[188:191], v[54:57]
	v_mfma_f32_16x16x32_bf16 v[46:49], v[156:159], v[188:191], v[46:49]
	v_mfma_f32_16x16x32_bf16 v[38:41], v[148:151], v[200:203], v[38:41]
	v_mfma_f32_16x16x32_bf16 v[30:33], v[156:159], v[200:203], v[30:33]
	v_mfma_f32_16x16x32_bf16 v[22:25], v[148:151], v[208:211], v[22:25]
	v_mfma_f32_16x16x32_bf16 v[14:17], v[156:159], v[208:211], v[14:17]
	v_mfma_f32_16x16x32_bf16 v[50:53], v[160:163], v[176:179], v[50:53]
	v_mfma_f32_16x16x32_bf16 v[42:45], v[168:171], v[176:179], v[42:45]
	v_mfma_f32_16x16x32_bf16 v[34:37], v[160:163], v[184:187], v[34:37]
	v_mfma_f32_16x16x32_bf16 v[26:29], v[168:171], v[184:187], v[26:29]
	v_mfma_f32_16x16x32_bf16 v[18:21], v[160:163], v[196:199], v[18:21]
	v_mfma_f32_16x16x32_bf16 v[10:13], v[168:171], v[196:199], v[10:13]
	v_mfma_f32_16x16x32_bf16 v[6:9], v[160:163], v[204:207], v[6:9]
	v_mfma_f32_16x16x32_bf16 v[2:5], v[168:171], v[204:207], v[2:5]
	v_mfma_f32_16x16x32_bf16 v[50:53], v[164:167], v[180:183], v[50:53]
	v_mfma_f32_16x16x32_bf16 v[42:45], v[172:175], v[180:183], v[42:45]
	v_mfma_f32_16x16x32_bf16 v[34:37], v[164:167], v[188:191], v[34:37]
	v_mfma_f32_16x16x32_bf16 v[26:29], v[172:175], v[188:191], v[26:29]
	v_mfma_f32_16x16x32_bf16 v[18:21], v[164:167], v[200:203], v[18:21]
	v_mfma_f32_16x16x32_bf16 v[10:13], v[172:175], v[200:203], v[10:13]
	v_mfma_f32_16x16x32_bf16 v[6:9], v[164:167], v[208:211], v[6:9]
	v_mfma_f32_16x16x32_bf16 v[2:5], v[172:175], v[208:211], v[2:5]
	s_setprio 0
	s_barrier
	s_add_i32 s68, 0, 0x18000
	s_add_i32 s69, 0, 0x1c000
	v_add_u32_e32 v156, s68, v139
	v_add_u32_e32 v172, s69, v139
	ds_read_b128 v[144:147], v156
	ds_read_b128 v[148:151], v156 offset:1024
	ds_read_b128 v[152:155], v156 offset:2048
	ds_read_b128 v[156:159], v156 offset:3072
	ds_read_b128 v[160:163], v172
	ds_read_b128 v[164:167], v172 offset:1024
	ds_read_b128 v[168:171], v172 offset:2048
	ds_read_b128 v[172:175], v172 offset:3072
	s_add_u32 s46, s46, 0x100000
	s_addc_u32 s47, s47, 0
	s_mov_b32 m0, s53
	v_lshl_add_u64 v[218:219], s[46:47], 0, v[130:131]
	ds_read_b128 v[176:179], v143 offset:32768
	ds_read_b128 v[180:183], v143 offset:33792
	ds_read_b128 v[184:187], v143 offset:34816
	ds_read_b128 v[188:191], v143 offset:35840
	ds_read_b128 v[196:199], v143 offset:36864
	ds_read_b128 v[200:203], v143 offset:37888
	ds_read_b128 v[204:207], v143 offset:38912
	ds_read_b128 v[208:211], v143 offset:39936
	global_load_lds_dwordx4 v[218:219], off
	v_lshl_add_u64 v[218:219], s[46:47], 0, v[132:133]
	s_mov_b32 m0, s54
	s_nop 0
	global_load_lds_dwordx4 v[218:219], off
	s_waitcnt vmcnt(8)
	s_waitcnt lgkmcnt(0)
	s_barrier
	s_setprio 1
	v_mfma_f32_16x16x32_bf16 v[126:129], v[144:147], v[176:179], v[126:129]
	v_mfma_f32_16x16x32_bf16 v[122:125], v[152:155], v[176:179], v[122:125]
	v_mfma_f32_16x16x32_bf16 v[118:121], v[144:147], v[184:187], v[118:121]
	v_mfma_f32_16x16x32_bf16 v[110:113], v[152:155], v[184:187], v[110:113]
	v_mfma_f32_16x16x32_bf16 v[102:105], v[144:147], v[196:199], v[102:105]
	v_mfma_f32_16x16x32_bf16 v[94:97], v[152:155], v[196:199], v[94:97]
	v_mfma_f32_16x16x32_bf16 v[86:89], v[144:147], v[204:207], v[86:89]
	v_mfma_f32_16x16x32_bf16 v[78:81], v[152:155], v[204:207], v[78:81]
	v_mfma_f32_16x16x32_bf16 v[126:129], v[148:151], v[180:183], v[126:129]
	v_mfma_f32_16x16x32_bf16 v[122:125], v[156:159], v[180:183], v[122:125]
	v_mfma_f32_16x16x32_bf16 v[118:121], v[148:151], v[188:191], v[118:121]
	v_mfma_f32_16x16x32_bf16 v[110:113], v[156:159], v[188:191], v[110:113]
	v_mfma_f32_16x16x32_bf16 v[102:105], v[148:151], v[200:203], v[102:105]
	v_mfma_f32_16x16x32_bf16 v[94:97], v[156:159], v[200:203], v[94:97]
	v_mfma_f32_16x16x32_bf16 v[86:89], v[148:151], v[208:211], v[86:89]
	v_mfma_f32_16x16x32_bf16 v[78:81], v[156:159], v[208:211], v[78:81]
	v_mfma_f32_16x16x32_bf16 v[114:117], v[160:163], v[176:179], v[114:117]
	v_mfma_f32_16x16x32_bf16 v[106:109], v[168:171], v[176:179], v[106:109]
	v_mfma_f32_16x16x32_bf16 v[98:101], v[160:163], v[184:187], v[98:101]
	v_mfma_f32_16x16x32_bf16 v[90:93], v[168:171], v[184:187], v[90:93]
	v_mfma_f32_16x16x32_bf16 v[82:85], v[160:163], v[196:199], v[82:85]
	v_mfma_f32_16x16x32_bf16 v[74:77], v[168:171], v[196:199], v[74:77]
	v_mfma_f32_16x16x32_bf16 v[70:73], v[160:163], v[204:207], v[70:73]
	v_mfma_f32_16x16x32_bf16 v[66:69], v[168:171], v[204:207], v[66:69]
	v_mfma_f32_16x16x32_bf16 v[114:117], v[164:167], v[180:183], v[114:117]
	v_mfma_f32_16x16x32_bf16 v[106:109], v[172:175], v[180:183], v[106:109]
	v_mfma_f32_16x16x32_bf16 v[98:101], v[164:167], v[188:191], v[98:101]
	v_mfma_f32_16x16x32_bf16 v[90:93], v[172:175], v[188:191], v[90:93]
	v_mfma_f32_16x16x32_bf16 v[82:85], v[164:167], v[200:203], v[82:85]
	v_mfma_f32_16x16x32_bf16 v[74:77], v[172:175], v[200:203], v[74:77]
	v_mfma_f32_16x16x32_bf16 v[70:73], v[164:167], v[208:211], v[70:73]
	v_mfma_f32_16x16x32_bf16 v[66:69], v[172:175], v[208:211], v[66:69]
	s_setprio 0
	s_barrier
	s_add_i32 s46, s68, s51
	v_lshl_add_u64 v[192:193], v[192:193], 0, s[10:11]
	s_mov_b32 m0, s46
	ds_read_b128 v[176:179], v143 offset:49152
	ds_read_b128 v[180:183], v143 offset:50176
	ds_read_b128 v[184:187], v143 offset:51200
	ds_read_b128 v[188:191], v143 offset:52224
	ds_read_b128 v[196:199], v143 offset:53248
	ds_read_b128 v[200:203], v143 offset:54272
	ds_read_b128 v[204:207], v143 offset:55296
	ds_read_b128 v[208:211], v143 offset:56320
	global_load_lds_dwordx4 v[192:193], off
	s_add_i32 m0, s46, 0x2000
	s_add_u32 s42, s42, 0x100080
	v_lshl_add_u64 v[192:193], v[212:213], 0, s[10:11]
	s_addc_u32 s43, s43, 0
	s_add_i32 s46, s69, s51
	global_load_lds_dwordx4 v[192:193], off
	v_lshl_add_u64 v[192:193], s[42:43], 0, v[130:131]
	s_mov_b32 m0, s46
	s_nop 0
	global_load_lds_dwordx4 v[192:193], off
	v_lshl_add_u64 v[192:193], s[42:43], 0, v[132:133]
	s_add_i32 m0, s46, 0x2000
	s_nop 0
	global_load_lds_dwordx4 v[192:193], off
	v_lshl_add_u64 v[192:193], v[214:215], 0, s[10:11]
	s_mov_b32 m0, s56
	s_nop 0
	global_load_lds_dwordx4 v[192:193], off
	v_lshl_add_u64 v[192:193], v[216:217], 0, s[10:11]
	s_mov_b32 m0, s57
	s_nop 0
	global_load_lds_dwordx4 v[192:193], off
	s_waitcnt vmcnt(8)
	s_waitcnt lgkmcnt(0)
	s_barrier
	s_setprio 1
	v_mfma_f32_16x16x32_bf16 v[62:65], v[144:147], v[176:179], v[62:65]
	v_mfma_f32_16x16x32_bf16 v[58:61], v[152:155], v[176:179], v[58:61]
	v_mfma_f32_16x16x32_bf16 v[54:57], v[144:147], v[184:187], v[54:57]
	v_mfma_f32_16x16x32_bf16 v[46:49], v[152:155], v[184:187], v[46:49]
	v_mfma_f32_16x16x32_bf16 v[38:41], v[144:147], v[196:199], v[38:41]
	v_mfma_f32_16x16x32_bf16 v[30:33], v[152:155], v[196:199], v[30:33]
	v_mfma_f32_16x16x32_bf16 v[22:25], v[144:147], v[204:207], v[22:25]
	v_mfma_f32_16x16x32_bf16 v[14:17], v[152:155], v[204:207], v[14:17]
	v_mfma_f32_16x16x32_bf16 v[62:65], v[148:151], v[180:183], v[62:65]
	v_mfma_f32_16x16x32_bf16 v[58:61], v[156:159], v[180:183], v[58:61]
	v_mfma_f32_16x16x32_bf16 v[54:57], v[148:151], v[188:191], v[54:57]
	v_mfma_f32_16x16x32_bf16 v[46:49], v[156:159], v[188:191], v[46:49]
	v_mfma_f32_16x16x32_bf16 v[38:41], v[148:151], v[200:203], v[38:41]
	v_mfma_f32_16x16x32_bf16 v[30:33], v[156:159], v[200:203], v[30:33]
	v_mfma_f32_16x16x32_bf16 v[22:25], v[148:151], v[208:211], v[22:25]
	v_mfma_f32_16x16x32_bf16 v[14:17], v[156:159], v[208:211], v[14:17]
	v_mfma_f32_16x16x32_bf16 v[50:53], v[160:163], v[176:179], v[50:53]
	v_mfma_f32_16x16x32_bf16 v[42:45], v[168:171], v[176:179], v[42:45]
	v_mfma_f32_16x16x32_bf16 v[34:37], v[160:163], v[184:187], v[34:37]
	v_mfma_f32_16x16x32_bf16 v[26:29], v[168:171], v[184:187], v[26:29]
	v_mfma_f32_16x16x32_bf16 v[18:21], v[160:163], v[196:199], v[18:21]
	v_mfma_f32_16x16x32_bf16 v[10:13], v[168:171], v[196:199], v[10:13]
	v_mfma_f32_16x16x32_bf16 v[6:9], v[160:163], v[204:207], v[6:9]
	v_mfma_f32_16x16x32_bf16 v[2:5], v[168:171], v[204:207], v[2:5]
	v_mfma_f32_16x16x32_bf16 v[50:53], v[164:167], v[180:183], v[50:53]
	v_mfma_f32_16x16x32_bf16 v[42:45], v[172:175], v[180:183], v[42:45]
	v_mfma_f32_16x16x32_bf16 v[34:37], v[164:167], v[188:191], v[34:37]
	v_mfma_f32_16x16x32_bf16 v[26:29], v[172:175], v[188:191], v[26:29]
	v_mfma_f32_16x16x32_bf16 v[18:21], v[164:167], v[200:203], v[18:21]
	v_mfma_f32_16x16x32_bf16 v[10:13], v[172:175], v[200:203], v[10:13]
	v_mfma_f32_16x16x32_bf16 v[6:9], v[164:167], v[208:211], v[6:9]
	v_mfma_f32_16x16x32_bf16 v[2:5], v[172:175], v[208:211], v[2:5]
	s_setprio 0
	s_barrier
	s_add_i32 s67, s67, 2
	s_add_u32 s40, s40, 0x100
	s_addc_u32 s41, s41, 0
	s_add_u32 s65, s65, 0x100
	s_addc_u32 s66, s66, 0
	s_cmp_gt_u32 s67, 61
	s_cbranch_scc0 .LBB0_335
	s_and_b64 vcc, exec, s[12:13]
	s_cbranch_vccz .LBB0_338
	s_barrier

.LBB0_657:
	ds_read_b128 v[158:161], v155
	ds_read_b128 v[162:165], v155 offset:1024
	ds_read_b128 v[166:169], v155 offset:2048
	ds_read_b128 v[170:173], v155 offset:3072
	ds_read_b128 v[174:177], v156
	ds_read_b128 v[178:181], v156 offset:1024
	ds_read_b128 v[182:185], v156 offset:2048
	ds_read_b128 v[186:189], v156 offset:3072
	s_add_u32 s28, s26, 0xfff00080
	s_addc_u32 s29, s27, -1
	s_cmp_eq_u32 s58, 60
	s_cselect_b32 s31, s21, s29
	s_cselect_b32 s30, s54, s28
	s_cselect_b32 s29, s19, s57
	s_cselect_b32 s28, s55, s56
	v_lshl_add_u64 v[224:225], s[26:27], 0, v[138:139]
	s_add_i32 m0, s17, 0xc000
	ds_read_b128 v[190:193], v157
	ds_read_b128 v[196:199], v157 offset:1024
	ds_read_b128 v[200:203], v157 offset:2048
	ds_read_b128 v[204:207], v157 offset:3072
	ds_read_b128 v[208:211], v157 offset:4096
	ds_read_b128 v[212:215], v157 offset:5120
	ds_read_b128 v[216:219], v157 offset:6144
	ds_read_b128 v[220:223], v157 offset:7168
	global_load_lds_dwordx4 v[224:225], off
	v_lshl_add_u64 v[224:225], s[26:27], 0, v[140:141]
	s_add_i32 m0, s17, 0xe000
	s_nop 0
	global_load_lds_dwordx4 v[224:225], off
	s_waitcnt vmcnt(8)
	s_waitcnt lgkmcnt(0)
	s_barrier
	s_setprio 1
	v_mfma_f32_16x16x32_bf16 v[126:129], v[158:161], v[190:193], v[126:129]
	v_mfma_f32_16x16x32_bf16 v[122:125], v[166:169], v[190:193], v[122:125]
	v_mfma_f32_16x16x32_bf16 v[118:121], v[158:161], v[200:203], v[118:121]
	v_mfma_f32_16x16x32_bf16 v[114:117], v[166:169], v[200:203], v[114:117]
	v_mfma_f32_16x16x32_bf16 v[102:105], v[158:161], v[208:211], v[102:105]
	v_mfma_f32_16x16x32_bf16 v[98:101], v[166:169], v[208:211], v[98:101]
	v_mfma_f32_16x16x32_bf16 v[86:89], v[158:161], v[216:219], v[86:89]
	v_mfma_f32_16x16x32_bf16 v[82:85], v[166:169], v[216:219], v[82:85]
	v_mfma_f32_16x16x32_bf16 v[126:129], v[162:165], v[196:199], v[126:129]
	v_mfma_f32_16x16x32_bf16 v[122:125], v[170:173], v[196:199], v[122:125]
	v_mfma_f32_16x16x32_bf16 v[118:121], v[162:165], v[204:207], v[118:121]
	v_mfma_f32_16x16x32_bf16 v[114:117], v[170:173], v[204:207], v[114:117]
	v_mfma_f32_16x16x32_bf16 v[102:105], v[162:165], v[212:215], v[102:105]
	v_mfma_f32_16x16x32_bf16 v[98:101], v[170:173], v[212:215], v[98:101]
	v_mfma_f32_16x16x32_bf16 v[86:89], v[162:165], v[220:223], v[86:89]
	v_mfma_f32_16x16x32_bf16 v[82:85], v[170:173], v[220:223], v[82:85]
	v_mfma_f32_16x16x32_bf16 v[110:113], v[174:177], v[190:193], v[110:113]
	v_mfma_f32_16x16x32_bf16 v[106:109], v[182:185], v[190:193], v[106:109]
	v_mfma_f32_16x16x32_bf16 v[94:97], v[174:177], v[200:203], v[94:97]
	v_mfma_f32_16x16x32_bf16 v[90:93], v[182:185], v[200:203], v[90:93]
	v_mfma_f32_16x16x32_bf16 v[78:81], v[174:177], v[208:211], v[78:81]
	v_mfma_f32_16x16x32_bf16 v[74:77], v[182:185], v[208:211], v[74:77]
	v_mfma_f32_16x16x32_bf16 v[70:73], v[174:177], v[216:219], v[70:73]
	v_mfma_f32_16x16x32_bf16 v[66:69], v[182:185], v[216:219], v[66:69]
	v_mfma_f32_16x16x32_bf16 v[110:113], v[178:181], v[196:199], v[110:113]
	v_mfma_f32_16x16x32_bf16 v[106:109], v[186:189], v[196:199], v[106:109]
	v_mfma_f32_16x16x32_bf16 v[94:97], v[178:181], v[204:207], v[94:97]
	v_mfma_f32_16x16x32_bf16 v[90:93], v[186:189], v[204:207], v[90:93]
	v_mfma_f32_16x16x32_bf16 v[78:81], v[178:181], v[212:215], v[78:81]
	v_mfma_f32_16x16x32_bf16 v[74:77], v[186:189], v[212:215], v[74:77]
	v_mfma_f32_16x16x32_bf16 v[70:73], v[178:181], v[220:223], v[70:73]
	v_mfma_f32_16x16x32_bf16 v[66:69], v[186:189], v[220:223], v[66:69]
	s_setprio 0
	s_barrier
	s_add_i32 s59, s50, s41
	v_lshl_add_u64 v[224:225], s[28:29], 0, v[134:135]
	s_mov_b32 m0, s59
	ds_read_b128 v[190:193], v157 offset:16384
	ds_read_b128 v[196:199], v157 offset:17408
	ds_read_b128 v[200:203], v157 offset:18432
	ds_read_b128 v[204:207], v157 offset:19456
	ds_read_b128 v[208:211], v157 offset:20480
	ds_read_b128 v[212:215], v157 offset:21504
	ds_read_b128 v[216:219], v157 offset:22528
	ds_read_b128 v[220:223], v157 offset:23552
	global_load_lds_dwordx4 v[224:225], off
	s_add_i32 m0, s59, 0x2000
	s_add_u32 s60, s28, 0x100000
	v_lshl_add_u64 v[226:227], s[28:29], 0, v[136:137]
	s_addc_u32 s61, s29, 0
	s_add_i32 s59, s51, s41
	global_load_lds_dwordx4 v[226:227], off
	v_lshl_add_u64 v[228:229], s[60:61], 0, v[134:135]
	s_mov_b32 m0, s59
	v_lshl_add_u64 v[230:231], s[30:31], 0, v[132:133]
	global_load_lds_dwordx4 v[228:229], off
	v_lshl_add_u64 v[228:229], s[60:61], 0, v[136:137]
	s_add_i32 m0, s59, 0x2000
	s_nop 0
	global_load_lds_dwordx4 v[228:229], off
	v_lshl_add_u64 v[228:229], s[30:31], 0, v[130:131]
	s_mov_b32 m0, s17
	s_nop 0
	global_load_lds_dwordx4 v[228:229], off
	s_mov_b32 m0, s42
	s_nop 0
	global_load_lds_dwordx4 v[230:231], off
	s_waitcnt vmcnt(8)
	s_waitcnt lgkmcnt(0)
	s_barrier
	s_setprio 1
	v_mfma_f32_16x16x32_bf16 v[62:65], v[158:161], v[190:193], v[62:65]
	v_mfma_f32_16x16x32_bf16 v[58:61], v[166:169], v[190:193], v[58:61]
	v_mfma_f32_16x16x32_bf16 v[54:57], v[158:161], v[200:203], v[54:57]
	v_mfma_f32_16x16x32_bf16 v[50:53], v[166:169], v[200:203], v[50:53]
	v_mfma_f32_16x16x32_bf16 v[38:41], v[158:161], v[208:211], v[38:41]
	v_mfma_f32_16x16x32_bf16 v[34:37], v[166:169], v[208:211], v[34:37]
	v_mfma_f32_16x16x32_bf16 v[22:25], v[158:161], v[216:219], v[22:25]
	v_mfma_f32_16x16x32_bf16 v[18:21], v[166:169], v[216:219], v[18:21]
	v_mfma_f32_16x16x32_bf16 v[62:65], v[162:165], v[196:199], v[62:65]
	v_mfma_f32_16x16x32_bf16 v[58:61], v[170:173], v[196:199], v[58:61]
	v_mfma_f32_16x16x32_bf16 v[54:57], v[162:165], v[204:207], v[54:57]
	v_mfma_f32_16x16x32_bf16 v[50:53], v[170:173], v[204:207], v[50:53]
	v_mfma_f32_16x16x32_bf16 v[38:41], v[162:165], v[212:215], v[38:41]
	v_mfma_f32_16x16x32_bf16 v[34:37], v[170:173], v[212:215], v[34:37]
	v_mfma_f32_16x16x32_bf16 v[22:25], v[162:165], v[220:223], v[22:25]
	v_mfma_f32_16x16x32_bf16 v[18:21], v[170:173], v[220:223], v[18:21]
	v_mfma_f32_16x16x32_bf16 v[46:49], v[174:177], v[190:193], v[46:49]
	v_mfma_f32_16x16x32_bf16 v[42:45], v[182:185], v[190:193], v[42:45]
	v_mfma_f32_16x16x32_bf16 v[30:33], v[174:177], v[200:203], v[30:33]
	v_mfma_f32_16x16x32_bf16 v[26:29], v[182:185], v[200:203], v[26:29]
	v_mfma_f32_16x16x32_bf16 v[14:17], v[174:177], v[208:211], v[14:17]
	v_mfma_f32_16x16x32_bf16 v[10:13], v[182:185], v[208:211], v[10:13]
	v_mfma_f32_16x16x32_bf16 v[6:9], v[174:177], v[216:219], v[6:9]
	v_mfma_f32_16x16x32_bf16 v[2:5], v[182:185], v[216:219], v[2:5]
	v_mfma_f32_16x16x32_bf16 v[46:49], v[178:181], v[196:199], v[46:49]
	v_mfma_f32_16x16x32_bf16 v[42:45], v[186:189], v[196:199], v[42:45]
	v_mfma_f32_16x16x32_bf16 v[30:33], v[178:181], v[204:207], v[30:33]
	v_mfma_f32_16x16x32_bf16 v[26:29], v[186:189], v[204:207], v[26:29]
	v_mfma_f32_16x16x32_bf16 v[14:17], v[178:181], v[212:215], v[14:17]
	v_mfma_f32_16x16x32_bf16 v[10:13], v[186:189], v[212:215], v[10:13]
	v_mfma_f32_16x16x32_bf16 v[6:9], v[178:181], v[220:223], v[6:9]
	v_mfma_f32_16x16x32_bf16 v[2:5], v[186:189], v[220:223], v[2:5]
	s_setprio 0
	s_barrier
	s_add_i32 s59, 0, 0x18000
	s_add_i32 s60, 0, 0x1c000
	v_add_u32_e32 v170, s59, v153
	v_add_u32_e32 v186, s60, v153
	ds_read_b128 v[158:161], v170
	ds_read_b128 v[162:165], v170 offset:1024
	ds_read_b128 v[166:169], v170 offset:2048
	ds_read_b128 v[170:173], v170 offset:3072
	ds_read_b128 v[174:177], v186
	ds_read_b128 v[178:181], v186 offset:1024
	ds_read_b128 v[182:185], v186 offset:2048
	ds_read_b128 v[186:189], v186 offset:3072
	s_add_u32 s30, s30, 0x100000
	s_addc_u32 s31, s31, 0
	s_mov_b32 m0, s43
	v_lshl_add_u64 v[232:233], s[30:31], 0, v[130:131]
	ds_read_b128 v[190:193], v157 offset:32768
	ds_read_b128 v[196:199], v157 offset:33792
	ds_read_b128 v[200:203], v157 offset:34816
	ds_read_b128 v[204:207], v157 offset:35840
	ds_read_b128 v[208:211], v157 offset:36864
	ds_read_b128 v[212:215], v157 offset:37888
	ds_read_b128 v[216:219], v157 offset:38912
	ds_read_b128 v[220:223], v157 offset:39936
	global_load_lds_dwordx4 v[232:233], off
	v_lshl_add_u64 v[232:233], s[30:31], 0, v[132:133]
	s_mov_b32 m0, s45
	s_nop 0
	global_load_lds_dwordx4 v[232:233], off
	s_waitcnt vmcnt(8)
	s_waitcnt lgkmcnt(0)
	s_barrier
	s_setprio 1
	v_mfma_f32_16x16x32_bf16 v[126:129], v[158:161], v[190:193], v[126:129]
	v_mfma_f32_16x16x32_bf16 v[122:125], v[166:169], v[190:193], v[122:125]
	v_mfma_f32_16x16x32_bf16 v[118:121], v[158:161], v[200:203], v[118:121]
	v_mfma_f32_16x16x32_bf16 v[114:117], v[166:169], v[200:203], v[114:117]
	v_mfma_f32_16x16x32_bf16 v[102:105], v[158:161], v[208:211], v[102:105]
	v_mfma_f32_16x16x32_bf16 v[98:101], v[166:169], v[208:211], v[98:101]
	v_mfma_f32_16x16x32_bf16 v[86:89], v[158:161], v[216:219], v[86:89]
	v_mfma_f32_16x16x32_bf16 v[82:85], v[166:169], v[216:219], v[82:85]
	v_mfma_f32_16x16x32_bf16 v[126:129], v[162:165], v[196:199], v[126:129]
	v_mfma_f32_16x16x32_bf16 v[122:125], v[170:173], v[196:199], v[122:125]
	v_mfma_f32_16x16x32_bf16 v[118:121], v[162:165], v[204:207], v[118:121]
	v_mfma_f32_16x16x32_bf16 v[114:117], v[170:173], v[204:207], v[114:117]
	v_mfma_f32_16x16x32_bf16 v[102:105], v[162:165], v[212:215], v[102:105]
	v_mfma_f32_16x16x32_bf16 v[98:101], v[170:173], v[212:215], v[98:101]
	v_mfma_f32_16x16x32_bf16 v[86:89], v[162:165], v[220:223], v[86:89]
	v_mfma_f32_16x16x32_bf16 v[82:85], v[170:173], v[220:223], v[82:85]
	v_mfma_f32_16x16x32_bf16 v[110:113], v[174:177], v[190:193], v[110:113]
	v_mfma_f32_16x16x32_bf16 v[106:109], v[182:185], v[190:193], v[106:109]
	v_mfma_f32_16x16x32_bf16 v[94:97], v[174:177], v[200:203], v[94:97]
	v_mfma_f32_16x16x32_bf16 v[90:93], v[182:185], v[200:203], v[90:93]
	v_mfma_f32_16x16x32_bf16 v[78:81], v[174:177], v[208:211], v[78:81]
	v_mfma_f32_16x16x32_bf16 v[74:77], v[182:185], v[208:211], v[74:77]
	v_mfma_f32_16x16x32_bf16 v[70:73], v[174:177], v[216:219], v[70:73]
	v_mfma_f32_16x16x32_bf16 v[66:69], v[182:185], v[216:219], v[66:69]
	v_mfma_f32_16x16x32_bf16 v[110:113], v[178:181], v[196:199], v[110:113]
	v_mfma_f32_16x16x32_bf16 v[106:109], v[186:189], v[196:199], v[106:109]
	v_mfma_f32_16x16x32_bf16 v[94:97], v[178:181], v[204:207], v[94:97]
	v_mfma_f32_16x16x32_bf16 v[90:93], v[186:189], v[204:207], v[90:93]
	v_mfma_f32_16x16x32_bf16 v[78:81], v[178:181], v[212:215], v[78:81]
	v_mfma_f32_16x16x32_bf16 v[74:77], v[186:189], v[212:215], v[74:77]
	v_mfma_f32_16x16x32_bf16 v[70:73], v[178:181], v[220:223], v[70:73]
	v_mfma_f32_16x16x32_bf16 v[66:69], v[186:189], v[220:223], v[66:69]
	s_setprio 0
	s_barrier
	s_add_i32 s30, s59, s41
	v_lshl_add_u64 v[224:225], v[224:225], 0, s[12:13]
	s_mov_b32 m0, s30
	ds_read_b128 v[190:193], v157 offset:49152
	ds_read_b128 v[196:199], v157 offset:50176
	ds_read_b128 v[200:203], v157 offset:51200
	ds_read_b128 v[204:207], v157 offset:52224
	ds_read_b128 v[208:211], v157 offset:53248
	ds_read_b128 v[212:215], v157 offset:54272
	ds_read_b128 v[216:219], v157 offset:55296
	ds_read_b128 v[220:223], v157 offset:56320
	global_load_lds_dwordx4 v[224:225], off
	s_add_i32 m0, s30, 0x2000
	s_add_u32 s28, s28, 0x100080
	v_lshl_add_u64 v[224:225], v[226:227], 0, s[12:13]
	s_addc_u32 s29, s29, 0
	s_add_i32 s30, s60, s41
	global_load_lds_dwordx4 v[224:225], off
	v_lshl_add_u64 v[224:225], s[28:29], 0, v[134:135]
	s_mov_b32 m0, s30
	s_nop 0
	global_load_lds_dwordx4 v[224:225], off
	v_lshl_add_u64 v[224:225], s[28:29], 0, v[136:137]
	s_add_i32 m0, s30, 0x2000
	s_nop 0
	global_load_lds_dwordx4 v[224:225], off
	v_lshl_add_u64 v[224:225], v[228:229], 0, s[12:13]
	s_mov_b32 m0, s47
	s_nop 0
	global_load_lds_dwordx4 v[224:225], off
	v_lshl_add_u64 v[224:225], v[230:231], 0, s[12:13]
	s_mov_b32 m0, s48
	s_nop 0
	global_load_lds_dwordx4 v[224:225], off
	s_waitcnt vmcnt(8)
	s_waitcnt lgkmcnt(0)
	s_barrier
	s_setprio 1
	v_mfma_f32_16x16x32_bf16 v[62:65], v[158:161], v[190:193], v[62:65]
	v_mfma_f32_16x16x32_bf16 v[58:61], v[166:169], v[190:193], v[58:61]
	v_mfma_f32_16x16x32_bf16 v[54:57], v[158:161], v[200:203], v[54:57]
	v_mfma_f32_16x16x32_bf16 v[50:53], v[166:169], v[200:203], v[50:53]
	v_mfma_f32_16x16x32_bf16 v[38:41], v[158:161], v[208:211], v[38:41]
	v_mfma_f32_16x16x32_bf16 v[34:37], v[166:169], v[208:211], v[34:37]
	v_mfma_f32_16x16x32_bf16 v[22:25], v[158:161], v[216:219], v[22:25]
	v_mfma_f32_16x16x32_bf16 v[18:21], v[166:169], v[216:219], v[18:21]
	v_mfma_f32_16x16x32_bf16 v[62:65], v[162:165], v[196:199], v[62:65]
	v_mfma_f32_16x16x32_bf16 v[58:61], v[170:173], v[196:199], v[58:61]
	v_mfma_f32_16x16x32_bf16 v[54:57], v[162:165], v[204:207], v[54:57]
	v_mfma_f32_16x16x32_bf16 v[50:53], v[170:173], v[204:207], v[50:53]
	v_mfma_f32_16x16x32_bf16 v[38:41], v[162:165], v[212:215], v[38:41]
	v_mfma_f32_16x16x32_bf16 v[34:37], v[170:173], v[212:215], v[34:37]
	v_mfma_f32_16x16x32_bf16 v[22:25], v[162:165], v[220:223], v[22:25]
	v_mfma_f32_16x16x32_bf16 v[18:21], v[170:173], v[220:223], v[18:21]
	v_mfma_f32_16x16x32_bf16 v[46:49], v[174:177], v[190:193], v[46:49]
	v_mfma_f32_16x16x32_bf16 v[42:45], v[182:185], v[190:193], v[42:45]
	v_mfma_f32_16x16x32_bf16 v[30:33], v[174:177], v[200:203], v[30:33]
	v_mfma_f32_16x16x32_bf16 v[26:29], v[182:185], v[200:203], v[26:29]
	v_mfma_f32_16x16x32_bf16 v[14:17], v[174:177], v[208:211], v[14:17]
	v_mfma_f32_16x16x32_bf16 v[10:13], v[182:185], v[208:211], v[10:13]
	v_mfma_f32_16x16x32_bf16 v[6:9], v[174:177], v[216:219], v[6:9]
	v_mfma_f32_16x16x32_bf16 v[2:5], v[182:185], v[216:219], v[2:5]
	v_mfma_f32_16x16x32_bf16 v[46:49], v[178:181], v[196:199], v[46:49]
	v_mfma_f32_16x16x32_bf16 v[42:45], v[186:189], v[196:199], v[42:45]
	v_mfma_f32_16x16x32_bf16 v[30:33], v[178:181], v[204:207], v[30:33]
	v_mfma_f32_16x16x32_bf16 v[26:29], v[186:189], v[204:207], v[26:29]
	v_mfma_f32_16x16x32_bf16 v[14:17], v[178:181], v[212:215], v[14:17]
	v_mfma_f32_16x16x32_bf16 v[10:13], v[186:189], v[212:215], v[10:13]
	v_mfma_f32_16x16x32_bf16 v[6:9], v[178:181], v[220:223], v[6:9]
	v_mfma_f32_16x16x32_bf16 v[2:5], v[186:189], v[220:223], v[2:5]
	s_setprio 0
	s_barrier
	s_add_i32 s58, s58, 2
	s_add_u32 s26, s26, 0x100
	s_addc_u32 s27, s27, 0
	s_add_u32 s56, s56, 0x100
	s_addc_u32 s57, s57, 0
	s_cmp_gt_u32 s58, 61
	s_cbranch_scc0 .LBB0_657
	s_and_b64 vcc, exec, s[14:15]
	s_cbranch_vccz .LBB0_660
	s_barrier

.LBB0_681:
	ds_read_b128 v[152:155], v144
	ds_read_b128 v[156:159], v144 offset:1024
	ds_read_b128 v[160:163], v144 offset:2048
	ds_read_b128 v[164:167], v144 offset:3072
	ds_read_b128 v[168:171], v145
	ds_read_b128 v[172:175], v145 offset:1024
	ds_read_b128 v[176:179], v145 offset:2048
	ds_read_b128 v[180:183], v145 offset:3072
	s_add_u32 s42, s40, 0xfff00080
	s_addc_u32 s43, s41, -1
	s_cmp_eq_u32 s70, 60
	s_cselect_b32 s47, s27, s43
	s_cselect_b32 s46, s66, s42
	s_cselect_b32 s43, s25, s69
	s_cselect_b32 s42, s67, s68
	v_lshl_add_u64 v[192:193], s[40:41], 0, v[134:135]
	s_add_i32 m0, s29, 0xc000
	ds_read_b128 v[184:187], v150
	ds_read_b128 v[188:191], v150 offset:1024
	ds_read_b128 v[196:199], v150 offset:2048
	ds_read_b128 v[200:203], v150 offset:3072
	ds_read_b128 v[204:207], v150 offset:4096
	ds_read_b128 v[208:211], v150 offset:5120
	ds_read_b128 v[212:215], v150 offset:6144
	ds_read_b128 v[216:219], v150 offset:7168
	global_load_lds_dwordx4 v[192:193], off
	v_lshl_add_u64 v[192:193], s[40:41], 0, v[136:137]
	s_add_i32 m0, s29, 0xe000
	s_nop 0
	global_load_lds_dwordx4 v[192:193], off
	s_waitcnt vmcnt(8)
	s_waitcnt lgkmcnt(0)
	s_barrier
	s_setprio 1
	v_mfma_f32_16x16x32_bf16 v[126:129], v[152:155], v[184:187], v[126:129]
	v_mfma_f32_16x16x32_bf16 v[122:125], v[160:163], v[184:187], v[122:125]
	v_mfma_f32_16x16x32_bf16 v[118:121], v[152:155], v[196:199], v[118:121]
	v_mfma_f32_16x16x32_bf16 v[110:113], v[160:163], v[196:199], v[110:113]
	v_mfma_f32_16x16x32_bf16 v[102:105], v[152:155], v[204:207], v[102:105]
	v_mfma_f32_16x16x32_bf16 v[94:97], v[160:163], v[204:207], v[94:97]
	v_mfma_f32_16x16x32_bf16 v[86:89], v[152:155], v[212:215], v[86:89]
	v_mfma_f32_16x16x32_bf16 v[78:81], v[160:163], v[212:215], v[78:81]
	v_mfma_f32_16x16x32_bf16 v[126:129], v[156:159], v[188:191], v[126:129]
	v_mfma_f32_16x16x32_bf16 v[122:125], v[164:167], v[188:191], v[122:125]
	v_mfma_f32_16x16x32_bf16 v[118:121], v[156:159], v[200:203], v[118:121]
	v_mfma_f32_16x16x32_bf16 v[110:113], v[164:167], v[200:203], v[110:113]
	v_mfma_f32_16x16x32_bf16 v[102:105], v[156:159], v[208:211], v[102:105]
	v_mfma_f32_16x16x32_bf16 v[94:97], v[164:167], v[208:211], v[94:97]
	v_mfma_f32_16x16x32_bf16 v[86:89], v[156:159], v[216:219], v[86:89]
	v_mfma_f32_16x16x32_bf16 v[78:81], v[164:167], v[216:219], v[78:81]
	v_mfma_f32_16x16x32_bf16 v[114:117], v[168:171], v[184:187], v[114:117]
	v_mfma_f32_16x16x32_bf16 v[106:109], v[176:179], v[184:187], v[106:109]
	v_mfma_f32_16x16x32_bf16 v[98:101], v[168:171], v[196:199], v[98:101]
	v_mfma_f32_16x16x32_bf16 v[90:93], v[176:179], v[196:199], v[90:93]
	v_mfma_f32_16x16x32_bf16 v[82:85], v[168:171], v[204:207], v[82:85]
	v_mfma_f32_16x16x32_bf16 v[74:77], v[176:179], v[204:207], v[74:77]
	v_mfma_f32_16x16x32_bf16 v[70:73], v[168:171], v[212:215], v[70:73]
	v_mfma_f32_16x16x32_bf16 v[66:69], v[176:179], v[212:215], v[66:69]
	v_mfma_f32_16x16x32_bf16 v[114:117], v[172:175], v[188:191], v[114:117]
	v_mfma_f32_16x16x32_bf16 v[106:109], v[180:183], v[188:191], v[106:109]
	v_mfma_f32_16x16x32_bf16 v[98:101], v[172:175], v[200:203], v[98:101]
	v_mfma_f32_16x16x32_bf16 v[90:93], v[180:183], v[200:203], v[90:93]
	v_mfma_f32_16x16x32_bf16 v[82:85], v[172:175], v[208:211], v[82:85]
	v_mfma_f32_16x16x32_bf16 v[74:77], v[180:183], v[208:211], v[74:77]
	v_mfma_f32_16x16x32_bf16 v[70:73], v[172:175], v[216:219], v[70:73]
	v_mfma_f32_16x16x32_bf16 v[66:69], v[180:183], v[216:219], v[66:69]
	s_setprio 0
	s_barrier
	s_add_i32 s71, s62, s54
	v_lshl_add_u64 v[192:193], s[42:43], 0, v[130:131]
	s_mov_b32 m0, s71
	ds_read_b128 v[184:187], v150 offset:16384
	ds_read_b128 v[188:191], v150 offset:17408
	ds_read_b128 v[196:199], v150 offset:18432
	ds_read_b128 v[200:203], v150 offset:19456
	ds_read_b128 v[204:207], v150 offset:20480
	ds_read_b128 v[208:211], v150 offset:21504
	ds_read_b128 v[212:215], v150 offset:22528
	ds_read_b128 v[216:219], v150 offset:23552
	global_load_lds_dwordx4 v[192:193], off
	s_add_i32 m0, s71, 0x2000
	s_add_u32 s72, s42, 0x100000
	v_lshl_add_u64 v[220:221], s[42:43], 0, v[132:133]
	s_addc_u32 s73, s43, 0
	s_add_i32 s71, s63, s54
	global_load_lds_dwordx4 v[220:221], off
	v_lshl_add_u64 v[222:223], s[72:73], 0, v[130:131]
	s_mov_b32 m0, s71
	v_lshl_add_u64 v[224:225], s[46:47], 0, v[132:133]
	global_load_lds_dwordx4 v[222:223], off
	v_lshl_add_u64 v[222:223], s[72:73], 0, v[132:133]
	s_add_i32 m0, s71, 0x2000
	s_nop 0
	global_load_lds_dwordx4 v[222:223], off
	v_lshl_add_u64 v[222:223], s[46:47], 0, v[130:131]
	s_mov_b32 m0, s29
	s_nop 0
	global_load_lds_dwordx4 v[222:223], off
	s_mov_b32 m0, s55
	s_nop 0
	global_load_lds_dwordx4 v[224:225], off
	s_waitcnt vmcnt(8)
	s_waitcnt lgkmcnt(0)
	s_barrier
	s_setprio 1
	v_mfma_f32_16x16x32_bf16 v[62:65], v[152:155], v[184:187], v[62:65]
	v_mfma_f32_16x16x32_bf16 v[58:61], v[160:163], v[184:187], v[58:61]
	v_mfma_f32_16x16x32_bf16 v[54:57], v[152:155], v[196:199], v[54:57]
	v_mfma_f32_16x16x32_bf16 v[46:49], v[160:163], v[196:199], v[46:49]
	v_mfma_f32_16x16x32_bf16 v[38:41], v[152:155], v[204:207], v[38:41]
	v_mfma_f32_16x16x32_bf16 v[30:33], v[160:163], v[204:207], v[30:33]
	v_mfma_f32_16x16x32_bf16 v[22:25], v[152:155], v[212:215], v[22:25]
	v_mfma_f32_16x16x32_bf16 v[14:17], v[160:163], v[212:215], v[14:17]
	v_mfma_f32_16x16x32_bf16 v[62:65], v[156:159], v[188:191], v[62:65]
	v_mfma_f32_16x16x32_bf16 v[58:61], v[164:167], v[188:191], v[58:61]
	v_mfma_f32_16x16x32_bf16 v[54:57], v[156:159], v[200:203], v[54:57]
	v_mfma_f32_16x16x32_bf16 v[46:49], v[164:167], v[200:203], v[46:49]
	v_mfma_f32_16x16x32_bf16 v[38:41], v[156:159], v[208:211], v[38:41]
	v_mfma_f32_16x16x32_bf16 v[30:33], v[164:167], v[208:211], v[30:33]
	v_mfma_f32_16x16x32_bf16 v[22:25], v[156:159], v[216:219], v[22:25]
	v_mfma_f32_16x16x32_bf16 v[14:17], v[164:167], v[216:219], v[14:17]
	v_mfma_f32_16x16x32_bf16 v[50:53], v[168:171], v[184:187], v[50:53]
	v_mfma_f32_16x16x32_bf16 v[42:45], v[176:179], v[184:187], v[42:45]
	v_mfma_f32_16x16x32_bf16 v[34:37], v[168:171], v[196:199], v[34:37]
	v_mfma_f32_16x16x32_bf16 v[26:29], v[176:179], v[196:199], v[26:29]
	v_mfma_f32_16x16x32_bf16 v[18:21], v[168:171], v[204:207], v[18:21]
	v_mfma_f32_16x16x32_bf16 v[10:13], v[176:179], v[204:207], v[10:13]
	v_mfma_f32_16x16x32_bf16 v[6:9], v[168:171], v[212:215], v[6:9]
	v_mfma_f32_16x16x32_bf16 v[2:5], v[176:179], v[212:215], v[2:5]
	v_mfma_f32_16x16x32_bf16 v[50:53], v[172:175], v[188:191], v[50:53]
	v_mfma_f32_16x16x32_bf16 v[42:45], v[180:183], v[188:191], v[42:45]
	v_mfma_f32_16x16x32_bf16 v[34:37], v[172:175], v[200:203], v[34:37]
	v_mfma_f32_16x16x32_bf16 v[26:29], v[180:183], v[200:203], v[26:29]
	v_mfma_f32_16x16x32_bf16 v[18:21], v[172:175], v[208:211], v[18:21]
	v_mfma_f32_16x16x32_bf16 v[10:13], v[180:183], v[208:211], v[10:13]
	v_mfma_f32_16x16x32_bf16 v[6:9], v[172:175], v[216:219], v[6:9]
	v_mfma_f32_16x16x32_bf16 v[2:5], v[180:183], v[216:219], v[2:5]
	s_setprio 0
	s_barrier
	s_add_i32 s71, 0, 0x18000
	v_add_u32_e32 v151, s71, v142
	s_add_i32 s72, 0, 0x1c000
	ds_read_b128 v[152:155], v151
	ds_read_b128 v[156:159], v151 offset:1024
	ds_read_b128 v[160:163], v151 offset:2048
	ds_read_b128 v[164:167], v151 offset:3072
	v_add_u32_e32 v151, s72, v142
	ds_read_b128 v[168:171], v151
	ds_read_b128 v[172:175], v151 offset:1024
	ds_read_b128 v[176:179], v151 offset:2048
	ds_read_b128 v[180:183], v151 offset:3072
	s_add_u32 s46, s46, 0x100000
	s_addc_u32 s47, s47, 0
	s_mov_b32 m0, s56
	v_lshl_add_u64 v[226:227], s[46:47], 0, v[130:131]
	ds_read_b128 v[184:187], v150 offset:32768
	ds_read_b128 v[188:191], v150 offset:33792
	ds_read_b128 v[196:199], v150 offset:34816
	ds_read_b128 v[200:203], v150 offset:35840
	ds_read_b128 v[204:207], v150 offset:36864
	ds_read_b128 v[208:211], v150 offset:37888
	ds_read_b128 v[212:215], v150 offset:38912
	ds_read_b128 v[216:219], v150 offset:39936
	global_load_lds_dwordx4 v[226:227], off
	v_lshl_add_u64 v[226:227], s[46:47], 0, v[132:133]
	s_mov_b32 m0, s57
	s_nop 0
	global_load_lds_dwordx4 v[226:227], off
	s_waitcnt vmcnt(8)
	s_waitcnt lgkmcnt(0)
	s_barrier
	s_setprio 1
	v_mfma_f32_16x16x32_bf16 v[126:129], v[152:155], v[184:187], v[126:129]
	v_mfma_f32_16x16x32_bf16 v[122:125], v[160:163], v[184:187], v[122:125]
	v_mfma_f32_16x16x32_bf16 v[118:121], v[152:155], v[196:199], v[118:121]
	v_mfma_f32_16x16x32_bf16 v[110:113], v[160:163], v[196:199], v[110:113]
	v_mfma_f32_16x16x32_bf16 v[102:105], v[152:155], v[204:207], v[102:105]
	v_mfma_f32_16x16x32_bf16 v[94:97], v[160:163], v[204:207], v[94:97]
	v_mfma_f32_16x16x32_bf16 v[86:89], v[152:155], v[212:215], v[86:89]
	v_mfma_f32_16x16x32_bf16 v[78:81], v[160:163], v[212:215], v[78:81]
	v_mfma_f32_16x16x32_bf16 v[126:129], v[156:159], v[188:191], v[126:129]
	v_mfma_f32_16x16x32_bf16 v[122:125], v[164:167], v[188:191], v[122:125]
	v_mfma_f32_16x16x32_bf16 v[118:121], v[156:159], v[200:203], v[118:121]
	v_mfma_f32_16x16x32_bf16 v[110:113], v[164:167], v[200:203], v[110:113]
	v_mfma_f32_16x16x32_bf16 v[102:105], v[156:159], v[208:211], v[102:105]
	v_mfma_f32_16x16x32_bf16 v[94:97], v[164:167], v[208:211], v[94:97]
	v_mfma_f32_16x16x32_bf16 v[86:89], v[156:159], v[216:219], v[86:89]
	v_mfma_f32_16x16x32_bf16 v[78:81], v[164:167], v[216:219], v[78:81]
	v_mfma_f32_16x16x32_bf16 v[114:117], v[168:171], v[184:187], v[114:117]
	v_mfma_f32_16x16x32_bf16 v[106:109], v[176:179], v[184:187], v[106:109]
	v_mfma_f32_16x16x32_bf16 v[98:101], v[168:171], v[196:199], v[98:101]
	v_mfma_f32_16x16x32_bf16 v[90:93], v[176:179], v[196:199], v[90:93]
	v_mfma_f32_16x16x32_bf16 v[82:85], v[168:171], v[204:207], v[82:85]
	v_mfma_f32_16x16x32_bf16 v[74:77], v[176:179], v[204:207], v[74:77]
	v_mfma_f32_16x16x32_bf16 v[70:73], v[168:171], v[212:215], v[70:73]
	v_mfma_f32_16x16x32_bf16 v[66:69], v[176:179], v[212:215], v[66:69]
	v_mfma_f32_16x16x32_bf16 v[114:117], v[172:175], v[188:191], v[114:117]
	v_mfma_f32_16x16x32_bf16 v[106:109], v[180:183], v[188:191], v[106:109]
	v_mfma_f32_16x16x32_bf16 v[98:101], v[172:175], v[200:203], v[98:101]
	v_mfma_f32_16x16x32_bf16 v[90:93], v[180:183], v[200:203], v[90:93]
	v_mfma_f32_16x16x32_bf16 v[82:85], v[172:175], v[208:211], v[82:85]
	v_mfma_f32_16x16x32_bf16 v[74:77], v[180:183], v[208:211], v[74:77]
	v_mfma_f32_16x16x32_bf16 v[70:73], v[172:175], v[216:219], v[70:73]
	v_mfma_f32_16x16x32_bf16 v[66:69], v[180:183], v[216:219], v[66:69]
	s_setprio 0
	s_barrier
	s_add_i32 s46, s71, s54
	v_lshl_add_u64 v[192:193], v[192:193], 0, s[10:11]
	s_mov_b32 m0, s46
	ds_read_b128 v[184:187], v150 offset:49152
	ds_read_b128 v[188:191], v150 offset:50176
	ds_read_b128 v[196:199], v150 offset:51200
	ds_read_b128 v[200:203], v150 offset:52224
	ds_read_b128 v[204:207], v150 offset:53248
	ds_read_b128 v[208:211], v150 offset:54272
	ds_read_b128 v[212:215], v150 offset:55296
	ds_read_b128 v[216:219], v150 offset:56320
	global_load_lds_dwordx4 v[192:193], off
	s_add_i32 m0, s46, 0x2000
	s_add_u32 s42, s42, 0x100080
	v_lshl_add_u64 v[192:193], v[220:221], 0, s[10:11]
	s_addc_u32 s43, s43, 0
	s_add_i32 s46, s72, s54
	global_load_lds_dwordx4 v[192:193], off
	v_lshl_add_u64 v[192:193], s[42:43], 0, v[130:131]
	s_mov_b32 m0, s46
	s_nop 0
	global_load_lds_dwordx4 v[192:193], off
	v_lshl_add_u64 v[192:193], s[42:43], 0, v[132:133]
	s_add_i32 m0, s46, 0x2000
	s_nop 0
	global_load_lds_dwordx4 v[192:193], off
	v_lshl_add_u64 v[192:193], v[222:223], 0, s[10:11]
	s_mov_b32 m0, s59
	s_nop 0
	global_load_lds_dwordx4 v[192:193], off
	v_lshl_add_u64 v[192:193], v[224:225], 0, s[10:11]
	s_mov_b32 m0, s60
	s_nop 0
	global_load_lds_dwordx4 v[192:193], off
	s_waitcnt vmcnt(8)
	s_waitcnt lgkmcnt(0)
	s_barrier
	s_setprio 1
	v_mfma_f32_16x16x32_bf16 v[62:65], v[152:155], v[184:187], v[62:65]
	v_mfma_f32_16x16x32_bf16 v[58:61], v[160:163], v[184:187], v[58:61]
	v_mfma_f32_16x16x32_bf16 v[54:57], v[152:155], v[196:199], v[54:57]
	v_mfma_f32_16x16x32_bf16 v[46:49], v[160:163], v[196:199], v[46:49]
	v_mfma_f32_16x16x32_bf16 v[38:41], v[152:155], v[204:207], v[38:41]
	v_mfma_f32_16x16x32_bf16 v[30:33], v[160:163], v[204:207], v[30:33]
	v_mfma_f32_16x16x32_bf16 v[22:25], v[152:155], v[212:215], v[22:25]
	v_mfma_f32_16x16x32_bf16 v[14:17], v[160:163], v[212:215], v[14:17]
	v_mfma_f32_16x16x32_bf16 v[62:65], v[156:159], v[188:191], v[62:65]
	v_mfma_f32_16x16x32_bf16 v[58:61], v[164:167], v[188:191], v[58:61]
	v_mfma_f32_16x16x32_bf16 v[54:57], v[156:159], v[200:203], v[54:57]
	v_mfma_f32_16x16x32_bf16 v[46:49], v[164:167], v[200:203], v[46:49]
	v_mfma_f32_16x16x32_bf16 v[38:41], v[156:159], v[208:211], v[38:41]
	v_mfma_f32_16x16x32_bf16 v[30:33], v[164:167], v[208:211], v[30:33]
	v_mfma_f32_16x16x32_bf16 v[22:25], v[156:159], v[216:219], v[22:25]
	v_mfma_f32_16x16x32_bf16 v[14:17], v[164:167], v[216:219], v[14:17]
	v_mfma_f32_16x16x32_bf16 v[50:53], v[168:171], v[184:187], v[50:53]
	v_mfma_f32_16x16x32_bf16 v[42:45], v[176:179], v[184:187], v[42:45]
	v_mfma_f32_16x16x32_bf16 v[34:37], v[168:171], v[196:199], v[34:37]
	v_mfma_f32_16x16x32_bf16 v[26:29], v[176:179], v[196:199], v[26:29]
	v_mfma_f32_16x16x32_bf16 v[18:21], v[168:171], v[204:207], v[18:21]
	v_mfma_f32_16x16x32_bf16 v[10:13], v[176:179], v[204:207], v[10:13]
	v_mfma_f32_16x16x32_bf16 v[6:9], v[168:171], v[212:215], v[6:9]
	v_mfma_f32_16x16x32_bf16 v[2:5], v[176:179], v[212:215], v[2:5]
	v_mfma_f32_16x16x32_bf16 v[50:53], v[172:175], v[188:191], v[50:53]
	v_mfma_f32_16x16x32_bf16 v[42:45], v[180:183], v[188:191], v[42:45]
	v_mfma_f32_16x16x32_bf16 v[34:37], v[172:175], v[200:203], v[34:37]
	v_mfma_f32_16x16x32_bf16 v[26:29], v[180:183], v[200:203], v[26:29]
	v_mfma_f32_16x16x32_bf16 v[18:21], v[172:175], v[208:211], v[18:21]
	v_mfma_f32_16x16x32_bf16 v[10:13], v[180:183], v[208:211], v[10:13]
	v_mfma_f32_16x16x32_bf16 v[6:9], v[172:175], v[216:219], v[6:9]
	v_mfma_f32_16x16x32_bf16 v[2:5], v[180:183], v[216:219], v[2:5]
	s_setprio 0
	s_barrier
	s_add_i32 s70, s70, 2
	s_add_u32 s40, s40, 0x100
	s_addc_u32 s41, s41, 0
	s_add_u32 s68, s68, 0x100
	s_addc_u32 s69, s69, 0
	s_cmp_gt_u32 s70, 61
	s_cbranch_scc0 .LBB0_681
	s_and_b64 vcc, exec, s[12:13]
	s_cbranch_vccz .LBB0_684
	s_barrier

.LBB0_705:
	ds_read_b128 v[144:147], v139
	ds_read_b128 v[148:151], v139 offset:1024
	ds_read_b128 v[152:155], v139 offset:2048
	ds_read_b128 v[156:159], v139 offset:3072
	ds_read_b128 v[160:163], v140
	ds_read_b128 v[164:167], v140 offset:1024
	ds_read_b128 v[168:171], v140 offset:2048
	ds_read_b128 v[172:175], v140 offset:3072
	s_add_u32 s42, s40, 0xfff00080
	s_addc_u32 s43, s41, -1
	s_cmp_eq_u32 s67, 60
	s_cselect_b32 s47, s27, s43
	s_cselect_b32 s46, s63, s42
	s_cselect_b32 s43, s25, s66
	s_cselect_b32 s42, s64, s65
	v_lshl_add_u64 v[192:193], s[40:41], 0, v[134:135]
	s_add_i32 m0, s29, 0xc000
	ds_read_b128 v[176:179], v142
	ds_read_b128 v[180:183], v142 offset:1024
	ds_read_b128 v[184:187], v142 offset:2048
	ds_read_b128 v[188:191], v142 offset:3072
	ds_read_b128 v[196:199], v142 offset:4096
	ds_read_b128 v[200:203], v142 offset:5120
	ds_read_b128 v[204:207], v142 offset:6144
	ds_read_b128 v[208:211], v142 offset:7168
	global_load_lds_dwordx4 v[192:193], off
	v_lshl_add_u64 v[192:193], s[40:41], 0, v[136:137]
	s_add_i32 m0, s29, 0xe000
	s_nop 0
	global_load_lds_dwordx4 v[192:193], off
	s_waitcnt vmcnt(8)
	s_waitcnt lgkmcnt(0)
	s_barrier
	s_setprio 1
	v_mfma_f32_16x16x32_bf16 v[126:129], v[144:147], v[176:179], v[126:129]
	v_mfma_f32_16x16x32_bf16 v[122:125], v[152:155], v[176:179], v[122:125]
	v_mfma_f32_16x16x32_bf16 v[118:121], v[144:147], v[184:187], v[118:121]
	v_mfma_f32_16x16x32_bf16 v[110:113], v[152:155], v[184:187], v[110:113]
	v_mfma_f32_16x16x32_bf16 v[102:105], v[144:147], v[196:199], v[102:105]
	v_mfma_f32_16x16x32_bf16 v[94:97], v[152:155], v[196:199], v[94:97]
	v_mfma_f32_16x16x32_bf16 v[86:89], v[144:147], v[204:207], v[86:89]
	v_mfma_f32_16x16x32_bf16 v[78:81], v[152:155], v[204:207], v[78:81]
	v_mfma_f32_16x16x32_bf16 v[126:129], v[148:151], v[180:183], v[126:129]
	v_mfma_f32_16x16x32_bf16 v[122:125], v[156:159], v[180:183], v[122:125]
	v_mfma_f32_16x16x32_bf16 v[118:121], v[148:151], v[188:191], v[118:121]
	v_mfma_f32_16x16x32_bf16 v[110:113], v[156:159], v[188:191], v[110:113]
	v_mfma_f32_16x16x32_bf16 v[102:105], v[148:151], v[200:203], v[102:105]
	v_mfma_f32_16x16x32_bf16 v[94:97], v[156:159], v[200:203], v[94:97]
	v_mfma_f32_16x16x32_bf16 v[86:89], v[148:151], v[208:211], v[86:89]
	v_mfma_f32_16x16x32_bf16 v[78:81], v[156:159], v[208:211], v[78:81]
	v_mfma_f32_16x16x32_bf16 v[114:117], v[160:163], v[176:179], v[114:117]
	v_mfma_f32_16x16x32_bf16 v[106:109], v[168:171], v[176:179], v[106:109]
	v_mfma_f32_16x16x32_bf16 v[98:101], v[160:163], v[184:187], v[98:101]
	v_mfma_f32_16x16x32_bf16 v[90:93], v[168:171], v[184:187], v[90:93]
	v_mfma_f32_16x16x32_bf16 v[82:85], v[160:163], v[196:199], v[82:85]
	v_mfma_f32_16x16x32_bf16 v[74:77], v[168:171], v[196:199], v[74:77]
	v_mfma_f32_16x16x32_bf16 v[70:73], v[160:163], v[204:207], v[70:73]
	v_mfma_f32_16x16x32_bf16 v[66:69], v[168:171], v[204:207], v[66:69]
	v_mfma_f32_16x16x32_bf16 v[114:117], v[164:167], v[180:183], v[114:117]
	v_mfma_f32_16x16x32_bf16 v[106:109], v[172:175], v[180:183], v[106:109]
	v_mfma_f32_16x16x32_bf16 v[98:101], v[164:167], v[188:191], v[98:101]
	v_mfma_f32_16x16x32_bf16 v[90:93], v[172:175], v[188:191], v[90:93]
	v_mfma_f32_16x16x32_bf16 v[82:85], v[164:167], v[200:203], v[82:85]
	v_mfma_f32_16x16x32_bf16 v[74:77], v[172:175], v[200:203], v[74:77]
	v_mfma_f32_16x16x32_bf16 v[70:73], v[164:167], v[208:211], v[70:73]
	v_mfma_f32_16x16x32_bf16 v[66:69], v[172:175], v[208:211], v[66:69]
	s_setprio 0
	s_barrier
	s_add_i32 s68, s59, s51
	v_lshl_add_u64 v[192:193], s[42:43], 0, v[130:131]
	s_mov_b32 m0, s68
	ds_read_b128 v[176:179], v142 offset:16384
	ds_read_b128 v[180:183], v142 offset:17408
	ds_read_b128 v[184:187], v142 offset:18432
	ds_read_b128 v[188:191], v142 offset:19456
	ds_read_b128 v[196:199], v142 offset:20480
	ds_read_b128 v[200:203], v142 offset:21504
	ds_read_b128 v[204:207], v142 offset:22528
	ds_read_b128 v[208:211], v142 offset:23552
	global_load_lds_dwordx4 v[192:193], off
	s_add_i32 m0, s68, 0x2000
	s_add_u32 s68, s42, 0x100000
	v_lshl_add_u64 v[212:213], s[42:43], 0, v[132:133]
	s_addc_u32 s69, s43, 0
	s_add_i32 s70, s60, s51
	global_load_lds_dwordx4 v[212:213], off
	v_lshl_add_u64 v[214:215], s[68:69], 0, v[130:131]
	s_mov_b32 m0, s70
	v_lshl_add_u64 v[216:217], s[46:47], 0, v[132:133]
	global_load_lds_dwordx4 v[214:215], off
	v_lshl_add_u64 v[214:215], s[68:69], 0, v[132:133]
	s_add_i32 m0, s70, 0x2000
	s_nop 0
	global_load_lds_dwordx4 v[214:215], off
	v_lshl_add_u64 v[214:215], s[46:47], 0, v[130:131]
	s_mov_b32 m0, s29
	s_nop 0
	global_load_lds_dwordx4 v[214:215], off
	s_mov_b32 m0, s52
	s_nop 0
	global_load_lds_dwordx4 v[216:217], off
	s_waitcnt vmcnt(8)
	s_waitcnt lgkmcnt(0)
	s_barrier
	s_setprio 1
	v_mfma_f32_16x16x32_bf16 v[62:65], v[144:147], v[176:179], v[62:65]
	v_mfma_f32_16x16x32_bf16 v[58:61], v[152:155], v[176:179], v[58:61]
	v_mfma_f32_16x16x32_bf16 v[54:57], v[144:147], v[184:187], v[54:57]
	v_mfma_f32_16x16x32_bf16 v[46:49], v[152:155], v[184:187], v[46:49]
	v_mfma_f32_16x16x32_bf16 v[38:41], v[144:147], v[196:199], v[38:41]
	v_mfma_f32_16x16x32_bf16 v[30:33], v[152:155], v[196:199], v[30:33]
	v_mfma_f32_16x16x32_bf16 v[22:25], v[144:147], v[204:207], v[22:25]
	v_mfma_f32_16x16x32_bf16 v[14:17], v[152:155], v[204:207], v[14:17]
	v_mfma_f32_16x16x32_bf16 v[62:65], v[148:151], v[180:183], v[62:65]
	v_mfma_f32_16x16x32_bf16 v[58:61], v[156:159], v[180:183], v[58:61]
	v_mfma_f32_16x16x32_bf16 v[54:57], v[148:151], v[188:191], v[54:57]
	v_mfma_f32_16x16x32_bf16 v[46:49], v[156:159], v[188:191], v[46:49]
	v_mfma_f32_16x16x32_bf16 v[38:41], v[148:151], v[200:203], v[38:41]
	v_mfma_f32_16x16x32_bf16 v[30:33], v[156:159], v[200:203], v[30:33]
	v_mfma_f32_16x16x32_bf16 v[22:25], v[148:151], v[208:211], v[22:25]
	v_mfma_f32_16x16x32_bf16 v[14:17], v[156:159], v[208:211], v[14:17]
	v_mfma_f32_16x16x32_bf16 v[50:53], v[160:163], v[176:179], v[50:53]
	v_mfma_f32_16x16x32_bf16 v[42:45], v[168:171], v[176:179], v[42:45]
	v_mfma_f32_16x16x32_bf16 v[34:37], v[160:163], v[184:187], v[34:37]
	v_mfma_f32_16x16x32_bf16 v[26:29], v[168:171], v[184:187], v[26:29]
	v_mfma_f32_16x16x32_bf16 v[18:21], v[160:163], v[196:199], v[18:21]
	v_mfma_f32_16x16x32_bf16 v[10:13], v[168:171], v[196:199], v[10:13]
	v_mfma_f32_16x16x32_bf16 v[6:9], v[160:163], v[204:207], v[6:9]
	v_mfma_f32_16x16x32_bf16 v[2:5], v[168:171], v[204:207], v[2:5]
	v_mfma_f32_16x16x32_bf16 v[50:53], v[164:167], v[180:183], v[50:53]
	v_mfma_f32_16x16x32_bf16 v[42:45], v[172:175], v[180:183], v[42:45]
	v_mfma_f32_16x16x32_bf16 v[34:37], v[164:167], v[188:191], v[34:37]
	v_mfma_f32_16x16x32_bf16 v[26:29], v[172:175], v[188:191], v[26:29]
	v_mfma_f32_16x16x32_bf16 v[18:21], v[164:167], v[200:203], v[18:21]
	v_mfma_f32_16x16x32_bf16 v[10:13], v[172:175], v[200:203], v[10:13]
	v_mfma_f32_16x16x32_bf16 v[6:9], v[164:167], v[208:211], v[6:9]
	v_mfma_f32_16x16x32_bf16 v[2:5], v[172:175], v[208:211], v[2:5]
	s_setprio 0
	s_barrier
	s_add_i32 s68, 0, 0x18000
	v_add_u32_e32 v143, s68, v1
	s_add_i32 s69, 0, 0x1c000
	ds_read_b128 v[144:147], v143
	ds_read_b128 v[148:151], v143 offset:1024
	ds_read_b128 v[152:155], v143 offset:2048
	ds_read_b128 v[156:159], v143 offset:3072
	v_add_u32_e32 v143, s69, v1
	ds_read_b128 v[160:163], v143
	ds_read_b128 v[164:167], v143 offset:1024
	ds_read_b128 v[168:171], v143 offset:2048
	ds_read_b128 v[172:175], v143 offset:3072
	s_add_u32 s46, s46, 0x100000
	s_addc_u32 s47, s47, 0
	s_mov_b32 m0, s53
	v_lshl_add_u64 v[218:219], s[46:47], 0, v[130:131]
	ds_read_b128 v[176:179], v142 offset:32768
	ds_read_b128 v[180:183], v142 offset:33792
	ds_read_b128 v[184:187], v142 offset:34816
	ds_read_b128 v[188:191], v142 offset:35840
	ds_read_b128 v[196:199], v142 offset:36864
	ds_read_b128 v[200:203], v142 offset:37888
	ds_read_b128 v[204:207], v142 offset:38912
	ds_read_b128 v[208:211], v142 offset:39936
	global_load_lds_dwordx4 v[218:219], off
	v_lshl_add_u64 v[218:219], s[46:47], 0, v[132:133]
	s_mov_b32 m0, s54
	s_nop 0
	global_load_lds_dwordx4 v[218:219], off
	s_waitcnt vmcnt(8)
	s_waitcnt lgkmcnt(0)
	s_barrier
	s_setprio 1
	v_mfma_f32_16x16x32_bf16 v[126:129], v[144:147], v[176:179], v[126:129]
	v_mfma_f32_16x16x32_bf16 v[122:125], v[152:155], v[176:179], v[122:125]
	v_mfma_f32_16x16x32_bf16 v[118:121], v[144:147], v[184:187], v[118:121]
	v_mfma_f32_16x16x32_bf16 v[110:113], v[152:155], v[184:187], v[110:113]
	v_mfma_f32_16x16x32_bf16 v[102:105], v[144:147], v[196:199], v[102:105]
	v_mfma_f32_16x16x32_bf16 v[94:97], v[152:155], v[196:199], v[94:97]
	v_mfma_f32_16x16x32_bf16 v[86:89], v[144:147], v[204:207], v[86:89]
	v_mfma_f32_16x16x32_bf16 v[78:81], v[152:155], v[204:207], v[78:81]
	v_mfma_f32_16x16x32_bf16 v[126:129], v[148:151], v[180:183], v[126:129]
	v_mfma_f32_16x16x32_bf16 v[122:125], v[156:159], v[180:183], v[122:125]
	v_mfma_f32_16x16x32_bf16 v[118:121], v[148:151], v[188:191], v[118:121]
	v_mfma_f32_16x16x32_bf16 v[110:113], v[156:159], v[188:191], v[110:113]
	v_mfma_f32_16x16x32_bf16 v[102:105], v[148:151], v[200:203], v[102:105]
	v_mfma_f32_16x16x32_bf16 v[94:97], v[156:159], v[200:203], v[94:97]
	v_mfma_f32_16x16x32_bf16 v[86:89], v[148:151], v[208:211], v[86:89]
	v_mfma_f32_16x16x32_bf16 v[78:81], v[156:159], v[208:211], v[78:81]
	v_mfma_f32_16x16x32_bf16 v[114:117], v[160:163], v[176:179], v[114:117]
	v_mfma_f32_16x16x32_bf16 v[106:109], v[168:171], v[176:179], v[106:109]
	v_mfma_f32_16x16x32_bf16 v[98:101], v[160:163], v[184:187], v[98:101]
	v_mfma_f32_16x16x32_bf16 v[90:93], v[168:171], v[184:187], v[90:93]
	v_mfma_f32_16x16x32_bf16 v[82:85], v[160:163], v[196:199], v[82:85]
	v_mfma_f32_16x16x32_bf16 v[74:77], v[168:171], v[196:199], v[74:77]
	v_mfma_f32_16x16x32_bf16 v[70:73], v[160:163], v[204:207], v[70:73]
	v_mfma_f32_16x16x32_bf16 v[66:69], v[168:171], v[204:207], v[66:69]
	v_mfma_f32_16x16x32_bf16 v[114:117], v[164:167], v[180:183], v[114:117]
	v_mfma_f32_16x16x32_bf16 v[106:109], v[172:175], v[180:183], v[106:109]
	v_mfma_f32_16x16x32_bf16 v[98:101], v[164:167], v[188:191], v[98:101]
	v_mfma_f32_16x16x32_bf16 v[90:93], v[172:175], v[188:191], v[90:93]
	v_mfma_f32_16x16x32_bf16 v[82:85], v[164:167], v[200:203], v[82:85]
	v_mfma_f32_16x16x32_bf16 v[74:77], v[172:175], v[200:203], v[74:77]
	v_mfma_f32_16x16x32_bf16 v[70:73], v[164:167], v[208:211], v[70:73]
	v_mfma_f32_16x16x32_bf16 v[66:69], v[172:175], v[208:211], v[66:69]
	s_setprio 0
	s_barrier
	s_add_i32 s46, s68, s51
	v_lshl_add_u64 v[192:193], v[192:193], 0, s[10:11]
	s_mov_b32 m0, s46
	ds_read_b128 v[176:179], v142 offset:49152
	ds_read_b128 v[180:183], v142 offset:50176
	ds_read_b128 v[184:187], v142 offset:51200
	ds_read_b128 v[188:191], v142 offset:52224
	ds_read_b128 v[196:199], v142 offset:53248
	ds_read_b128 v[200:203], v142 offset:54272
	ds_read_b128 v[204:207], v142 offset:55296
	ds_read_b128 v[208:211], v142 offset:56320
	global_load_lds_dwordx4 v[192:193], off
	s_add_i32 m0, s46, 0x2000
	s_add_u32 s42, s42, 0x100080
	v_lshl_add_u64 v[192:193], v[212:213], 0, s[10:11]
	s_addc_u32 s43, s43, 0
	s_add_i32 s46, s69, s51
	global_load_lds_dwordx4 v[192:193], off
	v_lshl_add_u64 v[192:193], s[42:43], 0, v[130:131]
	s_mov_b32 m0, s46
	s_nop 0
	global_load_lds_dwordx4 v[192:193], off
	v_lshl_add_u64 v[192:193], s[42:43], 0, v[132:133]
	s_add_i32 m0, s46, 0x2000
	s_nop 0
	global_load_lds_dwordx4 v[192:193], off
	v_lshl_add_u64 v[192:193], v[214:215], 0, s[10:11]
	s_mov_b32 m0, s56
	s_nop 0
	global_load_lds_dwordx4 v[192:193], off
	v_lshl_add_u64 v[192:193], v[216:217], 0, s[10:11]
	s_mov_b32 m0, s57
	s_nop 0
	global_load_lds_dwordx4 v[192:193], off
	s_waitcnt vmcnt(8)
	s_waitcnt lgkmcnt(0)
	s_barrier
	s_setprio 1
	v_mfma_f32_16x16x32_bf16 v[62:65], v[144:147], v[176:179], v[62:65]
	v_mfma_f32_16x16x32_bf16 v[58:61], v[152:155], v[176:179], v[58:61]
	v_mfma_f32_16x16x32_bf16 v[54:57], v[144:147], v[184:187], v[54:57]
	v_mfma_f32_16x16x32_bf16 v[46:49], v[152:155], v[184:187], v[46:49]
	v_mfma_f32_16x16x32_bf16 v[38:41], v[144:147], v[196:199], v[38:41]
	v_mfma_f32_16x16x32_bf16 v[30:33], v[152:155], v[196:199], v[30:33]
	v_mfma_f32_16x16x32_bf16 v[22:25], v[144:147], v[204:207], v[22:25]
	v_mfma_f32_16x16x32_bf16 v[14:17], v[152:155], v[204:207], v[14:17]
	v_mfma_f32_16x16x32_bf16 v[62:65], v[148:151], v[180:183], v[62:65]
	v_mfma_f32_16x16x32_bf16 v[58:61], v[156:159], v[180:183], v[58:61]
	v_mfma_f32_16x16x32_bf16 v[54:57], v[148:151], v[188:191], v[54:57]
	v_mfma_f32_16x16x32_bf16 v[46:49], v[156:159], v[188:191], v[46:49]
	v_mfma_f32_16x16x32_bf16 v[38:41], v[148:151], v[200:203], v[38:41]
	v_mfma_f32_16x16x32_bf16 v[30:33], v[156:159], v[200:203], v[30:33]
	v_mfma_f32_16x16x32_bf16 v[22:25], v[148:151], v[208:211], v[22:25]
	v_mfma_f32_16x16x32_bf16 v[14:17], v[156:159], v[208:211], v[14:17]
	v_mfma_f32_16x16x32_bf16 v[50:53], v[160:163], v[176:179], v[50:53]
	v_mfma_f32_16x16x32_bf16 v[42:45], v[168:171], v[176:179], v[42:45]
	v_mfma_f32_16x16x32_bf16 v[34:37], v[160:163], v[184:187], v[34:37]
	v_mfma_f32_16x16x32_bf16 v[26:29], v[168:171], v[184:187], v[26:29]
	v_mfma_f32_16x16x32_bf16 v[18:21], v[160:163], v[196:199], v[18:21]
	v_mfma_f32_16x16x32_bf16 v[10:13], v[168:171], v[196:199], v[10:13]
	v_mfma_f32_16x16x32_bf16 v[6:9], v[160:163], v[204:207], v[6:9]
	v_mfma_f32_16x16x32_bf16 v[2:5], v[168:171], v[204:207], v[2:5]
	v_mfma_f32_16x16x32_bf16 v[50:53], v[164:167], v[180:183], v[50:53]
	v_mfma_f32_16x16x32_bf16 v[42:45], v[172:175], v[180:183], v[42:45]
	v_mfma_f32_16x16x32_bf16 v[34:37], v[164:167], v[188:191], v[34:37]
	v_mfma_f32_16x16x32_bf16 v[26:29], v[172:175], v[188:191], v[26:29]
	v_mfma_f32_16x16x32_bf16 v[18:21], v[164:167], v[200:203], v[18:21]
	v_mfma_f32_16x16x32_bf16 v[10:13], v[172:175], v[200:203], v[10:13]
	v_mfma_f32_16x16x32_bf16 v[6:9], v[164:167], v[208:211], v[6:9]
	v_mfma_f32_16x16x32_bf16 v[2:5], v[172:175], v[208:211], v[2:5]
	s_setprio 0
	s_barrier
	s_add_i32 s67, s67, 2
	s_add_u32 s40, s40, 0x100
	s_addc_u32 s41, s41, 0
	s_add_u32 s65, s65, 0x100
	s_addc_u32 s66, s66, 0
	s_cmp_gt_u32 s67, 61
	s_cbranch_scc0 .LBB0_705
	s_and_b64 vcc, exec, s[12:13]
	s_cbranch_vccz .LBB0_708
	s_barrier

.LBB0_967:
	ds_read_b128 v[146:149], v152
	ds_read_b128 v[156:159], v152 offset:1024
	ds_read_b128 v[160:163], v152 offset:2048
	ds_read_b128 v[164:167], v152 offset:3072
	ds_read_b128 v[168:171], v153
	ds_read_b128 v[172:175], v153 offset:1024
	ds_read_b128 v[176:179], v153 offset:2048
	ds_read_b128 v[180:183], v153 offset:3072
	s_add_u32 s30, s28, 0xfff80080
	s_addc_u32 s31, s29, -1
	s_cmp_eq_u32 s57, 28
	s_cselect_b32 s35, s21, s31
	s_cselect_b32 s34, s53, s30
	s_cselect_b32 s31, s19, s56
	s_cselect_b32 s30, s54, s55
	v_lshl_add_u64 v[192:193], s[28:29], 0, v[138:139]
	s_add_i32 m0, s27, 0xc000
	ds_read_b128 v[184:187], v154
	ds_read_b128 v[188:191], v154 offset:1024
	ds_read_b128 v[196:199], v154 offset:2048
	ds_read_b128 v[200:203], v154 offset:3072
	ds_read_b128 v[206:209], v154 offset:4096
	ds_read_b128 v[210:213], v154 offset:5120
	ds_read_b128 v[214:217], v154 offset:6144
	ds_read_b128 v[218:221], v154 offset:7168
	global_load_lds_dwordx4 v[192:193], off
	v_lshl_add_u64 v[192:193], s[28:29], 0, v[140:141]
	s_add_i32 m0, s27, 0xe000
	s_nop 0
	global_load_lds_dwordx4 v[192:193], off
	s_waitcnt vmcnt(8)
	s_waitcnt lgkmcnt(0)
	s_barrier
	s_setprio 1
	v_mfma_f32_16x16x32_bf16 v[126:129], v[146:149], v[184:187], v[126:129]
	v_mfma_f32_16x16x32_bf16 v[122:125], v[160:163], v[184:187], v[122:125]
	v_mfma_f32_16x16x32_bf16 v[110:113], v[146:149], v[196:199], v[110:113]
	v_mfma_f32_16x16x32_bf16 v[106:109], v[160:163], v[196:199], v[106:109]
	v_mfma_f32_16x16x32_bf16 v[98:101], v[146:149], v[206:209], v[98:101]
	v_mfma_f32_16x16x32_bf16 v[90:93], v[160:163], v[206:209], v[90:93]
	v_mfma_f32_16x16x32_bf16 v[78:81], v[146:149], v[214:217], v[78:81]
	v_mfma_f32_16x16x32_bf16 v[74:77], v[160:163], v[214:217], v[74:77]
	v_mfma_f32_16x16x32_bf16 v[126:129], v[156:159], v[188:191], v[126:129]
	v_mfma_f32_16x16x32_bf16 v[122:125], v[164:167], v[188:191], v[122:125]
	v_mfma_f32_16x16x32_bf16 v[110:113], v[156:159], v[200:203], v[110:113]
	v_mfma_f32_16x16x32_bf16 v[106:109], v[164:167], v[200:203], v[106:109]
	v_mfma_f32_16x16x32_bf16 v[98:101], v[156:159], v[210:213], v[98:101]
	v_mfma_f32_16x16x32_bf16 v[90:93], v[164:167], v[210:213], v[90:93]
	v_mfma_f32_16x16x32_bf16 v[78:81], v[156:159], v[218:221], v[78:81]
	v_mfma_f32_16x16x32_bf16 v[74:77], v[164:167], v[218:221], v[74:77]
	v_mfma_f32_16x16x32_bf16 v[118:121], v[168:171], v[184:187], v[118:121]
	v_mfma_f32_16x16x32_bf16 v[114:117], v[176:179], v[184:187], v[114:117]
	v_mfma_f32_16x16x32_bf16 v[102:105], v[168:171], v[196:199], v[102:105]
	v_mfma_f32_16x16x32_bf16 v[94:97], v[176:179], v[196:199], v[94:97]
	v_mfma_f32_16x16x32_bf16 v[86:89], v[168:171], v[206:209], v[86:89]
	v_mfma_f32_16x16x32_bf16 v[82:85], v[176:179], v[206:209], v[82:85]
	v_mfma_f32_16x16x32_bf16 v[70:73], v[168:171], v[214:217], v[70:73]
	v_mfma_f32_16x16x32_bf16 v[66:69], v[176:179], v[214:217], v[66:69]
	v_mfma_f32_16x16x32_bf16 v[118:121], v[172:175], v[188:191], v[118:121]
	v_mfma_f32_16x16x32_bf16 v[114:117], v[180:183], v[188:191], v[114:117]
	v_mfma_f32_16x16x32_bf16 v[102:105], v[172:175], v[200:203], v[102:105]
	v_mfma_f32_16x16x32_bf16 v[94:97], v[180:183], v[200:203], v[94:97]
	v_mfma_f32_16x16x32_bf16 v[86:89], v[172:175], v[210:213], v[86:89]
	v_mfma_f32_16x16x32_bf16 v[82:85], v[180:183], v[210:213], v[82:85]
	v_mfma_f32_16x16x32_bf16 v[70:73], v[172:175], v[218:221], v[70:73]
	v_mfma_f32_16x16x32_bf16 v[66:69], v[180:183], v[218:221], v[66:69]
	s_setprio 0
	s_barrier
	s_add_i32 s58, s50, s40
	v_lshl_add_u64 v[192:193], s[30:31], 0, v[134:135]
	s_mov_b32 m0, s58
	ds_read_b128 v[184:187], v154 offset:16384
	ds_read_b128 v[188:191], v154 offset:17408
	ds_read_b128 v[196:199], v154 offset:18432
	ds_read_b128 v[200:203], v154 offset:19456
	ds_read_b128 v[206:209], v154 offset:20480
	ds_read_b128 v[210:213], v154 offset:21504
	ds_read_b128 v[214:217], v154 offset:22528
	ds_read_b128 v[218:221], v154 offset:23552
	global_load_lds_dwordx4 v[192:193], off
	s_add_i32 m0, s58, 0x2000
	s_add_u32 s58, s30, 0x80000
	v_lshl_add_u64 v[222:223], s[30:31], 0, v[130:131]
	s_addc_u32 s59, s31, 0
	s_add_i32 s60, s51, s40
	global_load_lds_dwordx4 v[222:223], off
	v_lshl_add_u64 v[224:225], s[58:59], 0, v[134:135]
	s_mov_b32 m0, s60
	v_lshl_add_u64 v[226:227], s[34:35], 0, v[132:133]
	global_load_lds_dwordx4 v[224:225], off
	v_lshl_add_u64 v[224:225], s[58:59], 0, v[130:131]
	s_add_i32 m0, s60, 0x2000
	s_nop 0
	global_load_lds_dwordx4 v[224:225], off
	v_lshl_add_u64 v[224:225], s[34:35], 0, v[136:137]
	s_mov_b32 m0, s27
	s_nop 0
	global_load_lds_dwordx4 v[224:225], off
	s_mov_b32 m0, s42
	s_nop 0
	global_load_lds_dwordx4 v[226:227], off
	s_waitcnt vmcnt(8)
	s_waitcnt lgkmcnt(0)
	s_barrier
	s_setprio 1
	v_mfma_f32_16x16x32_bf16 v[62:65], v[146:149], v[184:187], v[62:65]
	v_mfma_f32_16x16x32_bf16 v[58:61], v[160:163], v[184:187], v[58:61]
	v_mfma_f32_16x16x32_bf16 v[46:49], v[146:149], v[196:199], v[46:49]
	v_mfma_f32_16x16x32_bf16 v[42:45], v[160:163], v[196:199], v[42:45]
	v_mfma_f32_16x16x32_bf16 v[30:33], v[146:149], v[206:209], v[30:33]
	v_mfma_f32_16x16x32_bf16 v[26:29], v[160:163], v[206:209], v[26:29]
	v_mfma_f32_16x16x32_bf16 v[14:17], v[146:149], v[214:217], v[14:17]
	v_mfma_f32_16x16x32_bf16 v[10:13], v[160:163], v[214:217], v[10:13]
	v_mfma_f32_16x16x32_bf16 v[62:65], v[156:159], v[188:191], v[62:65]
	v_mfma_f32_16x16x32_bf16 v[58:61], v[164:167], v[188:191], v[58:61]
	v_mfma_f32_16x16x32_bf16 v[46:49], v[156:159], v[200:203], v[46:49]
	v_mfma_f32_16x16x32_bf16 v[42:45], v[164:167], v[200:203], v[42:45]
	v_mfma_f32_16x16x32_bf16 v[30:33], v[156:159], v[210:213], v[30:33]
	v_mfma_f32_16x16x32_bf16 v[26:29], v[164:167], v[210:213], v[26:29]
	v_mfma_f32_16x16x32_bf16 v[14:17], v[156:159], v[218:221], v[14:17]
	v_mfma_f32_16x16x32_bf16 v[10:13], v[164:167], v[218:221], v[10:13]
	v_mfma_f32_16x16x32_bf16 v[54:57], v[168:171], v[184:187], v[54:57]
	v_mfma_f32_16x16x32_bf16 v[50:53], v[176:179], v[184:187], v[50:53]
	v_mfma_f32_16x16x32_bf16 v[38:41], v[168:171], v[196:199], v[38:41]
	v_mfma_f32_16x16x32_bf16 v[34:37], v[176:179], v[196:199], v[34:37]
	v_mfma_f32_16x16x32_bf16 v[22:25], v[168:171], v[206:209], v[22:25]
	v_mfma_f32_16x16x32_bf16 v[18:21], v[176:179], v[206:209], v[18:21]
	v_mfma_f32_16x16x32_bf16 v[6:9], v[168:171], v[214:217], v[6:9]
	v_mfma_f32_16x16x32_bf16 v[2:5], v[176:179], v[214:217], v[2:5]
	v_mfma_f32_16x16x32_bf16 v[54:57], v[172:175], v[188:191], v[54:57]
	v_mfma_f32_16x16x32_bf16 v[50:53], v[180:183], v[188:191], v[50:53]
	v_mfma_f32_16x16x32_bf16 v[38:41], v[172:175], v[200:203], v[38:41]
	v_mfma_f32_16x16x32_bf16 v[34:37], v[180:183], v[200:203], v[34:37]
	v_mfma_f32_16x16x32_bf16 v[22:25], v[172:175], v[210:213], v[22:25]
	v_mfma_f32_16x16x32_bf16 v[18:21], v[180:183], v[210:213], v[18:21]
	v_mfma_f32_16x16x32_bf16 v[6:9], v[172:175], v[218:221], v[6:9]
	v_mfma_f32_16x16x32_bf16 v[2:5], v[180:183], v[218:221], v[2:5]
	s_setprio 0
	s_barrier
	s_add_i32 s58, 0, 0x18000
	v_add_u32_e32 v155, s58, v150
	s_add_i32 s59, 0, 0x1c000
	ds_read_b128 v[146:149], v155
	ds_read_b128 v[156:159], v155 offset:1024
	ds_read_b128 v[160:163], v155 offset:2048
	ds_read_b128 v[164:167], v155 offset:3072
	v_add_u32_e32 v155, s59, v150
	ds_read_b128 v[168:171], v155
	ds_read_b128 v[172:175], v155 offset:1024
	ds_read_b128 v[176:179], v155 offset:2048
	ds_read_b128 v[180:183], v155 offset:3072
	s_add_u32 s34, s34, 0x80000
	s_addc_u32 s35, s35, 0
	s_mov_b32 m0, s43
	v_lshl_add_u64 v[228:229], s[34:35], 0, v[136:137]
	ds_read_b128 v[184:187], v154 offset:32768
	ds_read_b128 v[188:191], v154 offset:33792
	ds_read_b128 v[196:199], v154 offset:34816
	ds_read_b128 v[200:203], v154 offset:35840
	ds_read_b128 v[206:209], v154 offset:36864
	ds_read_b128 v[210:213], v154 offset:37888
	ds_read_b128 v[214:217], v154 offset:38912
	ds_read_b128 v[218:221], v154 offset:39936
	global_load_lds_dwordx4 v[228:229], off
	v_lshl_add_u64 v[228:229], s[34:35], 0, v[132:133]
	s_mov_b32 m0, s45
	s_nop 0
	global_load_lds_dwordx4 v[228:229], off
	s_waitcnt vmcnt(8)
	s_waitcnt lgkmcnt(0)
	s_barrier
	s_setprio 1
	v_mfma_f32_16x16x32_bf16 v[126:129], v[146:149], v[184:187], v[126:129]
	v_mfma_f32_16x16x32_bf16 v[122:125], v[160:163], v[184:187], v[122:125]
	v_mfma_f32_16x16x32_bf16 v[110:113], v[146:149], v[196:199], v[110:113]
	v_mfma_f32_16x16x32_bf16 v[106:109], v[160:163], v[196:199], v[106:109]
	v_mfma_f32_16x16x32_bf16 v[98:101], v[146:149], v[206:209], v[98:101]
	v_mfma_f32_16x16x32_bf16 v[90:93], v[160:163], v[206:209], v[90:93]
	v_mfma_f32_16x16x32_bf16 v[78:81], v[146:149], v[214:217], v[78:81]
	v_mfma_f32_16x16x32_bf16 v[74:77], v[160:163], v[214:217], v[74:77]
	v_mfma_f32_16x16x32_bf16 v[126:129], v[156:159], v[188:191], v[126:129]
	v_mfma_f32_16x16x32_bf16 v[122:125], v[164:167], v[188:191], v[122:125]
	v_mfma_f32_16x16x32_bf16 v[110:113], v[156:159], v[200:203], v[110:113]
	v_mfma_f32_16x16x32_bf16 v[106:109], v[164:167], v[200:203], v[106:109]
	v_mfma_f32_16x16x32_bf16 v[98:101], v[156:159], v[210:213], v[98:101]
	v_mfma_f32_16x16x32_bf16 v[90:93], v[164:167], v[210:213], v[90:93]
	v_mfma_f32_16x16x32_bf16 v[78:81], v[156:159], v[218:221], v[78:81]
	v_mfma_f32_16x16x32_bf16 v[74:77], v[164:167], v[218:221], v[74:77]
	v_mfma_f32_16x16x32_bf16 v[118:121], v[168:171], v[184:187], v[118:121]
	v_mfma_f32_16x16x32_bf16 v[114:117], v[176:179], v[184:187], v[114:117]
	v_mfma_f32_16x16x32_bf16 v[102:105], v[168:171], v[196:199], v[102:105]
	v_mfma_f32_16x16x32_bf16 v[94:97], v[176:179], v[196:199], v[94:97]
	v_mfma_f32_16x16x32_bf16 v[86:89], v[168:171], v[206:209], v[86:89]
	v_mfma_f32_16x16x32_bf16 v[82:85], v[176:179], v[206:209], v[82:85]
	v_mfma_f32_16x16x32_bf16 v[70:73], v[168:171], v[214:217], v[70:73]
	v_mfma_f32_16x16x32_bf16 v[66:69], v[176:179], v[214:217], v[66:69]
	v_mfma_f32_16x16x32_bf16 v[118:121], v[172:175], v[188:191], v[118:121]
	v_mfma_f32_16x16x32_bf16 v[114:117], v[180:183], v[188:191], v[114:117]
	v_mfma_f32_16x16x32_bf16 v[102:105], v[172:175], v[200:203], v[102:105]
	v_mfma_f32_16x16x32_bf16 v[94:97], v[180:183], v[200:203], v[94:97]
	v_mfma_f32_16x16x32_bf16 v[86:89], v[172:175], v[210:213], v[86:89]
	v_mfma_f32_16x16x32_bf16 v[82:85], v[180:183], v[210:213], v[82:85]
	v_mfma_f32_16x16x32_bf16 v[70:73], v[172:175], v[218:221], v[70:73]
	v_mfma_f32_16x16x32_bf16 v[66:69], v[180:183], v[218:221], v[66:69]
	s_setprio 0
	s_barrier
	s_add_i32 s34, s58, s40
	v_lshl_add_u64 v[192:193], v[192:193], 0, s[14:15]
	s_mov_b32 m0, s34
	ds_read_b128 v[184:187], v154 offset:49152
	ds_read_b128 v[188:191], v154 offset:50176
	ds_read_b128 v[196:199], v154 offset:51200
	ds_read_b128 v[200:203], v154 offset:52224
	ds_read_b128 v[206:209], v154 offset:53248
	ds_read_b128 v[210:213], v154 offset:54272
	ds_read_b128 v[214:217], v154 offset:55296
	ds_read_b128 v[218:221], v154 offset:56320
	global_load_lds_dwordx4 v[192:193], off
	s_add_i32 m0, s34, 0x2000
	s_add_u32 s30, s30, 0x80080
	v_lshl_add_u64 v[192:193], v[222:223], 0, s[14:15]
	s_addc_u32 s31, s31, 0
	s_add_i32 s34, s59, s40
	global_load_lds_dwordx4 v[192:193], off
	v_lshl_add_u64 v[192:193], s[30:31], 0, v[134:135]
	s_mov_b32 m0, s34
	s_nop 0
	global_load_lds_dwordx4 v[192:193], off
	v_lshl_add_u64 v[192:193], s[30:31], 0, v[130:131]
	s_add_i32 m0, s34, 0x2000
	s_nop 0
	global_load_lds_dwordx4 v[192:193], off
	v_lshl_add_u64 v[192:193], v[224:225], 0, s[14:15]
	s_mov_b32 m0, s47
	s_nop 0
	global_load_lds_dwordx4 v[192:193], off
	v_lshl_add_u64 v[192:193], v[226:227], 0, s[14:15]
	s_mov_b32 m0, s48
	s_nop 0
	global_load_lds_dwordx4 v[192:193], off
	s_waitcnt vmcnt(8)
	s_waitcnt lgkmcnt(0)
	s_barrier
	s_setprio 1
	v_mfma_f32_16x16x32_bf16 v[62:65], v[146:149], v[184:187], v[62:65]
	v_mfma_f32_16x16x32_bf16 v[58:61], v[160:163], v[184:187], v[58:61]
	v_mfma_f32_16x16x32_bf16 v[46:49], v[146:149], v[196:199], v[46:49]
	v_mfma_f32_16x16x32_bf16 v[42:45], v[160:163], v[196:199], v[42:45]
	v_mfma_f32_16x16x32_bf16 v[30:33], v[146:149], v[206:209], v[30:33]
	v_mfma_f32_16x16x32_bf16 v[26:29], v[160:163], v[206:209], v[26:29]
	v_mfma_f32_16x16x32_bf16 v[14:17], v[146:149], v[214:217], v[14:17]
	v_mfma_f32_16x16x32_bf16 v[10:13], v[160:163], v[214:217], v[10:13]
	v_mfma_f32_16x16x32_bf16 v[62:65], v[156:159], v[188:191], v[62:65]
	v_mfma_f32_16x16x32_bf16 v[58:61], v[164:167], v[188:191], v[58:61]
	v_mfma_f32_16x16x32_bf16 v[46:49], v[156:159], v[200:203], v[46:49]
	v_mfma_f32_16x16x32_bf16 v[42:45], v[164:167], v[200:203], v[42:45]
	v_mfma_f32_16x16x32_bf16 v[30:33], v[156:159], v[210:213], v[30:33]
	v_mfma_f32_16x16x32_bf16 v[26:29], v[164:167], v[210:213], v[26:29]
	v_mfma_f32_16x16x32_bf16 v[14:17], v[156:159], v[218:221], v[14:17]
	v_mfma_f32_16x16x32_bf16 v[10:13], v[164:167], v[218:221], v[10:13]
	v_mfma_f32_16x16x32_bf16 v[54:57], v[168:171], v[184:187], v[54:57]
	v_mfma_f32_16x16x32_bf16 v[50:53], v[176:179], v[184:187], v[50:53]
	v_mfma_f32_16x16x32_bf16 v[38:41], v[168:171], v[196:199], v[38:41]
	v_mfma_f32_16x16x32_bf16 v[34:37], v[176:179], v[196:199], v[34:37]
	v_mfma_f32_16x16x32_bf16 v[22:25], v[168:171], v[206:209], v[22:25]
	v_mfma_f32_16x16x32_bf16 v[18:21], v[176:179], v[206:209], v[18:21]
	v_mfma_f32_16x16x32_bf16 v[6:9], v[168:171], v[214:217], v[6:9]
	v_mfma_f32_16x16x32_bf16 v[2:5], v[176:179], v[214:217], v[2:5]
	v_mfma_f32_16x16x32_bf16 v[54:57], v[172:175], v[188:191], v[54:57]
	v_mfma_f32_16x16x32_bf16 v[50:53], v[180:183], v[188:191], v[50:53]
	v_mfma_f32_16x16x32_bf16 v[38:41], v[172:175], v[200:203], v[38:41]
	v_mfma_f32_16x16x32_bf16 v[34:37], v[180:183], v[200:203], v[34:37]
	v_mfma_f32_16x16x32_bf16 v[22:25], v[172:175], v[210:213], v[22:25]
	v_mfma_f32_16x16x32_bf16 v[18:21], v[180:183], v[210:213], v[18:21]
	v_mfma_f32_16x16x32_bf16 v[6:9], v[172:175], v[218:221], v[6:9]
	v_mfma_f32_16x16x32_bf16 v[2:5], v[180:183], v[218:221], v[2:5]
	s_setprio 0
	s_barrier
	s_add_i32 s57, s57, 2
	s_add_u32 s28, s28, 0x100
	s_addc_u32 s29, s29, 0
	s_add_u32 s55, s55, 0x100
	s_addc_u32 s56, s56, 0
	s_cmp_gt_u32 s57, 29
	s_cbranch_scc0 .LBB0_967
	s_and_b64 vcc, exec, s[16:17]
	s_cbranch_vccz .LBB0_970
	s_barrier

.LBB0_1057:
	ds_read_b128 v[150:153], v158
	ds_read_b128 v[162:165], v158 offset:1024
	ds_read_b128 v[166:169], v158 offset:2048
	ds_read_b128 v[170:173], v158 offset:3072
	ds_read_b128 v[174:177], v159
	ds_read_b128 v[178:181], v159 offset:1024
	ds_read_b128 v[182:185], v159 offset:2048
	ds_read_b128 v[186:189], v159 offset:3072
	s_add_i32 s84, s48, 2
	s_add_u32 s49, s62, 0xfff00080
	s_addc_u32 s64, s63, -1
	s_cmp_eq_u32 s51, s48
	s_cselect_b32 s48, s56, s53
	s_cselect_b32 s65, s9, s64
	s_cselect_b32 s64, s8, s49
	s_cselect_b32 s49, s57, s55
	v_lshl_add_u64 v[154:155], s[62:63], 0, v[138:139]
	s_add_i32 m0, s59, 0xc000
	ds_read_b128 v[190:193], v160
	ds_read_b128 v[196:199], v160 offset:1024
	ds_read_b128 v[200:203], v160 offset:2048
	ds_read_b128 v[206:209], v160 offset:3072
	ds_read_b128 v[210:213], v160 offset:4096
	ds_read_b128 v[214:217], v160 offset:5120
	ds_read_b128 v[218:221], v160 offset:6144
	ds_read_b128 v[222:225], v160 offset:7168
	global_load_lds_dwordx4 v[154:155], off
	v_lshl_add_u64 v[154:155], s[62:63], 0, v[140:141]
	s_add_i32 m0, s59, 0xe000
	s_nop 0
	global_load_lds_dwordx4 v[154:155], off
	s_waitcnt vmcnt(8)
	s_waitcnt lgkmcnt(0)
	s_barrier
	s_setprio 1
	v_mfma_f32_16x16x32_bf16 v[126:129], v[150:153], v[190:193], v[126:129]
	v_mfma_f32_16x16x32_bf16 v[122:125], v[166:169], v[190:193], v[122:125]
	v_mfma_f32_16x16x32_bf16 v[110:113], v[150:153], v[200:203], v[110:113]
	v_mfma_f32_16x16x32_bf16 v[106:109], v[166:169], v[200:203], v[106:109]
	v_mfma_f32_16x16x32_bf16 v[94:97], v[150:153], v[210:213], v[94:97]
	v_mfma_f32_16x16x32_bf16 v[90:93], v[166:169], v[210:213], v[90:93]
	v_mfma_f32_16x16x32_bf16 v[78:81], v[150:153], v[218:221], v[78:81]
	v_mfma_f32_16x16x32_bf16 v[74:77], v[166:169], v[218:221], v[74:77]
	v_mfma_f32_16x16x32_bf16 v[126:129], v[162:165], v[196:199], v[126:129]
	v_mfma_f32_16x16x32_bf16 v[122:125], v[170:173], v[196:199], v[122:125]
	v_mfma_f32_16x16x32_bf16 v[110:113], v[162:165], v[206:209], v[110:113]
	v_mfma_f32_16x16x32_bf16 v[106:109], v[170:173], v[206:209], v[106:109]
	v_mfma_f32_16x16x32_bf16 v[94:97], v[162:165], v[214:217], v[94:97]
	v_mfma_f32_16x16x32_bf16 v[90:93], v[170:173], v[214:217], v[90:93]
	v_mfma_f32_16x16x32_bf16 v[78:81], v[162:165], v[222:225], v[78:81]
	v_mfma_f32_16x16x32_bf16 v[74:77], v[170:173], v[222:225], v[74:77]
	v_mfma_f32_16x16x32_bf16 v[118:121], v[174:177], v[190:193], v[118:121]
	v_mfma_f32_16x16x32_bf16 v[114:117], v[182:185], v[190:193], v[114:117]
	v_mfma_f32_16x16x32_bf16 v[102:105], v[174:177], v[200:203], v[102:105]
	v_mfma_f32_16x16x32_bf16 v[98:101], v[182:185], v[200:203], v[98:101]
	v_mfma_f32_16x16x32_bf16 v[86:89], v[174:177], v[210:213], v[86:89]
	v_mfma_f32_16x16x32_bf16 v[82:85], v[182:185], v[210:213], v[82:85]
	v_mfma_f32_16x16x32_bf16 v[70:73], v[174:177], v[218:221], v[70:73]
	v_mfma_f32_16x16x32_bf16 v[66:69], v[182:185], v[218:221], v[66:69]
	v_mfma_f32_16x16x32_bf16 v[118:121], v[178:181], v[196:199], v[118:121]
	v_mfma_f32_16x16x32_bf16 v[114:117], v[186:189], v[196:199], v[114:117]
	v_mfma_f32_16x16x32_bf16 v[102:105], v[178:181], v[206:209], v[102:105]
	v_mfma_f32_16x16x32_bf16 v[98:101], v[186:189], v[206:209], v[98:101]
	v_mfma_f32_16x16x32_bf16 v[86:89], v[178:181], v[214:217], v[86:89]
	v_mfma_f32_16x16x32_bf16 v[82:85], v[186:189], v[214:217], v[82:85]
	v_mfma_f32_16x16x32_bf16 v[70:73], v[178:181], v[222:225], v[70:73]
	v_mfma_f32_16x16x32_bf16 v[66:69], v[186:189], v[222:225], v[66:69]
	s_setprio 0
	s_barrier
	s_add_i32 s85, s75, s66
	v_lshl_add_u64 v[154:155], s[48:49], 0, v[132:133]
	s_mov_b32 m0, s85
	ds_read_b128 v[190:193], v160 offset:16384
	ds_read_b128 v[196:199], v160 offset:17408
	ds_read_b128 v[200:203], v160 offset:18432
	ds_read_b128 v[206:209], v160 offset:19456
	ds_read_b128 v[210:213], v160 offset:20480
	ds_read_b128 v[214:217], v160 offset:21504
	ds_read_b128 v[218:221], v160 offset:22528
	ds_read_b128 v[222:225], v160 offset:23552
	global_load_lds_dwordx4 v[154:155], off
	s_add_i32 m0, s85, 0x2000
	s_add_u32 s86, s48, 0x100000
	v_lshl_add_u64 v[226:227], s[48:49], 0, v[136:137]
	s_addc_u32 s87, s49, 0
	s_add_i32 s85, s76, s66
	global_load_lds_dwordx4 v[226:227], off
	v_lshl_add_u64 v[228:229], s[86:87], 0, v[132:133]
	s_mov_b32 m0, s85
	v_lshl_add_u64 v[230:231], s[64:65], 0, v[134:135]
	global_load_lds_dwordx4 v[228:229], off
	v_lshl_add_u64 v[228:229], s[86:87], 0, v[136:137]
	s_add_i32 m0, s85, 0x2000
	s_nop 0
	global_load_lds_dwordx4 v[228:229], off
	v_lshl_add_u64 v[228:229], s[64:65], 0, v[130:131]
	s_mov_b32 m0, s59
	s_nop 0
	global_load_lds_dwordx4 v[228:229], off
	s_mov_b32 m0, s61
	s_nop 0
	global_load_lds_dwordx4 v[230:231], off
	s_waitcnt vmcnt(8)
	s_waitcnt lgkmcnt(0)
	s_barrier
	s_setprio 1
	v_mfma_f32_16x16x32_bf16 v[62:65], v[150:153], v[190:193], v[62:65]
	v_mfma_f32_16x16x32_bf16 v[58:61], v[166:169], v[190:193], v[58:61]
	v_mfma_f32_16x16x32_bf16 v[46:49], v[150:153], v[200:203], v[46:49]
	v_mfma_f32_16x16x32_bf16 v[42:45], v[166:169], v[200:203], v[42:45]
	v_mfma_f32_16x16x32_bf16 v[30:33], v[150:153], v[210:213], v[30:33]
	v_mfma_f32_16x16x32_bf16 v[26:29], v[166:169], v[210:213], v[26:29]
	v_mfma_f32_16x16x32_bf16 v[14:17], v[150:153], v[218:221], v[14:17]
	v_mfma_f32_16x16x32_bf16 v[10:13], v[166:169], v[218:221], v[10:13]
	v_mfma_f32_16x16x32_bf16 v[62:65], v[162:165], v[196:199], v[62:65]
	v_mfma_f32_16x16x32_bf16 v[58:61], v[170:173], v[196:199], v[58:61]
	v_mfma_f32_16x16x32_bf16 v[46:49], v[162:165], v[206:209], v[46:49]
	v_mfma_f32_16x16x32_bf16 v[42:45], v[170:173], v[206:209], v[42:45]
	v_mfma_f32_16x16x32_bf16 v[30:33], v[162:165], v[214:217], v[30:33]
	v_mfma_f32_16x16x32_bf16 v[26:29], v[170:173], v[214:217], v[26:29]
	v_mfma_f32_16x16x32_bf16 v[14:17], v[162:165], v[222:225], v[14:17]
	v_mfma_f32_16x16x32_bf16 v[10:13], v[170:173], v[222:225], v[10:13]
	v_mfma_f32_16x16x32_bf16 v[54:57], v[174:177], v[190:193], v[54:57]
	v_mfma_f32_16x16x32_bf16 v[50:53], v[182:185], v[190:193], v[50:53]
	v_mfma_f32_16x16x32_bf16 v[38:41], v[174:177], v[200:203], v[38:41]
	v_mfma_f32_16x16x32_bf16 v[34:37], v[182:185], v[200:203], v[34:37]
	v_mfma_f32_16x16x32_bf16 v[22:25], v[174:177], v[210:213], v[22:25]
	v_mfma_f32_16x16x32_bf16 v[18:21], v[182:185], v[210:213], v[18:21]
	v_mfma_f32_16x16x32_bf16 v[6:9], v[174:177], v[218:221], v[6:9]
	v_mfma_f32_16x16x32_bf16 v[2:5], v[182:185], v[218:221], v[2:5]
	v_mfma_f32_16x16x32_bf16 v[54:57], v[178:181], v[196:199], v[54:57]
	v_mfma_f32_16x16x32_bf16 v[50:53], v[186:189], v[196:199], v[50:53]
	v_mfma_f32_16x16x32_bf16 v[38:41], v[178:181], v[206:209], v[38:41]
	v_mfma_f32_16x16x32_bf16 v[34:37], v[186:189], v[206:209], v[34:37]
	v_mfma_f32_16x16x32_bf16 v[22:25], v[178:181], v[214:217], v[22:25]
	v_mfma_f32_16x16x32_bf16 v[18:21], v[186:189], v[214:217], v[18:21]
	v_mfma_f32_16x16x32_bf16 v[6:9], v[178:181], v[222:225], v[6:9]
	v_mfma_f32_16x16x32_bf16 v[2:5], v[186:189], v[222:225], v[2:5]
	s_setprio 0
	s_barrier
	s_add_i32 s85, 0, 0x18000
	v_add_u32_e32 v161, s85, v156
	s_add_i32 s86, 0, 0x1c000
	ds_read_b128 v[150:153], v161
	ds_read_b128 v[162:165], v161 offset:1024
	ds_read_b128 v[166:169], v161 offset:2048
	ds_read_b128 v[170:173], v161 offset:3072
	v_add_u32_e32 v161, s86, v156
	ds_read_b128 v[174:177], v161
	ds_read_b128 v[178:181], v161 offset:1024
	ds_read_b128 v[182:185], v161 offset:2048
	ds_read_b128 v[186:189], v161 offset:3072
	s_add_u32 s64, s64, 0x100000
	s_addc_u32 s65, s65, 0
	s_mov_b32 m0, s67
	v_lshl_add_u64 v[232:233], s[64:65], 0, v[130:131]
	ds_read_b128 v[190:193], v160 offset:32768
	ds_read_b128 v[196:199], v160 offset:33792
	ds_read_b128 v[200:203], v160 offset:34816
	ds_read_b128 v[206:209], v160 offset:35840
	ds_read_b128 v[210:213], v160 offset:36864
	ds_read_b128 v[214:217], v160 offset:37888
	ds_read_b128 v[218:221], v160 offset:38912
	ds_read_b128 v[222:225], v160 offset:39936
	global_load_lds_dwordx4 v[232:233], off
	v_lshl_add_u64 v[232:233], s[64:65], 0, v[134:135]
	s_mov_b32 m0, s68
	s_nop 0
	global_load_lds_dwordx4 v[232:233], off
	s_waitcnt vmcnt(8)
	s_waitcnt lgkmcnt(0)
	s_barrier
	s_setprio 1
	v_mfma_f32_16x16x32_bf16 v[126:129], v[150:153], v[190:193], v[126:129]
	v_mfma_f32_16x16x32_bf16 v[122:125], v[166:169], v[190:193], v[122:125]
	v_mfma_f32_16x16x32_bf16 v[110:113], v[150:153], v[200:203], v[110:113]
	v_mfma_f32_16x16x32_bf16 v[106:109], v[166:169], v[200:203], v[106:109]
	v_mfma_f32_16x16x32_bf16 v[94:97], v[150:153], v[210:213], v[94:97]
	v_mfma_f32_16x16x32_bf16 v[90:93], v[166:169], v[210:213], v[90:93]
	v_mfma_f32_16x16x32_bf16 v[78:81], v[150:153], v[218:221], v[78:81]
	v_mfma_f32_16x16x32_bf16 v[74:77], v[166:169], v[218:221], v[74:77]
	v_mfma_f32_16x16x32_bf16 v[126:129], v[162:165], v[196:199], v[126:129]
	v_mfma_f32_16x16x32_bf16 v[122:125], v[170:173], v[196:199], v[122:125]
	v_mfma_f32_16x16x32_bf16 v[110:113], v[162:165], v[206:209], v[110:113]
	v_mfma_f32_16x16x32_bf16 v[106:109], v[170:173], v[206:209], v[106:109]
	v_mfma_f32_16x16x32_bf16 v[94:97], v[162:165], v[214:217], v[94:97]
	v_mfma_f32_16x16x32_bf16 v[90:93], v[170:173], v[214:217], v[90:93]
	v_mfma_f32_16x16x32_bf16 v[78:81], v[162:165], v[222:225], v[78:81]
	v_mfma_f32_16x16x32_bf16 v[74:77], v[170:173], v[222:225], v[74:77]
	v_mfma_f32_16x16x32_bf16 v[118:121], v[174:177], v[190:193], v[118:121]
	v_mfma_f32_16x16x32_bf16 v[114:117], v[182:185], v[190:193], v[114:117]
	v_mfma_f32_16x16x32_bf16 v[102:105], v[174:177], v[200:203], v[102:105]
	v_mfma_f32_16x16x32_bf16 v[98:101], v[182:185], v[200:203], v[98:101]
	v_mfma_f32_16x16x32_bf16 v[86:89], v[174:177], v[210:213], v[86:89]
	v_mfma_f32_16x16x32_bf16 v[82:85], v[182:185], v[210:213], v[82:85]
	v_mfma_f32_16x16x32_bf16 v[70:73], v[174:177], v[218:221], v[70:73]
	v_mfma_f32_16x16x32_bf16 v[66:69], v[182:185], v[218:221], v[66:69]
	v_mfma_f32_16x16x32_bf16 v[118:121], v[178:181], v[196:199], v[118:121]
	v_mfma_f32_16x16x32_bf16 v[114:117], v[186:189], v[196:199], v[114:117]
	v_mfma_f32_16x16x32_bf16 v[102:105], v[178:181], v[206:209], v[102:105]
	v_mfma_f32_16x16x32_bf16 v[98:101], v[186:189], v[206:209], v[98:101]
	v_mfma_f32_16x16x32_bf16 v[86:89], v[178:181], v[214:217], v[86:89]
	v_mfma_f32_16x16x32_bf16 v[82:85], v[186:189], v[214:217], v[82:85]
	v_mfma_f32_16x16x32_bf16 v[70:73], v[178:181], v[222:225], v[70:73]
	v_mfma_f32_16x16x32_bf16 v[66:69], v[186:189], v[222:225], v[66:69]
	s_setprio 0
	s_barrier
	s_add_i32 s64, s85, s66
	v_lshl_add_u64 v[154:155], v[154:155], 0, s[20:21]
	s_mov_b32 m0, s64
	ds_read_b128 v[190:193], v160 offset:49152
	ds_read_b128 v[196:199], v160 offset:50176
	ds_read_b128 v[200:203], v160 offset:51200
	ds_read_b128 v[206:209], v160 offset:52224
	ds_read_b128 v[210:213], v160 offset:53248
	ds_read_b128 v[214:217], v160 offset:54272
	ds_read_b128 v[218:221], v160 offset:55296
	ds_read_b128 v[222:225], v160 offset:56320
	global_load_lds_dwordx4 v[154:155], off
	s_add_i32 m0, s64, 0x2000
	s_add_u32 s48, s48, 0x100080
	v_lshl_add_u64 v[154:155], v[226:227], 0, s[20:21]
	s_addc_u32 s49, s49, 0
	s_add_i32 s64, s86, s66
	global_load_lds_dwordx4 v[154:155], off
	v_lshl_add_u64 v[154:155], s[48:49], 0, v[132:133]
	s_mov_b32 m0, s64
	s_nop 0
	global_load_lds_dwordx4 v[154:155], off
	v_lshl_add_u64 v[154:155], s[48:49], 0, v[136:137]
	s_add_i32 m0, s64, 0x2000
	s_nop 0
	global_load_lds_dwordx4 v[154:155], off
	v_lshl_add_u64 v[154:155], v[228:229], 0, s[20:21]
	s_mov_b32 m0, s72
	s_nop 0
	global_load_lds_dwordx4 v[154:155], off
	v_lshl_add_u64 v[154:155], v[230:231], 0, s[20:21]
	s_mov_b32 m0, s73
	s_nop 0
	global_load_lds_dwordx4 v[154:155], off
	s_waitcnt vmcnt(8)
	s_waitcnt lgkmcnt(0)
	s_barrier
	s_setprio 1
	v_mfma_f32_16x16x32_bf16 v[62:65], v[150:153], v[190:193], v[62:65]
	v_mfma_f32_16x16x32_bf16 v[58:61], v[166:169], v[190:193], v[58:61]
	v_mfma_f32_16x16x32_bf16 v[46:49], v[150:153], v[200:203], v[46:49]
	v_mfma_f32_16x16x32_bf16 v[42:45], v[166:169], v[200:203], v[42:45]
	v_mfma_f32_16x16x32_bf16 v[30:33], v[150:153], v[210:213], v[30:33]
	v_mfma_f32_16x16x32_bf16 v[26:29], v[166:169], v[210:213], v[26:29]
	v_mfma_f32_16x16x32_bf16 v[14:17], v[150:153], v[218:221], v[14:17]
	v_mfma_f32_16x16x32_bf16 v[10:13], v[166:169], v[218:221], v[10:13]
	v_mfma_f32_16x16x32_bf16 v[62:65], v[162:165], v[196:199], v[62:65]
	v_mfma_f32_16x16x32_bf16 v[58:61], v[170:173], v[196:199], v[58:61]
	v_mfma_f32_16x16x32_bf16 v[46:49], v[162:165], v[206:209], v[46:49]
	v_mfma_f32_16x16x32_bf16 v[42:45], v[170:173], v[206:209], v[42:45]
	v_mfma_f32_16x16x32_bf16 v[30:33], v[162:165], v[214:217], v[30:33]
	v_mfma_f32_16x16x32_bf16 v[26:29], v[170:173], v[214:217], v[26:29]
	v_mfma_f32_16x16x32_bf16 v[14:17], v[162:165], v[222:225], v[14:17]
	v_mfma_f32_16x16x32_bf16 v[10:13], v[170:173], v[222:225], v[10:13]
	v_mfma_f32_16x16x32_bf16 v[54:57], v[174:177], v[190:193], v[54:57]
	v_mfma_f32_16x16x32_bf16 v[50:53], v[182:185], v[190:193], v[50:53]
	v_mfma_f32_16x16x32_bf16 v[38:41], v[174:177], v[200:203], v[38:41]
	v_mfma_f32_16x16x32_bf16 v[34:37], v[182:185], v[200:203], v[34:37]
	v_mfma_f32_16x16x32_bf16 v[22:25], v[174:177], v[210:213], v[22:25]
	v_mfma_f32_16x16x32_bf16 v[18:21], v[182:185], v[210:213], v[18:21]
	v_mfma_f32_16x16x32_bf16 v[6:9], v[174:177], v[218:221], v[6:9]
	v_mfma_f32_16x16x32_bf16 v[2:5], v[182:185], v[218:221], v[2:5]
	v_mfma_f32_16x16x32_bf16 v[54:57], v[178:181], v[196:199], v[54:57]
	v_mfma_f32_16x16x32_bf16 v[50:53], v[186:189], v[196:199], v[50:53]
	v_mfma_f32_16x16x32_bf16 v[38:41], v[178:181], v[206:209], v[38:41]
	v_mfma_f32_16x16x32_bf16 v[34:37], v[186:189], v[206:209], v[34:37]
	v_mfma_f32_16x16x32_bf16 v[22:25], v[178:181], v[214:217], v[22:25]
	v_mfma_f32_16x16x32_bf16 v[18:21], v[186:189], v[214:217], v[18:21]
	v_mfma_f32_16x16x32_bf16 v[6:9], v[178:181], v[222:225], v[6:9]
	v_mfma_f32_16x16x32_bf16 v[2:5], v[186:189], v[222:225], v[2:5]
	s_setprio 0
	s_barrier
	s_add_u32 s62, s62, 0x100
	s_addc_u32 s63, s63, 0
	s_add_u32 s53, s53, 0x100
	s_addc_u32 s55, s55, 0
	s_cmp_ge_i32 s84, s83
	s_mov_b32 s48, s84
	s_cbranch_scc0 .LBB0_1057
	s_and_b64 vcc, exec, s[22:23]
	s_cbranch_vccz .LBB0_1060
	s_barrier

.LBB0_1197:
	ds_read_b128 v[162:165], v141
	ds_read_b128 v[166:169], v141 offset:1024
	ds_read_b128 v[170:173], v141 offset:2048
	ds_read_b128 v[174:177], v141 offset:3072
	ds_read_b128 v[178:181], v145
	ds_read_b128 v[182:185], v145 offset:1024
	ds_read_b128 v[186:189], v145 offset:2048
	ds_read_b128 v[190:193], v145 offset:3072
	s_add_i32 s65, s34, 2
	s_add_u32 s35, s30, 0xfff00080
	s_addc_u32 s40, s31, -1
	s_cmp_eq_u32 s62, s34
	s_cselect_b32 s34, s61, s63
	s_cselect_b32 s41, s21, s40
	s_cselect_b32 s40, s25, s35
	s_cselect_b32 s35, s23, s64
	v_lshl_add_u64 v[158:159], s[30:31], 0, v[148:149]
	s_add_i32 m0, s8, 0xc000
	ds_read_b128 v[196:199], v160
	ds_read_b128 v[200:203], v160 offset:1024
	ds_read_b128 v[206:209], v160 offset:2048
	ds_read_b128 v[210:213], v160 offset:3072
	ds_read_b128 v[214:217], v160 offset:4096
	ds_read_b128 v[218:221], v160 offset:5120
	ds_read_b128 v[222:225], v160 offset:6144
	ds_read_b128 v[226:229], v160 offset:7168
	global_load_lds_dwordx4 v[158:159], off
	v_lshl_add_u64 v[158:159], s[30:31], 0, v[150:151]
	s_add_i32 m0, s8, 0xe000
	s_nop 0
	global_load_lds_dwordx4 v[158:159], off
	s_waitcnt vmcnt(8)
	s_waitcnt lgkmcnt(0)
	s_barrier
	s_setprio 1
	v_mfma_f32_16x16x32_bf16 v[126:129], v[162:165], v[196:199], v[126:129]
	v_mfma_f32_16x16x32_bf16 v[122:125], v[170:173], v[196:199], v[122:125]
	v_mfma_f32_16x16x32_bf16 v[118:121], v[162:165], v[206:209], v[118:121]
	v_mfma_f32_16x16x32_bf16 v[114:117], v[170:173], v[206:209], v[114:117]
	v_mfma_f32_16x16x32_bf16 v[102:105], v[162:165], v[214:217], v[102:105]
	v_mfma_f32_16x16x32_bf16 v[98:101], v[170:173], v[214:217], v[98:101]
	v_mfma_f32_16x16x32_bf16 v[42:45], v[162:165], v[222:225], v[42:45]
	v_mfma_f32_16x16x32_bf16 v[34:37], v[170:173], v[222:225], v[34:37]
	v_mfma_f32_16x16x32_bf16 v[126:129], v[166:169], v[200:203], v[126:129]
	v_mfma_f32_16x16x32_bf16 v[122:125], v[174:177], v[200:203], v[122:125]
	v_mfma_f32_16x16x32_bf16 v[118:121], v[166:169], v[210:213], v[118:121]
	v_mfma_f32_16x16x32_bf16 v[114:117], v[174:177], v[210:213], v[114:117]
	v_mfma_f32_16x16x32_bf16 v[102:105], v[166:169], v[218:221], v[102:105]
	v_mfma_f32_16x16x32_bf16 v[98:101], v[174:177], v[218:221], v[98:101]
	v_mfma_f32_16x16x32_bf16 v[42:45], v[166:169], v[226:229], v[42:45]
	v_mfma_f32_16x16x32_bf16 v[34:37], v[174:177], v[226:229], v[34:37]
	v_mfma_f32_16x16x32_bf16 v[110:113], v[178:181], v[196:199], v[110:113]
	v_mfma_f32_16x16x32_bf16 v[106:109], v[186:189], v[196:199], v[106:109]
	v_mfma_f32_16x16x32_bf16 v[94:97], v[178:181], v[206:209], v[94:97]
	v_mfma_f32_16x16x32_bf16 v[90:93], v[186:189], v[206:209], v[90:93]
	v_mfma_f32_16x16x32_bf16 v[86:89], v[178:181], v[214:217], v[86:89]
	v_mfma_f32_16x16x32_bf16 v[82:85], v[186:189], v[214:217], v[82:85]
	v_mfma_f32_16x16x32_bf16 v[30:33], v[178:181], v[222:225], v[30:33]
	v_mfma_f32_16x16x32_bf16 v[26:29], v[186:189], v[222:225], v[26:29]
	v_mfma_f32_16x16x32_bf16 v[110:113], v[182:185], v[200:203], v[110:113]
	v_mfma_f32_16x16x32_bf16 v[106:109], v[190:193], v[200:203], v[106:109]
	v_mfma_f32_16x16x32_bf16 v[94:97], v[182:185], v[210:213], v[94:97]
	v_mfma_f32_16x16x32_bf16 v[90:93], v[190:193], v[210:213], v[90:93]
	v_mfma_f32_16x16x32_bf16 v[86:89], v[182:185], v[218:221], v[86:89]
	v_mfma_f32_16x16x32_bf16 v[82:85], v[190:193], v[218:221], v[82:85]
	v_mfma_f32_16x16x32_bf16 v[30:33], v[182:185], v[226:229], v[30:33]
	v_mfma_f32_16x16x32_bf16 v[26:29], v[190:193], v[226:229], v[26:29]
	s_setprio 0
	s_barrier
	s_add_i32 s66, s56, s42
	v_lshl_add_u64 v[158:159], s[34:35], 0, v[134:135]
	s_mov_b32 m0, s66
	ds_read_b128 v[196:199], v160 offset:16384
	ds_read_b128 v[200:203], v160 offset:17408
	ds_read_b128 v[206:209], v160 offset:18432
	ds_read_b128 v[210:213], v160 offset:19456
	ds_read_b128 v[214:217], v160 offset:20480
	ds_read_b128 v[218:221], v160 offset:21504
	ds_read_b128 v[222:225], v160 offset:22528
	ds_read_b128 v[226:229], v160 offset:23552
	global_load_lds_dwordx4 v[158:159], off
	s_add_i32 m0, s66, 0x2000
	s_add_u32 s66, s34, 0x100000
	v_lshl_add_u64 v[230:231], s[34:35], 0, v[132:133]
	s_addc_u32 s67, s35, 0
	s_add_i32 s68, s57, s42
	global_load_lds_dwordx4 v[230:231], off
	v_lshl_add_u64 v[232:233], s[66:67], 0, v[134:135]
	s_mov_b32 m0, s68
	v_lshl_add_u64 v[234:235], s[40:41], 0, v[132:133]
	global_load_lds_dwordx4 v[232:233], off
	v_lshl_add_u64 v[232:233], s[66:67], 0, v[132:133]
	s_add_i32 m0, s68, 0x2000
	s_nop 0
	global_load_lds_dwordx4 v[232:233], off
	v_lshl_add_u64 v[232:233], s[40:41], 0, v[134:135]
	s_mov_b32 m0, s8
	s_nop 0
	global_load_lds_dwordx4 v[232:233], off
	s_mov_b32 m0, s15
	s_nop 0
	global_load_lds_dwordx4 v[234:235], off
	s_waitcnt vmcnt(8)
	s_waitcnt lgkmcnt(0)
	s_barrier
	s_setprio 1
	v_mfma_f32_16x16x32_bf16 v[78:81], v[162:165], v[196:199], v[78:81]
	v_mfma_f32_16x16x32_bf16 v[74:77], v[170:173], v[196:199], v[74:77]
	v_mfma_f32_16x16x32_bf16 v[70:73], v[162:165], v[206:209], v[70:73]
	v_mfma_f32_16x16x32_bf16 v[66:69], v[170:173], v[206:209], v[66:69]
	v_mfma_f32_16x16x32_bf16 v[54:57], v[162:165], v[214:217], v[54:57]
	v_mfma_f32_16x16x32_bf16 v[50:53], v[170:173], v[214:217], v[50:53]
	v_mfma_f32_16x16x32_bf16 v[14:17], v[162:165], v[222:225], v[14:17]
	v_mfma_f32_16x16x32_bf16 v[10:13], v[170:173], v[222:225], v[10:13]
	v_mfma_f32_16x16x32_bf16 v[78:81], v[166:169], v[200:203], v[78:81]
	v_mfma_f32_16x16x32_bf16 v[74:77], v[174:177], v[200:203], v[74:77]
	v_mfma_f32_16x16x32_bf16 v[70:73], v[166:169], v[210:213], v[70:73]
	v_mfma_f32_16x16x32_bf16 v[66:69], v[174:177], v[210:213], v[66:69]
	v_mfma_f32_16x16x32_bf16 v[54:57], v[166:169], v[218:221], v[54:57]
	v_mfma_f32_16x16x32_bf16 v[50:53], v[174:177], v[218:221], v[50:53]
	v_mfma_f32_16x16x32_bf16 v[14:17], v[166:169], v[226:229], v[14:17]
	v_mfma_f32_16x16x32_bf16 v[10:13], v[174:177], v[226:229], v[10:13]
	v_mfma_f32_16x16x32_bf16 v[62:65], v[178:181], v[196:199], v[62:65]
	v_mfma_f32_16x16x32_bf16 v[58:61], v[186:189], v[196:199], v[58:61]
	v_mfma_f32_16x16x32_bf16 v[46:49], v[178:181], v[206:209], v[46:49]
	v_mfma_f32_16x16x32_bf16 v[38:41], v[186:189], v[206:209], v[38:41]
	v_mfma_f32_16x16x32_bf16 v[22:25], v[178:181], v[214:217], v[22:25]
	v_mfma_f32_16x16x32_bf16 v[18:21], v[186:189], v[214:217], v[18:21]
	v_mfma_f32_16x16x32_bf16 v[6:9], v[178:181], v[222:225], v[6:9]
	v_mfma_f32_16x16x32_bf16 v[2:5], v[186:189], v[222:225], v[2:5]
	v_mfma_f32_16x16x32_bf16 v[62:65], v[182:185], v[200:203], v[62:65]
	v_mfma_f32_16x16x32_bf16 v[58:61], v[190:193], v[200:203], v[58:61]
	v_mfma_f32_16x16x32_bf16 v[46:49], v[182:185], v[210:213], v[46:49]
	v_mfma_f32_16x16x32_bf16 v[38:41], v[190:193], v[210:213], v[38:41]
	v_mfma_f32_16x16x32_bf16 v[22:25], v[182:185], v[218:221], v[22:25]
	v_mfma_f32_16x16x32_bf16 v[18:21], v[190:193], v[218:221], v[18:21]
	v_mfma_f32_16x16x32_bf16 v[6:9], v[182:185], v[226:229], v[6:9]
	v_mfma_f32_16x16x32_bf16 v[2:5], v[190:193], v[226:229], v[2:5]
	s_setprio 0
	s_barrier
	s_add_i32 s66, 0, 0x18000
	v_add_u32_e32 v161, s66, v1
	s_add_i32 s67, 0, 0x1c000
	ds_read_b128 v[162:165], v161
	ds_read_b128 v[166:169], v161 offset:1024
	ds_read_b128 v[170:173], v161 offset:2048
	ds_read_b128 v[174:177], v161 offset:3072
	v_add_u32_e32 v161, s67, v1
	ds_read_b128 v[178:181], v161
	ds_read_b128 v[182:185], v161 offset:1024
	ds_read_b128 v[186:189], v161 offset:2048
	ds_read_b128 v[190:193], v161 offset:3072
	s_add_u32 s40, s40, 0x100000
	s_addc_u32 s41, s41, 0
	s_mov_b32 m0, s46
	v_lshl_add_u64 v[236:237], s[40:41], 0, v[134:135]
	ds_read_b128 v[196:199], v160 offset:32768
	ds_read_b128 v[200:203], v160 offset:33792
	ds_read_b128 v[206:209], v160 offset:34816
	ds_read_b128 v[210:213], v160 offset:35840
	ds_read_b128 v[214:217], v160 offset:36864
	ds_read_b128 v[218:221], v160 offset:37888
	ds_read_b128 v[222:225], v160 offset:38912
	ds_read_b128 v[226:229], v160 offset:39936
	global_load_lds_dwordx4 v[236:237], off
	v_lshl_add_u64 v[236:237], s[40:41], 0, v[132:133]
	s_mov_b32 m0, s47
	s_nop 0
	global_load_lds_dwordx4 v[236:237], off
	s_waitcnt vmcnt(8)
	s_waitcnt lgkmcnt(0)
	s_barrier
	s_setprio 1
	v_mfma_f32_16x16x32_bf16 v[126:129], v[162:165], v[196:199], v[126:129]
	v_mfma_f32_16x16x32_bf16 v[122:125], v[170:173], v[196:199], v[122:125]
	v_mfma_f32_16x16x32_bf16 v[118:121], v[162:165], v[206:209], v[118:121]
	v_mfma_f32_16x16x32_bf16 v[114:117], v[170:173], v[206:209], v[114:117]
	v_mfma_f32_16x16x32_bf16 v[102:105], v[162:165], v[214:217], v[102:105]
	v_mfma_f32_16x16x32_bf16 v[98:101], v[170:173], v[214:217], v[98:101]
	v_mfma_f32_16x16x32_bf16 v[42:45], v[162:165], v[222:225], v[42:45]
	v_mfma_f32_16x16x32_bf16 v[34:37], v[170:173], v[222:225], v[34:37]
	v_mfma_f32_16x16x32_bf16 v[126:129], v[166:169], v[200:203], v[126:129]
	v_mfma_f32_16x16x32_bf16 v[122:125], v[174:177], v[200:203], v[122:125]
	v_mfma_f32_16x16x32_bf16 v[118:121], v[166:169], v[210:213], v[118:121]
	v_mfma_f32_16x16x32_bf16 v[114:117], v[174:177], v[210:213], v[114:117]
	v_mfma_f32_16x16x32_bf16 v[102:105], v[166:169], v[218:221], v[102:105]
	v_mfma_f32_16x16x32_bf16 v[98:101], v[174:177], v[218:221], v[98:101]
	v_mfma_f32_16x16x32_bf16 v[42:45], v[166:169], v[226:229], v[42:45]
	v_mfma_f32_16x16x32_bf16 v[34:37], v[174:177], v[226:229], v[34:37]
	v_mfma_f32_16x16x32_bf16 v[110:113], v[178:181], v[196:199], v[110:113]
	v_mfma_f32_16x16x32_bf16 v[106:109], v[186:189], v[196:199], v[106:109]
	v_mfma_f32_16x16x32_bf16 v[94:97], v[178:181], v[206:209], v[94:97]
	v_mfma_f32_16x16x32_bf16 v[90:93], v[186:189], v[206:209], v[90:93]
	v_mfma_f32_16x16x32_bf16 v[86:89], v[178:181], v[214:217], v[86:89]
	v_mfma_f32_16x16x32_bf16 v[82:85], v[186:189], v[214:217], v[82:85]
	v_mfma_f32_16x16x32_bf16 v[30:33], v[178:181], v[222:225], v[30:33]
	v_mfma_f32_16x16x32_bf16 v[26:29], v[186:189], v[222:225], v[26:29]
	v_mfma_f32_16x16x32_bf16 v[110:113], v[182:185], v[200:203], v[110:113]
	v_mfma_f32_16x16x32_bf16 v[106:109], v[190:193], v[200:203], v[106:109]
	v_mfma_f32_16x16x32_bf16 v[94:97], v[182:185], v[210:213], v[94:97]
	v_mfma_f32_16x16x32_bf16 v[90:93], v[190:193], v[210:213], v[90:93]
	v_mfma_f32_16x16x32_bf16 v[86:89], v[182:185], v[218:221], v[86:89]
	v_mfma_f32_16x16x32_bf16 v[82:85], v[190:193], v[218:221], v[82:85]
	v_mfma_f32_16x16x32_bf16 v[30:33], v[182:185], v[226:229], v[30:33]
	v_mfma_f32_16x16x32_bf16 v[26:29], v[190:193], v[226:229], v[26:29]
	s_setprio 0
	s_barrier
	s_add_i32 s40, s66, s42
	v_lshl_add_u64 v[158:159], v[158:159], 0, s[12:13]
	s_mov_b32 m0, s40
	ds_read_b128 v[196:199], v160 offset:49152
	ds_read_b128 v[200:203], v160 offset:50176
	ds_read_b128 v[206:209], v160 offset:51200
	ds_read_b128 v[210:213], v160 offset:52224
	ds_read_b128 v[214:217], v160 offset:53248
	ds_read_b128 v[218:221], v160 offset:54272
	ds_read_b128 v[222:225], v160 offset:55296
	ds_read_b128 v[226:229], v160 offset:56320
	global_load_lds_dwordx4 v[158:159], off
	s_add_i32 m0, s40, 0x2000
	s_add_u32 s34, s34, 0x100080
	v_lshl_add_u64 v[158:159], v[230:231], 0, s[12:13]
	s_addc_u32 s35, s35, 0
	s_add_i32 s40, s67, s42
	global_load_lds_dwordx4 v[158:159], off
	v_lshl_add_u64 v[158:159], s[34:35], 0, v[134:135]
	s_mov_b32 m0, s40
	s_nop 0
	global_load_lds_dwordx4 v[158:159], off
	v_lshl_add_u64 v[158:159], s[34:35], 0, v[132:133]
	s_add_i32 m0, s40, 0x2000
	s_nop 0
	global_load_lds_dwordx4 v[158:159], off
	v_lshl_add_u64 v[158:159], v[232:233], 0, s[12:13]
	s_mov_b32 m0, s52
	s_nop 0
	global_load_lds_dwordx4 v[158:159], off
	v_lshl_add_u64 v[158:159], v[234:235], 0, s[12:13]
	s_mov_b32 m0, s53
	s_nop 0
	global_load_lds_dwordx4 v[158:159], off
	s_waitcnt vmcnt(8)
	s_waitcnt lgkmcnt(0)
	s_barrier
	s_setprio 1
	v_mfma_f32_16x16x32_bf16 v[78:81], v[162:165], v[196:199], v[78:81]
	v_mfma_f32_16x16x32_bf16 v[74:77], v[170:173], v[196:199], v[74:77]
	v_mfma_f32_16x16x32_bf16 v[70:73], v[162:165], v[206:209], v[70:73]
	v_mfma_f32_16x16x32_bf16 v[66:69], v[170:173], v[206:209], v[66:69]
	v_mfma_f32_16x16x32_bf16 v[54:57], v[162:165], v[214:217], v[54:57]
	v_mfma_f32_16x16x32_bf16 v[50:53], v[170:173], v[214:217], v[50:53]
	v_mfma_f32_16x16x32_bf16 v[14:17], v[162:165], v[222:225], v[14:17]
	v_mfma_f32_16x16x32_bf16 v[10:13], v[170:173], v[222:225], v[10:13]
	v_mfma_f32_16x16x32_bf16 v[78:81], v[166:169], v[200:203], v[78:81]
	v_mfma_f32_16x16x32_bf16 v[74:77], v[174:177], v[200:203], v[74:77]
	v_mfma_f32_16x16x32_bf16 v[70:73], v[166:169], v[210:213], v[70:73]
	v_mfma_f32_16x16x32_bf16 v[66:69], v[174:177], v[210:213], v[66:69]
	v_mfma_f32_16x16x32_bf16 v[54:57], v[166:169], v[218:221], v[54:57]
	v_mfma_f32_16x16x32_bf16 v[50:53], v[174:177], v[218:221], v[50:53]
	v_mfma_f32_16x16x32_bf16 v[14:17], v[166:169], v[226:229], v[14:17]
	v_mfma_f32_16x16x32_bf16 v[10:13], v[174:177], v[226:229], v[10:13]
	v_mfma_f32_16x16x32_bf16 v[62:65], v[178:181], v[196:199], v[62:65]
	v_mfma_f32_16x16x32_bf16 v[58:61], v[186:189], v[196:199], v[58:61]
	v_mfma_f32_16x16x32_bf16 v[46:49], v[178:181], v[206:209], v[46:49]
	v_mfma_f32_16x16x32_bf16 v[38:41], v[186:189], v[206:209], v[38:41]
	v_mfma_f32_16x16x32_bf16 v[22:25], v[178:181], v[214:217], v[22:25]
	v_mfma_f32_16x16x32_bf16 v[18:21], v[186:189], v[214:217], v[18:21]
	v_mfma_f32_16x16x32_bf16 v[6:9], v[178:181], v[222:225], v[6:9]
	v_mfma_f32_16x16x32_bf16 v[2:5], v[186:189], v[222:225], v[2:5]
	v_mfma_f32_16x16x32_bf16 v[62:65], v[182:185], v[200:203], v[62:65]
	v_mfma_f32_16x16x32_bf16 v[58:61], v[190:193], v[200:203], v[58:61]
	v_mfma_f32_16x16x32_bf16 v[46:49], v[182:185], v[210:213], v[46:49]
	v_mfma_f32_16x16x32_bf16 v[38:41], v[190:193], v[210:213], v[38:41]
	v_mfma_f32_16x16x32_bf16 v[22:25], v[182:185], v[218:221], v[22:25]
	v_mfma_f32_16x16x32_bf16 v[18:21], v[190:193], v[218:221], v[18:21]
	v_mfma_f32_16x16x32_bf16 v[6:9], v[182:185], v[226:229], v[6:9]
	v_mfma_f32_16x16x32_bf16 v[2:5], v[190:193], v[226:229], v[2:5]
	s_setprio 0
	s_barrier
	s_add_u32 s30, s30, 0x100
	s_addc_u32 s31, s31, 0
	s_add_u32 s63, s63, 0x100
	s_addc_u32 s64, s64, 0
	s_cmp_ge_i32 s65, s60
	s_mov_b32 s34, s65
	s_cbranch_scc0 .LBB0_1197
	s_and_b64 vcc, exec, s[18:19]
	s_cbranch_vccz .LBB0_1200
	s_barrier

.LBB0_1391:
	ds_read_b128 v[152:155], v159
	ds_read_b128 v[162:165], v159 offset:1024
	ds_read_b128 v[166:169], v159 offset:2048
	ds_read_b128 v[170:173], v159 offset:3072
	ds_read_b128 v[174:177], v160
	ds_read_b128 v[178:181], v160 offset:1024
	ds_read_b128 v[182:185], v160 offset:2048
	ds_read_b128 v[186:189], v160 offset:3072
	s_add_i32 s82, s48, 2
	s_add_u32 s49, s60, 0xfffe0080
	s_addc_u32 s62, s61, -1
	s_cmp_eq_u32 s47, s48
	s_cselect_b32 s48, s54, s51
	s_cselect_b32 s63, s9, s62
	s_cselect_b32 s62, s8, s49
	s_cselect_b32 s49, s55, s53
	v_lshl_add_u64 v[156:157], s[60:61], 0, v[140:141]
	s_add_i32 m0, s57, 0xc000
	ds_read_b128 v[190:193], v161
	ds_read_b128 v[196:199], v161 offset:1024
	ds_read_b128 v[200:203], v161 offset:2048
	ds_read_b128 v[206:209], v161 offset:3072
	ds_read_b128 v[210:213], v161 offset:4096
	ds_read_b128 v[214:217], v161 offset:5120
	ds_read_b128 v[218:221], v161 offset:6144
	ds_read_b128 v[222:225], v161 offset:7168
	global_load_lds_dwordx4 v[156:157], off
	v_lshl_add_u64 v[156:157], s[60:61], 0, v[142:143]
	s_add_i32 m0, s57, 0xe000
	s_nop 0
	global_load_lds_dwordx4 v[156:157], off
	s_waitcnt vmcnt(8)
	s_waitcnt lgkmcnt(0)
	s_barrier
	s_setprio 1
	v_mfma_f32_16x16x32_bf16 v[126:129], v[152:155], v[190:193], v[126:129]
	v_mfma_f32_16x16x32_bf16 v[122:125], v[166:169], v[190:193], v[122:125]
	v_mfma_f32_16x16x32_bf16 v[110:113], v[152:155], v[200:203], v[110:113]
	v_mfma_f32_16x16x32_bf16 v[106:109], v[166:169], v[200:203], v[106:109]
	v_mfma_f32_16x16x32_bf16 v[94:97], v[152:155], v[210:213], v[94:97]
	v_mfma_f32_16x16x32_bf16 v[90:93], v[166:169], v[210:213], v[90:93]
	v_mfma_f32_16x16x32_bf16 v[78:81], v[152:155], v[218:221], v[78:81]
	v_mfma_f32_16x16x32_bf16 v[74:77], v[166:169], v[218:221], v[74:77]
	v_mfma_f32_16x16x32_bf16 v[126:129], v[162:165], v[196:199], v[126:129]
	v_mfma_f32_16x16x32_bf16 v[122:125], v[170:173], v[196:199], v[122:125]
	v_mfma_f32_16x16x32_bf16 v[110:113], v[162:165], v[206:209], v[110:113]
	v_mfma_f32_16x16x32_bf16 v[106:109], v[170:173], v[206:209], v[106:109]
	v_mfma_f32_16x16x32_bf16 v[94:97], v[162:165], v[214:217], v[94:97]
	v_mfma_f32_16x16x32_bf16 v[90:93], v[170:173], v[214:217], v[90:93]
	v_mfma_f32_16x16x32_bf16 v[78:81], v[162:165], v[222:225], v[78:81]
	v_mfma_f32_16x16x32_bf16 v[74:77], v[170:173], v[222:225], v[74:77]
	v_mfma_f32_16x16x32_bf16 v[118:121], v[174:177], v[190:193], v[118:121]
	v_mfma_f32_16x16x32_bf16 v[114:117], v[182:185], v[190:193], v[114:117]
	v_mfma_f32_16x16x32_bf16 v[102:105], v[174:177], v[200:203], v[102:105]
	v_mfma_f32_16x16x32_bf16 v[98:101], v[182:185], v[200:203], v[98:101]
	v_mfma_f32_16x16x32_bf16 v[86:89], v[174:177], v[210:213], v[86:89]
	v_mfma_f32_16x16x32_bf16 v[82:85], v[182:185], v[210:213], v[82:85]
	v_mfma_f32_16x16x32_bf16 v[70:73], v[174:177], v[218:221], v[70:73]
	v_mfma_f32_16x16x32_bf16 v[66:69], v[182:185], v[218:221], v[66:69]
	v_mfma_f32_16x16x32_bf16 v[118:121], v[178:181], v[196:199], v[118:121]
	v_mfma_f32_16x16x32_bf16 v[114:117], v[186:189], v[196:199], v[114:117]
	v_mfma_f32_16x16x32_bf16 v[102:105], v[178:181], v[206:209], v[102:105]
	v_mfma_f32_16x16x32_bf16 v[98:101], v[186:189], v[206:209], v[98:101]
	v_mfma_f32_16x16x32_bf16 v[86:89], v[178:181], v[214:217], v[86:89]
	v_mfma_f32_16x16x32_bf16 v[82:85], v[186:189], v[214:217], v[82:85]
	v_mfma_f32_16x16x32_bf16 v[70:73], v[178:181], v[222:225], v[70:73]
	v_mfma_f32_16x16x32_bf16 v[66:69], v[186:189], v[222:225], v[66:69]
	s_setprio 0
	s_barrier
	s_add_i32 s83, s73, s64
	v_lshl_add_u64 v[156:157], s[48:49], 0, v[134:135]
	s_mov_b32 m0, s83
	ds_read_b128 v[190:193], v161 offset:16384
	ds_read_b128 v[196:199], v161 offset:17408
	ds_read_b128 v[200:203], v161 offset:18432
	ds_read_b128 v[206:209], v161 offset:19456
	ds_read_b128 v[210:213], v161 offset:20480
	ds_read_b128 v[214:217], v161 offset:21504
	ds_read_b128 v[218:221], v161 offset:22528
	ds_read_b128 v[222:225], v161 offset:23552
	global_load_lds_dwordx4 v[156:157], off
	s_add_i32 m0, s83, 0x2000
	s_add_u32 s84, s48, 0x20000
	v_lshl_add_u64 v[226:227], s[48:49], 0, v[138:139]
	s_addc_u32 s85, s49, 0
	s_add_i32 s83, s74, s64
	global_load_lds_dwordx4 v[226:227], off
	v_lshl_add_u64 v[228:229], s[84:85], 0, v[134:135]
	s_mov_b32 m0, s83
	v_lshl_add_u64 v[230:231], s[62:63], 0, v[136:137]
	global_load_lds_dwordx4 v[228:229], off
	v_lshl_add_u64 v[228:229], s[84:85], 0, v[138:139]
	s_add_i32 m0, s83, 0x2000
	s_nop 0
	global_load_lds_dwordx4 v[228:229], off
	v_lshl_add_u64 v[228:229], s[62:63], 0, v[132:133]
	s_mov_b32 m0, s57
	s_nop 0
	global_load_lds_dwordx4 v[228:229], off
	s_mov_b32 m0, s59
	s_nop 0
	global_load_lds_dwordx4 v[230:231], off
	s_waitcnt vmcnt(8)
	s_waitcnt lgkmcnt(0)
	s_barrier
	s_setprio 1
	v_mfma_f32_16x16x32_bf16 v[62:65], v[152:155], v[190:193], v[62:65]
	v_mfma_f32_16x16x32_bf16 v[58:61], v[166:169], v[190:193], v[58:61]
	v_mfma_f32_16x16x32_bf16 v[46:49], v[152:155], v[200:203], v[46:49]
	v_mfma_f32_16x16x32_bf16 v[42:45], v[166:169], v[200:203], v[42:45]
	v_mfma_f32_16x16x32_bf16 v[30:33], v[152:155], v[210:213], v[30:33]
	v_mfma_f32_16x16x32_bf16 v[26:29], v[166:169], v[210:213], v[26:29]
	v_mfma_f32_16x16x32_bf16 v[14:17], v[152:155], v[218:221], v[14:17]
	v_mfma_f32_16x16x32_bf16 v[10:13], v[166:169], v[218:221], v[10:13]
	v_mfma_f32_16x16x32_bf16 v[62:65], v[162:165], v[196:199], v[62:65]
	v_mfma_f32_16x16x32_bf16 v[58:61], v[170:173], v[196:199], v[58:61]
	v_mfma_f32_16x16x32_bf16 v[46:49], v[162:165], v[206:209], v[46:49]
	v_mfma_f32_16x16x32_bf16 v[42:45], v[170:173], v[206:209], v[42:45]
	v_mfma_f32_16x16x32_bf16 v[30:33], v[162:165], v[214:217], v[30:33]
	v_mfma_f32_16x16x32_bf16 v[26:29], v[170:173], v[214:217], v[26:29]
	v_mfma_f32_16x16x32_bf16 v[14:17], v[162:165], v[222:225], v[14:17]
	v_mfma_f32_16x16x32_bf16 v[10:13], v[170:173], v[222:225], v[10:13]
	v_mfma_f32_16x16x32_bf16 v[54:57], v[174:177], v[190:193], v[54:57]
	v_mfma_f32_16x16x32_bf16 v[50:53], v[182:185], v[190:193], v[50:53]
	v_mfma_f32_16x16x32_bf16 v[38:41], v[174:177], v[200:203], v[38:41]
	v_mfma_f32_16x16x32_bf16 v[34:37], v[182:185], v[200:203], v[34:37]
	v_mfma_f32_16x16x32_bf16 v[22:25], v[174:177], v[210:213], v[22:25]
	v_mfma_f32_16x16x32_bf16 v[18:21], v[182:185], v[210:213], v[18:21]
	v_mfma_f32_16x16x32_bf16 v[6:9], v[174:177], v[218:221], v[6:9]
	v_mfma_f32_16x16x32_bf16 v[2:5], v[182:185], v[218:221], v[2:5]
	v_mfma_f32_16x16x32_bf16 v[54:57], v[178:181], v[196:199], v[54:57]
	v_mfma_f32_16x16x32_bf16 v[50:53], v[186:189], v[196:199], v[50:53]
	v_mfma_f32_16x16x32_bf16 v[38:41], v[178:181], v[206:209], v[38:41]
	v_mfma_f32_16x16x32_bf16 v[34:37], v[186:189], v[206:209], v[34:37]
	v_mfma_f32_16x16x32_bf16 v[22:25], v[178:181], v[214:217], v[22:25]
	v_mfma_f32_16x16x32_bf16 v[18:21], v[186:189], v[214:217], v[18:21]
	v_mfma_f32_16x16x32_bf16 v[6:9], v[178:181], v[222:225], v[6:9]
	v_mfma_f32_16x16x32_bf16 v[2:5], v[186:189], v[222:225], v[2:5]
	s_setprio 0
	s_barrier
	s_add_i32 s83, 0, 0x18000
	s_add_i32 s84, 0, 0x1c000
	v_add_u32_e32 v170, s83, v131
	v_add_u32_e32 v186, s84, v131
	ds_read_b128 v[152:155], v170
	ds_read_b128 v[162:165], v170 offset:1024
	ds_read_b128 v[166:169], v170 offset:2048
	ds_read_b128 v[170:173], v170 offset:3072
	ds_read_b128 v[174:177], v186
	ds_read_b128 v[178:181], v186 offset:1024
	ds_read_b128 v[182:185], v186 offset:2048
	ds_read_b128 v[186:189], v186 offset:3072
	s_add_u32 s62, s62, 0x20000
	s_addc_u32 s63, s63, 0
	s_mov_b32 m0, s65
	v_lshl_add_u64 v[232:233], s[62:63], 0, v[132:133]
	ds_read_b128 v[190:193], v161 offset:32768
	ds_read_b128 v[196:199], v161 offset:33792
	ds_read_b128 v[200:203], v161 offset:34816
	ds_read_b128 v[206:209], v161 offset:35840
	ds_read_b128 v[210:213], v161 offset:36864
	ds_read_b128 v[214:217], v161 offset:37888
	ds_read_b128 v[218:221], v161 offset:38912
	ds_read_b128 v[222:225], v161 offset:39936
	global_load_lds_dwordx4 v[232:233], off
	v_lshl_add_u64 v[232:233], s[62:63], 0, v[136:137]
	s_mov_b32 m0, s66
	s_nop 0
	global_load_lds_dwordx4 v[232:233], off
	s_waitcnt vmcnt(8)
	s_waitcnt lgkmcnt(0)
	s_barrier
	s_setprio 1
	v_mfma_f32_16x16x32_bf16 v[126:129], v[152:155], v[190:193], v[126:129]
	v_mfma_f32_16x16x32_bf16 v[122:125], v[166:169], v[190:193], v[122:125]
	v_mfma_f32_16x16x32_bf16 v[110:113], v[152:155], v[200:203], v[110:113]
	v_mfma_f32_16x16x32_bf16 v[106:109], v[166:169], v[200:203], v[106:109]
	v_mfma_f32_16x16x32_bf16 v[94:97], v[152:155], v[210:213], v[94:97]
	v_mfma_f32_16x16x32_bf16 v[90:93], v[166:169], v[210:213], v[90:93]
	v_mfma_f32_16x16x32_bf16 v[78:81], v[152:155], v[218:221], v[78:81]
	v_mfma_f32_16x16x32_bf16 v[74:77], v[166:169], v[218:221], v[74:77]
	v_mfma_f32_16x16x32_bf16 v[126:129], v[162:165], v[196:199], v[126:129]
	v_mfma_f32_16x16x32_bf16 v[122:125], v[170:173], v[196:199], v[122:125]
	v_mfma_f32_16x16x32_bf16 v[110:113], v[162:165], v[206:209], v[110:113]
	v_mfma_f32_16x16x32_bf16 v[106:109], v[170:173], v[206:209], v[106:109]
	v_mfma_f32_16x16x32_bf16 v[94:97], v[162:165], v[214:217], v[94:97]
	v_mfma_f32_16x16x32_bf16 v[90:93], v[170:173], v[214:217], v[90:93]
	v_mfma_f32_16x16x32_bf16 v[78:81], v[162:165], v[222:225], v[78:81]
	v_mfma_f32_16x16x32_bf16 v[74:77], v[170:173], v[222:225], v[74:77]
	v_mfma_f32_16x16x32_bf16 v[118:121], v[174:177], v[190:193], v[118:121]
	v_mfma_f32_16x16x32_bf16 v[114:117], v[182:185], v[190:193], v[114:117]
	v_mfma_f32_16x16x32_bf16 v[102:105], v[174:177], v[200:203], v[102:105]
	v_mfma_f32_16x16x32_bf16 v[98:101], v[182:185], v[200:203], v[98:101]
	v_mfma_f32_16x16x32_bf16 v[86:89], v[174:177], v[210:213], v[86:89]
	v_mfma_f32_16x16x32_bf16 v[82:85], v[182:185], v[210:213], v[82:85]
	v_mfma_f32_16x16x32_bf16 v[70:73], v[174:177], v[218:221], v[70:73]
	v_mfma_f32_16x16x32_bf16 v[66:69], v[182:185], v[218:221], v[66:69]
	v_mfma_f32_16x16x32_bf16 v[118:121], v[178:181], v[196:199], v[118:121]
	v_mfma_f32_16x16x32_bf16 v[114:117], v[186:189], v[196:199], v[114:117]
	v_mfma_f32_16x16x32_bf16 v[102:105], v[178:181], v[206:209], v[102:105]
	v_mfma_f32_16x16x32_bf16 v[98:101], v[186:189], v[206:209], v[98:101]
	v_mfma_f32_16x16x32_bf16 v[86:89], v[178:181], v[214:217], v[86:89]
	v_mfma_f32_16x16x32_bf16 v[82:85], v[186:189], v[214:217], v[82:85]
	v_mfma_f32_16x16x32_bf16 v[70:73], v[178:181], v[222:225], v[70:73]
	v_mfma_f32_16x16x32_bf16 v[66:69], v[186:189], v[222:225], v[66:69]
	s_setprio 0
	s_barrier
	s_add_i32 s62, s83, s64
	v_lshl_add_u64 v[156:157], v[156:157], 0, s[18:19]
	s_mov_b32 m0, s62
	ds_read_b128 v[190:193], v161 offset:49152
	ds_read_b128 v[196:199], v161 offset:50176
	ds_read_b128 v[200:203], v161 offset:51200
	ds_read_b128 v[206:209], v161 offset:52224
	ds_read_b128 v[210:213], v161 offset:53248
	ds_read_b128 v[214:217], v161 offset:54272
	ds_read_b128 v[218:221], v161 offset:55296
	ds_read_b128 v[222:225], v161 offset:56320
	global_load_lds_dwordx4 v[156:157], off
	s_add_i32 m0, s62, 0x2000
	s_add_u32 s48, s48, 0x20080
	v_lshl_add_u64 v[156:157], v[226:227], 0, s[18:19]
	s_addc_u32 s49, s49, 0
	s_add_i32 s62, s84, s64
	global_load_lds_dwordx4 v[156:157], off
	v_lshl_add_u64 v[156:157], s[48:49], 0, v[134:135]
	s_mov_b32 m0, s62
	s_nop 0
	global_load_lds_dwordx4 v[156:157], off
	v_lshl_add_u64 v[156:157], s[48:49], 0, v[138:139]
	s_add_i32 m0, s62, 0x2000
	s_nop 0
	global_load_lds_dwordx4 v[156:157], off
	v_lshl_add_u64 v[156:157], v[228:229], 0, s[18:19]
	s_mov_b32 m0, s70
	s_nop 0
	global_load_lds_dwordx4 v[156:157], off
	v_lshl_add_u64 v[156:157], v[230:231], 0, s[18:19]
	s_mov_b32 m0, s71
	s_nop 0
	global_load_lds_dwordx4 v[156:157], off
	s_waitcnt vmcnt(8)
	s_waitcnt lgkmcnt(0)
	s_barrier
	s_setprio 1
	v_mfma_f32_16x16x32_bf16 v[62:65], v[152:155], v[190:193], v[62:65]
	v_mfma_f32_16x16x32_bf16 v[58:61], v[166:169], v[190:193], v[58:61]
	v_mfma_f32_16x16x32_bf16 v[46:49], v[152:155], v[200:203], v[46:49]
	v_mfma_f32_16x16x32_bf16 v[42:45], v[166:169], v[200:203], v[42:45]
	v_mfma_f32_16x16x32_bf16 v[30:33], v[152:155], v[210:213], v[30:33]
	v_mfma_f32_16x16x32_bf16 v[26:29], v[166:169], v[210:213], v[26:29]
	v_mfma_f32_16x16x32_bf16 v[14:17], v[152:155], v[218:221], v[14:17]
	v_mfma_f32_16x16x32_bf16 v[10:13], v[166:169], v[218:221], v[10:13]
	v_mfma_f32_16x16x32_bf16 v[62:65], v[162:165], v[196:199], v[62:65]
	v_mfma_f32_16x16x32_bf16 v[58:61], v[170:173], v[196:199], v[58:61]
	v_mfma_f32_16x16x32_bf16 v[46:49], v[162:165], v[206:209], v[46:49]
	v_mfma_f32_16x16x32_bf16 v[42:45], v[170:173], v[206:209], v[42:45]
	v_mfma_f32_16x16x32_bf16 v[30:33], v[162:165], v[214:217], v[30:33]
	v_mfma_f32_16x16x32_bf16 v[26:29], v[170:173], v[214:217], v[26:29]
	v_mfma_f32_16x16x32_bf16 v[14:17], v[162:165], v[222:225], v[14:17]
	v_mfma_f32_16x16x32_bf16 v[10:13], v[170:173], v[222:225], v[10:13]
	v_mfma_f32_16x16x32_bf16 v[54:57], v[174:177], v[190:193], v[54:57]
	v_mfma_f32_16x16x32_bf16 v[50:53], v[182:185], v[190:193], v[50:53]
	v_mfma_f32_16x16x32_bf16 v[38:41], v[174:177], v[200:203], v[38:41]
	v_mfma_f32_16x16x32_bf16 v[34:37], v[182:185], v[200:203], v[34:37]
	v_mfma_f32_16x16x32_bf16 v[22:25], v[174:177], v[210:213], v[22:25]
	v_mfma_f32_16x16x32_bf16 v[18:21], v[182:185], v[210:213], v[18:21]
	v_mfma_f32_16x16x32_bf16 v[6:9], v[174:177], v[218:221], v[6:9]
	v_mfma_f32_16x16x32_bf16 v[2:5], v[182:185], v[218:221], v[2:5]
	v_mfma_f32_16x16x32_bf16 v[54:57], v[178:181], v[196:199], v[54:57]
	v_mfma_f32_16x16x32_bf16 v[50:53], v[186:189], v[196:199], v[50:53]
	v_mfma_f32_16x16x32_bf16 v[38:41], v[178:181], v[206:209], v[38:41]
	v_mfma_f32_16x16x32_bf16 v[34:37], v[186:189], v[206:209], v[34:37]
	v_mfma_f32_16x16x32_bf16 v[22:25], v[178:181], v[214:217], v[22:25]
	v_mfma_f32_16x16x32_bf16 v[18:21], v[186:189], v[214:217], v[18:21]
	v_mfma_f32_16x16x32_bf16 v[6:9], v[178:181], v[222:225], v[6:9]
	v_mfma_f32_16x16x32_bf16 v[2:5], v[186:189], v[222:225], v[2:5]
	s_setprio 0
	s_barrier
	s_add_u32 s60, s60, 0x100
	s_addc_u32 s61, s61, 0
	s_add_u32 s51, s51, 0x100
	s_addc_u32 s53, s53, 0
	s_cmp_ge_i32 s82, s81
	s_mov_b32 s48, s82
	s_cbranch_scc0 .LBB0_1391
	s_and_b64 vcc, exec, s[20:21]
	s_cbranch_vccz .LBB0_1394
	s_barrier

.LBB0_1553:
	ds_read_b128 v[156:159], v161
	ds_read_b128 v[164:167], v161 offset:1024
	ds_read_b128 v[168:171], v161 offset:2048
	ds_read_b128 v[172:175], v161 offset:3072
	ds_read_b128 v[176:179], v162
	ds_read_b128 v[180:183], v162 offset:1024
	ds_read_b128 v[184:187], v162 offset:2048
	ds_read_b128 v[188:191], v162 offset:3072
	s_add_i32 s76, s48, 2
	s_add_u32 s49, s46, 0xfff00080
	s_addc_u32 s50, s47, -1
	s_cmp_eq_u32 s73, s48
	s_cselect_b32 s48, s29, s74
	s_cselect_b32 s51, s9, s50
	s_cselect_b32 s50, s27, s49
	s_cselect_b32 s49, s25, s75
	v_lshl_add_u64 v[192:193], s[46:47], 0, v[148:149]
	s_add_i32 m0, s43, 0xc000
	ds_read_b128 v[196:199], v163
	ds_read_b128 v[200:203], v163 offset:1024
	ds_read_b128 v[206:209], v163 offset:2048
	ds_read_b128 v[210:213], v163 offset:3072
	ds_read_b128 v[214:217], v163 offset:4096
	ds_read_b128 v[218:221], v163 offset:5120
	ds_read_b128 v[222:225], v163 offset:6144
	ds_read_b128 v[226:229], v163 offset:7168
	global_load_lds_dwordx4 v[192:193], off
	v_lshl_add_u64 v[192:193], s[46:47], 0, v[150:151]
	s_add_i32 m0, s43, 0xe000
	s_nop 0
	global_load_lds_dwordx4 v[192:193], off
	s_waitcnt vmcnt(8)
	s_waitcnt lgkmcnt(0)
	s_barrier
	s_setprio 1
	v_mfma_f32_16x16x32_bf16 v[78:81], v[156:159], v[196:199], v[78:81]
	v_mfma_f32_16x16x32_bf16 v[74:77], v[168:171], v[196:199], v[74:77]
	v_mfma_f32_16x16x32_bf16 v[70:73], v[156:159], v[206:209], v[70:73]
	v_mfma_f32_16x16x32_bf16 v[62:65], v[168:171], v[206:209], v[62:65]
	v_mfma_f32_16x16x32_bf16 v[58:61], v[156:159], v[214:217], v[58:61]
	v_mfma_f32_16x16x32_bf16 v[54:57], v[168:171], v[214:217], v[54:57]
	v_mfma_f32_16x16x32_bf16 v[46:49], v[156:159], v[222:225], v[46:49]
	v_mfma_f32_16x16x32_bf16 v[38:41], v[168:171], v[222:225], v[38:41]
	v_mfma_f32_16x16x32_bf16 v[78:81], v[164:167], v[200:203], v[78:81]
	v_mfma_f32_16x16x32_bf16 v[74:77], v[172:175], v[200:203], v[74:77]
	v_mfma_f32_16x16x32_bf16 v[70:73], v[164:167], v[210:213], v[70:73]
	v_mfma_f32_16x16x32_bf16 v[62:65], v[172:175], v[210:213], v[62:65]
	v_mfma_f32_16x16x32_bf16 v[58:61], v[164:167], v[218:221], v[58:61]
	v_mfma_f32_16x16x32_bf16 v[54:57], v[172:175], v[218:221], v[54:57]
	v_mfma_f32_16x16x32_bf16 v[46:49], v[164:167], v[226:229], v[46:49]
	v_mfma_f32_16x16x32_bf16 v[38:41], v[172:175], v[226:229], v[38:41]
	v_mfma_f32_16x16x32_bf16 v[50:53], v[176:179], v[196:199], v[50:53]
	v_mfma_f32_16x16x32_bf16 v[42:45], v[184:187], v[196:199], v[42:45]
	v_mfma_f32_16x16x32_bf16 v[34:37], v[176:179], v[206:209], v[34:37]
	v_mfma_f32_16x16x32_bf16 v[26:29], v[184:187], v[206:209], v[26:29]
	v_mfma_f32_16x16x32_bf16 v[18:21], v[176:179], v[214:217], v[18:21]
	v_mfma_f32_16x16x32_bf16 v[14:17], v[184:187], v[214:217], v[14:17]
	v_mfma_f32_16x16x32_bf16 v[10:13], v[176:179], v[222:225], v[10:13]
	v_mfma_f32_16x16x32_bf16 v[6:9], v[184:187], v[222:225], v[6:9]
	v_mfma_f32_16x16x32_bf16 v[50:53], v[180:183], v[200:203], v[50:53]
	v_mfma_f32_16x16x32_bf16 v[42:45], v[188:191], v[200:203], v[42:45]
	v_mfma_f32_16x16x32_bf16 v[34:37], v[180:183], v[210:213], v[34:37]
	v_mfma_f32_16x16x32_bf16 v[26:29], v[188:191], v[210:213], v[26:29]
	v_mfma_f32_16x16x32_bf16 v[18:21], v[180:183], v[218:221], v[18:21]
	v_mfma_f32_16x16x32_bf16 v[14:17], v[188:191], v[218:221], v[14:17]
	v_mfma_f32_16x16x32_bf16 v[10:13], v[180:183], v[226:229], v[10:13]
	v_mfma_f32_16x16x32_bf16 v[6:9], v[188:191], v[226:229], v[6:9]
	s_setprio 0
	s_barrier
	s_add_i32 s77, s66, s53
	v_lshl_add_u64 v[192:193], s[48:49], 0, v[134:135]
	s_mov_b32 m0, s77
	ds_read_b128 v[196:199], v163 offset:16384
	ds_read_b128 v[200:203], v163 offset:17408
	ds_read_b128 v[206:209], v163 offset:18432
	ds_read_b128 v[210:213], v163 offset:19456
	ds_read_b128 v[214:217], v163 offset:20480
	ds_read_b128 v[218:221], v163 offset:21504
	ds_read_b128 v[222:225], v163 offset:22528
	ds_read_b128 v[226:229], v163 offset:23552
	global_load_lds_dwordx4 v[192:193], off
	s_add_i32 m0, s77, 0x2000
	s_add_u32 s78, s48, 0x100000
	v_lshl_add_u64 v[230:231], s[48:49], 0, v[138:139]
	s_addc_u32 s79, s49, 0
	s_add_i32 s77, s67, s53
	global_load_lds_dwordx4 v[230:231], off
	v_lshl_add_u64 v[232:233], s[78:79], 0, v[134:135]
	s_mov_b32 m0, s77
	v_lshl_add_u64 v[234:235], s[50:51], 0, v[136:137]
	global_load_lds_dwordx4 v[232:233], off
	v_lshl_add_u64 v[232:233], s[78:79], 0, v[138:139]
	s_add_i32 m0, s77, 0x2000
	s_nop 0
	global_load_lds_dwordx4 v[232:233], off
	v_lshl_add_u64 v[232:233], s[50:51], 0, v[132:133]
	s_mov_b32 m0, s43
	s_nop 0
	global_load_lds_dwordx4 v[232:233], off
	s_mov_b32 m0, s54
	s_nop 0
	global_load_lds_dwordx4 v[234:235], off
	s_waitcnt vmcnt(8)
	s_waitcnt lgkmcnt(0)
	s_barrier
	s_setprio 1
	v_mfma_f32_16x16x32_bf16 v[126:129], v[156:159], v[196:199], v[126:129]
	v_mfma_f32_16x16x32_bf16 v[118:121], v[168:171], v[196:199], v[118:121]
	v_mfma_f32_16x16x32_bf16 v[110:113], v[156:159], v[206:209], v[110:113]
	v_mfma_f32_16x16x32_bf16 v[102:105], v[168:171], v[206:209], v[102:105]
	v_mfma_f32_16x16x32_bf16 v[94:97], v[156:159], v[214:217], v[94:97]
	v_mfma_f32_16x16x32_bf16 v[86:89], v[168:171], v[214:217], v[86:89]
	v_mfma_f32_16x16x32_bf16 v[66:69], v[156:159], v[222:225], v[66:69]
	v_mfma_f32_16x16x32_bf16 v[22:25], v[168:171], v[222:225], v[22:25]
	v_mfma_f32_16x16x32_bf16 v[126:129], v[164:167], v[200:203], v[126:129]
	v_mfma_f32_16x16x32_bf16 v[118:121], v[172:175], v[200:203], v[118:121]
	v_mfma_f32_16x16x32_bf16 v[110:113], v[164:167], v[210:213], v[110:113]
	v_mfma_f32_16x16x32_bf16 v[102:105], v[172:175], v[210:213], v[102:105]
	v_mfma_f32_16x16x32_bf16 v[94:97], v[164:167], v[218:221], v[94:97]
	v_mfma_f32_16x16x32_bf16 v[86:89], v[172:175], v[218:221], v[86:89]
	v_mfma_f32_16x16x32_bf16 v[66:69], v[164:167], v[226:229], v[66:69]
	v_mfma_f32_16x16x32_bf16 v[22:25], v[172:175], v[226:229], v[22:25]
	v_mfma_f32_16x16x32_bf16 v[122:125], v[176:179], v[196:199], v[122:125]
	v_mfma_f32_16x16x32_bf16 v[114:117], v[184:187], v[196:199], v[114:117]
	v_mfma_f32_16x16x32_bf16 v[106:109], v[176:179], v[206:209], v[106:109]
	v_mfma_f32_16x16x32_bf16 v[98:101], v[184:187], v[206:209], v[98:101]
	v_mfma_f32_16x16x32_bf16 v[90:93], v[176:179], v[214:217], v[90:93]
	v_mfma_f32_16x16x32_bf16 v[82:85], v[184:187], v[214:217], v[82:85]
	v_mfma_f32_16x16x32_bf16 v[30:33], v[176:179], v[222:225], v[30:33]
	v_mfma_f32_16x16x32_bf16 v[2:5], v[184:187], v[222:225], v[2:5]
	v_mfma_f32_16x16x32_bf16 v[122:125], v[180:183], v[200:203], v[122:125]
	v_mfma_f32_16x16x32_bf16 v[114:117], v[188:191], v[200:203], v[114:117]
	v_mfma_f32_16x16x32_bf16 v[106:109], v[180:183], v[210:213], v[106:109]
	v_mfma_f32_16x16x32_bf16 v[98:101], v[188:191], v[210:213], v[98:101]
	v_mfma_f32_16x16x32_bf16 v[90:93], v[180:183], v[218:221], v[90:93]
	v_mfma_f32_16x16x32_bf16 v[82:85], v[188:191], v[218:221], v[82:85]
	v_mfma_f32_16x16x32_bf16 v[30:33], v[180:183], v[226:229], v[30:33]
	v_mfma_f32_16x16x32_bf16 v[2:5], v[188:191], v[226:229], v[2:5]
	s_setprio 0
	s_barrier
	s_add_i32 s77, 0, 0x18000
	s_add_i32 s78, 0, 0x1c000
	v_add_u32_e32 v172, s77, v131
	v_add_u32_e32 v188, s78, v131
	ds_read_b128 v[156:159], v172
	ds_read_b128 v[164:167], v172 offset:1024
	ds_read_b128 v[168:171], v172 offset:2048
	ds_read_b128 v[172:175], v172 offset:3072
	ds_read_b128 v[176:179], v188
	ds_read_b128 v[180:183], v188 offset:1024
	ds_read_b128 v[184:187], v188 offset:2048
	ds_read_b128 v[188:191], v188 offset:3072
	s_add_u32 s50, s50, 0x100000
	s_addc_u32 s51, s51, 0
	s_mov_b32 m0, s55
	v_lshl_add_u64 v[236:237], s[50:51], 0, v[132:133]
	ds_read_b128 v[196:199], v163 offset:32768
	ds_read_b128 v[200:203], v163 offset:33792
	ds_read_b128 v[206:209], v163 offset:34816
	ds_read_b128 v[210:213], v163 offset:35840
	ds_read_b128 v[214:217], v163 offset:36864
	ds_read_b128 v[218:221], v163 offset:37888
	ds_read_b128 v[222:225], v163 offset:38912
	ds_read_b128 v[226:229], v163 offset:39936
	global_load_lds_dwordx4 v[236:237], off
	v_lshl_add_u64 v[236:237], s[50:51], 0, v[136:137]
	s_mov_b32 m0, s56
	s_nop 0
	global_load_lds_dwordx4 v[236:237], off
	s_waitcnt vmcnt(8)
	s_waitcnt lgkmcnt(0)
	s_barrier
	s_setprio 1
	v_mfma_f32_16x16x32_bf16 v[78:81], v[156:159], v[196:199], v[78:81]
	v_mfma_f32_16x16x32_bf16 v[74:77], v[168:171], v[196:199], v[74:77]
	v_mfma_f32_16x16x32_bf16 v[70:73], v[156:159], v[206:209], v[70:73]
	v_mfma_f32_16x16x32_bf16 v[62:65], v[168:171], v[206:209], v[62:65]
	v_mfma_f32_16x16x32_bf16 v[58:61], v[156:159], v[214:217], v[58:61]
	v_mfma_f32_16x16x32_bf16 v[54:57], v[168:171], v[214:217], v[54:57]
	v_mfma_f32_16x16x32_bf16 v[46:49], v[156:159], v[222:225], v[46:49]
	v_mfma_f32_16x16x32_bf16 v[38:41], v[168:171], v[222:225], v[38:41]
	v_mfma_f32_16x16x32_bf16 v[78:81], v[164:167], v[200:203], v[78:81]
	v_mfma_f32_16x16x32_bf16 v[74:77], v[172:175], v[200:203], v[74:77]
	v_mfma_f32_16x16x32_bf16 v[70:73], v[164:167], v[210:213], v[70:73]
	v_mfma_f32_16x16x32_bf16 v[62:65], v[172:175], v[210:213], v[62:65]
	v_mfma_f32_16x16x32_bf16 v[58:61], v[164:167], v[218:221], v[58:61]
	v_mfma_f32_16x16x32_bf16 v[54:57], v[172:175], v[218:221], v[54:57]
	v_mfma_f32_16x16x32_bf16 v[46:49], v[164:167], v[226:229], v[46:49]
	v_mfma_f32_16x16x32_bf16 v[38:41], v[172:175], v[226:229], v[38:41]
	v_mfma_f32_16x16x32_bf16 v[50:53], v[176:179], v[196:199], v[50:53]
	v_mfma_f32_16x16x32_bf16 v[42:45], v[184:187], v[196:199], v[42:45]
	v_mfma_f32_16x16x32_bf16 v[34:37], v[176:179], v[206:209], v[34:37]
	v_mfma_f32_16x16x32_bf16 v[26:29], v[184:187], v[206:209], v[26:29]
	v_mfma_f32_16x16x32_bf16 v[18:21], v[176:179], v[214:217], v[18:21]
	v_mfma_f32_16x16x32_bf16 v[14:17], v[184:187], v[214:217], v[14:17]
	v_mfma_f32_16x16x32_bf16 v[10:13], v[176:179], v[222:225], v[10:13]
	v_mfma_f32_16x16x32_bf16 v[6:9], v[184:187], v[222:225], v[6:9]
	v_mfma_f32_16x16x32_bf16 v[50:53], v[180:183], v[200:203], v[50:53]
	v_mfma_f32_16x16x32_bf16 v[42:45], v[188:191], v[200:203], v[42:45]
	v_mfma_f32_16x16x32_bf16 v[34:37], v[180:183], v[210:213], v[34:37]
	v_mfma_f32_16x16x32_bf16 v[26:29], v[188:191], v[210:213], v[26:29]
	v_mfma_f32_16x16x32_bf16 v[18:21], v[180:183], v[218:221], v[18:21]
	v_mfma_f32_16x16x32_bf16 v[14:17], v[188:191], v[218:221], v[14:17]
	v_mfma_f32_16x16x32_bf16 v[10:13], v[180:183], v[226:229], v[10:13]
	v_mfma_f32_16x16x32_bf16 v[6:9], v[188:191], v[226:229], v[6:9]
	s_setprio 0
	s_barrier
	s_add_i32 s50, s77, s53
	v_lshl_add_u64 v[192:193], v[192:193], 0, s[14:15]
	s_mov_b32 m0, s50
	ds_read_b128 v[196:199], v163 offset:49152
	ds_read_b128 v[200:203], v163 offset:50176
	ds_read_b128 v[206:209], v163 offset:51200
	ds_read_b128 v[210:213], v163 offset:52224
	ds_read_b128 v[214:217], v163 offset:53248
	ds_read_b128 v[218:221], v163 offset:54272
	ds_read_b128 v[222:225], v163 offset:55296
	ds_read_b128 v[226:229], v163 offset:56320
	global_load_lds_dwordx4 v[192:193], off
	s_add_i32 m0, s50, 0x2000
	s_add_u32 s48, s48, 0x100080
	v_lshl_add_u64 v[192:193], v[230:231], 0, s[14:15]
	s_addc_u32 s49, s49, 0
	s_add_i32 s50, s78, s53
	global_load_lds_dwordx4 v[192:193], off
	v_lshl_add_u64 v[192:193], s[48:49], 0, v[134:135]
	s_mov_b32 m0, s50
	s_nop 0
	global_load_lds_dwordx4 v[192:193], off
	v_lshl_add_u64 v[192:193], s[48:49], 0, v[138:139]
	s_add_i32 m0, s50, 0x2000
	s_nop 0
	global_load_lds_dwordx4 v[192:193], off
	v_lshl_add_u64 v[192:193], v[232:233], 0, s[14:15]
	s_mov_b32 m0, s59
	s_nop 0
	global_load_lds_dwordx4 v[192:193], off
	v_lshl_add_u64 v[192:193], v[234:235], 0, s[14:15]
	s_mov_b32 m0, s60
	s_nop 0
	global_load_lds_dwordx4 v[192:193], off
	s_waitcnt vmcnt(8)
	s_waitcnt lgkmcnt(0)
	s_barrier
	s_setprio 1
	v_mfma_f32_16x16x32_bf16 v[126:129], v[156:159], v[196:199], v[126:129]
	v_mfma_f32_16x16x32_bf16 v[118:121], v[168:171], v[196:199], v[118:121]
	v_mfma_f32_16x16x32_bf16 v[110:113], v[156:159], v[206:209], v[110:113]
	v_mfma_f32_16x16x32_bf16 v[102:105], v[168:171], v[206:209], v[102:105]
	v_mfma_f32_16x16x32_bf16 v[94:97], v[156:159], v[214:217], v[94:97]
	v_mfma_f32_16x16x32_bf16 v[86:89], v[168:171], v[214:217], v[86:89]
	v_mfma_f32_16x16x32_bf16 v[66:69], v[156:159], v[222:225], v[66:69]
	v_mfma_f32_16x16x32_bf16 v[22:25], v[168:171], v[222:225], v[22:25]
	v_mfma_f32_16x16x32_bf16 v[126:129], v[164:167], v[200:203], v[126:129]
	v_mfma_f32_16x16x32_bf16 v[118:121], v[172:175], v[200:203], v[118:121]
	v_mfma_f32_16x16x32_bf16 v[110:113], v[164:167], v[210:213], v[110:113]
	v_mfma_f32_16x16x32_bf16 v[102:105], v[172:175], v[210:213], v[102:105]
	v_mfma_f32_16x16x32_bf16 v[94:97], v[164:167], v[218:221], v[94:97]
	v_mfma_f32_16x16x32_bf16 v[86:89], v[172:175], v[218:221], v[86:89]
	v_mfma_f32_16x16x32_bf16 v[66:69], v[164:167], v[226:229], v[66:69]
	v_mfma_f32_16x16x32_bf16 v[22:25], v[172:175], v[226:229], v[22:25]
	v_mfma_f32_16x16x32_bf16 v[122:125], v[176:179], v[196:199], v[122:125]
	v_mfma_f32_16x16x32_bf16 v[114:117], v[184:187], v[196:199], v[114:117]
	v_mfma_f32_16x16x32_bf16 v[106:109], v[176:179], v[206:209], v[106:109]
	v_mfma_f32_16x16x32_bf16 v[98:101], v[184:187], v[206:209], v[98:101]
	v_mfma_f32_16x16x32_bf16 v[90:93], v[176:179], v[214:217], v[90:93]
	v_mfma_f32_16x16x32_bf16 v[82:85], v[184:187], v[214:217], v[82:85]
	v_mfma_f32_16x16x32_bf16 v[30:33], v[176:179], v[222:225], v[30:33]
	v_mfma_f32_16x16x32_bf16 v[2:5], v[184:187], v[222:225], v[2:5]
	v_mfma_f32_16x16x32_bf16 v[122:125], v[180:183], v[200:203], v[122:125]
	v_mfma_f32_16x16x32_bf16 v[114:117], v[188:191], v[200:203], v[114:117]
	v_mfma_f32_16x16x32_bf16 v[106:109], v[180:183], v[210:213], v[106:109]
	v_mfma_f32_16x16x32_bf16 v[98:101], v[188:191], v[210:213], v[98:101]
	v_mfma_f32_16x16x32_bf16 v[90:93], v[180:183], v[218:221], v[90:93]
	v_mfma_f32_16x16x32_bf16 v[82:85], v[188:191], v[218:221], v[82:85]
	v_mfma_f32_16x16x32_bf16 v[30:33], v[180:183], v[226:229], v[30:33]
	v_mfma_f32_16x16x32_bf16 v[2:5], v[188:191], v[226:229], v[2:5]
	s_setprio 0
	s_barrier
	s_add_u32 s46, s46, 0x100
	s_addc_u32 s47, s47, 0
	s_add_u32 s74, s74, 0x100
	s_addc_u32 s75, s75, 0
	s_cmp_ge_i32 s76, s72
	s_mov_b32 s48, s76
	s_cbranch_scc0 .LBB0_1553
	s_and_b64 vcc, exec, s[16:17]
	s_cbranch_vccz .LBB0_1558
	s_barrier
	s_cmp_lt_i32 s52, 0
	s_mov_b64 s[46:47], -1
	s_cbranch_scc1 .LBB0_1559

.LBB0_1559:
	v_mul_f32_e32 v156, 0xbfb8aa3b, v78
	v_mul_f32_e32 v157, 0xbfb8aa3b, v79
	v_exp_f32_e32 v156, v156
	v_exp_f32_e32 v157, v157
	v_mul_f32_e32 v165, 0xbfb8aa3b, v80
	v_exp_f32_e32 v165, v165
	v_mul_f32_e32 v166, 0xbfb8aa3b, v81
	v_exp_f32_e32 v166, v166
	v_add_f32_e32 v156, 1.0, v156
	v_add_f32_e32 v157, 1.0, v157
	v_rcp_f32_e32 v156, v156
	v_rcp_f32_e32 v157, v157
	v_add_f32_e32 v165, 1.0, v165
	v_rcp_f32_e32 v168, v165
	v_add_f32_e32 v165, 1.0, v166
	v_rcp_f32_e32 v169, v165
	v_pk_mul_f32 v[156:157], v[78:79], v[156:157]
	v_mul_f32_e32 v165, 0xbfb8aa3b, v74
	v_pk_mul_f32 v[156:157], v[50:51], v[156:157]
	v_exp_f32_e32 v165, v165
	v_mul_f32_e32 v167, 0xbfb8aa3b, v75
	v_cvt_pk_bf16_f32 v166, v156, v157
	v_pk_mul_f32 v[156:157], v[80:81], v[168:169]
	v_exp_f32_e32 v168, v167
	v_pk_mul_f32 v[156:157], v[52:53], v[156:157]
	v_lshl_or_b32 v158, s8, 7, v160
	v_cvt_pk_bf16_f32 v167, v156, v157
	v_add_f32_e32 v156, 1.0, v165
	v_mul_f32_e32 v165, 0xbfb8aa3b, v76
	v_add_f32_e32 v157, 1.0, v168
	v_exp_f32_e32 v165, v165
	v_mul_f32_e32 v168, 0xbfb8aa3b, v77
	v_exp_f32_e32 v168, v168
	v_rcp_f32_e32 v156, v156
	v_rcp_f32_e32 v157, v157
	v_add_f32_e32 v165, 1.0, v165
	v_rcp_f32_e32 v170, v165
	v_add_f32_e32 v165, 1.0, v168
	v_rcp_f32_e32 v171, v165
	v_pk_mul_f32 v[156:157], v[74:75], v[156:157]
	v_lshl_add_u32 v164, s42, 8, v1
	v_pk_mul_f32 v[156:157], v[42:43], v[156:157]
	v_ashrrev_i32_e32 v159, 31, v158
	v_cvt_pk_bf16_f32 v168, v156, v157
	v_pk_mul_f32 v[156:157], v[76:77], v[170:171]
	v_lshlrev_b64 v[158:159], 1, v[158:159]
	v_pk_mul_f32 v[156:157], v[44:45], v[156:157]
	v_mul_f32_e32 v165, 0xbfb8aa3b, v70
	v_cvt_pk_bf16_f32 v169, v156, v157
	v_mov_b64_e32 v[156:157], s[12:13]
	v_mad_i64_i32 v[170:171], s[46:47], v164, s68, v[156:157]
	v_lshl_add_u64 v[170:171], v[170:171], 0, v[158:159]
	global_store_dwordx4 v[170:171], v[166:169], off nt
	v_exp_f32_e32 v165, v165
	v_or_b32_e32 v172, 16, v164
	v_mul_f32_e32 v166, 0xbfb8aa3b, v71
	v_exp_f32_e32 v167, v166
	v_add_f32_e32 v165, 1.0, v165
	v_rcp_f32_e32 v166, v165
	v_add_f32_e32 v165, 1.0, v167
	v_mul_f32_e32 v167, 0xbfb8aa3b, v72
	v_exp_f32_e32 v168, v167
	v_mul_f32_e32 v167, 0xbfb8aa3b, v73
	v_exp_f32_e32 v169, v167
	v_rcp_f32_e32 v167, v165
	v_add_f32_e32 v165, 1.0, v168
	v_rcp_f32_e32 v168, v165
	v_add_f32_e32 v165, 1.0, v169
	v_rcp_f32_e32 v169, v165
	v_pk_mul_f32 v[166:167], v[70:71], v[166:167]
	v_mul_f32_e32 v165, 0xbfb8aa3b, v62
	v_pk_mul_f32 v[166:167], v[34:35], v[166:167]
	v_exp_f32_e32 v165, v165
	v_cvt_pk_bf16_f32 v166, v166, v167
	v_mul_f32_e32 v167, 0xbfb8aa3b, v63
	v_exp_f32_e32 v170, v167
	v_pk_mul_f32 v[168:169], v[72:73], v[168:169]
	v_add_f32_e32 v165, 1.0, v165
	v_pk_mul_f32 v[168:169], v[36:37], v[168:169]
	s_nop 0
	v_cvt_pk_bf16_f32 v167, v168, v169
	v_mul_f32_e32 v169, 0xbfb8aa3b, v64
	v_rcp_f32_e32 v168, v165
	v_add_f32_e32 v165, 1.0, v170
	v_exp_f32_e32 v170, v169
	v_mul_f32_e32 v169, 0xbfb8aa3b, v65
	v_exp_f32_e32 v171, v169
	v_rcp_f32_e32 v169, v165
	v_add_f32_e32 v165, 1.0, v170
	v_rcp_f32_e32 v170, v165
	v_add_f32_e32 v165, 1.0, v171
	v_rcp_f32_e32 v171, v165
	v_pk_mul_f32 v[168:169], v[62:63], v[168:169]
	v_mul_f32_e32 v165, 0xbfb8aa3b, v58
	v_pk_mul_f32 v[168:169], v[26:27], v[168:169]
	v_pk_mul_f32 v[170:171], v[64:65], v[170:171]
	v_cvt_pk_bf16_f32 v168, v168, v169
	v_pk_mul_f32 v[170:171], v[28:29], v[170:171]
	v_exp_f32_e32 v165, v165
	v_cvt_pk_bf16_f32 v169, v170, v171
	v_mad_i64_i32 v[170:171], s[46:47], v172, s68, v[156:157]
	v_lshl_add_u64 v[170:171], v[170:171], 0, v[158:159]
	global_store_dwordx4 v[170:171], v[166:169], off nt
	v_add_f32_e32 v165, 1.0, v165
	v_or_b32_e32 v172, 32, v164
	v_mul_f32_e32 v166, 0xbfb8aa3b, v59
	v_exp_f32_e32 v167, v166
	v_rcp_f32_e32 v166, v165
	v_add_f32_e32 v165, 1.0, v167
	v_mul_f32_e32 v167, 0xbfb8aa3b, v60
	v_exp_f32_e32 v168, v167
	v_mul_f32_e32 v167, 0xbfb8aa3b, v61
	v_exp_f32_e32 v169, v167
	v_rcp_f32_e32 v167, v165
	v_add_f32_e32 v165, 1.0, v168
	v_rcp_f32_e32 v168, v165
	v_add_f32_e32 v165, 1.0, v169
	v_rcp_f32_e32 v169, v165
	v_pk_mul_f32 v[166:167], v[58:59], v[166:167]
	v_mul_f32_e32 v165, 0xbfb8aa3b, v54
	v_pk_mul_f32 v[166:167], v[18:19], v[166:167]
	v_exp_f32_e32 v165, v165
	v_cvt_pk_bf16_f32 v166, v166, v167
	v_mul_f32_e32 v167, 0xbfb8aa3b, v55
	v_exp_f32_e32 v170, v167
	v_pk_mul_f32 v[168:169], v[60:61], v[168:169]
	v_add_f32_e32 v165, 1.0, v165
	v_pk_mul_f32 v[168:169], v[20:21], v[168:169]
	s_nop 0
	v_cvt_pk_bf16_f32 v167, v168, v169
	v_mul_f32_e32 v169, 0xbfb8aa3b, v56
	v_rcp_f32_e32 v168, v165
	v_add_f32_e32 v165, 1.0, v170
	v_exp_f32_e32 v170, v169
	v_mul_f32_e32 v169, 0xbfb8aa3b, v57
	v_exp_f32_e32 v171, v169
	v_rcp_f32_e32 v169, v165
	v_add_f32_e32 v165, 1.0, v170
	v_rcp_f32_e32 v170, v165
	v_add_f32_e32 v165, 1.0, v171
	v_rcp_f32_e32 v171, v165
	v_pk_mul_f32 v[168:169], v[54:55], v[168:169]
	v_mul_f32_e32 v165, 0xbfb8aa3b, v46
	v_pk_mul_f32 v[168:169], v[14:15], v[168:169]
	v_pk_mul_f32 v[170:171], v[56:57], v[170:171]
	v_cvt_pk_bf16_f32 v168, v168, v169
	v_pk_mul_f32 v[170:171], v[16:17], v[170:171]
	v_exp_f32_e32 v165, v165
	v_cvt_pk_bf16_f32 v169, v170, v171
	v_mad_i64_i32 v[170:171], s[46:47], v172, s68, v[156:157]
	v_lshl_add_u64 v[170:171], v[170:171], 0, v[158:159]
	global_store_dwordx4 v[170:171], v[166:169], off nt
	v_add_f32_e32 v165, 1.0, v165
	v_or_b32_e32 v172, 48, v164
	v_mul_f32_e32 v166, 0xbfb8aa3b, v47
	v_exp_f32_e32 v167, v166
	v_rcp_f32_e32 v166, v165
	v_add_f32_e32 v165, 1.0, v167
	v_mul_f32_e32 v167, 0xbfb8aa3b, v48
	v_exp_f32_e32 v168, v167
	v_mul_f32_e32 v167, 0xbfb8aa3b, v49
	v_exp_f32_e32 v169, v167
	v_rcp_f32_e32 v167, v165
	v_add_f32_e32 v165, 1.0, v168
	v_rcp_f32_e32 v168, v165
	v_add_f32_e32 v165, 1.0, v169
	v_rcp_f32_e32 v169, v165
	v_pk_mul_f32 v[166:167], v[46:47], v[166:167]
	v_mul_f32_e32 v165, 0xbfb8aa3b, v38
	v_pk_mul_f32 v[166:167], v[10:11], v[166:167]
	v_exp_f32_e32 v165, v165
	v_cvt_pk_bf16_f32 v166, v166, v167
	v_mul_f32_e32 v167, 0xbfb8aa3b, v39
	v_exp_f32_e32 v170, v167
	v_pk_mul_f32 v[168:169], v[48:49], v[168:169]
	v_add_f32_e32 v165, 1.0, v165
	v_pk_mul_f32 v[168:169], v[12:13], v[168:169]
	s_nop 0
	v_cvt_pk_bf16_f32 v167, v168, v169
	v_mul_f32_e32 v169, 0xbfb8aa3b, v40
	v_rcp_f32_e32 v168, v165
	v_add_f32_e32 v165, 1.0, v170
	v_exp_f32_e32 v170, v169
	v_mul_f32_e32 v169, 0xbfb8aa3b, v41
	v_exp_f32_e32 v171, v169
	v_rcp_f32_e32 v169, v165
	v_add_f32_e32 v165, 1.0, v170
	v_rcp_f32_e32 v170, v165
	v_add_f32_e32 v165, 1.0, v171
	v_rcp_f32_e32 v171, v165
	v_pk_mul_f32 v[168:169], v[38:39], v[168:169]
	v_mul_f32_e32 v165, 0xbfb8aa3b, v126
	v_pk_mul_f32 v[168:169], v[6:7], v[168:169]
	v_pk_mul_f32 v[170:171], v[40:41], v[170:171]
	v_cvt_pk_bf16_f32 v168, v168, v169
	v_pk_mul_f32 v[170:171], v[8:9], v[170:171]
	v_exp_f32_e32 v165, v165
	v_cvt_pk_bf16_f32 v169, v170, v171
	v_mad_i64_i32 v[170:171], s[46:47], v172, s68, v[156:157]
	v_lshl_add_u64 v[170:171], v[170:171], 0, v[158:159]
	global_store_dwordx4 v[170:171], v[166:169], off nt
	v_add_f32_e32 v165, 1.0, v165
	v_add_u32_e32 v170, 0x80, v164
	v_mul_f32_e32 v166, 0xbfb8aa3b, v127
	v_exp_f32_e32 v167, v166
	v_rcp_f32_e32 v166, v165
	v_add_f32_e32 v165, 1.0, v167
	v_mul_f32_e32 v167, 0xbfb8aa3b, v128
	v_exp_f32_e32 v168, v167
	v_mul_f32_e32 v167, 0xbfb8aa3b, v129
	v_exp_f32_e32 v169, v167
	v_rcp_f32_e32 v167, v165
	v_add_f32_e32 v165, 1.0, v168
	v_rcp_f32_e32 v168, v165
	v_add_f32_e32 v165, 1.0, v169
	v_rcp_f32_e32 v169, v165
	v_pk_mul_f32 v[126:127], v[126:127], v[166:167]
	s_nop 0
	v_pk_mul_f32 v[122:123], v[122:123], v[126:127]
	v_pk_mul_f32 v[126:127], v[128:129], v[168:169]
	v_cvt_pk_bf16_f32 v122, v122, v123
	v_mul_f32_e32 v123, 0xbfb8aa3b, v118
	v_pk_mul_f32 v[124:125], v[124:125], v[126:127]
	v_exp_f32_e32 v126, v123
	v_mul_f32_e32 v123, 0xbfb8aa3b, v119
	v_exp_f32_e32 v127, v123
	v_cvt_pk_bf16_f32 v123, v124, v125
	v_add_f32_e32 v124, 1.0, v126
	v_mul_f32_e32 v126, 0xbfb8aa3b, v120
	v_add_f32_e32 v125, 1.0, v127
	v_mul_f32_e32 v127, 0xbfb8aa3b, v121
	v_exp_f32_e32 v126, v126
	v_exp_f32_e32 v127, v127
	v_rcp_f32_e32 v124, v124
	v_rcp_f32_e32 v125, v125
	v_add_f32_e32 v126, 1.0, v126
	v_add_f32_e32 v127, 1.0, v127
	v_rcp_f32_e32 v126, v126
	v_rcp_f32_e32 v127, v127
	v_pk_mul_f32 v[118:119], v[118:119], v[124:125]
	s_nop 0
	v_pk_mul_f32 v[114:115], v[114:115], v[118:119]
	v_add_u32_e32 v118, 0x90, v164
	v_cvt_pk_bf16_f32 v124, v114, v115
	v_pk_mul_f32 v[114:115], v[120:121], v[126:127]
	s_nop 0
	v_pk_mul_f32 v[114:115], v[116:117], v[114:115]
	v_mul_f32_e32 v116, 0xbfb8aa3b, v112
	v_cvt_pk_bf16_f32 v125, v114, v115
	v_mad_i64_i32 v[114:115], s[46:47], v170, s68, v[156:157]
	v_lshl_add_u64 v[114:115], v[114:115], 0, v[158:159]
	global_store_dwordx4 v[114:115], v[122:125], off nt
	v_mul_f32_e32 v114, 0xbfb8aa3b, v110
	v_mul_f32_e32 v115, 0xbfb8aa3b, v111
	v_exp_f32_e32 v114, v114
	v_exp_f32_e32 v115, v115
	v_mul_f32_e32 v117, 0xbfb8aa3b, v113
	v_exp_f32_e32 v116, v116
	v_exp_f32_e32 v117, v117
	v_add_f32_e32 v114, 1.0, v114
	v_add_f32_e32 v115, 1.0, v115
	v_rcp_f32_e32 v114, v114
	v_rcp_f32_e32 v115, v115
	v_add_f32_e32 v116, 1.0, v116
	v_add_f32_e32 v117, 1.0, v117
	v_rcp_f32_e32 v116, v116
	v_rcp_f32_e32 v117, v117
	v_pk_mul_f32 v[110:111], v[110:111], v[114:115]
	s_nop 0
	v_pk_mul_f32 v[106:107], v[106:107], v[110:111]
	v_pk_mul_f32 v[110:111], v[112:113], v[116:117]
	v_cvt_pk_bf16_f32 v106, v106, v107
	v_mul_f32_e32 v107, 0xbfb8aa3b, v102
	v_pk_mul_f32 v[108:109], v[108:109], v[110:111]
	v_exp_f32_e32 v110, v107
	v_mul_f32_e32 v107, 0xbfb8aa3b, v103
	v_exp_f32_e32 v111, v107
	v_cvt_pk_bf16_f32 v107, v108, v109
	v_add_f32_e32 v108, 1.0, v110
	v_mul_f32_e32 v110, 0xbfb8aa3b, v104
	v_add_f32_e32 v109, 1.0, v111
	v_mul_f32_e32 v111, 0xbfb8aa3b, v105
	v_exp_f32_e32 v110, v110
	v_exp_f32_e32 v111, v111
	v_rcp_f32_e32 v108, v108
	v_rcp_f32_e32 v109, v109
	v_add_f32_e32 v110, 1.0, v110
	v_add_f32_e32 v111, 1.0, v111
	v_rcp_f32_e32 v110, v110
	v_rcp_f32_e32 v111, v111
	v_pk_mul_f32 v[102:103], v[102:103], v[108:109]
	s_nop 0
	v_pk_mul_f32 v[98:99], v[98:99], v[102:103]
	v_add_u32_e32 v102, 0xa0, v164
	v_cvt_pk_bf16_f32 v108, v98, v99
	v_pk_mul_f32 v[98:99], v[104:105], v[110:111]
	s_nop 0
	v_pk_mul_f32 v[98:99], v[100:101], v[98:99]
	v_mul_f32_e32 v100, 0xbfb8aa3b, v96
	v_cvt_pk_bf16_f32 v109, v98, v99
	v_mad_i64_i32 v[98:99], s[46:47], v118, s68, v[156:157]
	v_lshl_add_u64 v[98:99], v[98:99], 0, v[158:159]
	global_store_dwordx4 v[98:99], v[106:109], off nt
	v_mul_f32_e32 v98, 0xbfb8aa3b, v94
	v_mul_f32_e32 v99, 0xbfb8aa3b, v95
	v_exp_f32_e32 v98, v98
	v_exp_f32_e32 v99, v99
	v_mul_f32_e32 v101, 0xbfb8aa3b, v97
	v_exp_f32_e32 v100, v100
	v_exp_f32_e32 v101, v101
	v_add_f32_e32 v98, 1.0, v98
	v_add_f32_e32 v99, 1.0, v99
	v_rcp_f32_e32 v98, v98
	v_rcp_f32_e32 v99, v99
	v_add_f32_e32 v100, 1.0, v100
	v_add_f32_e32 v101, 1.0, v101
	v_rcp_f32_e32 v100, v100
	v_rcp_f32_e32 v101, v101
	v_pk_mul_f32 v[94:95], v[94:95], v[98:99]
	s_nop 0
	v_pk_mul_f32 v[90:91], v[90:91], v[94:95]
	v_pk_mul_f32 v[94:95], v[96:97], v[100:101]
	v_cvt_pk_bf16_f32 v90, v90, v91
	v_mul_f32_e32 v91, 0xbfb8aa3b, v86
	v_pk_mul_f32 v[92:93], v[92:93], v[94:95]
	v_exp_f32_e32 v94, v91
	v_mul_f32_e32 v91, 0xbfb8aa3b, v87
	v_exp_f32_e32 v95, v91
	v_cvt_pk_bf16_f32 v91, v92, v93
	v_add_f32_e32 v92, 1.0, v94
	v_mul_f32_e32 v94, 0xbfb8aa3b, v88
	v_add_f32_e32 v93, 1.0, v95
	v_mul_f32_e32 v95, 0xbfb8aa3b, v89
	v_exp_f32_e32 v94, v94
	v_exp_f32_e32 v95, v95
	v_rcp_f32_e32 v92, v92
	v_rcp_f32_e32 v93, v93
	v_add_f32_e32 v94, 1.0, v94
	v_add_f32_e32 v95, 1.0, v95
	v_rcp_f32_e32 v94, v94
	v_rcp_f32_e32 v95, v95
	v_pk_mul_f32 v[86:87], v[86:87], v[92:93]
	s_nop 0
	v_pk_mul_f32 v[82:83], v[82:83], v[86:87]
	v_add_u32_e32 v86, 0xb0, v164
	v_cvt_pk_bf16_f32 v92, v82, v83
	v_pk_mul_f32 v[82:83], v[88:89], v[94:95]
	s_nop 0
	v_pk_mul_f32 v[82:83], v[84:85], v[82:83]
	v_mul_f32_e32 v84, 0xbfb8aa3b, v68
	v_cvt_pk_bf16_f32 v93, v82, v83
	v_mad_i64_i32 v[82:83], s[46:47], v102, s68, v[156:157]
	v_lshl_add_u64 v[82:83], v[82:83], 0, v[158:159]
	global_store_dwordx4 v[82:83], v[90:93], off nt
	v_mul_f32_e32 v82, 0xbfb8aa3b, v66
	v_mul_f32_e32 v83, 0xbfb8aa3b, v67
	v_exp_f32_e32 v82, v82
	v_exp_f32_e32 v83, v83
	v_mul_f32_e32 v85, 0xbfb8aa3b, v69
	v_exp_f32_e32 v84, v84
	v_exp_f32_e32 v85, v85
	v_add_f32_e32 v82, 1.0, v82
	v_add_f32_e32 v83, 1.0, v83
	v_rcp_f32_e32 v82, v82
	v_rcp_f32_e32 v83, v83
	v_add_f32_e32 v84, 1.0, v84
	v_add_f32_e32 v85, 1.0, v85
	v_rcp_f32_e32 v84, v84
	v_rcp_f32_e32 v85, v85
	v_pk_mul_f32 v[66:67], v[66:67], v[82:83]
	s_nop 0
	v_pk_mul_f32 v[30:31], v[30:31], v[66:67]
	v_pk_mul_f32 v[66:67], v[68:69], v[84:85]
	v_cvt_pk_bf16_f32 v30, v30, v31
	v_mul_f32_e32 v31, 0xbfb8aa3b, v22
	v_pk_mul_f32 v[32:33], v[32:33], v[66:67]
	v_exp_f32_e32 v66, v31
	v_mul_f32_e32 v31, 0xbfb8aa3b, v23
	v_exp_f32_e32 v67, v31
	v_cvt_pk_bf16_f32 v31, v32, v33
	v_add_f32_e32 v32, 1.0, v66
	v_mul_f32_e32 v66, 0xbfb8aa3b, v24
	v_add_f32_e32 v33, 1.0, v67
	v_mul_f32_e32 v67, 0xbfb8aa3b, v25
	v_exp_f32_e32 v66, v66
	v_exp_f32_e32 v67, v67
	v_rcp_f32_e32 v32, v32
	v_rcp_f32_e32 v33, v33
	v_add_f32_e32 v66, 1.0, v66
	v_add_f32_e32 v67, 1.0, v67
	v_rcp_f32_e32 v66, v66
	v_rcp_f32_e32 v67, v67
	v_pk_mul_f32 v[22:23], v[22:23], v[32:33]
	s_nop 0
	v_pk_mul_f32 v[2:3], v[2:3], v[22:23]
	s_nop 0
	v_cvt_pk_bf16_f32 v32, v2, v3
	v_pk_mul_f32 v[2:3], v[24:25], v[66:67]
	s_nop 0
	v_pk_mul_f32 v[2:3], v[4:5], v[2:3]
	s_nop 0
	v_cvt_pk_bf16_f32 v33, v2, v3
	v_mad_i64_i32 v[2:3], s[46:47], v86, s68, v[156:157]
	v_lshl_add_u64 v[2:3], v[2:3], 0, v[158:159]
	global_store_dwordx4 v[2:3], v[30:33], off nt
	s_cbranch_execz .LBB0_1557

.LBB0_1712:
	ds_read_b128 v[152:155], v160
	ds_read_b128 v[164:167], v160 offset:1024
	ds_read_b128 v[168:171], v160 offset:2048
	ds_read_b128 v[172:175], v160 offset:3072
	ds_read_b128 v[176:179], v161
	ds_read_b128 v[180:183], v161 offset:1024
	ds_read_b128 v[184:187], v161 offset:2048
	ds_read_b128 v[188:191], v161 offset:3072
	s_add_i32 s82, s48, 2
	s_add_u32 s49, s52, 0xffd50080
	s_addc_u32 s54, s53, -1
	s_cmp_eq_u32 s47, s48
	s_cselect_b32 s48, s50, s80
	s_cselect_b32 s55, s9, s54
	s_cselect_b32 s54, s8, s49
	s_cselect_b32 s49, s51, s81
	v_lshl_add_u64 v[156:157], s[52:53], 0, v[140:141]
	s_add_i32 m0, s57, 0xc000
	ds_read_b128 v[196:199], v162
	ds_read_b128 v[200:203], v162 offset:1024
	ds_read_b128 v[206:209], v162 offset:2048
	ds_read_b128 v[210:213], v162 offset:3072
	ds_read_b128 v[214:217], v162 offset:4096
	ds_read_b128 v[218:221], v162 offset:5120
	ds_read_b128 v[222:225], v162 offset:6144
	ds_read_b128 v[226:229], v162 offset:7168
	global_load_lds_dwordx4 v[156:157], off
	v_lshl_add_u64 v[156:157], s[52:53], 0, v[142:143]
	s_add_i32 m0, s57, 0xe000
	s_nop 0
	global_load_lds_dwordx4 v[156:157], off
	s_waitcnt vmcnt(8)
	s_waitcnt lgkmcnt(0)
	s_barrier
	s_setprio 1
	v_mfma_f32_16x16x32_bf16 v[126:129], v[152:155], v[196:199], v[126:129]
	v_mfma_f32_16x16x32_bf16 v[122:125], v[168:171], v[196:199], v[122:125]
	v_mfma_f32_16x16x32_bf16 v[110:113], v[152:155], v[206:209], v[110:113]
	v_mfma_f32_16x16x32_bf16 v[106:109], v[168:171], v[206:209], v[106:109]
	v_mfma_f32_16x16x32_bf16 v[94:97], v[152:155], v[214:217], v[94:97]
	v_mfma_f32_16x16x32_bf16 v[90:93], v[168:171], v[214:217], v[90:93]
	v_mfma_f32_16x16x32_bf16 v[78:81], v[152:155], v[222:225], v[78:81]
	v_mfma_f32_16x16x32_bf16 v[74:77], v[168:171], v[222:225], v[74:77]
	v_mfma_f32_16x16x32_bf16 v[126:129], v[164:167], v[200:203], v[126:129]
	v_mfma_f32_16x16x32_bf16 v[122:125], v[172:175], v[200:203], v[122:125]
	v_mfma_f32_16x16x32_bf16 v[110:113], v[164:167], v[210:213], v[110:113]
	v_mfma_f32_16x16x32_bf16 v[106:109], v[172:175], v[210:213], v[106:109]
	v_mfma_f32_16x16x32_bf16 v[94:97], v[164:167], v[218:221], v[94:97]
	v_mfma_f32_16x16x32_bf16 v[90:93], v[172:175], v[218:221], v[90:93]
	v_mfma_f32_16x16x32_bf16 v[78:81], v[164:167], v[226:229], v[78:81]
	v_mfma_f32_16x16x32_bf16 v[74:77], v[172:175], v[226:229], v[74:77]
	v_mfma_f32_16x16x32_bf16 v[118:121], v[176:179], v[196:199], v[118:121]
	v_mfma_f32_16x16x32_bf16 v[114:117], v[184:187], v[196:199], v[114:117]
	v_mfma_f32_16x16x32_bf16 v[102:105], v[176:179], v[206:209], v[102:105]
	v_mfma_f32_16x16x32_bf16 v[98:101], v[184:187], v[206:209], v[98:101]
	v_mfma_f32_16x16x32_bf16 v[86:89], v[176:179], v[214:217], v[86:89]
	v_mfma_f32_16x16x32_bf16 v[82:85], v[184:187], v[214:217], v[82:85]
	v_mfma_f32_16x16x32_bf16 v[70:73], v[176:179], v[222:225], v[70:73]
	v_mfma_f32_16x16x32_bf16 v[66:69], v[184:187], v[222:225], v[66:69]
	v_mfma_f32_16x16x32_bf16 v[118:121], v[180:183], v[200:203], v[118:121]
	v_mfma_f32_16x16x32_bf16 v[114:117], v[188:191], v[200:203], v[114:117]
	v_mfma_f32_16x16x32_bf16 v[102:105], v[180:183], v[210:213], v[102:105]
	v_mfma_f32_16x16x32_bf16 v[98:101], v[188:191], v[210:213], v[98:101]
	v_mfma_f32_16x16x32_bf16 v[86:89], v[180:183], v[218:221], v[86:89]
	v_mfma_f32_16x16x32_bf16 v[82:85], v[188:191], v[218:221], v[82:85]
	v_mfma_f32_16x16x32_bf16 v[70:73], v[180:183], v[226:229], v[70:73]
	v_mfma_f32_16x16x32_bf16 v[66:69], v[188:191], v[226:229], v[66:69]
	s_setprio 0
	s_barrier
	s_add_i32 s83, s67, s56
	v_lshl_add_u64 v[156:157], s[48:49], 0, v[134:135]
	s_mov_b32 m0, s83
	ds_read_b128 v[196:199], v162 offset:16384
	ds_read_b128 v[200:203], v162 offset:17408
	ds_read_b128 v[206:209], v162 offset:18432
	ds_read_b128 v[210:213], v162 offset:19456
	ds_read_b128 v[214:217], v162 offset:20480
	ds_read_b128 v[218:221], v162 offset:21504
	ds_read_b128 v[222:225], v162 offset:22528
	ds_read_b128 v[226:229], v162 offset:23552
	global_load_lds_dwordx4 v[156:157], off
	s_add_i32 m0, s83, 0x2000
	s_add_u32 s84, s48, 0x2b0000
	v_lshl_add_u64 v[192:193], s[48:49], 0, v[138:139]
	s_addc_u32 s85, s49, 0
	s_add_i32 s83, s68, s56
	global_load_lds_dwordx4 v[192:193], off
	v_lshl_add_u64 v[230:231], s[84:85], 0, v[134:135]
	s_mov_b32 m0, s83
	v_lshl_add_u64 v[232:233], s[54:55], 0, v[136:137]
	global_load_lds_dwordx4 v[230:231], off
	v_lshl_add_u64 v[230:231], s[84:85], 0, v[138:139]
	s_add_i32 m0, s83, 0x2000
	s_nop 0
	global_load_lds_dwordx4 v[230:231], off
	v_lshl_add_u64 v[230:231], s[54:55], 0, v[132:133]
	s_mov_b32 m0, s57
	s_nop 0
	global_load_lds_dwordx4 v[230:231], off
	s_mov_b32 m0, s58
	s_nop 0
	global_load_lds_dwordx4 v[232:233], off
	s_waitcnt vmcnt(8)
	s_waitcnt lgkmcnt(0)
	s_barrier
	s_setprio 1
	v_mfma_f32_16x16x32_bf16 v[62:65], v[152:155], v[196:199], v[62:65]
	v_mfma_f32_16x16x32_bf16 v[58:61], v[168:171], v[196:199], v[58:61]
	v_mfma_f32_16x16x32_bf16 v[46:49], v[152:155], v[206:209], v[46:49]
	v_mfma_f32_16x16x32_bf16 v[42:45], v[168:171], v[206:209], v[42:45]
	v_mfma_f32_16x16x32_bf16 v[30:33], v[152:155], v[214:217], v[30:33]
	v_mfma_f32_16x16x32_bf16 v[26:29], v[168:171], v[214:217], v[26:29]
	v_mfma_f32_16x16x32_bf16 v[14:17], v[152:155], v[222:225], v[14:17]
	v_mfma_f32_16x16x32_bf16 v[10:13], v[168:171], v[222:225], v[10:13]
	v_mfma_f32_16x16x32_bf16 v[62:65], v[164:167], v[200:203], v[62:65]
	v_mfma_f32_16x16x32_bf16 v[58:61], v[172:175], v[200:203], v[58:61]
	v_mfma_f32_16x16x32_bf16 v[46:49], v[164:167], v[210:213], v[46:49]
	v_mfma_f32_16x16x32_bf16 v[42:45], v[172:175], v[210:213], v[42:45]
	v_mfma_f32_16x16x32_bf16 v[30:33], v[164:167], v[218:221], v[30:33]
	v_mfma_f32_16x16x32_bf16 v[26:29], v[172:175], v[218:221], v[26:29]
	v_mfma_f32_16x16x32_bf16 v[14:17], v[164:167], v[226:229], v[14:17]
	v_mfma_f32_16x16x32_bf16 v[10:13], v[172:175], v[226:229], v[10:13]
	v_mfma_f32_16x16x32_bf16 v[54:57], v[176:179], v[196:199], v[54:57]
	v_mfma_f32_16x16x32_bf16 v[50:53], v[184:187], v[196:199], v[50:53]
	v_mfma_f32_16x16x32_bf16 v[38:41], v[176:179], v[206:209], v[38:41]
	v_mfma_f32_16x16x32_bf16 v[34:37], v[184:187], v[206:209], v[34:37]
	v_mfma_f32_16x16x32_bf16 v[22:25], v[176:179], v[214:217], v[22:25]
	v_mfma_f32_16x16x32_bf16 v[18:21], v[184:187], v[214:217], v[18:21]
	v_mfma_f32_16x16x32_bf16 v[6:9], v[176:179], v[222:225], v[6:9]
	v_mfma_f32_16x16x32_bf16 v[2:5], v[184:187], v[222:225], v[2:5]
	v_mfma_f32_16x16x32_bf16 v[54:57], v[180:183], v[200:203], v[54:57]
	v_mfma_f32_16x16x32_bf16 v[50:53], v[188:191], v[200:203], v[50:53]
	v_mfma_f32_16x16x32_bf16 v[38:41], v[180:183], v[210:213], v[38:41]
	v_mfma_f32_16x16x32_bf16 v[34:37], v[188:191], v[210:213], v[34:37]
	v_mfma_f32_16x16x32_bf16 v[22:25], v[180:183], v[218:221], v[22:25]
	v_mfma_f32_16x16x32_bf16 v[18:21], v[188:191], v[218:221], v[18:21]
	v_mfma_f32_16x16x32_bf16 v[6:9], v[180:183], v[226:229], v[6:9]
	v_mfma_f32_16x16x32_bf16 v[2:5], v[188:191], v[226:229], v[2:5]
	s_setprio 0
	s_barrier
	s_add_i32 s83, 0, 0x18000
	v_add_u32_e32 v163, s83, v158
	s_add_i32 s84, 0, 0x1c000
	ds_read_b128 v[152:155], v163
	ds_read_b128 v[164:167], v163 offset:1024
	ds_read_b128 v[168:171], v163 offset:2048
	ds_read_b128 v[172:175], v163 offset:3072
	v_add_u32_e32 v163, s84, v158
	ds_read_b128 v[176:179], v163
	ds_read_b128 v[180:183], v163 offset:1024
	ds_read_b128 v[184:187], v163 offset:2048
	ds_read_b128 v[188:191], v163 offset:3072
	s_add_u32 s54, s54, 0x2b0000
	s_addc_u32 s55, s55, 0
	s_mov_b32 m0, s59
	v_lshl_add_u64 v[234:235], s[54:55], 0, v[132:133]
	ds_read_b128 v[196:199], v162 offset:32768
	ds_read_b128 v[200:203], v162 offset:33792
	ds_read_b128 v[206:209], v162 offset:34816
	ds_read_b128 v[210:213], v162 offset:35840
	ds_read_b128 v[214:217], v162 offset:36864
	ds_read_b128 v[218:221], v162 offset:37888
	ds_read_b128 v[222:225], v162 offset:38912
	ds_read_b128 v[226:229], v162 offset:39936
	global_load_lds_dwordx4 v[234:235], off
	v_lshl_add_u64 v[234:235], s[54:55], 0, v[136:137]
	s_mov_b32 m0, s60
	s_nop 0
	global_load_lds_dwordx4 v[234:235], off
	s_waitcnt vmcnt(8)
	s_waitcnt lgkmcnt(0)
	s_barrier
	s_setprio 1
	v_mfma_f32_16x16x32_bf16 v[126:129], v[152:155], v[196:199], v[126:129]
	v_mfma_f32_16x16x32_bf16 v[122:125], v[168:171], v[196:199], v[122:125]
	v_mfma_f32_16x16x32_bf16 v[110:113], v[152:155], v[206:209], v[110:113]
	v_mfma_f32_16x16x32_bf16 v[106:109], v[168:171], v[206:209], v[106:109]
	v_mfma_f32_16x16x32_bf16 v[94:97], v[152:155], v[214:217], v[94:97]
	v_mfma_f32_16x16x32_bf16 v[90:93], v[168:171], v[214:217], v[90:93]
	v_mfma_f32_16x16x32_bf16 v[78:81], v[152:155], v[222:225], v[78:81]
	v_mfma_f32_16x16x32_bf16 v[74:77], v[168:171], v[222:225], v[74:77]
	v_mfma_f32_16x16x32_bf16 v[126:129], v[164:167], v[200:203], v[126:129]
	v_mfma_f32_16x16x32_bf16 v[122:125], v[172:175], v[200:203], v[122:125]
	v_mfma_f32_16x16x32_bf16 v[110:113], v[164:167], v[210:213], v[110:113]
	v_mfma_f32_16x16x32_bf16 v[106:109], v[172:175], v[210:213], v[106:109]
	v_mfma_f32_16x16x32_bf16 v[94:97], v[164:167], v[218:221], v[94:97]
	v_mfma_f32_16x16x32_bf16 v[90:93], v[172:175], v[218:221], v[90:93]
	v_mfma_f32_16x16x32_bf16 v[78:81], v[164:167], v[226:229], v[78:81]
	v_mfma_f32_16x16x32_bf16 v[74:77], v[172:175], v[226:229], v[74:77]
	v_mfma_f32_16x16x32_bf16 v[118:121], v[176:179], v[196:199], v[118:121]
	v_mfma_f32_16x16x32_bf16 v[114:117], v[184:187], v[196:199], v[114:117]
	v_mfma_f32_16x16x32_bf16 v[102:105], v[176:179], v[206:209], v[102:105]
	v_mfma_f32_16x16x32_bf16 v[98:101], v[184:187], v[206:209], v[98:101]
	v_mfma_f32_16x16x32_bf16 v[86:89], v[176:179], v[214:217], v[86:89]
	v_mfma_f32_16x16x32_bf16 v[82:85], v[184:187], v[214:217], v[82:85]
	v_mfma_f32_16x16x32_bf16 v[70:73], v[176:179], v[222:225], v[70:73]
	v_mfma_f32_16x16x32_bf16 v[66:69], v[184:187], v[222:225], v[66:69]
	v_mfma_f32_16x16x32_bf16 v[118:121], v[180:183], v[200:203], v[118:121]
	v_mfma_f32_16x16x32_bf16 v[114:117], v[188:191], v[200:203], v[114:117]
	v_mfma_f32_16x16x32_bf16 v[102:105], v[180:183], v[210:213], v[102:105]
	v_mfma_f32_16x16x32_bf16 v[98:101], v[188:191], v[210:213], v[98:101]
	v_mfma_f32_16x16x32_bf16 v[86:89], v[180:183], v[218:221], v[86:89]
	v_mfma_f32_16x16x32_bf16 v[82:85], v[188:191], v[218:221], v[82:85]
	v_mfma_f32_16x16x32_bf16 v[70:73], v[180:183], v[226:229], v[70:73]
	v_mfma_f32_16x16x32_bf16 v[66:69], v[188:191], v[226:229], v[66:69]
	s_setprio 0
	s_barrier
	s_add_i32 s54, s83, s56
	v_lshl_add_u64 v[156:157], v[156:157], 0, s[18:19]
	s_mov_b32 m0, s54
	ds_read_b128 v[196:199], v162 offset:49152
	ds_read_b128 v[200:203], v162 offset:50176
	ds_read_b128 v[206:209], v162 offset:51200
	ds_read_b128 v[210:213], v162 offset:52224
	ds_read_b128 v[214:217], v162 offset:53248
	ds_read_b128 v[218:221], v162 offset:54272
	ds_read_b128 v[222:225], v162 offset:55296
	ds_read_b128 v[226:229], v162 offset:56320
	global_load_lds_dwordx4 v[156:157], off
	s_add_i32 m0, s54, 0x2000
	s_add_u32 s48, s48, 0x2b0080
	v_lshl_add_u64 v[156:157], v[192:193], 0, s[18:19]
	s_addc_u32 s49, s49, 0
	s_add_i32 s54, s84, s56
	global_load_lds_dwordx4 v[156:157], off
	v_lshl_add_u64 v[156:157], s[48:49], 0, v[134:135]
	s_mov_b32 m0, s54
	s_nop 0
	global_load_lds_dwordx4 v[156:157], off
	v_lshl_add_u64 v[156:157], s[48:49], 0, v[138:139]
	s_add_i32 m0, s54, 0x2000
	s_nop 0
	global_load_lds_dwordx4 v[156:157], off
	v_lshl_add_u64 v[156:157], v[230:231], 0, s[18:19]
	s_mov_b32 m0, s64
	s_nop 0
	global_load_lds_dwordx4 v[156:157], off
	v_lshl_add_u64 v[156:157], v[232:233], 0, s[18:19]
	s_mov_b32 m0, s65
	s_nop 0
	global_load_lds_dwordx4 v[156:157], off
	s_waitcnt vmcnt(8)
	s_waitcnt lgkmcnt(0)
	s_barrier
	s_setprio 1
	v_mfma_f32_16x16x32_bf16 v[62:65], v[152:155], v[196:199], v[62:65]
	v_mfma_f32_16x16x32_bf16 v[58:61], v[168:171], v[196:199], v[58:61]
	v_mfma_f32_16x16x32_bf16 v[46:49], v[152:155], v[206:209], v[46:49]
	v_mfma_f32_16x16x32_bf16 v[42:45], v[168:171], v[206:209], v[42:45]
	v_mfma_f32_16x16x32_bf16 v[30:33], v[152:155], v[214:217], v[30:33]
	v_mfma_f32_16x16x32_bf16 v[26:29], v[168:171], v[214:217], v[26:29]
	v_mfma_f32_16x16x32_bf16 v[14:17], v[152:155], v[222:225], v[14:17]
	v_mfma_f32_16x16x32_bf16 v[10:13], v[168:171], v[222:225], v[10:13]
	v_mfma_f32_16x16x32_bf16 v[62:65], v[164:167], v[200:203], v[62:65]
	v_mfma_f32_16x16x32_bf16 v[58:61], v[172:175], v[200:203], v[58:61]
	v_mfma_f32_16x16x32_bf16 v[46:49], v[164:167], v[210:213], v[46:49]
	v_mfma_f32_16x16x32_bf16 v[42:45], v[172:175], v[210:213], v[42:45]
	v_mfma_f32_16x16x32_bf16 v[30:33], v[164:167], v[218:221], v[30:33]
	v_mfma_f32_16x16x32_bf16 v[26:29], v[172:175], v[218:221], v[26:29]
	v_mfma_f32_16x16x32_bf16 v[14:17], v[164:167], v[226:229], v[14:17]
	v_mfma_f32_16x16x32_bf16 v[10:13], v[172:175], v[226:229], v[10:13]
	v_mfma_f32_16x16x32_bf16 v[54:57], v[176:179], v[196:199], v[54:57]
	v_mfma_f32_16x16x32_bf16 v[50:53], v[184:187], v[196:199], v[50:53]
	v_mfma_f32_16x16x32_bf16 v[38:41], v[176:179], v[206:209], v[38:41]
	v_mfma_f32_16x16x32_bf16 v[34:37], v[184:187], v[206:209], v[34:37]
	v_mfma_f32_16x16x32_bf16 v[22:25], v[176:179], v[214:217], v[22:25]
	v_mfma_f32_16x16x32_bf16 v[18:21], v[184:187], v[214:217], v[18:21]
	v_mfma_f32_16x16x32_bf16 v[6:9], v[176:179], v[222:225], v[6:9]
	v_mfma_f32_16x16x32_bf16 v[2:5], v[184:187], v[222:225], v[2:5]
	v_mfma_f32_16x16x32_bf16 v[54:57], v[180:183], v[200:203], v[54:57]
	v_mfma_f32_16x16x32_bf16 v[50:53], v[188:191], v[200:203], v[50:53]
	v_mfma_f32_16x16x32_bf16 v[38:41], v[180:183], v[210:213], v[38:41]
	v_mfma_f32_16x16x32_bf16 v[34:37], v[188:191], v[210:213], v[34:37]
	v_mfma_f32_16x16x32_bf16 v[22:25], v[180:183], v[218:221], v[22:25]
	v_mfma_f32_16x16x32_bf16 v[18:21], v[188:191], v[218:221], v[18:21]
	v_mfma_f32_16x16x32_bf16 v[6:9], v[180:183], v[226:229], v[6:9]
	v_mfma_f32_16x16x32_bf16 v[2:5], v[188:191], v[226:229], v[2:5]
	s_setprio 0
	s_barrier
	s_add_u32 s52, s52, 0x100
	s_addc_u32 s53, s53, 0
	s_add_u32 s80, s80, 0x100
	s_addc_u32 s81, s81, 0
	s_cmp_ge_i32 s82, s78
	s_mov_b32 s48, s82
	s_cbranch_scc0 .LBB0_1712
	s_and_b64 vcc, exec, s[20:21]
	s_cbranch_vccz .LBB0_1715
	s_barrier

.LBB0_1869:
	ds_read_b128 v[162:165], v168
	s_waitcnt vmcnt(0)
	ds_read_b128 v[172:175], v168 offset:1024
	ds_read_b128 v[176:179], v168 offset:2048
	ds_read_b128 v[180:183], v168 offset:3072
	ds_read_b128 v[184:187], v169
	ds_read_b128 v[188:191], v169 offset:1024
	ds_read_b128 v[196:199], v169 offset:2048
	ds_read_b128 v[200:203], v169 offset:3072
	s_add_i32 s55, s42, 2
	s_add_u32 s43, s8, 0xfff00080
	s_addc_u32 s46, s9, -1
	s_cmp_eq_u32 s48, s42
	s_cselect_b32 s42, s41, s49
	s_cselect_b32 s47, s31, s46
	s_cselect_b32 s46, s33, s43
	s_cselect_b32 s43, s35, s53
	v_lshl_add_u64 v[166:167], s[8:9], 0, v[150:151]
	s_add_i32 m0, s62, 0xc000
	ds_read_b128 v[206:209], v170
	ds_read_b128 v[210:213], v170 offset:1024
	ds_read_b128 v[214:217], v170 offset:2048
	ds_read_b128 v[218:221], v170 offset:3072
	ds_read_b128 v[222:225], v170 offset:4096
	ds_read_b128 v[226:229], v170 offset:5120
	ds_read_b128 v[230:233], v170 offset:6144
	ds_read_b128 v[234:237], v170 offset:7168
	global_load_lds_dwordx4 v[166:167], off
	v_lshl_add_u64 v[166:167], s[8:9], 0, v[152:153]
	s_add_i32 m0, s62, 0xe000
	s_nop 0
	global_load_lds_dwordx4 v[166:167], off
	s_waitcnt vmcnt(8)
	s_waitcnt lgkmcnt(0)
	s_barrier
	s_setprio 1
	v_mfma_f32_16x16x32_bf16 v[66:69], v[162:165], v[206:209], v[66:69]
	v_mfma_f32_16x16x32_bf16 v[62:65], v[176:179], v[206:209], v[62:65]
	v_mfma_f32_16x16x32_bf16 v[58:61], v[162:165], v[214:217], v[58:61]
	v_mfma_f32_16x16x32_bf16 v[54:57], v[176:179], v[214:217], v[54:57]
	v_mfma_f32_16x16x32_bf16 v[50:53], v[162:165], v[222:225], v[50:53]
	v_mfma_f32_16x16x32_bf16 v[46:49], v[176:179], v[222:225], v[46:49]
	v_mfma_f32_16x16x32_bf16 v[38:41], v[162:165], v[230:233], v[38:41]
	v_mfma_f32_16x16x32_bf16 v[30:33], v[176:179], v[230:233], v[30:33]
	v_mfma_f32_16x16x32_bf16 v[66:69], v[172:175], v[210:213], v[66:69]
	v_mfma_f32_16x16x32_bf16 v[62:65], v[180:183], v[210:213], v[62:65]
	v_mfma_f32_16x16x32_bf16 v[58:61], v[172:175], v[218:221], v[58:61]
	v_mfma_f32_16x16x32_bf16 v[54:57], v[180:183], v[218:221], v[54:57]
	v_mfma_f32_16x16x32_bf16 v[50:53], v[172:175], v[226:229], v[50:53]
	v_mfma_f32_16x16x32_bf16 v[46:49], v[180:183], v[226:229], v[46:49]
	v_mfma_f32_16x16x32_bf16 v[38:41], v[172:175], v[234:237], v[38:41]
	v_mfma_f32_16x16x32_bf16 v[30:33], v[180:183], v[234:237], v[30:33]
	v_mfma_f32_16x16x32_bf16 v[42:45], v[184:187], v[206:209], v[42:45]
	v_mfma_f32_16x16x32_bf16 v[34:37], v[196:199], v[206:209], v[34:37]
	v_mfma_f32_16x16x32_bf16 v[26:29], v[184:187], v[214:217], v[26:29]
	v_mfma_f32_16x16x32_bf16 v[22:25], v[196:199], v[214:217], v[22:25]
	v_mfma_f32_16x16x32_bf16 v[18:21], v[184:187], v[222:225], v[18:21]
	v_mfma_f32_16x16x32_bf16 v[14:17], v[196:199], v[222:225], v[14:17]
	v_mfma_f32_16x16x32_bf16 v[10:13], v[184:187], v[230:233], v[10:13]
	v_mfma_f32_16x16x32_bf16 v[6:9], v[196:199], v[230:233], v[6:9]
	v_mfma_f32_16x16x32_bf16 v[42:45], v[188:191], v[210:213], v[42:45]
	v_mfma_f32_16x16x32_bf16 v[34:37], v[200:203], v[210:213], v[34:37]
	v_mfma_f32_16x16x32_bf16 v[26:29], v[188:191], v[218:221], v[26:29]
	v_mfma_f32_16x16x32_bf16 v[22:25], v[200:203], v[218:221], v[22:25]
	v_mfma_f32_16x16x32_bf16 v[18:21], v[188:191], v[226:229], v[18:21]
	v_mfma_f32_16x16x32_bf16 v[14:17], v[200:203], v[226:229], v[14:17]
	v_mfma_f32_16x16x32_bf16 v[10:13], v[188:191], v[234:237], v[10:13]
	v_mfma_f32_16x16x32_bf16 v[6:9], v[200:203], v[234:237], v[6:9]
	s_setprio 0
	s_barrier
	s_add_i32 s80, s72, s61
	v_lshl_add_u64 v[166:167], s[42:43], 0, v[134:135]
	s_mov_b32 m0, s80
	ds_read_b128 v[206:209], v170 offset:16384
	ds_read_b128 v[210:213], v170 offset:17408
	ds_read_b128 v[214:217], v170 offset:18432
	ds_read_b128 v[218:221], v170 offset:19456
	ds_read_b128 v[222:225], v170 offset:20480
	ds_read_b128 v[226:229], v170 offset:21504
	ds_read_b128 v[230:233], v170 offset:22528
	ds_read_b128 v[234:237], v170 offset:23552
	global_load_lds_dwordx4 v[166:167], off
	s_add_i32 m0, s80, 0x2000
	s_add_u32 s80, s42, 0x100000
	v_lshl_add_u64 v[192:193], s[42:43], 0, v[138:139]
	s_addc_u32 s81, s43, 0
	s_add_i32 s82, s73, s61
	global_load_lds_dwordx4 v[192:193], off
	v_lshl_add_u64 v[238:239], s[80:81], 0, v[134:135]
	s_mov_b32 m0, s82
	v_lshl_add_u64 v[240:241], s[46:47], 0, v[136:137]
	global_load_lds_dwordx4 v[238:239], off
	v_lshl_add_u64 v[238:239], s[80:81], 0, v[138:139]
	s_add_i32 m0, s82, 0x2000
	s_nop 0
	global_load_lds_dwordx4 v[238:239], off
	v_lshl_add_u64 v[238:239], s[46:47], 0, v[132:133]
	s_mov_b32 m0, s62
	s_nop 0
	global_load_lds_dwordx4 v[238:239], off
	s_mov_b32 m0, s63
	s_nop 0
	global_load_lds_dwordx4 v[240:241], off
	s_waitcnt vmcnt(8)
	s_waitcnt lgkmcnt(0)
	s_barrier
	s_setprio 1
	v_mfma_f32_16x16x32_bf16 v[126:129], v[162:165], v[206:209], v[126:129]
	v_mfma_f32_16x16x32_bf16 v[122:125], v[176:179], v[206:209], v[122:125]
	v_mfma_f32_16x16x32_bf16 v[110:113], v[162:165], v[214:217], v[110:113]
	v_mfma_f32_16x16x32_bf16 v[106:109], v[176:179], v[214:217], v[106:109]
	v_mfma_f32_16x16x32_bf16 v[94:97], v[162:165], v[222:225], v[94:97]
	v_mfma_f32_16x16x32_bf16 v[90:93], v[176:179], v[222:225], v[90:93]
	v_mfma_f32_16x16x32_bf16 v[78:81], v[162:165], v[230:233], v[78:81]
	v_mfma_f32_16x16x32_bf16 v[74:77], v[176:179], v[230:233], v[74:77]
	v_mfma_f32_16x16x32_bf16 v[126:129], v[172:175], v[210:213], v[126:129]
	v_mfma_f32_16x16x32_bf16 v[122:125], v[180:183], v[210:213], v[122:125]
	v_mfma_f32_16x16x32_bf16 v[110:113], v[172:175], v[218:221], v[110:113]
	v_mfma_f32_16x16x32_bf16 v[106:109], v[180:183], v[218:221], v[106:109]
	v_mfma_f32_16x16x32_bf16 v[94:97], v[172:175], v[226:229], v[94:97]
	v_mfma_f32_16x16x32_bf16 v[90:93], v[180:183], v[226:229], v[90:93]
	v_mfma_f32_16x16x32_bf16 v[78:81], v[172:175], v[234:237], v[78:81]
	v_mfma_f32_16x16x32_bf16 v[74:77], v[180:183], v[234:237], v[74:77]
	v_mfma_f32_16x16x32_bf16 v[118:121], v[184:187], v[206:209], v[118:121]
	v_mfma_f32_16x16x32_bf16 v[114:117], v[196:199], v[206:209], v[114:117]
	v_mfma_f32_16x16x32_bf16 v[102:105], v[184:187], v[214:217], v[102:105]
	v_mfma_f32_16x16x32_bf16 v[98:101], v[196:199], v[214:217], v[98:101]
	v_mfma_f32_16x16x32_bf16 v[86:89], v[184:187], v[222:225], v[86:89]
	v_mfma_f32_16x16x32_bf16 v[82:85], v[196:199], v[222:225], v[82:85]
	v_mfma_f32_16x16x32_bf16 v[70:73], v[184:187], v[230:233], v[70:73]
	v_mfma_f32_16x16x32_bf16 v[2:5], v[196:199], v[230:233], v[2:5]
	v_mfma_f32_16x16x32_bf16 v[118:121], v[188:191], v[210:213], v[118:121]
	v_mfma_f32_16x16x32_bf16 v[114:117], v[200:203], v[210:213], v[114:117]
	v_mfma_f32_16x16x32_bf16 v[102:105], v[188:191], v[218:221], v[102:105]
	v_mfma_f32_16x16x32_bf16 v[98:101], v[200:203], v[218:221], v[98:101]
	v_mfma_f32_16x16x32_bf16 v[86:89], v[188:191], v[226:229], v[86:89]
	v_mfma_f32_16x16x32_bf16 v[82:85], v[200:203], v[226:229], v[82:85]
	v_mfma_f32_16x16x32_bf16 v[70:73], v[188:191], v[234:237], v[70:73]
	v_mfma_f32_16x16x32_bf16 v[2:5], v[200:203], v[234:237], v[2:5]
	s_setprio 0
	s_barrier
	s_add_i32 s80, 0, 0x18000
	s_add_i32 s81, 0, 0x1c000
	v_add_u32_e32 v180, s80, v131
	v_add_u32_e32 v200, s81, v131
	ds_read_b128 v[162:165], v180
	ds_read_b128 v[172:175], v180 offset:1024
	ds_read_b128 v[176:179], v180 offset:2048
	ds_read_b128 v[180:183], v180 offset:3072
	ds_read_b128 v[184:187], v200
	ds_read_b128 v[188:191], v200 offset:1024
	ds_read_b128 v[196:199], v200 offset:2048
	ds_read_b128 v[200:203], v200 offset:3072
	s_add_u32 s46, s46, 0x100000
	s_addc_u32 s47, s47, 0
	s_mov_b32 m0, s64
	v_lshl_add_u64 v[242:243], s[46:47], 0, v[132:133]
	ds_read_b128 v[206:209], v170 offset:32768
	ds_read_b128 v[210:213], v170 offset:33792
	ds_read_b128 v[214:217], v170 offset:34816
	ds_read_b128 v[218:221], v170 offset:35840
	ds_read_b128 v[222:225], v170 offset:36864
	ds_read_b128 v[226:229], v170 offset:37888
	ds_read_b128 v[230:233], v170 offset:38912
	ds_read_b128 v[234:237], v170 offset:39936
	global_load_lds_dwordx4 v[242:243], off
	v_lshl_add_u64 v[242:243], s[46:47], 0, v[136:137]
	s_mov_b32 m0, s65
	s_nop 0
	global_load_lds_dwordx4 v[242:243], off
	s_waitcnt vmcnt(8)
	s_waitcnt lgkmcnt(0)
	s_barrier
	s_setprio 1
	v_mfma_f32_16x16x32_bf16 v[66:69], v[162:165], v[206:209], v[66:69]
	v_mfma_f32_16x16x32_bf16 v[62:65], v[176:179], v[206:209], v[62:65]
	v_mfma_f32_16x16x32_bf16 v[58:61], v[162:165], v[214:217], v[58:61]
	v_mfma_f32_16x16x32_bf16 v[54:57], v[176:179], v[214:217], v[54:57]
	v_mfma_f32_16x16x32_bf16 v[50:53], v[162:165], v[222:225], v[50:53]
	v_mfma_f32_16x16x32_bf16 v[46:49], v[176:179], v[222:225], v[46:49]
	v_mfma_f32_16x16x32_bf16 v[38:41], v[162:165], v[230:233], v[38:41]
	v_mfma_f32_16x16x32_bf16 v[30:33], v[176:179], v[230:233], v[30:33]
	v_mfma_f32_16x16x32_bf16 v[66:69], v[172:175], v[210:213], v[66:69]
	v_mfma_f32_16x16x32_bf16 v[62:65], v[180:183], v[210:213], v[62:65]
	v_mfma_f32_16x16x32_bf16 v[58:61], v[172:175], v[218:221], v[58:61]
	v_mfma_f32_16x16x32_bf16 v[54:57], v[180:183], v[218:221], v[54:57]
	v_mfma_f32_16x16x32_bf16 v[50:53], v[172:175], v[226:229], v[50:53]
	v_mfma_f32_16x16x32_bf16 v[46:49], v[180:183], v[226:229], v[46:49]
	v_mfma_f32_16x16x32_bf16 v[38:41], v[172:175], v[234:237], v[38:41]
	v_mfma_f32_16x16x32_bf16 v[30:33], v[180:183], v[234:237], v[30:33]
	v_mfma_f32_16x16x32_bf16 v[42:45], v[184:187], v[206:209], v[42:45]
	v_mfma_f32_16x16x32_bf16 v[34:37], v[196:199], v[206:209], v[34:37]
	v_mfma_f32_16x16x32_bf16 v[26:29], v[184:187], v[214:217], v[26:29]
	v_mfma_f32_16x16x32_bf16 v[22:25], v[196:199], v[214:217], v[22:25]
	v_mfma_f32_16x16x32_bf16 v[18:21], v[184:187], v[222:225], v[18:21]
	v_mfma_f32_16x16x32_bf16 v[14:17], v[196:199], v[222:225], v[14:17]
	v_mfma_f32_16x16x32_bf16 v[10:13], v[184:187], v[230:233], v[10:13]
	v_mfma_f32_16x16x32_bf16 v[6:9], v[196:199], v[230:233], v[6:9]
	v_mfma_f32_16x16x32_bf16 v[42:45], v[188:191], v[210:213], v[42:45]
	v_mfma_f32_16x16x32_bf16 v[34:37], v[200:203], v[210:213], v[34:37]
	v_mfma_f32_16x16x32_bf16 v[26:29], v[188:191], v[218:221], v[26:29]
	v_mfma_f32_16x16x32_bf16 v[22:25], v[200:203], v[218:221], v[22:25]
	v_mfma_f32_16x16x32_bf16 v[18:21], v[188:191], v[226:229], v[18:21]
	v_mfma_f32_16x16x32_bf16 v[14:17], v[200:203], v[226:229], v[14:17]
	v_mfma_f32_16x16x32_bf16 v[10:13], v[188:191], v[234:237], v[10:13]
	v_mfma_f32_16x16x32_bf16 v[6:9], v[200:203], v[234:237], v[6:9]
	s_setprio 0
	s_barrier
	s_add_i32 s46, s80, s61
	v_lshl_add_u64 v[166:167], v[166:167], 0, s[18:19]
	s_mov_b32 m0, s46
	ds_read_b128 v[206:209], v170 offset:49152
	ds_read_b128 v[210:213], v170 offset:50176
	ds_read_b128 v[214:217], v170 offset:51200
	ds_read_b128 v[218:221], v170 offset:52224
	ds_read_b128 v[222:225], v170 offset:53248
	ds_read_b128 v[226:229], v170 offset:54272
	ds_read_b128 v[230:233], v170 offset:55296
	ds_read_b128 v[234:237], v170 offset:56320
	global_load_lds_dwordx4 v[166:167], off
	s_add_i32 m0, s46, 0x2000
	s_add_u32 s42, s42, 0x100080
	v_lshl_add_u64 v[166:167], v[192:193], 0, s[18:19]
	s_addc_u32 s43, s43, 0
	s_add_i32 s46, s81, s61
	global_load_lds_dwordx4 v[166:167], off
	v_lshl_add_u64 v[166:167], s[42:43], 0, v[134:135]
	s_mov_b32 m0, s46
	s_nop 0
	global_load_lds_dwordx4 v[166:167], off
	v_lshl_add_u64 v[166:167], s[42:43], 0, v[138:139]
	s_add_i32 m0, s46, 0x2000
	s_nop 0
	global_load_lds_dwordx4 v[166:167], off
	v_lshl_add_u64 v[166:167], v[238:239], 0, s[18:19]
	s_mov_b32 m0, s69
	s_nop 0
	global_load_lds_dwordx4 v[166:167], off
	v_lshl_add_u64 v[166:167], v[240:241], 0, s[18:19]
	s_mov_b32 m0, s70
	s_nop 0
	global_load_lds_dwordx4 v[166:167], off
	s_waitcnt vmcnt(8)
	s_waitcnt lgkmcnt(0)
	s_barrier
	s_setprio 1
	v_mfma_f32_16x16x32_bf16 v[126:129], v[162:165], v[206:209], v[126:129]
	v_mfma_f32_16x16x32_bf16 v[122:125], v[176:179], v[206:209], v[122:125]
	v_mfma_f32_16x16x32_bf16 v[110:113], v[162:165], v[214:217], v[110:113]
	v_mfma_f32_16x16x32_bf16 v[106:109], v[176:179], v[214:217], v[106:109]
	v_mfma_f32_16x16x32_bf16 v[94:97], v[162:165], v[222:225], v[94:97]
	v_mfma_f32_16x16x32_bf16 v[90:93], v[176:179], v[222:225], v[90:93]
	v_mfma_f32_16x16x32_bf16 v[78:81], v[162:165], v[230:233], v[78:81]
	v_mfma_f32_16x16x32_bf16 v[74:77], v[176:179], v[230:233], v[74:77]
	v_mfma_f32_16x16x32_bf16 v[126:129], v[172:175], v[210:213], v[126:129]
	v_mfma_f32_16x16x32_bf16 v[122:125], v[180:183], v[210:213], v[122:125]
	v_mfma_f32_16x16x32_bf16 v[110:113], v[172:175], v[218:221], v[110:113]
	v_mfma_f32_16x16x32_bf16 v[106:109], v[180:183], v[218:221], v[106:109]
	v_mfma_f32_16x16x32_bf16 v[94:97], v[172:175], v[226:229], v[94:97]
	v_mfma_f32_16x16x32_bf16 v[90:93], v[180:183], v[226:229], v[90:93]
	v_mfma_f32_16x16x32_bf16 v[78:81], v[172:175], v[234:237], v[78:81]
	v_mfma_f32_16x16x32_bf16 v[74:77], v[180:183], v[234:237], v[74:77]
	v_mfma_f32_16x16x32_bf16 v[118:121], v[184:187], v[206:209], v[118:121]
	v_mfma_f32_16x16x32_bf16 v[114:117], v[196:199], v[206:209], v[114:117]
	v_mfma_f32_16x16x32_bf16 v[102:105], v[184:187], v[214:217], v[102:105]
	v_mfma_f32_16x16x32_bf16 v[98:101], v[196:199], v[214:217], v[98:101]
	v_mfma_f32_16x16x32_bf16 v[86:89], v[184:187], v[222:225], v[86:89]
	v_mfma_f32_16x16x32_bf16 v[82:85], v[196:199], v[222:225], v[82:85]
	v_mfma_f32_16x16x32_bf16 v[70:73], v[184:187], v[230:233], v[70:73]
	v_mfma_f32_16x16x32_bf16 v[2:5], v[196:199], v[230:233], v[2:5]
	v_mfma_f32_16x16x32_bf16 v[118:121], v[188:191], v[210:213], v[118:121]
	v_mfma_f32_16x16x32_bf16 v[114:117], v[200:203], v[210:213], v[114:117]
	v_mfma_f32_16x16x32_bf16 v[102:105], v[188:191], v[218:221], v[102:105]
	v_mfma_f32_16x16x32_bf16 v[98:101], v[200:203], v[218:221], v[98:101]
	v_mfma_f32_16x16x32_bf16 v[86:89], v[188:191], v[226:229], v[86:89]
	v_mfma_f32_16x16x32_bf16 v[82:85], v[200:203], v[226:229], v[82:85]
	v_mfma_f32_16x16x32_bf16 v[70:73], v[188:191], v[234:237], v[70:73]
	v_mfma_f32_16x16x32_bf16 v[2:5], v[200:203], v[234:237], v[2:5]
	s_setprio 0
	s_barrier
	s_add_u32 s8, s8, 0x100
	s_addc_u32 s9, s9, 0
	s_add_u32 s49, s49, 0x100
	s_addc_u32 s53, s53, 0
	s_cmp_ge_i32 s55, s3
	s_mov_b32 s42, s55
	s_cbranch_scc0 .LBB0_1869
	s_and_b64 vcc, exec, s[20:21]
	s_cbranch_vccz .LBB0_1874
	s_barrier
	v_lshl_or_b32 v162, s40, 8, v141
	s_cmp_lt_i32 s10, 0
	s_mov_b64 s[8:9], -1
	s_cbranch_scc1 .LBB0_1875

.LBB0_3649:
	ds_read_b128 v[152:155], v162
	ds_read_b128 v[156:159], v162 offset:1024
	ds_read_b128 v[168:171], v162 offset:2048
	ds_read_b128 v[172:175], v162 offset:3072
	ds_read_b128 v[176:179], v163
	ds_read_b128 v[180:183], v163 offset:1024
	ds_read_b128 v[184:187], v163 offset:2048
	ds_read_b128 v[188:191], v163 offset:3072
	s_add_i32 s86, s48, 2
	s_add_u32 s49, s6, 0xfff00080
	s_addc_u32 s64, s7, -1
	s_cmp_eq_u32 s51, s48
	s_cselect_b32 s48, s58, s53
	s_cselect_b32 s65, s57, s64
	s_cselect_b32 s64, s56, s49
	s_cselect_b32 s49, s59, s55
	v_lshl_add_u64 v[192:193], s[6:7], 0, v[140:141]
	s_add_i32 m0, s61, 0xc000
	ds_read_b128 v[196:199], v164
	ds_read_b128 v[200:203], v164 offset:1024
	ds_read_b128 v[206:209], v164 offset:2048
	ds_read_b128 v[210:213], v164 offset:3072
	ds_read_b128 v[214:217], v164 offset:4096
	ds_read_b128 v[218:221], v164 offset:5120
	ds_read_b128 v[222:225], v164 offset:6144
	ds_read_b128 v[226:229], v164 offset:7168
	global_load_lds_dwordx4 v[192:193], off
	v_lshl_add_u64 v[192:193], s[6:7], 0, v[142:143]
	s_add_i32 m0, s61, 0xe000
	s_nop 0
	global_load_lds_dwordx4 v[192:193], off
	s_waitcnt vmcnt(8)
	s_waitcnt lgkmcnt(0)
	s_barrier
	s_setprio 1
	v_mfma_f32_16x16x32_bf16 v[126:129], v[152:155], v[196:199], v[126:129]
	v_mfma_f32_16x16x32_bf16 v[122:125], v[168:171], v[196:199], v[122:125]
	v_mfma_f32_16x16x32_bf16 v[110:113], v[152:155], v[206:209], v[110:113]
	v_mfma_f32_16x16x32_bf16 v[106:109], v[168:171], v[206:209], v[106:109]
	v_mfma_f32_16x16x32_bf16 v[94:97], v[152:155], v[214:217], v[94:97]
	v_mfma_f32_16x16x32_bf16 v[90:93], v[168:171], v[214:217], v[90:93]
	v_mfma_f32_16x16x32_bf16 v[78:81], v[152:155], v[222:225], v[78:81]
	v_mfma_f32_16x16x32_bf16 v[74:77], v[168:171], v[222:225], v[74:77]
	v_mfma_f32_16x16x32_bf16 v[126:129], v[156:159], v[200:203], v[126:129]
	v_mfma_f32_16x16x32_bf16 v[122:125], v[172:175], v[200:203], v[122:125]
	v_mfma_f32_16x16x32_bf16 v[110:113], v[156:159], v[210:213], v[110:113]
	v_mfma_f32_16x16x32_bf16 v[106:109], v[172:175], v[210:213], v[106:109]
	v_mfma_f32_16x16x32_bf16 v[94:97], v[156:159], v[218:221], v[94:97]
	v_mfma_f32_16x16x32_bf16 v[90:93], v[172:175], v[218:221], v[90:93]
	v_mfma_f32_16x16x32_bf16 v[78:81], v[156:159], v[226:229], v[78:81]
	v_mfma_f32_16x16x32_bf16 v[74:77], v[172:175], v[226:229], v[74:77]
	v_mfma_f32_16x16x32_bf16 v[118:121], v[176:179], v[196:199], v[118:121]
	v_mfma_f32_16x16x32_bf16 v[114:117], v[184:187], v[196:199], v[114:117]
	v_mfma_f32_16x16x32_bf16 v[102:105], v[176:179], v[206:209], v[102:105]
	v_mfma_f32_16x16x32_bf16 v[98:101], v[184:187], v[206:209], v[98:101]
	v_mfma_f32_16x16x32_bf16 v[86:89], v[176:179], v[214:217], v[86:89]
	v_mfma_f32_16x16x32_bf16 v[82:85], v[184:187], v[214:217], v[82:85]
	v_mfma_f32_16x16x32_bf16 v[70:73], v[176:179], v[222:225], v[70:73]
	v_mfma_f32_16x16x32_bf16 v[66:69], v[184:187], v[222:225], v[66:69]
	v_mfma_f32_16x16x32_bf16 v[118:121], v[180:183], v[200:203], v[118:121]
	v_mfma_f32_16x16x32_bf16 v[114:117], v[188:191], v[200:203], v[114:117]
	v_mfma_f32_16x16x32_bf16 v[102:105], v[180:183], v[210:213], v[102:105]
	v_mfma_f32_16x16x32_bf16 v[98:101], v[188:191], v[210:213], v[98:101]
	v_mfma_f32_16x16x32_bf16 v[86:89], v[180:183], v[218:221], v[86:89]
	v_mfma_f32_16x16x32_bf16 v[82:85], v[188:191], v[218:221], v[82:85]
	v_mfma_f32_16x16x32_bf16 v[70:73], v[180:183], v[226:229], v[70:73]
	v_mfma_f32_16x16x32_bf16 v[66:69], v[188:191], v[226:229], v[66:69]
	s_setprio 0
	s_barrier
	s_add_i32 s87, s75, s66
	v_lshl_add_u64 v[192:193], s[48:49], 0, v[134:135]
	s_mov_b32 m0, s87
	ds_read_b128 v[196:199], v164 offset:16384
	ds_read_b128 v[200:203], v164 offset:17408
	ds_read_b128 v[206:209], v164 offset:18432
	ds_read_b128 v[210:213], v164 offset:19456
	ds_read_b128 v[214:217], v164 offset:20480
	ds_read_b128 v[218:221], v164 offset:21504
	ds_read_b128 v[222:225], v164 offset:22528
	ds_read_b128 v[226:229], v164 offset:23552
	global_load_lds_dwordx4 v[192:193], off
	s_add_i32 m0, s87, 0x2000
	s_add_u32 s88, s48, 0x100000
	v_lshl_add_u64 v[230:231], s[48:49], 0, v[138:139]
	s_addc_u32 s89, s49, 0
	s_add_i32 s87, s76, s66
	global_load_lds_dwordx4 v[230:231], off
	v_lshl_add_u64 v[232:233], s[88:89], 0, v[134:135]
	s_mov_b32 m0, s87
	v_lshl_add_u64 v[234:235], s[64:65], 0, v[136:137]
	global_load_lds_dwordx4 v[232:233], off
	v_lshl_add_u64 v[232:233], s[88:89], 0, v[138:139]
	s_add_i32 m0, s87, 0x2000
	s_nop 0
	global_load_lds_dwordx4 v[232:233], off
	v_lshl_add_u64 v[232:233], s[64:65], 0, v[132:133]
	s_mov_b32 m0, s61
	s_nop 0
	global_load_lds_dwordx4 v[232:233], off
	s_mov_b32 m0, s63
	s_nop 0
	global_load_lds_dwordx4 v[234:235], off
	s_waitcnt vmcnt(8)
	s_waitcnt lgkmcnt(0)
	s_barrier
	s_setprio 1
	v_mfma_f32_16x16x32_bf16 v[62:65], v[152:155], v[196:199], v[62:65]
	v_mfma_f32_16x16x32_bf16 v[58:61], v[168:171], v[196:199], v[58:61]
	v_mfma_f32_16x16x32_bf16 v[46:49], v[152:155], v[206:209], v[46:49]
	v_mfma_f32_16x16x32_bf16 v[42:45], v[168:171], v[206:209], v[42:45]
	v_mfma_f32_16x16x32_bf16 v[30:33], v[152:155], v[214:217], v[30:33]
	v_mfma_f32_16x16x32_bf16 v[26:29], v[168:171], v[214:217], v[26:29]
	v_mfma_f32_16x16x32_bf16 v[14:17], v[152:155], v[222:225], v[14:17]
	v_mfma_f32_16x16x32_bf16 v[10:13], v[168:171], v[222:225], v[10:13]
	v_mfma_f32_16x16x32_bf16 v[62:65], v[156:159], v[200:203], v[62:65]
	v_mfma_f32_16x16x32_bf16 v[58:61], v[172:175], v[200:203], v[58:61]
	v_mfma_f32_16x16x32_bf16 v[46:49], v[156:159], v[210:213], v[46:49]
	v_mfma_f32_16x16x32_bf16 v[42:45], v[172:175], v[210:213], v[42:45]
	v_mfma_f32_16x16x32_bf16 v[30:33], v[156:159], v[218:221], v[30:33]
	v_mfma_f32_16x16x32_bf16 v[26:29], v[172:175], v[218:221], v[26:29]
	v_mfma_f32_16x16x32_bf16 v[14:17], v[156:159], v[226:229], v[14:17]
	v_mfma_f32_16x16x32_bf16 v[10:13], v[172:175], v[226:229], v[10:13]
	v_mfma_f32_16x16x32_bf16 v[54:57], v[176:179], v[196:199], v[54:57]
	v_mfma_f32_16x16x32_bf16 v[50:53], v[184:187], v[196:199], v[50:53]
	v_mfma_f32_16x16x32_bf16 v[38:41], v[176:179], v[206:209], v[38:41]
	v_mfma_f32_16x16x32_bf16 v[34:37], v[184:187], v[206:209], v[34:37]
	v_mfma_f32_16x16x32_bf16 v[22:25], v[176:179], v[214:217], v[22:25]
	v_mfma_f32_16x16x32_bf16 v[18:21], v[184:187], v[214:217], v[18:21]
	v_mfma_f32_16x16x32_bf16 v[6:9], v[176:179], v[222:225], v[6:9]
	v_mfma_f32_16x16x32_bf16 v[2:5], v[184:187], v[222:225], v[2:5]
	v_mfma_f32_16x16x32_bf16 v[54:57], v[180:183], v[200:203], v[54:57]
	v_mfma_f32_16x16x32_bf16 v[50:53], v[188:191], v[200:203], v[50:53]
	v_mfma_f32_16x16x32_bf16 v[38:41], v[180:183], v[210:213], v[38:41]
	v_mfma_f32_16x16x32_bf16 v[34:37], v[188:191], v[210:213], v[34:37]
	v_mfma_f32_16x16x32_bf16 v[22:25], v[180:183], v[218:221], v[22:25]
	v_mfma_f32_16x16x32_bf16 v[18:21], v[188:191], v[218:221], v[18:21]
	v_mfma_f32_16x16x32_bf16 v[6:9], v[180:183], v[226:229], v[6:9]
	v_mfma_f32_16x16x32_bf16 v[2:5], v[188:191], v[226:229], v[2:5]
	s_setprio 0
	s_barrier
	s_add_i32 s87, 0, 0x18000
	v_add_u32_e32 v167, s87, v160
	s_add_i32 s88, 0, 0x1c000
	ds_read_b128 v[152:155], v167
	ds_read_b128 v[156:159], v167 offset:1024
	ds_read_b128 v[168:171], v167 offset:2048
	ds_read_b128 v[172:175], v167 offset:3072
	v_add_u32_e32 v167, s88, v160
	ds_read_b128 v[176:179], v167
	ds_read_b128 v[180:183], v167 offset:1024
	ds_read_b128 v[184:187], v167 offset:2048
	ds_read_b128 v[188:191], v167 offset:3072
	s_add_u32 s64, s64, 0x100000
	s_addc_u32 s65, s65, 0
	s_mov_b32 m0, s67
	v_lshl_add_u64 v[236:237], s[64:65], 0, v[132:133]
	ds_read_b128 v[196:199], v164 offset:32768
	ds_read_b128 v[200:203], v164 offset:33792
	ds_read_b128 v[206:209], v164 offset:34816
	ds_read_b128 v[210:213], v164 offset:35840
	ds_read_b128 v[214:217], v164 offset:36864
	ds_read_b128 v[218:221], v164 offset:37888
	ds_read_b128 v[222:225], v164 offset:38912
	ds_read_b128 v[226:229], v164 offset:39936
	global_load_lds_dwordx4 v[236:237], off
	v_lshl_add_u64 v[236:237], s[64:65], 0, v[136:137]
	s_mov_b32 m0, s68
	s_nop 0
	global_load_lds_dwordx4 v[236:237], off
	s_waitcnt vmcnt(8)
	s_waitcnt lgkmcnt(0)
	s_barrier
	s_setprio 1
	v_mfma_f32_16x16x32_bf16 v[126:129], v[152:155], v[196:199], v[126:129]
	v_mfma_f32_16x16x32_bf16 v[122:125], v[168:171], v[196:199], v[122:125]
	v_mfma_f32_16x16x32_bf16 v[110:113], v[152:155], v[206:209], v[110:113]
	v_mfma_f32_16x16x32_bf16 v[106:109], v[168:171], v[206:209], v[106:109]
	v_mfma_f32_16x16x32_bf16 v[94:97], v[152:155], v[214:217], v[94:97]
	v_mfma_f32_16x16x32_bf16 v[90:93], v[168:171], v[214:217], v[90:93]
	v_mfma_f32_16x16x32_bf16 v[78:81], v[152:155], v[222:225], v[78:81]
	v_mfma_f32_16x16x32_bf16 v[74:77], v[168:171], v[222:225], v[74:77]
	v_mfma_f32_16x16x32_bf16 v[126:129], v[156:159], v[200:203], v[126:129]
	v_mfma_f32_16x16x32_bf16 v[122:125], v[172:175], v[200:203], v[122:125]
	v_mfma_f32_16x16x32_bf16 v[110:113], v[156:159], v[210:213], v[110:113]
	v_mfma_f32_16x16x32_bf16 v[106:109], v[172:175], v[210:213], v[106:109]
	v_mfma_f32_16x16x32_bf16 v[94:97], v[156:159], v[218:221], v[94:97]
	v_mfma_f32_16x16x32_bf16 v[90:93], v[172:175], v[218:221], v[90:93]
	v_mfma_f32_16x16x32_bf16 v[78:81], v[156:159], v[226:229], v[78:81]
	v_mfma_f32_16x16x32_bf16 v[74:77], v[172:175], v[226:229], v[74:77]
	v_mfma_f32_16x16x32_bf16 v[118:121], v[176:179], v[196:199], v[118:121]
	v_mfma_f32_16x16x32_bf16 v[114:117], v[184:187], v[196:199], v[114:117]
	v_mfma_f32_16x16x32_bf16 v[102:105], v[176:179], v[206:209], v[102:105]
	v_mfma_f32_16x16x32_bf16 v[98:101], v[184:187], v[206:209], v[98:101]
	v_mfma_f32_16x16x32_bf16 v[86:89], v[176:179], v[214:217], v[86:89]
	v_mfma_f32_16x16x32_bf16 v[82:85], v[184:187], v[214:217], v[82:85]
	v_mfma_f32_16x16x32_bf16 v[70:73], v[176:179], v[222:225], v[70:73]
	v_mfma_f32_16x16x32_bf16 v[66:69], v[184:187], v[222:225], v[66:69]
	v_mfma_f32_16x16x32_bf16 v[118:121], v[180:183], v[200:203], v[118:121]
	v_mfma_f32_16x16x32_bf16 v[114:117], v[188:191], v[200:203], v[114:117]
	v_mfma_f32_16x16x32_bf16 v[102:105], v[180:183], v[210:213], v[102:105]
	v_mfma_f32_16x16x32_bf16 v[98:101], v[188:191], v[210:213], v[98:101]
	v_mfma_f32_16x16x32_bf16 v[86:89], v[180:183], v[218:221], v[86:89]
	v_mfma_f32_16x16x32_bf16 v[82:85], v[188:191], v[218:221], v[82:85]
	v_mfma_f32_16x16x32_bf16 v[70:73], v[180:183], v[226:229], v[70:73]
	v_mfma_f32_16x16x32_bf16 v[66:69], v[188:191], v[226:229], v[66:69]
	s_setprio 0
	s_barrier
	s_add_i32 s64, s87, s66
	v_lshl_add_u64 v[192:193], v[192:193], 0, s[20:21]
	s_mov_b32 m0, s64
	ds_read_b128 v[196:199], v164 offset:49152
	ds_read_b128 v[200:203], v164 offset:50176
	ds_read_b128 v[206:209], v164 offset:51200
	ds_read_b128 v[210:213], v164 offset:52224
	ds_read_b128 v[214:217], v164 offset:53248
	ds_read_b128 v[218:221], v164 offset:54272
	ds_read_b128 v[222:225], v164 offset:55296
	ds_read_b128 v[226:229], v164 offset:56320
	global_load_lds_dwordx4 v[192:193], off
	s_add_i32 m0, s64, 0x2000
	s_add_u32 s48, s48, 0x100080
	v_lshl_add_u64 v[192:193], v[230:231], 0, s[20:21]
	s_addc_u32 s49, s49, 0
	s_add_i32 s64, s88, s66
	global_load_lds_dwordx4 v[192:193], off
	v_lshl_add_u64 v[192:193], s[48:49], 0, v[134:135]
	s_mov_b32 m0, s64
	s_nop 0
	global_load_lds_dwordx4 v[192:193], off
	v_lshl_add_u64 v[192:193], s[48:49], 0, v[138:139]
	s_add_i32 m0, s64, 0x2000
	s_nop 0
	global_load_lds_dwordx4 v[192:193], off
	v_lshl_add_u64 v[192:193], v[232:233], 0, s[20:21]
	s_mov_b32 m0, s72
	s_nop 0
	global_load_lds_dwordx4 v[192:193], off
	v_lshl_add_u64 v[192:193], v[234:235], 0, s[20:21]
	s_mov_b32 m0, s73
	s_nop 0
	global_load_lds_dwordx4 v[192:193], off
	s_waitcnt vmcnt(8)
	s_waitcnt lgkmcnt(0)
	s_barrier
	s_setprio 1
	v_mfma_f32_16x16x32_bf16 v[62:65], v[152:155], v[196:199], v[62:65]
	v_mfma_f32_16x16x32_bf16 v[58:61], v[168:171], v[196:199], v[58:61]
	v_mfma_f32_16x16x32_bf16 v[46:49], v[152:155], v[206:209], v[46:49]
	v_mfma_f32_16x16x32_bf16 v[42:45], v[168:171], v[206:209], v[42:45]
	v_mfma_f32_16x16x32_bf16 v[30:33], v[152:155], v[214:217], v[30:33]
	v_mfma_f32_16x16x32_bf16 v[26:29], v[168:171], v[214:217], v[26:29]
	v_mfma_f32_16x16x32_bf16 v[14:17], v[152:155], v[222:225], v[14:17]
	v_mfma_f32_16x16x32_bf16 v[10:13], v[168:171], v[222:225], v[10:13]
	v_mfma_f32_16x16x32_bf16 v[62:65], v[156:159], v[200:203], v[62:65]
	v_mfma_f32_16x16x32_bf16 v[58:61], v[172:175], v[200:203], v[58:61]
	v_mfma_f32_16x16x32_bf16 v[46:49], v[156:159], v[210:213], v[46:49]
	v_mfma_f32_16x16x32_bf16 v[42:45], v[172:175], v[210:213], v[42:45]
	v_mfma_f32_16x16x32_bf16 v[30:33], v[156:159], v[218:221], v[30:33]
	v_mfma_f32_16x16x32_bf16 v[26:29], v[172:175], v[218:221], v[26:29]
	v_mfma_f32_16x16x32_bf16 v[14:17], v[156:159], v[226:229], v[14:17]
	v_mfma_f32_16x16x32_bf16 v[10:13], v[172:175], v[226:229], v[10:13]
	v_mfma_f32_16x16x32_bf16 v[54:57], v[176:179], v[196:199], v[54:57]
	v_mfma_f32_16x16x32_bf16 v[50:53], v[184:187], v[196:199], v[50:53]
	v_mfma_f32_16x16x32_bf16 v[38:41], v[176:179], v[206:209], v[38:41]
	v_mfma_f32_16x16x32_bf16 v[34:37], v[184:187], v[206:209], v[34:37]
	v_mfma_f32_16x16x32_bf16 v[22:25], v[176:179], v[214:217], v[22:25]
	v_mfma_f32_16x16x32_bf16 v[18:21], v[184:187], v[214:217], v[18:21]
	v_mfma_f32_16x16x32_bf16 v[6:9], v[176:179], v[222:225], v[6:9]
	v_mfma_f32_16x16x32_bf16 v[2:5], v[184:187], v[222:225], v[2:5]
	v_mfma_f32_16x16x32_bf16 v[54:57], v[180:183], v[200:203], v[54:57]
	v_mfma_f32_16x16x32_bf16 v[50:53], v[188:191], v[200:203], v[50:53]
	v_mfma_f32_16x16x32_bf16 v[38:41], v[180:183], v[210:213], v[38:41]
	v_mfma_f32_16x16x32_bf16 v[34:37], v[188:191], v[210:213], v[34:37]
	v_mfma_f32_16x16x32_bf16 v[22:25], v[180:183], v[218:221], v[22:25]
	v_mfma_f32_16x16x32_bf16 v[18:21], v[188:191], v[218:221], v[18:21]
	v_mfma_f32_16x16x32_bf16 v[6:9], v[180:183], v[226:229], v[6:9]
	v_mfma_f32_16x16x32_bf16 v[2:5], v[188:191], v[226:229], v[2:5]
	s_setprio 0
	s_barrier
	s_add_u32 s6, s6, 0x100
	s_addc_u32 s7, s7, 0
	s_add_u32 s53, s53, 0x100
	s_addc_u32 s55, s55, 0
	s_cmp_ge_i32 s86, s85
	s_mov_b32 s48, s86
	s_cbranch_scc0 .LBB0_3649
	s_and_b64 vcc, exec, s[22:23]
	s_cbranch_vccz .LBB0_3652
	s_barrier

.LBB0_3789:
	ds_read_b128 v[162:165], v145
	ds_read_b128 v[166:169], v145 offset:1024
	ds_read_b128 v[170:173], v145 offset:2048
	ds_read_b128 v[174:177], v145 offset:3072
	ds_read_b128 v[178:181], v160
	ds_read_b128 v[182:185], v160 offset:1024
	ds_read_b128 v[186:189], v160 offset:2048
	ds_read_b128 v[190:193], v160 offset:3072
	s_add_i32 s63, s30, 2
	s_add_u32 s31, s28, 0xfff00080
	s_addc_u32 s34, s29, -1
	s_cmp_eq_u32 s60, s30
	s_cselect_b32 s30, s59, s61
	s_cselect_b32 s35, s19, s34
	s_cselect_b32 s34, s23, s31
	s_cselect_b32 s31, s21, s62
	v_lshl_add_u64 v[158:159], s[28:29], 0, v[148:149]
	s_add_i32 m0, s6, 0xc000
	ds_read_b128 v[196:199], v161
	ds_read_b128 v[200:203], v161 offset:1024
	ds_read_b128 v[206:209], v161 offset:2048
	ds_read_b128 v[210:213], v161 offset:3072
	ds_read_b128 v[214:217], v161 offset:4096
	ds_read_b128 v[218:221], v161 offset:5120
	ds_read_b128 v[222:225], v161 offset:6144
	ds_read_b128 v[226:229], v161 offset:7168
	global_load_lds_dwordx4 v[158:159], off
	v_lshl_add_u64 v[158:159], s[28:29], 0, v[150:151]
	s_add_i32 m0, s6, 0xe000
	s_nop 0
	global_load_lds_dwordx4 v[158:159], off
	s_waitcnt vmcnt(8)
	s_waitcnt lgkmcnt(0)
	s_barrier
	s_setprio 1
	v_mfma_f32_16x16x32_bf16 v[126:129], v[162:165], v[196:199], v[126:129]
	v_mfma_f32_16x16x32_bf16 v[122:125], v[170:173], v[196:199], v[122:125]
	v_mfma_f32_16x16x32_bf16 v[118:121], v[162:165], v[206:209], v[118:121]
	v_mfma_f32_16x16x32_bf16 v[114:117], v[170:173], v[206:209], v[114:117]
	v_mfma_f32_16x16x32_bf16 v[102:105], v[162:165], v[214:217], v[102:105]
	v_mfma_f32_16x16x32_bf16 v[98:101], v[170:173], v[214:217], v[98:101]
	v_mfma_f32_16x16x32_bf16 v[42:45], v[162:165], v[222:225], v[42:45]
	v_mfma_f32_16x16x32_bf16 v[34:37], v[170:173], v[222:225], v[34:37]
	v_mfma_f32_16x16x32_bf16 v[126:129], v[166:169], v[200:203], v[126:129]
	v_mfma_f32_16x16x32_bf16 v[122:125], v[174:177], v[200:203], v[122:125]
	v_mfma_f32_16x16x32_bf16 v[118:121], v[166:169], v[210:213], v[118:121]
	v_mfma_f32_16x16x32_bf16 v[114:117], v[174:177], v[210:213], v[114:117]
	v_mfma_f32_16x16x32_bf16 v[102:105], v[166:169], v[218:221], v[102:105]
	v_mfma_f32_16x16x32_bf16 v[98:101], v[174:177], v[218:221], v[98:101]
	v_mfma_f32_16x16x32_bf16 v[42:45], v[166:169], v[226:229], v[42:45]
	v_mfma_f32_16x16x32_bf16 v[34:37], v[174:177], v[226:229], v[34:37]
	v_mfma_f32_16x16x32_bf16 v[110:113], v[178:181], v[196:199], v[110:113]
	v_mfma_f32_16x16x32_bf16 v[106:109], v[186:189], v[196:199], v[106:109]
	v_mfma_f32_16x16x32_bf16 v[94:97], v[178:181], v[206:209], v[94:97]
	v_mfma_f32_16x16x32_bf16 v[90:93], v[186:189], v[206:209], v[90:93]
	v_mfma_f32_16x16x32_bf16 v[86:89], v[178:181], v[214:217], v[86:89]
	v_mfma_f32_16x16x32_bf16 v[82:85], v[186:189], v[214:217], v[82:85]
	v_mfma_f32_16x16x32_bf16 v[30:33], v[178:181], v[222:225], v[30:33]
	v_mfma_f32_16x16x32_bf16 v[26:29], v[186:189], v[222:225], v[26:29]
	v_mfma_f32_16x16x32_bf16 v[110:113], v[182:185], v[200:203], v[110:113]
	v_mfma_f32_16x16x32_bf16 v[106:109], v[190:193], v[200:203], v[106:109]
	v_mfma_f32_16x16x32_bf16 v[94:97], v[182:185], v[210:213], v[94:97]
	v_mfma_f32_16x16x32_bf16 v[90:93], v[190:193], v[210:213], v[90:93]
	v_mfma_f32_16x16x32_bf16 v[86:89], v[182:185], v[218:221], v[86:89]
	v_mfma_f32_16x16x32_bf16 v[82:85], v[190:193], v[218:221], v[82:85]
	v_mfma_f32_16x16x32_bf16 v[30:33], v[182:185], v[226:229], v[30:33]
	v_mfma_f32_16x16x32_bf16 v[26:29], v[190:193], v[226:229], v[26:29]
	s_setprio 0
	s_barrier
	s_add_i32 s64, s54, s40
	v_lshl_add_u64 v[158:159], s[30:31], 0, v[134:135]
	s_mov_b32 m0, s64
	ds_read_b128 v[196:199], v161 offset:16384
	ds_read_b128 v[200:203], v161 offset:17408
	ds_read_b128 v[206:209], v161 offset:18432
	ds_read_b128 v[210:213], v161 offset:19456
	ds_read_b128 v[214:217], v161 offset:20480
	ds_read_b128 v[218:221], v161 offset:21504
	ds_read_b128 v[222:225], v161 offset:22528
	ds_read_b128 v[226:229], v161 offset:23552
	global_load_lds_dwordx4 v[158:159], off
	s_add_i32 m0, s64, 0x2000
	s_add_u32 s64, s30, 0x100000
	v_lshl_add_u64 v[230:231], s[30:31], 0, v[132:133]
	s_addc_u32 s65, s31, 0
	s_add_i32 s66, s55, s40
	global_load_lds_dwordx4 v[230:231], off
	v_lshl_add_u64 v[232:233], s[64:65], 0, v[134:135]
	s_mov_b32 m0, s66
	v_lshl_add_u64 v[234:235], s[34:35], 0, v[132:133]
	global_load_lds_dwordx4 v[232:233], off
	v_lshl_add_u64 v[232:233], s[64:65], 0, v[132:133]
	s_add_i32 m0, s66, 0x2000
	s_nop 0
	global_load_lds_dwordx4 v[232:233], off
	v_lshl_add_u64 v[232:233], s[34:35], 0, v[134:135]
	s_mov_b32 m0, s6
	s_nop 0
	global_load_lds_dwordx4 v[232:233], off
	s_mov_b32 m0, s13
	s_nop 0
	global_load_lds_dwordx4 v[234:235], off
	s_waitcnt vmcnt(8)
	s_waitcnt lgkmcnt(0)
	s_barrier
	s_setprio 1
	v_mfma_f32_16x16x32_bf16 v[78:81], v[162:165], v[196:199], v[78:81]
	v_mfma_f32_16x16x32_bf16 v[74:77], v[170:173], v[196:199], v[74:77]
	v_mfma_f32_16x16x32_bf16 v[70:73], v[162:165], v[206:209], v[70:73]
	v_mfma_f32_16x16x32_bf16 v[66:69], v[170:173], v[206:209], v[66:69]
	v_mfma_f32_16x16x32_bf16 v[54:57], v[162:165], v[214:217], v[54:57]
	v_mfma_f32_16x16x32_bf16 v[50:53], v[170:173], v[214:217], v[50:53]
	v_mfma_f32_16x16x32_bf16 v[14:17], v[162:165], v[222:225], v[14:17]
	v_mfma_f32_16x16x32_bf16 v[10:13], v[170:173], v[222:225], v[10:13]
	v_mfma_f32_16x16x32_bf16 v[78:81], v[166:169], v[200:203], v[78:81]
	v_mfma_f32_16x16x32_bf16 v[74:77], v[174:177], v[200:203], v[74:77]
	v_mfma_f32_16x16x32_bf16 v[70:73], v[166:169], v[210:213], v[70:73]
	v_mfma_f32_16x16x32_bf16 v[66:69], v[174:177], v[210:213], v[66:69]
	v_mfma_f32_16x16x32_bf16 v[54:57], v[166:169], v[218:221], v[54:57]
	v_mfma_f32_16x16x32_bf16 v[50:53], v[174:177], v[218:221], v[50:53]
	v_mfma_f32_16x16x32_bf16 v[14:17], v[166:169], v[226:229], v[14:17]
	v_mfma_f32_16x16x32_bf16 v[10:13], v[174:177], v[226:229], v[10:13]
	v_mfma_f32_16x16x32_bf16 v[62:65], v[178:181], v[196:199], v[62:65]
	v_mfma_f32_16x16x32_bf16 v[58:61], v[186:189], v[196:199], v[58:61]
	v_mfma_f32_16x16x32_bf16 v[46:49], v[178:181], v[206:209], v[46:49]
	v_mfma_f32_16x16x32_bf16 v[38:41], v[186:189], v[206:209], v[38:41]
	v_mfma_f32_16x16x32_bf16 v[22:25], v[178:181], v[214:217], v[22:25]
	v_mfma_f32_16x16x32_bf16 v[18:21], v[186:189], v[214:217], v[18:21]
	v_mfma_f32_16x16x32_bf16 v[6:9], v[178:181], v[222:225], v[6:9]
	v_mfma_f32_16x16x32_bf16 v[2:5], v[186:189], v[222:225], v[2:5]
	v_mfma_f32_16x16x32_bf16 v[62:65], v[182:185], v[200:203], v[62:65]
	v_mfma_f32_16x16x32_bf16 v[58:61], v[190:193], v[200:203], v[58:61]
	v_mfma_f32_16x16x32_bf16 v[46:49], v[182:185], v[210:213], v[46:49]
	v_mfma_f32_16x16x32_bf16 v[38:41], v[190:193], v[210:213], v[38:41]
	v_mfma_f32_16x16x32_bf16 v[22:25], v[182:185], v[218:221], v[22:25]
	v_mfma_f32_16x16x32_bf16 v[18:21], v[190:193], v[218:221], v[18:21]
	v_mfma_f32_16x16x32_bf16 v[6:9], v[182:185], v[226:229], v[6:9]
	v_mfma_f32_16x16x32_bf16 v[2:5], v[190:193], v[226:229], v[2:5]
	s_setprio 0
	s_barrier
	s_add_i32 s64, 0, 0x18000
	s_add_i32 s65, 0, 0x1c000
	v_add_u32_e32 v174, s64, v131
	v_add_u32_e32 v190, s65, v131
	ds_read_b128 v[162:165], v174
	ds_read_b128 v[166:169], v174 offset:1024
	ds_read_b128 v[170:173], v174 offset:2048
	ds_read_b128 v[174:177], v174 offset:3072
	ds_read_b128 v[178:181], v190
	ds_read_b128 v[182:185], v190 offset:1024
	ds_read_b128 v[186:189], v190 offset:2048
	ds_read_b128 v[190:193], v190 offset:3072
	s_add_u32 s34, s34, 0x100000
	s_addc_u32 s35, s35, 0
	s_mov_b32 m0, s43
	v_lshl_add_u64 v[236:237], s[34:35], 0, v[134:135]
	ds_read_b128 v[196:199], v161 offset:32768
	ds_read_b128 v[200:203], v161 offset:33792
	ds_read_b128 v[206:209], v161 offset:34816
	ds_read_b128 v[210:213], v161 offset:35840
	ds_read_b128 v[214:217], v161 offset:36864
	ds_read_b128 v[218:221], v161 offset:37888
	ds_read_b128 v[222:225], v161 offset:38912
	ds_read_b128 v[226:229], v161 offset:39936
	global_load_lds_dwordx4 v[236:237], off
	v_lshl_add_u64 v[236:237], s[34:35], 0, v[132:133]
	s_mov_b32 m0, s45
	s_nop 0
	global_load_lds_dwordx4 v[236:237], off
	s_waitcnt vmcnt(8)
	s_waitcnt lgkmcnt(0)
	s_barrier
	s_setprio 1
	v_mfma_f32_16x16x32_bf16 v[126:129], v[162:165], v[196:199], v[126:129]
	v_mfma_f32_16x16x32_bf16 v[122:125], v[170:173], v[196:199], v[122:125]
	v_mfma_f32_16x16x32_bf16 v[118:121], v[162:165], v[206:209], v[118:121]
	v_mfma_f32_16x16x32_bf16 v[114:117], v[170:173], v[206:209], v[114:117]
	v_mfma_f32_16x16x32_bf16 v[102:105], v[162:165], v[214:217], v[102:105]
	v_mfma_f32_16x16x32_bf16 v[98:101], v[170:173], v[214:217], v[98:101]
	v_mfma_f32_16x16x32_bf16 v[42:45], v[162:165], v[222:225], v[42:45]
	v_mfma_f32_16x16x32_bf16 v[34:37], v[170:173], v[222:225], v[34:37]
	v_mfma_f32_16x16x32_bf16 v[126:129], v[166:169], v[200:203], v[126:129]
	v_mfma_f32_16x16x32_bf16 v[122:125], v[174:177], v[200:203], v[122:125]
	v_mfma_f32_16x16x32_bf16 v[118:121], v[166:169], v[210:213], v[118:121]
	v_mfma_f32_16x16x32_bf16 v[114:117], v[174:177], v[210:213], v[114:117]
	v_mfma_f32_16x16x32_bf16 v[102:105], v[166:169], v[218:221], v[102:105]
	v_mfma_f32_16x16x32_bf16 v[98:101], v[174:177], v[218:221], v[98:101]
	v_mfma_f32_16x16x32_bf16 v[42:45], v[166:169], v[226:229], v[42:45]
	v_mfma_f32_16x16x32_bf16 v[34:37], v[174:177], v[226:229], v[34:37]
	v_mfma_f32_16x16x32_bf16 v[110:113], v[178:181], v[196:199], v[110:113]
	v_mfma_f32_16x16x32_bf16 v[106:109], v[186:189], v[196:199], v[106:109]
	v_mfma_f32_16x16x32_bf16 v[94:97], v[178:181], v[206:209], v[94:97]
	v_mfma_f32_16x16x32_bf16 v[90:93], v[186:189], v[206:209], v[90:93]
	v_mfma_f32_16x16x32_bf16 v[86:89], v[178:181], v[214:217], v[86:89]
	v_mfma_f32_16x16x32_bf16 v[82:85], v[186:189], v[214:217], v[82:85]
	v_mfma_f32_16x16x32_bf16 v[30:33], v[178:181], v[222:225], v[30:33]
	v_mfma_f32_16x16x32_bf16 v[26:29], v[186:189], v[222:225], v[26:29]
	v_mfma_f32_16x16x32_bf16 v[110:113], v[182:185], v[200:203], v[110:113]
	v_mfma_f32_16x16x32_bf16 v[106:109], v[190:193], v[200:203], v[106:109]
	v_mfma_f32_16x16x32_bf16 v[94:97], v[182:185], v[210:213], v[94:97]
	v_mfma_f32_16x16x32_bf16 v[90:93], v[190:193], v[210:213], v[90:93]
	v_mfma_f32_16x16x32_bf16 v[86:89], v[182:185], v[218:221], v[86:89]
	v_mfma_f32_16x16x32_bf16 v[82:85], v[190:193], v[218:221], v[82:85]
	v_mfma_f32_16x16x32_bf16 v[30:33], v[182:185], v[226:229], v[30:33]
	v_mfma_f32_16x16x32_bf16 v[26:29], v[190:193], v[226:229], v[26:29]
	s_setprio 0
	s_barrier
	s_add_i32 s34, s64, s40
	v_lshl_add_u64 v[158:159], v[158:159], 0, s[10:11]
	s_mov_b32 m0, s34
	ds_read_b128 v[196:199], v161 offset:49152
	ds_read_b128 v[200:203], v161 offset:50176
	ds_read_b128 v[206:209], v161 offset:51200
	ds_read_b128 v[210:213], v161 offset:52224
	ds_read_b128 v[214:217], v161 offset:53248
	ds_read_b128 v[218:221], v161 offset:54272
	ds_read_b128 v[222:225], v161 offset:55296
	ds_read_b128 v[226:229], v161 offset:56320
	global_load_lds_dwordx4 v[158:159], off
	s_add_i32 m0, s34, 0x2000
	s_add_u32 s30, s30, 0x100080
	v_lshl_add_u64 v[158:159], v[230:231], 0, s[10:11]
	s_addc_u32 s31, s31, 0
	s_add_i32 s34, s65, s40
	global_load_lds_dwordx4 v[158:159], off
	v_lshl_add_u64 v[158:159], s[30:31], 0, v[134:135]
	s_mov_b32 m0, s34
	s_nop 0
	global_load_lds_dwordx4 v[158:159], off
	v_lshl_add_u64 v[158:159], s[30:31], 0, v[132:133]
	s_add_i32 m0, s34, 0x2000
	s_nop 0
	global_load_lds_dwordx4 v[158:159], off
	v_lshl_add_u64 v[158:159], v[232:233], 0, s[10:11]
	s_mov_b32 m0, s50
	s_nop 0
	global_load_lds_dwordx4 v[158:159], off
	v_lshl_add_u64 v[158:159], v[234:235], 0, s[10:11]
	s_mov_b32 m0, s51
	s_nop 0
	global_load_lds_dwordx4 v[158:159], off
	s_waitcnt vmcnt(8)
	s_waitcnt lgkmcnt(0)
	s_barrier
	s_setprio 1
	v_mfma_f32_16x16x32_bf16 v[78:81], v[162:165], v[196:199], v[78:81]
	v_mfma_f32_16x16x32_bf16 v[74:77], v[170:173], v[196:199], v[74:77]
	v_mfma_f32_16x16x32_bf16 v[70:73], v[162:165], v[206:209], v[70:73]
	v_mfma_f32_16x16x32_bf16 v[66:69], v[170:173], v[206:209], v[66:69]
	v_mfma_f32_16x16x32_bf16 v[54:57], v[162:165], v[214:217], v[54:57]
	v_mfma_f32_16x16x32_bf16 v[50:53], v[170:173], v[214:217], v[50:53]
	v_mfma_f32_16x16x32_bf16 v[14:17], v[162:165], v[222:225], v[14:17]
	v_mfma_f32_16x16x32_bf16 v[10:13], v[170:173], v[222:225], v[10:13]
	v_mfma_f32_16x16x32_bf16 v[78:81], v[166:169], v[200:203], v[78:81]
	v_mfma_f32_16x16x32_bf16 v[74:77], v[174:177], v[200:203], v[74:77]
	v_mfma_f32_16x16x32_bf16 v[70:73], v[166:169], v[210:213], v[70:73]
	v_mfma_f32_16x16x32_bf16 v[66:69], v[174:177], v[210:213], v[66:69]
	v_mfma_f32_16x16x32_bf16 v[54:57], v[166:169], v[218:221], v[54:57]
	v_mfma_f32_16x16x32_bf16 v[50:53], v[174:177], v[218:221], v[50:53]
	v_mfma_f32_16x16x32_bf16 v[14:17], v[166:169], v[226:229], v[14:17]
	v_mfma_f32_16x16x32_bf16 v[10:13], v[174:177], v[226:229], v[10:13]
	v_mfma_f32_16x16x32_bf16 v[62:65], v[178:181], v[196:199], v[62:65]
	v_mfma_f32_16x16x32_bf16 v[58:61], v[186:189], v[196:199], v[58:61]
	v_mfma_f32_16x16x32_bf16 v[46:49], v[178:181], v[206:209], v[46:49]
	v_mfma_f32_16x16x32_bf16 v[38:41], v[186:189], v[206:209], v[38:41]
	v_mfma_f32_16x16x32_bf16 v[22:25], v[178:181], v[214:217], v[22:25]
	v_mfma_f32_16x16x32_bf16 v[18:21], v[186:189], v[214:217], v[18:21]
	v_mfma_f32_16x16x32_bf16 v[6:9], v[178:181], v[222:225], v[6:9]
	v_mfma_f32_16x16x32_bf16 v[2:5], v[186:189], v[222:225], v[2:5]
	v_mfma_f32_16x16x32_bf16 v[62:65], v[182:185], v[200:203], v[62:65]
	v_mfma_f32_16x16x32_bf16 v[58:61], v[190:193], v[200:203], v[58:61]
	v_mfma_f32_16x16x32_bf16 v[46:49], v[182:185], v[210:213], v[46:49]
	v_mfma_f32_16x16x32_bf16 v[38:41], v[190:193], v[210:213], v[38:41]
	v_mfma_f32_16x16x32_bf16 v[22:25], v[182:185], v[218:221], v[22:25]
	v_mfma_f32_16x16x32_bf16 v[18:21], v[190:193], v[218:221], v[18:21]
	v_mfma_f32_16x16x32_bf16 v[6:9], v[182:185], v[226:229], v[6:9]
	v_mfma_f32_16x16x32_bf16 v[2:5], v[190:193], v[226:229], v[2:5]
	s_setprio 0
	s_barrier
	s_add_u32 s28, s28, 0x100
	s_addc_u32 s29, s29, 0
	s_add_u32 s61, s61, 0x100
	s_addc_u32 s62, s62, 0
	s_cmp_ge_i32 s63, s58
	s_mov_b32 s30, s63
	s_cbranch_scc0 .LBB0_3789
	s_and_b64 vcc, exec, s[16:17]
	s_cbranch_vccz .LBB0_3792
	s_barrier

.LBB0_3983:
	ds_read_b128 v[152:155], v160
	ds_read_b128 v[164:167], v160 offset:1024
	ds_read_b128 v[168:171], v160 offset:2048
	ds_read_b128 v[172:175], v160 offset:3072
	ds_read_b128 v[176:179], v161
	ds_read_b128 v[180:183], v161 offset:1024
	ds_read_b128 v[184:187], v161 offset:2048
	ds_read_b128 v[188:191], v161 offset:3072
	s_add_i32 s80, s48, 2
	s_add_u32 s49, s58, 0xfffe0080
	s_addc_u32 s60, s59, -1
	s_cmp_eq_u32 s43, s48
	s_cselect_b32 s48, s52, s47
	s_cselect_b32 s61, s5, s60
	s_cselect_b32 s60, s4, s49
	s_cselect_b32 s49, s53, s51
	v_lshl_add_u64 v[156:157], s[58:59], 0, v[140:141]
	s_add_i32 m0, s55, 0xc000
	ds_read_b128 v[196:199], v162
	ds_read_b128 v[200:203], v162 offset:1024
	ds_read_b128 v[204:207], v162 offset:2048
	ds_read_b128 v[208:211], v162 offset:3072
	ds_read_b128 v[212:215], v162 offset:4096
	ds_read_b128 v[216:219], v162 offset:5120
	ds_read_b128 v[220:223], v162 offset:6144
	ds_read_b128 v[224:227], v162 offset:7168
	global_load_lds_dwordx4 v[156:157], off
	v_lshl_add_u64 v[156:157], s[58:59], 0, v[142:143]
	s_add_i32 m0, s55, 0xe000
	s_nop 0
	global_load_lds_dwordx4 v[156:157], off
	s_waitcnt vmcnt(8)
	s_waitcnt lgkmcnt(0)
	s_barrier
	s_setprio 1
	v_mfma_f32_16x16x32_bf16 v[126:129], v[152:155], v[196:199], v[126:129]
	v_mfma_f32_16x16x32_bf16 v[122:125], v[168:171], v[196:199], v[122:125]
	v_mfma_f32_16x16x32_bf16 v[110:113], v[152:155], v[204:207], v[110:113]
	v_mfma_f32_16x16x32_bf16 v[106:109], v[168:171], v[204:207], v[106:109]
	v_mfma_f32_16x16x32_bf16 v[94:97], v[152:155], v[212:215], v[94:97]
	v_mfma_f32_16x16x32_bf16 v[90:93], v[168:171], v[212:215], v[90:93]
	v_mfma_f32_16x16x32_bf16 v[78:81], v[152:155], v[220:223], v[78:81]
	v_mfma_f32_16x16x32_bf16 v[74:77], v[168:171], v[220:223], v[74:77]
	v_mfma_f32_16x16x32_bf16 v[126:129], v[164:167], v[200:203], v[126:129]
	v_mfma_f32_16x16x32_bf16 v[122:125], v[172:175], v[200:203], v[122:125]
	v_mfma_f32_16x16x32_bf16 v[110:113], v[164:167], v[208:211], v[110:113]
	v_mfma_f32_16x16x32_bf16 v[106:109], v[172:175], v[208:211], v[106:109]
	v_mfma_f32_16x16x32_bf16 v[94:97], v[164:167], v[216:219], v[94:97]
	v_mfma_f32_16x16x32_bf16 v[90:93], v[172:175], v[216:219], v[90:93]
	v_mfma_f32_16x16x32_bf16 v[78:81], v[164:167], v[224:227], v[78:81]
	v_mfma_f32_16x16x32_bf16 v[74:77], v[172:175], v[224:227], v[74:77]
	v_mfma_f32_16x16x32_bf16 v[118:121], v[176:179], v[196:199], v[118:121]
	v_mfma_f32_16x16x32_bf16 v[114:117], v[184:187], v[196:199], v[114:117]
	v_mfma_f32_16x16x32_bf16 v[102:105], v[176:179], v[204:207], v[102:105]
	v_mfma_f32_16x16x32_bf16 v[98:101], v[184:187], v[204:207], v[98:101]
	v_mfma_f32_16x16x32_bf16 v[86:89], v[176:179], v[212:215], v[86:89]
	v_mfma_f32_16x16x32_bf16 v[82:85], v[184:187], v[212:215], v[82:85]
	v_mfma_f32_16x16x32_bf16 v[70:73], v[176:179], v[220:223], v[70:73]
	v_mfma_f32_16x16x32_bf16 v[66:69], v[184:187], v[220:223], v[66:69]
	v_mfma_f32_16x16x32_bf16 v[118:121], v[180:183], v[200:203], v[118:121]
	v_mfma_f32_16x16x32_bf16 v[114:117], v[188:191], v[200:203], v[114:117]
	v_mfma_f32_16x16x32_bf16 v[102:105], v[180:183], v[208:211], v[102:105]
	v_mfma_f32_16x16x32_bf16 v[98:101], v[188:191], v[208:211], v[98:101]
	v_mfma_f32_16x16x32_bf16 v[86:89], v[180:183], v[216:219], v[86:89]
	v_mfma_f32_16x16x32_bf16 v[82:85], v[188:191], v[216:219], v[82:85]
	v_mfma_f32_16x16x32_bf16 v[70:73], v[180:183], v[224:227], v[70:73]
	v_mfma_f32_16x16x32_bf16 v[66:69], v[188:191], v[224:227], v[66:69]
	s_setprio 0
	s_barrier
	s_add_i32 s81, s71, s62
	v_lshl_add_u64 v[156:157], s[48:49], 0, v[134:135]
	s_mov_b32 m0, s81
	ds_read_b128 v[196:199], v162 offset:16384
	ds_read_b128 v[200:203], v162 offset:17408
	ds_read_b128 v[204:207], v162 offset:18432
	ds_read_b128 v[208:211], v162 offset:19456
	ds_read_b128 v[212:215], v162 offset:20480
	ds_read_b128 v[216:219], v162 offset:21504
	ds_read_b128 v[220:223], v162 offset:22528
	ds_read_b128 v[224:227], v162 offset:23552
	global_load_lds_dwordx4 v[156:157], off
	s_add_i32 m0, s81, 0x2000
	s_add_u32 s82, s48, 0x20000
	v_lshl_add_u64 v[192:193], s[48:49], 0, v[138:139]
	s_addc_u32 s83, s49, 0
	s_add_i32 s81, s72, s62
	global_load_lds_dwordx4 v[192:193], off
	v_lshl_add_u64 v[228:229], s[82:83], 0, v[134:135]
	s_mov_b32 m0, s81
	v_lshl_add_u64 v[230:231], s[60:61], 0, v[136:137]
	global_load_lds_dwordx4 v[228:229], off
	v_lshl_add_u64 v[228:229], s[82:83], 0, v[138:139]
	s_add_i32 m0, s81, 0x2000
	s_nop 0
	global_load_lds_dwordx4 v[228:229], off
	v_lshl_add_u64 v[228:229], s[60:61], 0, v[132:133]
	s_mov_b32 m0, s55
	s_nop 0
	global_load_lds_dwordx4 v[228:229], off
	s_mov_b32 m0, s57
	s_nop 0
	global_load_lds_dwordx4 v[230:231], off
	s_waitcnt vmcnt(8)
	s_waitcnt lgkmcnt(0)
	s_barrier
	s_setprio 1
	v_mfma_f32_16x16x32_bf16 v[62:65], v[152:155], v[196:199], v[62:65]
	v_mfma_f32_16x16x32_bf16 v[58:61], v[168:171], v[196:199], v[58:61]
	v_mfma_f32_16x16x32_bf16 v[46:49], v[152:155], v[204:207], v[46:49]
	v_mfma_f32_16x16x32_bf16 v[42:45], v[168:171], v[204:207], v[42:45]
	v_mfma_f32_16x16x32_bf16 v[30:33], v[152:155], v[212:215], v[30:33]
	v_mfma_f32_16x16x32_bf16 v[26:29], v[168:171], v[212:215], v[26:29]
	v_mfma_f32_16x16x32_bf16 v[14:17], v[152:155], v[220:223], v[14:17]
	v_mfma_f32_16x16x32_bf16 v[10:13], v[168:171], v[220:223], v[10:13]
	v_mfma_f32_16x16x32_bf16 v[62:65], v[164:167], v[200:203], v[62:65]
	v_mfma_f32_16x16x32_bf16 v[58:61], v[172:175], v[200:203], v[58:61]
	v_mfma_f32_16x16x32_bf16 v[46:49], v[164:167], v[208:211], v[46:49]
	v_mfma_f32_16x16x32_bf16 v[42:45], v[172:175], v[208:211], v[42:45]
	v_mfma_f32_16x16x32_bf16 v[30:33], v[164:167], v[216:219], v[30:33]
	v_mfma_f32_16x16x32_bf16 v[26:29], v[172:175], v[216:219], v[26:29]
	v_mfma_f32_16x16x32_bf16 v[14:17], v[164:167], v[224:227], v[14:17]
	v_mfma_f32_16x16x32_bf16 v[10:13], v[172:175], v[224:227], v[10:13]
	v_mfma_f32_16x16x32_bf16 v[54:57], v[176:179], v[196:199], v[54:57]
	v_mfma_f32_16x16x32_bf16 v[50:53], v[184:187], v[196:199], v[50:53]
	v_mfma_f32_16x16x32_bf16 v[38:41], v[176:179], v[204:207], v[38:41]
	v_mfma_f32_16x16x32_bf16 v[34:37], v[184:187], v[204:207], v[34:37]
	v_mfma_f32_16x16x32_bf16 v[22:25], v[176:179], v[212:215], v[22:25]
	v_mfma_f32_16x16x32_bf16 v[18:21], v[184:187], v[212:215], v[18:21]
	v_mfma_f32_16x16x32_bf16 v[6:9], v[176:179], v[220:223], v[6:9]
	v_mfma_f32_16x16x32_bf16 v[2:5], v[184:187], v[220:223], v[2:5]
	v_mfma_f32_16x16x32_bf16 v[54:57], v[180:183], v[200:203], v[54:57]
	v_mfma_f32_16x16x32_bf16 v[50:53], v[188:191], v[200:203], v[50:53]
	v_mfma_f32_16x16x32_bf16 v[38:41], v[180:183], v[208:211], v[38:41]
	v_mfma_f32_16x16x32_bf16 v[34:37], v[188:191], v[208:211], v[34:37]
	v_mfma_f32_16x16x32_bf16 v[22:25], v[180:183], v[216:219], v[22:25]
	v_mfma_f32_16x16x32_bf16 v[18:21], v[188:191], v[216:219], v[18:21]
	v_mfma_f32_16x16x32_bf16 v[6:9], v[180:183], v[224:227], v[6:9]
	v_mfma_f32_16x16x32_bf16 v[2:5], v[188:191], v[224:227], v[2:5]
	s_setprio 0
	s_barrier
	s_add_i32 s81, 0, 0x18000
	v_add_u32_e32 v163, s81, v158
	s_add_i32 s82, 0, 0x1c000
	ds_read_b128 v[152:155], v163
	ds_read_b128 v[164:167], v163 offset:1024
	ds_read_b128 v[168:171], v163 offset:2048
	ds_read_b128 v[172:175], v163 offset:3072
	v_add_u32_e32 v163, s82, v158
	ds_read_b128 v[176:179], v163
	ds_read_b128 v[180:183], v163 offset:1024
	ds_read_b128 v[184:187], v163 offset:2048
	ds_read_b128 v[188:191], v163 offset:3072
	s_add_u32 s60, s60, 0x20000
	s_addc_u32 s61, s61, 0
	s_mov_b32 m0, s63
	v_lshl_add_u64 v[232:233], s[60:61], 0, v[132:133]
	ds_read_b128 v[196:199], v162 offset:32768
	ds_read_b128 v[200:203], v162 offset:33792
	ds_read_b128 v[204:207], v162 offset:34816
	ds_read_b128 v[208:211], v162 offset:35840
	ds_read_b128 v[212:215], v162 offset:36864
	ds_read_b128 v[216:219], v162 offset:37888
	ds_read_b128 v[220:223], v162 offset:38912
	ds_read_b128 v[224:227], v162 offset:39936
	global_load_lds_dwordx4 v[232:233], off
	v_lshl_add_u64 v[232:233], s[60:61], 0, v[136:137]
	s_mov_b32 m0, s64
	s_nop 0
	global_load_lds_dwordx4 v[232:233], off
	s_waitcnt vmcnt(8)
	s_waitcnt lgkmcnt(0)
	s_barrier
	s_setprio 1
	v_mfma_f32_16x16x32_bf16 v[126:129], v[152:155], v[196:199], v[126:129]
	v_mfma_f32_16x16x32_bf16 v[122:125], v[168:171], v[196:199], v[122:125]
	v_mfma_f32_16x16x32_bf16 v[110:113], v[152:155], v[204:207], v[110:113]
	v_mfma_f32_16x16x32_bf16 v[106:109], v[168:171], v[204:207], v[106:109]
	v_mfma_f32_16x16x32_bf16 v[94:97], v[152:155], v[212:215], v[94:97]
	v_mfma_f32_16x16x32_bf16 v[90:93], v[168:171], v[212:215], v[90:93]
	v_mfma_f32_16x16x32_bf16 v[78:81], v[152:155], v[220:223], v[78:81]
	v_mfma_f32_16x16x32_bf16 v[74:77], v[168:171], v[220:223], v[74:77]
	v_mfma_f32_16x16x32_bf16 v[126:129], v[164:167], v[200:203], v[126:129]
	v_mfma_f32_16x16x32_bf16 v[122:125], v[172:175], v[200:203], v[122:125]
	v_mfma_f32_16x16x32_bf16 v[110:113], v[164:167], v[208:211], v[110:113]
	v_mfma_f32_16x16x32_bf16 v[106:109], v[172:175], v[208:211], v[106:109]
	v_mfma_f32_16x16x32_bf16 v[94:97], v[164:167], v[216:219], v[94:97]
	v_mfma_f32_16x16x32_bf16 v[90:93], v[172:175], v[216:219], v[90:93]
	v_mfma_f32_16x16x32_bf16 v[78:81], v[164:167], v[224:227], v[78:81]
	v_mfma_f32_16x16x32_bf16 v[74:77], v[172:175], v[224:227], v[74:77]
	v_mfma_f32_16x16x32_bf16 v[118:121], v[176:179], v[196:199], v[118:121]
	v_mfma_f32_16x16x32_bf16 v[114:117], v[184:187], v[196:199], v[114:117]
	v_mfma_f32_16x16x32_bf16 v[102:105], v[176:179], v[204:207], v[102:105]
	v_mfma_f32_16x16x32_bf16 v[98:101], v[184:187], v[204:207], v[98:101]
	v_mfma_f32_16x16x32_bf16 v[86:89], v[176:179], v[212:215], v[86:89]
	v_mfma_f32_16x16x32_bf16 v[82:85], v[184:187], v[212:215], v[82:85]
	v_mfma_f32_16x16x32_bf16 v[70:73], v[176:179], v[220:223], v[70:73]
	v_mfma_f32_16x16x32_bf16 v[66:69], v[184:187], v[220:223], v[66:69]
	v_mfma_f32_16x16x32_bf16 v[118:121], v[180:183], v[200:203], v[118:121]
	v_mfma_f32_16x16x32_bf16 v[114:117], v[188:191], v[200:203], v[114:117]
	v_mfma_f32_16x16x32_bf16 v[102:105], v[180:183], v[208:211], v[102:105]
	v_mfma_f32_16x16x32_bf16 v[98:101], v[188:191], v[208:211], v[98:101]
	v_mfma_f32_16x16x32_bf16 v[86:89], v[180:183], v[216:219], v[86:89]
	v_mfma_f32_16x16x32_bf16 v[82:85], v[188:191], v[216:219], v[82:85]
	v_mfma_f32_16x16x32_bf16 v[70:73], v[180:183], v[224:227], v[70:73]
	v_mfma_f32_16x16x32_bf16 v[66:69], v[188:191], v[224:227], v[66:69]
	s_setprio 0
	s_barrier
	s_add_i32 s60, s81, s62
	v_lshl_add_u64 v[156:157], v[156:157], 0, s[14:15]
	s_mov_b32 m0, s60
	ds_read_b128 v[196:199], v162 offset:49152
	ds_read_b128 v[200:203], v162 offset:50176
	ds_read_b128 v[204:207], v162 offset:51200
	ds_read_b128 v[208:211], v162 offset:52224
	ds_read_b128 v[212:215], v162 offset:53248
	ds_read_b128 v[216:219], v162 offset:54272
	ds_read_b128 v[220:223], v162 offset:55296
	ds_read_b128 v[224:227], v162 offset:56320
	global_load_lds_dwordx4 v[156:157], off
	s_add_i32 m0, s60, 0x2000
	s_add_u32 s48, s48, 0x20080
	v_lshl_add_u64 v[156:157], v[192:193], 0, s[14:15]
	s_addc_u32 s49, s49, 0
	s_add_i32 s60, s82, s62
	global_load_lds_dwordx4 v[156:157], off
	v_lshl_add_u64 v[156:157], s[48:49], 0, v[134:135]
	s_mov_b32 m0, s60
	s_nop 0
	global_load_lds_dwordx4 v[156:157], off
	v_lshl_add_u64 v[156:157], s[48:49], 0, v[138:139]
	s_add_i32 m0, s60, 0x2000
	s_nop 0
	global_load_lds_dwordx4 v[156:157], off
	v_lshl_add_u64 v[156:157], v[228:229], 0, s[14:15]
	s_mov_b32 m0, s68
	s_nop 0
	global_load_lds_dwordx4 v[156:157], off
	v_lshl_add_u64 v[156:157], v[230:231], 0, s[14:15]
	s_mov_b32 m0, s69
	s_nop 0
	global_load_lds_dwordx4 v[156:157], off
	s_waitcnt vmcnt(8)
	s_waitcnt lgkmcnt(0)
	s_barrier
	s_setprio 1
	v_mfma_f32_16x16x32_bf16 v[62:65], v[152:155], v[196:199], v[62:65]
	v_mfma_f32_16x16x32_bf16 v[58:61], v[168:171], v[196:199], v[58:61]
	v_mfma_f32_16x16x32_bf16 v[46:49], v[152:155], v[204:207], v[46:49]
	v_mfma_f32_16x16x32_bf16 v[42:45], v[168:171], v[204:207], v[42:45]
	v_mfma_f32_16x16x32_bf16 v[30:33], v[152:155], v[212:215], v[30:33]
	v_mfma_f32_16x16x32_bf16 v[26:29], v[168:171], v[212:215], v[26:29]
	v_mfma_f32_16x16x32_bf16 v[14:17], v[152:155], v[220:223], v[14:17]
	v_mfma_f32_16x16x32_bf16 v[10:13], v[168:171], v[220:223], v[10:13]
	v_mfma_f32_16x16x32_bf16 v[62:65], v[164:167], v[200:203], v[62:65]
	v_mfma_f32_16x16x32_bf16 v[58:61], v[172:175], v[200:203], v[58:61]
	v_mfma_f32_16x16x32_bf16 v[46:49], v[164:167], v[208:211], v[46:49]
	v_mfma_f32_16x16x32_bf16 v[42:45], v[172:175], v[208:211], v[42:45]
	v_mfma_f32_16x16x32_bf16 v[30:33], v[164:167], v[216:219], v[30:33]
	v_mfma_f32_16x16x32_bf16 v[26:29], v[172:175], v[216:219], v[26:29]
	v_mfma_f32_16x16x32_bf16 v[14:17], v[164:167], v[224:227], v[14:17]
	v_mfma_f32_16x16x32_bf16 v[10:13], v[172:175], v[224:227], v[10:13]
	v_mfma_f32_16x16x32_bf16 v[54:57], v[176:179], v[196:199], v[54:57]
	v_mfma_f32_16x16x32_bf16 v[50:53], v[184:187], v[196:199], v[50:53]
	v_mfma_f32_16x16x32_bf16 v[38:41], v[176:179], v[204:207], v[38:41]
	v_mfma_f32_16x16x32_bf16 v[34:37], v[184:187], v[204:207], v[34:37]
	v_mfma_f32_16x16x32_bf16 v[22:25], v[176:179], v[212:215], v[22:25]
	v_mfma_f32_16x16x32_bf16 v[18:21], v[184:187], v[212:215], v[18:21]
	v_mfma_f32_16x16x32_bf16 v[6:9], v[176:179], v[220:223], v[6:9]
	v_mfma_f32_16x16x32_bf16 v[2:5], v[184:187], v[220:223], v[2:5]
	v_mfma_f32_16x16x32_bf16 v[54:57], v[180:183], v[200:203], v[54:57]
	v_mfma_f32_16x16x32_bf16 v[50:53], v[188:191], v[200:203], v[50:53]
	v_mfma_f32_16x16x32_bf16 v[38:41], v[180:183], v[208:211], v[38:41]
	v_mfma_f32_16x16x32_bf16 v[34:37], v[188:191], v[208:211], v[34:37]
	v_mfma_f32_16x16x32_bf16 v[22:25], v[180:183], v[216:219], v[22:25]
	v_mfma_f32_16x16x32_bf16 v[18:21], v[188:191], v[216:219], v[18:21]
	v_mfma_f32_16x16x32_bf16 v[6:9], v[180:183], v[224:227], v[6:9]
	v_mfma_f32_16x16x32_bf16 v[2:5], v[188:191], v[224:227], v[2:5]
	s_setprio 0
	s_barrier
	s_add_u32 s58, s58, 0x100
	s_addc_u32 s59, s59, 0
	s_add_u32 s47, s47, 0x100
	s_addc_u32 s51, s51, 0
	s_cmp_ge_i32 s80, s79
	s_mov_b32 s48, s80
	s_cbranch_scc0 .LBB0_3983
	s_and_b64 vcc, exec, s[16:17]
	s_cbranch_vccz .LBB0_3986
	s_barrier

.LBB0_4145:
	ds_read_b128 v[156:159], v162
	ds_read_b128 v[166:169], v162 offset:1024
	ds_read_b128 v[170:173], v162 offset:2048
	ds_read_b128 v[174:177], v162 offset:3072
	ds_read_b128 v[178:181], v163
	ds_read_b128 v[182:185], v163 offset:1024
	ds_read_b128 v[186:189], v163 offset:2048
	ds_read_b128 v[190:193], v163 offset:3072
	s_add_i32 s72, s42, 2
	s_add_u32 s43, s40, 0xfff00080
	s_addc_u32 s46, s41, -1
	s_cmp_eq_u32 s69, s42
	s_cselect_b32 s42, s25, s70
	s_cselect_b32 s47, s5, s46
	s_cselect_b32 s46, s23, s43
	s_cselect_b32 s43, s21, s71
	v_lshl_add_u64 v[228:229], s[40:41], 0, v[148:149]
	s_add_i32 m0, s35, 0xc000
	ds_read_b128 v[196:199], v164
	ds_read_b128 v[200:203], v164 offset:1024
	ds_read_b128 v[204:207], v164 offset:2048
	ds_read_b128 v[208:211], v164 offset:3072
	ds_read_b128 v[212:215], v164 offset:4096
	ds_read_b128 v[216:219], v164 offset:5120
	ds_read_b128 v[220:223], v164 offset:6144
	ds_read_b128 v[224:227], v164 offset:7168
	global_load_lds_dwordx4 v[228:229], off
	v_lshl_add_u64 v[228:229], s[40:41], 0, v[150:151]
	s_add_i32 m0, s35, 0xe000
	s_nop 0
	global_load_lds_dwordx4 v[228:229], off
	s_waitcnt vmcnt(8)
	s_waitcnt lgkmcnt(0)
	s_barrier
	s_setprio 1
	v_mfma_f32_16x16x32_bf16 v[78:81], v[156:159], v[196:199], v[78:81]
	v_mfma_f32_16x16x32_bf16 v[74:77], v[170:173], v[196:199], v[74:77]
	v_mfma_f32_16x16x32_bf16 v[70:73], v[156:159], v[204:207], v[70:73]
	v_mfma_f32_16x16x32_bf16 v[62:65], v[170:173], v[204:207], v[62:65]
	v_mfma_f32_16x16x32_bf16 v[58:61], v[156:159], v[212:215], v[58:61]
	v_mfma_f32_16x16x32_bf16 v[54:57], v[170:173], v[212:215], v[54:57]
	v_mfma_f32_16x16x32_bf16 v[46:49], v[156:159], v[220:223], v[46:49]
	v_mfma_f32_16x16x32_bf16 v[38:41], v[170:173], v[220:223], v[38:41]
	v_mfma_f32_16x16x32_bf16 v[78:81], v[166:169], v[200:203], v[78:81]
	v_mfma_f32_16x16x32_bf16 v[74:77], v[174:177], v[200:203], v[74:77]
	v_mfma_f32_16x16x32_bf16 v[70:73], v[166:169], v[208:211], v[70:73]
	v_mfma_f32_16x16x32_bf16 v[62:65], v[174:177], v[208:211], v[62:65]
	v_mfma_f32_16x16x32_bf16 v[58:61], v[166:169], v[216:219], v[58:61]
	v_mfma_f32_16x16x32_bf16 v[54:57], v[174:177], v[216:219], v[54:57]
	v_mfma_f32_16x16x32_bf16 v[46:49], v[166:169], v[224:227], v[46:49]
	v_mfma_f32_16x16x32_bf16 v[38:41], v[174:177], v[224:227], v[38:41]
	v_mfma_f32_16x16x32_bf16 v[50:53], v[178:181], v[196:199], v[50:53]
	v_mfma_f32_16x16x32_bf16 v[42:45], v[186:189], v[196:199], v[42:45]
	v_mfma_f32_16x16x32_bf16 v[34:37], v[178:181], v[204:207], v[34:37]
	v_mfma_f32_16x16x32_bf16 v[26:29], v[186:189], v[204:207], v[26:29]
	v_mfma_f32_16x16x32_bf16 v[18:21], v[178:181], v[212:215], v[18:21]
	v_mfma_f32_16x16x32_bf16 v[14:17], v[186:189], v[212:215], v[14:17]
	v_mfma_f32_16x16x32_bf16 v[10:13], v[178:181], v[220:223], v[10:13]
	v_mfma_f32_16x16x32_bf16 v[6:9], v[186:189], v[220:223], v[6:9]
	v_mfma_f32_16x16x32_bf16 v[50:53], v[182:185], v[200:203], v[50:53]
	v_mfma_f32_16x16x32_bf16 v[42:45], v[190:193], v[200:203], v[42:45]
	v_mfma_f32_16x16x32_bf16 v[34:37], v[182:185], v[208:211], v[34:37]
	v_mfma_f32_16x16x32_bf16 v[26:29], v[190:193], v[208:211], v[26:29]
	v_mfma_f32_16x16x32_bf16 v[18:21], v[182:185], v[216:219], v[18:21]
	v_mfma_f32_16x16x32_bf16 v[14:17], v[190:193], v[216:219], v[14:17]
	v_mfma_f32_16x16x32_bf16 v[10:13], v[182:185], v[224:227], v[10:13]
	v_mfma_f32_16x16x32_bf16 v[6:9], v[190:193], v[224:227], v[6:9]
	s_setprio 0
	s_barrier
	s_add_i32 s73, s62, s49
	v_lshl_add_u64 v[228:229], s[42:43], 0, v[134:135]
	s_mov_b32 m0, s73
	ds_read_b128 v[196:199], v164 offset:16384
	ds_read_b128 v[200:203], v164 offset:17408
	ds_read_b128 v[204:207], v164 offset:18432
	ds_read_b128 v[208:211], v164 offset:19456
	ds_read_b128 v[212:215], v164 offset:20480
	ds_read_b128 v[216:219], v164 offset:21504
	ds_read_b128 v[220:223], v164 offset:22528
	ds_read_b128 v[224:227], v164 offset:23552
	global_load_lds_dwordx4 v[228:229], off
	s_add_i32 m0, s73, 0x2000
	s_add_u32 s74, s42, 0x100000
	v_lshl_add_u64 v[230:231], s[42:43], 0, v[138:139]
	s_addc_u32 s75, s43, 0
	s_add_i32 s73, s63, s49
	global_load_lds_dwordx4 v[230:231], off
	v_lshl_add_u64 v[232:233], s[74:75], 0, v[134:135]
	s_mov_b32 m0, s73
	v_lshl_add_u64 v[234:235], s[46:47], 0, v[136:137]
	global_load_lds_dwordx4 v[232:233], off
	v_lshl_add_u64 v[232:233], s[74:75], 0, v[138:139]
	s_add_i32 m0, s73, 0x2000
	s_nop 0
	global_load_lds_dwordx4 v[232:233], off
	v_lshl_add_u64 v[232:233], s[46:47], 0, v[132:133]
	s_mov_b32 m0, s35
	s_nop 0
	global_load_lds_dwordx4 v[232:233], off
	s_mov_b32 m0, s50
	s_nop 0
	global_load_lds_dwordx4 v[234:235], off
	s_waitcnt vmcnt(8)
	s_waitcnt lgkmcnt(0)
	s_barrier
	s_setprio 1
	v_mfma_f32_16x16x32_bf16 v[126:129], v[156:159], v[196:199], v[126:129]
	v_mfma_f32_16x16x32_bf16 v[118:121], v[170:173], v[196:199], v[118:121]
	v_mfma_f32_16x16x32_bf16 v[110:113], v[156:159], v[204:207], v[110:113]
	v_mfma_f32_16x16x32_bf16 v[102:105], v[170:173], v[204:207], v[102:105]
	v_mfma_f32_16x16x32_bf16 v[94:97], v[156:159], v[212:215], v[94:97]
	v_mfma_f32_16x16x32_bf16 v[86:89], v[170:173], v[212:215], v[86:89]
	v_mfma_f32_16x16x32_bf16 v[66:69], v[156:159], v[220:223], v[66:69]
	v_mfma_f32_16x16x32_bf16 v[22:25], v[170:173], v[220:223], v[22:25]
	v_mfma_f32_16x16x32_bf16 v[126:129], v[166:169], v[200:203], v[126:129]
	v_mfma_f32_16x16x32_bf16 v[118:121], v[174:177], v[200:203], v[118:121]
	v_mfma_f32_16x16x32_bf16 v[110:113], v[166:169], v[208:211], v[110:113]
	v_mfma_f32_16x16x32_bf16 v[102:105], v[174:177], v[208:211], v[102:105]
	v_mfma_f32_16x16x32_bf16 v[94:97], v[166:169], v[216:219], v[94:97]
	v_mfma_f32_16x16x32_bf16 v[86:89], v[174:177], v[216:219], v[86:89]
	v_mfma_f32_16x16x32_bf16 v[66:69], v[166:169], v[224:227], v[66:69]
	v_mfma_f32_16x16x32_bf16 v[22:25], v[174:177], v[224:227], v[22:25]
	v_mfma_f32_16x16x32_bf16 v[122:125], v[178:181], v[196:199], v[122:125]
	v_mfma_f32_16x16x32_bf16 v[114:117], v[186:189], v[196:199], v[114:117]
	v_mfma_f32_16x16x32_bf16 v[106:109], v[178:181], v[204:207], v[106:109]
	v_mfma_f32_16x16x32_bf16 v[98:101], v[186:189], v[204:207], v[98:101]
	v_mfma_f32_16x16x32_bf16 v[90:93], v[178:181], v[212:215], v[90:93]
	v_mfma_f32_16x16x32_bf16 v[82:85], v[186:189], v[212:215], v[82:85]
	v_mfma_f32_16x16x32_bf16 v[30:33], v[178:181], v[220:223], v[30:33]
	v_mfma_f32_16x16x32_bf16 v[2:5], v[186:189], v[220:223], v[2:5]
	v_mfma_f32_16x16x32_bf16 v[122:125], v[182:185], v[200:203], v[122:125]
	v_mfma_f32_16x16x32_bf16 v[114:117], v[190:193], v[200:203], v[114:117]
	v_mfma_f32_16x16x32_bf16 v[106:109], v[182:185], v[208:211], v[106:109]
	v_mfma_f32_16x16x32_bf16 v[98:101], v[190:193], v[208:211], v[98:101]
	v_mfma_f32_16x16x32_bf16 v[90:93], v[182:185], v[216:219], v[90:93]
	v_mfma_f32_16x16x32_bf16 v[82:85], v[190:193], v[216:219], v[82:85]
	v_mfma_f32_16x16x32_bf16 v[30:33], v[182:185], v[224:227], v[30:33]
	v_mfma_f32_16x16x32_bf16 v[2:5], v[190:193], v[224:227], v[2:5]
	s_setprio 0
	s_barrier
	s_add_i32 s73, 0, 0x18000
	v_add_u32_e32 v165, s73, v160
	s_add_i32 s74, 0, 0x1c000
	ds_read_b128 v[156:159], v165
	ds_read_b128 v[166:169], v165 offset:1024
	ds_read_b128 v[170:173], v165 offset:2048
	ds_read_b128 v[174:177], v165 offset:3072
	v_add_u32_e32 v165, s74, v160
	ds_read_b128 v[178:181], v165
	ds_read_b128 v[182:185], v165 offset:1024
	ds_read_b128 v[186:189], v165 offset:2048
	ds_read_b128 v[190:193], v165 offset:3072
	s_add_u32 s46, s46, 0x100000
	s_addc_u32 s47, s47, 0
	s_mov_b32 m0, s51
	v_lshl_add_u64 v[236:237], s[46:47], 0, v[132:133]
	ds_read_b128 v[196:199], v164 offset:32768
	ds_read_b128 v[200:203], v164 offset:33792
	ds_read_b128 v[204:207], v164 offset:34816
	ds_read_b128 v[208:211], v164 offset:35840
	ds_read_b128 v[212:215], v164 offset:36864
	ds_read_b128 v[216:219], v164 offset:37888
	ds_read_b128 v[220:223], v164 offset:38912
	ds_read_b128 v[224:227], v164 offset:39936
	global_load_lds_dwordx4 v[236:237], off
	v_lshl_add_u64 v[236:237], s[46:47], 0, v[136:137]
	s_mov_b32 m0, s52
	s_nop 0
	global_load_lds_dwordx4 v[236:237], off
	s_waitcnt vmcnt(8)
	s_waitcnt lgkmcnt(0)
	s_barrier
	s_setprio 1
	v_mfma_f32_16x16x32_bf16 v[78:81], v[156:159], v[196:199], v[78:81]
	v_mfma_f32_16x16x32_bf16 v[74:77], v[170:173], v[196:199], v[74:77]
	v_mfma_f32_16x16x32_bf16 v[70:73], v[156:159], v[204:207], v[70:73]
	v_mfma_f32_16x16x32_bf16 v[62:65], v[170:173], v[204:207], v[62:65]
	v_mfma_f32_16x16x32_bf16 v[58:61], v[156:159], v[212:215], v[58:61]
	v_mfma_f32_16x16x32_bf16 v[54:57], v[170:173], v[212:215], v[54:57]
	v_mfma_f32_16x16x32_bf16 v[46:49], v[156:159], v[220:223], v[46:49]
	v_mfma_f32_16x16x32_bf16 v[38:41], v[170:173], v[220:223], v[38:41]
	v_mfma_f32_16x16x32_bf16 v[78:81], v[166:169], v[200:203], v[78:81]
	v_mfma_f32_16x16x32_bf16 v[74:77], v[174:177], v[200:203], v[74:77]
	v_mfma_f32_16x16x32_bf16 v[70:73], v[166:169], v[208:211], v[70:73]
	v_mfma_f32_16x16x32_bf16 v[62:65], v[174:177], v[208:211], v[62:65]
	v_mfma_f32_16x16x32_bf16 v[58:61], v[166:169], v[216:219], v[58:61]
	v_mfma_f32_16x16x32_bf16 v[54:57], v[174:177], v[216:219], v[54:57]
	v_mfma_f32_16x16x32_bf16 v[46:49], v[166:169], v[224:227], v[46:49]
	v_mfma_f32_16x16x32_bf16 v[38:41], v[174:177], v[224:227], v[38:41]
	v_mfma_f32_16x16x32_bf16 v[50:53], v[178:181], v[196:199], v[50:53]
	v_mfma_f32_16x16x32_bf16 v[42:45], v[186:189], v[196:199], v[42:45]
	v_mfma_f32_16x16x32_bf16 v[34:37], v[178:181], v[204:207], v[34:37]
	v_mfma_f32_16x16x32_bf16 v[26:29], v[186:189], v[204:207], v[26:29]
	v_mfma_f32_16x16x32_bf16 v[18:21], v[178:181], v[212:215], v[18:21]
	v_mfma_f32_16x16x32_bf16 v[14:17], v[186:189], v[212:215], v[14:17]
	v_mfma_f32_16x16x32_bf16 v[10:13], v[178:181], v[220:223], v[10:13]
	v_mfma_f32_16x16x32_bf16 v[6:9], v[186:189], v[220:223], v[6:9]
	v_mfma_f32_16x16x32_bf16 v[50:53], v[182:185], v[200:203], v[50:53]
	v_mfma_f32_16x16x32_bf16 v[42:45], v[190:193], v[200:203], v[42:45]
	v_mfma_f32_16x16x32_bf16 v[34:37], v[182:185], v[208:211], v[34:37]
	v_mfma_f32_16x16x32_bf16 v[26:29], v[190:193], v[208:211], v[26:29]
	v_mfma_f32_16x16x32_bf16 v[18:21], v[182:185], v[216:219], v[18:21]
	v_mfma_f32_16x16x32_bf16 v[14:17], v[190:193], v[216:219], v[14:17]
	v_mfma_f32_16x16x32_bf16 v[10:13], v[182:185], v[224:227], v[10:13]
	v_mfma_f32_16x16x32_bf16 v[6:9], v[190:193], v[224:227], v[6:9]
	s_setprio 0
	s_barrier
	s_add_i32 s46, s73, s49
	v_lshl_add_u64 v[228:229], v[228:229], 0, s[10:11]
	s_mov_b32 m0, s46
	ds_read_b128 v[196:199], v164 offset:49152
	ds_read_b128 v[200:203], v164 offset:50176
	ds_read_b128 v[204:207], v164 offset:51200
	ds_read_b128 v[208:211], v164 offset:52224
	ds_read_b128 v[212:215], v164 offset:53248
	ds_read_b128 v[216:219], v164 offset:54272
	ds_read_b128 v[220:223], v164 offset:55296
	ds_read_b128 v[224:227], v164 offset:56320
	global_load_lds_dwordx4 v[228:229], off
	s_add_i32 m0, s46, 0x2000
	s_add_u32 s42, s42, 0x100080
	v_lshl_add_u64 v[228:229], v[230:231], 0, s[10:11]
	s_addc_u32 s43, s43, 0
	s_add_i32 s46, s74, s49
	global_load_lds_dwordx4 v[228:229], off
	v_lshl_add_u64 v[228:229], s[42:43], 0, v[134:135]
	s_mov_b32 m0, s46
	s_nop 0
	global_load_lds_dwordx4 v[228:229], off
	v_lshl_add_u64 v[228:229], s[42:43], 0, v[138:139]
	s_add_i32 m0, s46, 0x2000
	s_nop 0
	global_load_lds_dwordx4 v[228:229], off
	v_lshl_add_u64 v[228:229], v[232:233], 0, s[10:11]
	s_mov_b32 m0, s55
	s_nop 0
	global_load_lds_dwordx4 v[228:229], off
	v_lshl_add_u64 v[228:229], v[234:235], 0, s[10:11]
	s_mov_b32 m0, s56
	s_nop 0
	global_load_lds_dwordx4 v[228:229], off
	s_waitcnt vmcnt(8)
	s_waitcnt lgkmcnt(0)
	s_barrier
	s_setprio 1
	v_mfma_f32_16x16x32_bf16 v[126:129], v[156:159], v[196:199], v[126:129]
	v_mfma_f32_16x16x32_bf16 v[118:121], v[170:173], v[196:199], v[118:121]
	v_mfma_f32_16x16x32_bf16 v[110:113], v[156:159], v[204:207], v[110:113]
	v_mfma_f32_16x16x32_bf16 v[102:105], v[170:173], v[204:207], v[102:105]
	v_mfma_f32_16x16x32_bf16 v[94:97], v[156:159], v[212:215], v[94:97]
	v_mfma_f32_16x16x32_bf16 v[86:89], v[170:173], v[212:215], v[86:89]
	v_mfma_f32_16x16x32_bf16 v[66:69], v[156:159], v[220:223], v[66:69]
	v_mfma_f32_16x16x32_bf16 v[22:25], v[170:173], v[220:223], v[22:25]
	v_mfma_f32_16x16x32_bf16 v[126:129], v[166:169], v[200:203], v[126:129]
	v_mfma_f32_16x16x32_bf16 v[118:121], v[174:177], v[200:203], v[118:121]
	v_mfma_f32_16x16x32_bf16 v[110:113], v[166:169], v[208:211], v[110:113]
	v_mfma_f32_16x16x32_bf16 v[102:105], v[174:177], v[208:211], v[102:105]
	v_mfma_f32_16x16x32_bf16 v[94:97], v[166:169], v[216:219], v[94:97]
	v_mfma_f32_16x16x32_bf16 v[86:89], v[174:177], v[216:219], v[86:89]
	v_mfma_f32_16x16x32_bf16 v[66:69], v[166:169], v[224:227], v[66:69]
	v_mfma_f32_16x16x32_bf16 v[22:25], v[174:177], v[224:227], v[22:25]
	v_mfma_f32_16x16x32_bf16 v[122:125], v[178:181], v[196:199], v[122:125]
	v_mfma_f32_16x16x32_bf16 v[114:117], v[186:189], v[196:199], v[114:117]
	v_mfma_f32_16x16x32_bf16 v[106:109], v[178:181], v[204:207], v[106:109]
	v_mfma_f32_16x16x32_bf16 v[98:101], v[186:189], v[204:207], v[98:101]
	v_mfma_f32_16x16x32_bf16 v[90:93], v[178:181], v[212:215], v[90:93]
	v_mfma_f32_16x16x32_bf16 v[82:85], v[186:189], v[212:215], v[82:85]
	v_mfma_f32_16x16x32_bf16 v[30:33], v[178:181], v[220:223], v[30:33]
	v_mfma_f32_16x16x32_bf16 v[2:5], v[186:189], v[220:223], v[2:5]
	v_mfma_f32_16x16x32_bf16 v[122:125], v[182:185], v[200:203], v[122:125]
	v_mfma_f32_16x16x32_bf16 v[114:117], v[190:193], v[200:203], v[114:117]
	v_mfma_f32_16x16x32_bf16 v[106:109], v[182:185], v[208:211], v[106:109]
	v_mfma_f32_16x16x32_bf16 v[98:101], v[190:193], v[208:211], v[98:101]
	v_mfma_f32_16x16x32_bf16 v[90:93], v[182:185], v[216:219], v[90:93]
	v_mfma_f32_16x16x32_bf16 v[82:85], v[190:193], v[216:219], v[82:85]
	v_mfma_f32_16x16x32_bf16 v[30:33], v[182:185], v[224:227], v[30:33]
	v_mfma_f32_16x16x32_bf16 v[2:5], v[190:193], v[224:227], v[2:5]
	s_setprio 0
	s_barrier
	s_add_u32 s40, s40, 0x100
	s_addc_u32 s41, s41, 0
	s_add_u32 s70, s70, 0x100
	s_addc_u32 s71, s71, 0
	s_cmp_ge_i32 s72, s68
	s_mov_b32 s42, s72
	s_cbranch_scc0 .LBB0_4145
	s_and_b64 vcc, exec, s[12:13]
	s_cbranch_vccz .LBB0_4150
	s_barrier
	s_cmp_lt_i32 s48, 0
	s_mov_b64 s[40:41], -1
	s_cbranch_scc1 .LBB0_4151

.LBB0_4151:
	v_mul_f32_e32 v156, 0xbfb8aa3b, v78
	v_mul_f32_e32 v157, 0xbfb8aa3b, v79
	v_exp_f32_e32 v156, v156
	v_exp_f32_e32 v157, v157
	v_mul_f32_e32 v166, 0xbfb8aa3b, v80
	v_exp_f32_e32 v166, v166
	v_mul_f32_e32 v167, 0xbfb8aa3b, v81
	v_exp_f32_e32 v167, v167
	v_add_f32_e32 v156, 1.0, v156
	v_add_f32_e32 v157, 1.0, v157
	v_rcp_f32_e32 v156, v156
	v_rcp_f32_e32 v157, v157
	v_add_f32_e32 v166, 1.0, v166
	v_rcp_f32_e32 v168, v166
	v_add_f32_e32 v166, 1.0, v167
	v_rcp_f32_e32 v169, v166
	v_pk_mul_f32 v[156:157], v[78:79], v[156:157]
	v_mul_f32_e32 v167, 0xbfb8aa3b, v74
	v_pk_mul_f32 v[156:157], v[50:51], v[156:157]
	v_lshl_or_b32 v158, s4, 7, v161
	v_cvt_pk_bf16_f32 v166, v156, v157
	v_pk_mul_f32 v[156:157], v[80:81], v[168:169]
	v_exp_f32_e32 v168, v167
	v_mul_f32_e32 v167, 0xbfb8aa3b, v75
	v_exp_f32_e32 v169, v167
	v_pk_mul_f32 v[156:157], v[52:53], v[156:157]
	v_lshl_add_u32 v165, s34, 8, v131
	v_cvt_pk_bf16_f32 v167, v156, v157
	v_add_f32_e32 v156, 1.0, v168
	v_mul_f32_e32 v168, 0xbfb8aa3b, v76
	v_add_f32_e32 v157, 1.0, v169
	v_exp_f32_e32 v168, v168
	v_mul_f32_e32 v169, 0xbfb8aa3b, v77
	v_exp_f32_e32 v169, v169
	v_rcp_f32_e32 v156, v156
	v_rcp_f32_e32 v157, v157
	v_add_f32_e32 v168, 1.0, v168
	v_rcp_f32_e32 v170, v168
	v_add_f32_e32 v168, 1.0, v169
	v_rcp_f32_e32 v171, v168
	v_pk_mul_f32 v[156:157], v[74:75], v[156:157]
	v_ashrrev_i32_e32 v159, 31, v158
	v_pk_mul_f32 v[156:157], v[42:43], v[156:157]
	v_lshlrev_b64 v[158:159], 1, v[158:159]
	v_cvt_pk_bf16_f32 v168, v156, v157
	v_pk_mul_f32 v[156:157], v[76:77], v[170:171]
	v_or_b32_e32 v172, 16, v165
	v_pk_mul_f32 v[156:157], v[44:45], v[156:157]
	s_nop 0
	v_cvt_pk_bf16_f32 v169, v156, v157
	v_mov_b64_e32 v[156:157], s[8:9]
	v_mad_i64_i32 v[170:171], s[40:41], v165, s64, v[156:157]
	v_lshl_add_u64 v[170:171], v[170:171], 0, v[158:159]
	global_store_dwordx4 v[170:171], v[166:169], off nt
	s_nop 1
	v_mul_f32_e32 v166, 0xbfb8aa3b, v70
	v_mul_f32_e32 v167, 0xbfb8aa3b, v71
	v_exp_f32_e32 v166, v166
	v_exp_f32_e32 v167, v167
	v_mul_f32_e32 v168, 0xbfb8aa3b, v72
	v_mul_f32_e32 v169, 0xbfb8aa3b, v73
	v_add_f32_e32 v166, 1.0, v166
	v_add_f32_e32 v167, 1.0, v167
	v_rcp_f32_e32 v166, v166
	v_rcp_f32_e32 v167, v167
	v_exp_f32_e32 v168, v168
	v_exp_f32_e32 v169, v169
	v_pk_mul_f32 v[166:167], v[70:71], v[166:167]
	v_add_f32_e32 v168, 1.0, v168
	v_add_f32_e32 v169, 1.0, v169
	v_pk_mul_f32 v[166:167], v[34:35], v[166:167]
	v_rcp_f32_e32 v168, v168
	v_rcp_f32_e32 v169, v169
	v_cvt_pk_bf16_f32 v166, v166, v167
	v_mul_f32_e32 v167, 0xbfb8aa3b, v62
	v_exp_f32_e32 v170, v167
	v_mul_f32_e32 v167, 0xbfb8aa3b, v63
	v_exp_f32_e32 v171, v167
	v_pk_mul_f32 v[168:169], v[72:73], v[168:169]
	s_nop 0
	v_pk_mul_f32 v[168:169], v[36:37], v[168:169]
	s_nop 0
	v_cvt_pk_bf16_f32 v167, v168, v169
	v_add_f32_e32 v168, 1.0, v170
	v_add_f32_e32 v169, 1.0, v171
	v_mul_f32_e32 v170, 0xbfb8aa3b, v64
	v_mul_f32_e32 v171, 0xbfb8aa3b, v65
	v_exp_f32_e32 v170, v170
	v_exp_f32_e32 v171, v171
	v_rcp_f32_e32 v168, v168
	v_rcp_f32_e32 v169, v169
	v_add_f32_e32 v170, 1.0, v170
	v_add_f32_e32 v171, 1.0, v171
	v_rcp_f32_e32 v170, v170
	v_rcp_f32_e32 v171, v171
	v_pk_mul_f32 v[168:169], v[62:63], v[168:169]
	v_pk_mul_f32 v[170:171], v[64:65], v[170:171]
	v_pk_mul_f32 v[168:169], v[26:27], v[168:169]
	v_pk_mul_f32 v[170:171], v[28:29], v[170:171]
	v_cvt_pk_bf16_f32 v168, v168, v169
	v_cvt_pk_bf16_f32 v169, v170, v171
	v_mad_i64_i32 v[170:171], s[40:41], v172, s64, v[156:157]
	v_lshl_add_u64 v[170:171], v[170:171], 0, v[158:159]
	global_store_dwordx4 v[170:171], v[166:169], off nt
	v_or_b32_e32 v172, 32, v165
	s_nop 0
	v_mul_f32_e32 v166, 0xbfb8aa3b, v58
	v_mul_f32_e32 v167, 0xbfb8aa3b, v59
	v_exp_f32_e32 v166, v166
	v_exp_f32_e32 v167, v167
	v_mul_f32_e32 v168, 0xbfb8aa3b, v60
	v_mul_f32_e32 v169, 0xbfb8aa3b, v61
	v_add_f32_e32 v166, 1.0, v166
	v_add_f32_e32 v167, 1.0, v167
	v_rcp_f32_e32 v166, v166
	v_rcp_f32_e32 v167, v167
	v_exp_f32_e32 v168, v168
	v_exp_f32_e32 v169, v169
	v_pk_mul_f32 v[166:167], v[58:59], v[166:167]
	v_add_f32_e32 v168, 1.0, v168
	v_add_f32_e32 v169, 1.0, v169
	v_pk_mul_f32 v[166:167], v[18:19], v[166:167]
	v_rcp_f32_e32 v168, v168
	v_rcp_f32_e32 v169, v169
	v_cvt_pk_bf16_f32 v166, v166, v167
	v_mul_f32_e32 v167, 0xbfb8aa3b, v54
	v_exp_f32_e32 v170, v167
	v_mul_f32_e32 v167, 0xbfb8aa3b, v55
	v_exp_f32_e32 v171, v167
	v_pk_mul_f32 v[168:169], v[60:61], v[168:169]
	s_nop 0
	v_pk_mul_f32 v[168:169], v[20:21], v[168:169]
	s_nop 0
	v_cvt_pk_bf16_f32 v167, v168, v169
	v_add_f32_e32 v168, 1.0, v170
	v_add_f32_e32 v169, 1.0, v171
	v_mul_f32_e32 v170, 0xbfb8aa3b, v56
	v_mul_f32_e32 v171, 0xbfb8aa3b, v57
	v_exp_f32_e32 v170, v170
	v_exp_f32_e32 v171, v171
	v_rcp_f32_e32 v168, v168
	v_rcp_f32_e32 v169, v169
	v_add_f32_e32 v170, 1.0, v170
	v_add_f32_e32 v171, 1.0, v171
	v_rcp_f32_e32 v170, v170
	v_rcp_f32_e32 v171, v171
	v_pk_mul_f32 v[168:169], v[54:55], v[168:169]
	v_pk_mul_f32 v[170:171], v[56:57], v[170:171]
	v_pk_mul_f32 v[168:169], v[14:15], v[168:169]
	v_pk_mul_f32 v[170:171], v[16:17], v[170:171]
	v_cvt_pk_bf16_f32 v168, v168, v169
	v_cvt_pk_bf16_f32 v169, v170, v171
	v_mad_i64_i32 v[170:171], s[40:41], v172, s64, v[156:157]
	v_lshl_add_u64 v[170:171], v[170:171], 0, v[158:159]
	global_store_dwordx4 v[170:171], v[166:169], off nt
	v_or_b32_e32 v172, 48, v165
	s_nop 0
	v_mul_f32_e32 v166, 0xbfb8aa3b, v46
	v_mul_f32_e32 v167, 0xbfb8aa3b, v47
	v_exp_f32_e32 v166, v166
	v_exp_f32_e32 v167, v167
	v_mul_f32_e32 v168, 0xbfb8aa3b, v48
	v_mul_f32_e32 v169, 0xbfb8aa3b, v49
	v_add_f32_e32 v166, 1.0, v166
	v_add_f32_e32 v167, 1.0, v167
	v_rcp_f32_e32 v166, v166
	v_rcp_f32_e32 v167, v167
	v_exp_f32_e32 v168, v168
	v_exp_f32_e32 v169, v169
	v_pk_mul_f32 v[166:167], v[46:47], v[166:167]
	v_add_f32_e32 v168, 1.0, v168
	v_add_f32_e32 v169, 1.0, v169
	v_pk_mul_f32 v[166:167], v[10:11], v[166:167]
	v_rcp_f32_e32 v168, v168
	v_rcp_f32_e32 v169, v169
	v_cvt_pk_bf16_f32 v166, v166, v167
	v_mul_f32_e32 v167, 0xbfb8aa3b, v38
	v_exp_f32_e32 v170, v167
	v_mul_f32_e32 v167, 0xbfb8aa3b, v39
	v_exp_f32_e32 v171, v167
	v_pk_mul_f32 v[168:169], v[48:49], v[168:169]
	s_nop 0
	v_pk_mul_f32 v[168:169], v[12:13], v[168:169]
	s_nop 0
	v_cvt_pk_bf16_f32 v167, v168, v169
	v_add_f32_e32 v168, 1.0, v170
	v_add_f32_e32 v169, 1.0, v171
	v_mul_f32_e32 v170, 0xbfb8aa3b, v40
	v_mul_f32_e32 v171, 0xbfb8aa3b, v41
	v_exp_f32_e32 v170, v170
	v_exp_f32_e32 v171, v171
	v_rcp_f32_e32 v168, v168
	v_rcp_f32_e32 v169, v169
	v_add_f32_e32 v170, 1.0, v170
	v_add_f32_e32 v171, 1.0, v171
	v_rcp_f32_e32 v170, v170
	v_rcp_f32_e32 v171, v171
	v_pk_mul_f32 v[168:169], v[38:39], v[168:169]
	v_pk_mul_f32 v[170:171], v[40:41], v[170:171]
	v_pk_mul_f32 v[168:169], v[6:7], v[168:169]
	v_pk_mul_f32 v[170:171], v[8:9], v[170:171]
	v_cvt_pk_bf16_f32 v168, v168, v169
	v_cvt_pk_bf16_f32 v169, v170, v171
	v_mad_i64_i32 v[170:171], s[40:41], v172, s64, v[156:157]
	v_lshl_add_u64 v[170:171], v[170:171], 0, v[158:159]
	global_store_dwordx4 v[170:171], v[166:169], off nt
	v_add_u32_e32 v170, 0x80, v165
	s_nop 0
	v_mul_f32_e32 v166, 0xbfb8aa3b, v126
	v_mul_f32_e32 v167, 0xbfb8aa3b, v127
	v_exp_f32_e32 v166, v166
	v_exp_f32_e32 v167, v167
	v_mul_f32_e32 v168, 0xbfb8aa3b, v128
	v_mul_f32_e32 v169, 0xbfb8aa3b, v129
	v_exp_f32_e32 v168, v168
	v_exp_f32_e32 v169, v169
	v_add_f32_e32 v166, 1.0, v166
	v_add_f32_e32 v167, 1.0, v167
	v_rcp_f32_e32 v166, v166
	v_rcp_f32_e32 v167, v167
	v_add_f32_e32 v168, 1.0, v168
	v_add_f32_e32 v169, 1.0, v169
	v_rcp_f32_e32 v168, v168
	v_rcp_f32_e32 v169, v169
	v_pk_mul_f32 v[126:127], v[126:127], v[166:167]
	s_nop 0
	v_pk_mul_f32 v[122:123], v[122:123], v[126:127]
	v_pk_mul_f32 v[126:127], v[128:129], v[168:169]
	v_cvt_pk_bf16_f32 v122, v122, v123
	v_mul_f32_e32 v123, 0xbfb8aa3b, v118
	v_pk_mul_f32 v[124:125], v[124:125], v[126:127]
	v_exp_f32_e32 v126, v123
	v_mul_f32_e32 v123, 0xbfb8aa3b, v119
	v_exp_f32_e32 v127, v123
	v_cvt_pk_bf16_f32 v123, v124, v125
	v_add_f32_e32 v124, 1.0, v126
	v_mul_f32_e32 v126, 0xbfb8aa3b, v120
	v_add_f32_e32 v125, 1.0, v127
	v_mul_f32_e32 v127, 0xbfb8aa3b, v121
	v_exp_f32_e32 v126, v126
	v_exp_f32_e32 v127, v127
	v_rcp_f32_e32 v124, v124
	v_rcp_f32_e32 v125, v125
	v_add_f32_e32 v126, 1.0, v126
	v_add_f32_e32 v127, 1.0, v127
	v_rcp_f32_e32 v126, v126
	v_rcp_f32_e32 v127, v127
	v_pk_mul_f32 v[118:119], v[118:119], v[124:125]
	s_nop 0
	v_pk_mul_f32 v[114:115], v[114:115], v[118:119]
	v_add_u32_e32 v118, 0x90, v165
	v_cvt_pk_bf16_f32 v124, v114, v115
	v_pk_mul_f32 v[114:115], v[120:121], v[126:127]
	s_nop 0
	v_pk_mul_f32 v[114:115], v[116:117], v[114:115]
	v_mul_f32_e32 v116, 0xbfb8aa3b, v112
	v_cvt_pk_bf16_f32 v125, v114, v115
	v_mad_i64_i32 v[114:115], s[40:41], v170, s64, v[156:157]
	v_lshl_add_u64 v[114:115], v[114:115], 0, v[158:159]
	global_store_dwordx4 v[114:115], v[122:125], off nt
	v_mul_f32_e32 v114, 0xbfb8aa3b, v110
	v_mul_f32_e32 v115, 0xbfb8aa3b, v111
	v_exp_f32_e32 v114, v114
	v_exp_f32_e32 v115, v115
	v_mul_f32_e32 v117, 0xbfb8aa3b, v113
	v_exp_f32_e32 v116, v116
	v_exp_f32_e32 v117, v117
	v_add_f32_e32 v114, 1.0, v114
	v_add_f32_e32 v115, 1.0, v115
	v_rcp_f32_e32 v114, v114
	v_rcp_f32_e32 v115, v115
	v_add_f32_e32 v116, 1.0, v116
	v_add_f32_e32 v117, 1.0, v117
	v_rcp_f32_e32 v116, v116
	v_rcp_f32_e32 v117, v117
	v_pk_mul_f32 v[110:111], v[110:111], v[114:115]
	s_nop 0
	v_pk_mul_f32 v[106:107], v[106:107], v[110:111]
	v_pk_mul_f32 v[110:111], v[112:113], v[116:117]
	v_cvt_pk_bf16_f32 v106, v106, v107
	v_mul_f32_e32 v107, 0xbfb8aa3b, v102
	v_pk_mul_f32 v[108:109], v[108:109], v[110:111]
	v_exp_f32_e32 v110, v107
	v_mul_f32_e32 v107, 0xbfb8aa3b, v103
	v_exp_f32_e32 v111, v107
	v_cvt_pk_bf16_f32 v107, v108, v109
	v_add_f32_e32 v108, 1.0, v110
	v_mul_f32_e32 v110, 0xbfb8aa3b, v104
	v_add_f32_e32 v109, 1.0, v111
	v_mul_f32_e32 v111, 0xbfb8aa3b, v105
	v_exp_f32_e32 v110, v110
	v_exp_f32_e32 v111, v111
	v_rcp_f32_e32 v108, v108
	v_rcp_f32_e32 v109, v109
	v_add_f32_e32 v110, 1.0, v110
	v_add_f32_e32 v111, 1.0, v111
	v_rcp_f32_e32 v110, v110
	v_rcp_f32_e32 v111, v111
	v_pk_mul_f32 v[102:103], v[102:103], v[108:109]
	s_nop 0
	v_pk_mul_f32 v[98:99], v[98:99], v[102:103]
	v_add_u32_e32 v102, 0xa0, v165
	v_cvt_pk_bf16_f32 v108, v98, v99
	v_pk_mul_f32 v[98:99], v[104:105], v[110:111]
	s_nop 0
	v_pk_mul_f32 v[98:99], v[100:101], v[98:99]
	v_mul_f32_e32 v100, 0xbfb8aa3b, v96
	v_cvt_pk_bf16_f32 v109, v98, v99
	v_mad_i64_i32 v[98:99], s[40:41], v118, s64, v[156:157]
	v_lshl_add_u64 v[98:99], v[98:99], 0, v[158:159]
	global_store_dwordx4 v[98:99], v[106:109], off nt
	v_mul_f32_e32 v98, 0xbfb8aa3b, v94
	v_mul_f32_e32 v99, 0xbfb8aa3b, v95
	v_exp_f32_e32 v98, v98
	v_exp_f32_e32 v99, v99
	v_mul_f32_e32 v101, 0xbfb8aa3b, v97
	v_exp_f32_e32 v100, v100
	v_exp_f32_e32 v101, v101
	v_add_f32_e32 v98, 1.0, v98
	v_add_f32_e32 v99, 1.0, v99
	v_rcp_f32_e32 v98, v98
	v_rcp_f32_e32 v99, v99
	v_add_f32_e32 v100, 1.0, v100
	v_add_f32_e32 v101, 1.0, v101
	v_rcp_f32_e32 v100, v100
	v_rcp_f32_e32 v101, v101
	v_pk_mul_f32 v[94:95], v[94:95], v[98:99]
	s_nop 0
	v_pk_mul_f32 v[90:91], v[90:91], v[94:95]
	v_pk_mul_f32 v[94:95], v[96:97], v[100:101]
	v_cvt_pk_bf16_f32 v90, v90, v91
	v_mul_f32_e32 v91, 0xbfb8aa3b, v86
	v_pk_mul_f32 v[92:93], v[92:93], v[94:95]
	v_exp_f32_e32 v94, v91
	v_mul_f32_e32 v91, 0xbfb8aa3b, v87
	v_exp_f32_e32 v95, v91
	v_cvt_pk_bf16_f32 v91, v92, v93
	v_add_f32_e32 v92, 1.0, v94
	v_mul_f32_e32 v94, 0xbfb8aa3b, v88
	v_add_f32_e32 v93, 1.0, v95
	v_mul_f32_e32 v95, 0xbfb8aa3b, v89
	v_exp_f32_e32 v94, v94
	v_exp_f32_e32 v95, v95
	v_rcp_f32_e32 v92, v92
	v_rcp_f32_e32 v93, v93
	v_add_f32_e32 v94, 1.0, v94
	v_add_f32_e32 v95, 1.0, v95
	v_rcp_f32_e32 v94, v94
	v_rcp_f32_e32 v95, v95
	v_pk_mul_f32 v[86:87], v[86:87], v[92:93]
	s_nop 0
	v_pk_mul_f32 v[82:83], v[82:83], v[86:87]
	v_add_u32_e32 v86, 0xb0, v165
	v_cvt_pk_bf16_f32 v92, v82, v83
	v_pk_mul_f32 v[82:83], v[88:89], v[94:95]
	s_nop 0
	v_pk_mul_f32 v[82:83], v[84:85], v[82:83]
	v_mul_f32_e32 v84, 0xbfb8aa3b, v68
	v_cvt_pk_bf16_f32 v93, v82, v83
	v_mad_i64_i32 v[82:83], s[40:41], v102, s64, v[156:157]
	v_lshl_add_u64 v[82:83], v[82:83], 0, v[158:159]
	global_store_dwordx4 v[82:83], v[90:93], off nt
	v_mul_f32_e32 v82, 0xbfb8aa3b, v66
	v_mul_f32_e32 v83, 0xbfb8aa3b, v67
	v_exp_f32_e32 v82, v82
	v_exp_f32_e32 v83, v83
	v_mul_f32_e32 v85, 0xbfb8aa3b, v69
	v_exp_f32_e32 v84, v84
	v_exp_f32_e32 v85, v85
	v_add_f32_e32 v82, 1.0, v82
	v_add_f32_e32 v83, 1.0, v83
	v_rcp_f32_e32 v82, v82
	v_rcp_f32_e32 v83, v83
	v_add_f32_e32 v84, 1.0, v84
	v_add_f32_e32 v85, 1.0, v85
	v_rcp_f32_e32 v84, v84
	v_rcp_f32_e32 v85, v85
	v_pk_mul_f32 v[66:67], v[66:67], v[82:83]
	s_nop 0
	v_pk_mul_f32 v[30:31], v[30:31], v[66:67]
	v_pk_mul_f32 v[66:67], v[68:69], v[84:85]
	v_cvt_pk_bf16_f32 v30, v30, v31
	v_mul_f32_e32 v31, 0xbfb8aa3b, v22
	v_pk_mul_f32 v[32:33], v[32:33], v[66:67]
	v_exp_f32_e32 v66, v31
	v_mul_f32_e32 v31, 0xbfb8aa3b, v23
	v_exp_f32_e32 v67, v31
	v_cvt_pk_bf16_f32 v31, v32, v33
	v_add_f32_e32 v32, 1.0, v66
	v_mul_f32_e32 v66, 0xbfb8aa3b, v24
	v_add_f32_e32 v33, 1.0, v67
	v_mul_f32_e32 v67, 0xbfb8aa3b, v25
	v_exp_f32_e32 v66, v66
	v_exp_f32_e32 v67, v67
	v_rcp_f32_e32 v32, v32
	v_rcp_f32_e32 v33, v33
	v_add_f32_e32 v66, 1.0, v66
	v_add_f32_e32 v67, 1.0, v67
	v_rcp_f32_e32 v66, v66
	v_rcp_f32_e32 v67, v67
	v_pk_mul_f32 v[22:23], v[22:23], v[32:33]
	s_nop 0
	v_pk_mul_f32 v[2:3], v[2:3], v[22:23]
	s_nop 0
	v_cvt_pk_bf16_f32 v32, v2, v3
	v_pk_mul_f32 v[2:3], v[24:25], v[66:67]
	s_nop 0
	v_pk_mul_f32 v[2:3], v[4:5], v[2:3]
	s_nop 0
	v_cvt_pk_bf16_f32 v33, v2, v3
	v_mad_i64_i32 v[2:3], s[40:41], v86, s64, v[156:157]
	v_lshl_add_u64 v[2:3], v[2:3], 0, v[158:159]
	global_store_dwordx4 v[2:3], v[30:33], off nt
	s_cbranch_execz .LBB0_4149

.LBB0_4304:
	ds_read_b128 v[150:153], v158
	ds_read_b128 v[162:165], v158 offset:1024
	ds_read_b128 v[166:169], v158 offset:2048
	ds_read_b128 v[170:173], v158 offset:3072
	ds_read_b128 v[174:177], v159
	ds_read_b128 v[178:181], v159 offset:1024
	ds_read_b128 v[182:185], v159 offset:2048
	ds_read_b128 v[186:189], v159 offset:3072
	s_add_i32 s80, s48, 2
	s_add_u32 s49, s50, 0xffd50080
	s_addc_u32 s52, s51, -1
	s_cmp_eq_u32 s43, s48
	s_cselect_b32 s48, s46, s78
	s_cselect_b32 s53, s5, s52
	s_cselect_b32 s52, s4, s49
	s_cselect_b32 s49, s47, s79
	v_lshl_add_u64 v[154:155], s[50:51], 0, v[138:139]
	s_add_i32 m0, s55, 0xc000
	ds_read_b128 v[190:193], v160
	ds_read_b128 v[196:199], v160 offset:1024
	ds_read_b128 v[200:203], v160 offset:2048
	ds_read_b128 v[204:207], v160 offset:3072
	ds_read_b128 v[208:211], v160 offset:4096
	ds_read_b128 v[212:215], v160 offset:5120
	ds_read_b128 v[216:219], v160 offset:6144
	ds_read_b128 v[220:223], v160 offset:7168
	global_load_lds_dwordx4 v[154:155], off
	v_lshl_add_u64 v[154:155], s[50:51], 0, v[140:141]
	s_add_i32 m0, s55, 0xe000
	s_nop 0
	global_load_lds_dwordx4 v[154:155], off
	s_waitcnt vmcnt(8)
	s_waitcnt lgkmcnt(0)
	s_barrier
	s_setprio 1
	v_mfma_f32_16x16x32_bf16 v[124:127], v[150:153], v[190:193], v[124:127]
	v_mfma_f32_16x16x32_bf16 v[120:123], v[166:169], v[190:193], v[120:123]
	v_mfma_f32_16x16x32_bf16 v[108:111], v[150:153], v[200:203], v[108:111]
	v_mfma_f32_16x16x32_bf16 v[104:107], v[166:169], v[200:203], v[104:107]
	v_mfma_f32_16x16x32_bf16 v[92:95], v[150:153], v[208:211], v[92:95]
	v_mfma_f32_16x16x32_bf16 v[88:91], v[166:169], v[208:211], v[88:91]
	v_mfma_f32_16x16x32_bf16 v[76:79], v[150:153], v[216:219], v[76:79]
	v_mfma_f32_16x16x32_bf16 v[72:75], v[166:169], v[216:219], v[72:75]
	v_mfma_f32_16x16x32_bf16 v[124:127], v[162:165], v[196:199], v[124:127]
	v_mfma_f32_16x16x32_bf16 v[120:123], v[170:173], v[196:199], v[120:123]
	v_mfma_f32_16x16x32_bf16 v[108:111], v[162:165], v[204:207], v[108:111]
	v_mfma_f32_16x16x32_bf16 v[104:107], v[170:173], v[204:207], v[104:107]
	v_mfma_f32_16x16x32_bf16 v[92:95], v[162:165], v[212:215], v[92:95]
	v_mfma_f32_16x16x32_bf16 v[88:91], v[170:173], v[212:215], v[88:91]
	v_mfma_f32_16x16x32_bf16 v[76:79], v[162:165], v[220:223], v[76:79]
	v_mfma_f32_16x16x32_bf16 v[72:75], v[170:173], v[220:223], v[72:75]
	v_mfma_f32_16x16x32_bf16 v[116:119], v[174:177], v[190:193], v[116:119]
	v_mfma_f32_16x16x32_bf16 v[112:115], v[182:185], v[190:193], v[112:115]
	v_mfma_f32_16x16x32_bf16 v[100:103], v[174:177], v[200:203], v[100:103]
	v_mfma_f32_16x16x32_bf16 v[96:99], v[182:185], v[200:203], v[96:99]
	v_mfma_f32_16x16x32_bf16 v[84:87], v[174:177], v[208:211], v[84:87]
	v_mfma_f32_16x16x32_bf16 v[80:83], v[182:185], v[208:211], v[80:83]
	v_mfma_f32_16x16x32_bf16 v[68:71], v[174:177], v[216:219], v[68:71]
	v_mfma_f32_16x16x32_bf16 v[64:67], v[182:185], v[216:219], v[64:67]
	v_mfma_f32_16x16x32_bf16 v[116:119], v[178:181], v[196:199], v[116:119]
	v_mfma_f32_16x16x32_bf16 v[112:115], v[186:189], v[196:199], v[112:115]
	v_mfma_f32_16x16x32_bf16 v[100:103], v[178:181], v[204:207], v[100:103]
	v_mfma_f32_16x16x32_bf16 v[96:99], v[186:189], v[204:207], v[96:99]
	v_mfma_f32_16x16x32_bf16 v[84:87], v[178:181], v[212:215], v[84:87]
	v_mfma_f32_16x16x32_bf16 v[80:83], v[186:189], v[212:215], v[80:83]
	v_mfma_f32_16x16x32_bf16 v[68:71], v[178:181], v[220:223], v[68:71]
	v_mfma_f32_16x16x32_bf16 v[64:67], v[186:189], v[220:223], v[64:67]
	s_setprio 0
	s_barrier
	s_add_i32 s81, s65, s54
	v_lshl_add_u64 v[154:155], s[48:49], 0, v[132:133]
	s_mov_b32 m0, s81
	ds_read_b128 v[190:193], v160 offset:16384
	ds_read_b128 v[196:199], v160 offset:17408
	ds_read_b128 v[200:203], v160 offset:18432
	ds_read_b128 v[204:207], v160 offset:19456
	ds_read_b128 v[208:211], v160 offset:20480
	ds_read_b128 v[212:215], v160 offset:21504
	ds_read_b128 v[216:219], v160 offset:22528
	ds_read_b128 v[220:223], v160 offset:23552
	global_load_lds_dwordx4 v[154:155], off
	s_add_i32 m0, s81, 0x2000
	s_add_u32 s82, s48, 0x2b0000
	v_lshl_add_u64 v[224:225], s[48:49], 0, v[136:137]
	s_addc_u32 s83, s49, 0
	s_add_i32 s81, s66, s54
	global_load_lds_dwordx4 v[224:225], off
	v_lshl_add_u64 v[226:227], s[82:83], 0, v[132:133]
	s_mov_b32 m0, s81
	v_lshl_add_u64 v[228:229], s[52:53], 0, v[134:135]
	global_load_lds_dwordx4 v[226:227], off
	v_lshl_add_u64 v[226:227], s[82:83], 0, v[136:137]
	s_add_i32 m0, s81, 0x2000
	s_nop 0
	global_load_lds_dwordx4 v[226:227], off
	v_lshl_add_u64 v[226:227], s[52:53], 0, v[128:129]
	s_mov_b32 m0, s55
	s_nop 0
	global_load_lds_dwordx4 v[226:227], off
	s_mov_b32 m0, s56
	s_nop 0
	global_load_lds_dwordx4 v[228:229], off
	s_waitcnt vmcnt(8)
	s_waitcnt lgkmcnt(0)
	s_barrier
	s_setprio 1
	v_mfma_f32_16x16x32_bf16 v[60:63], v[150:153], v[190:193], v[60:63]
	v_mfma_f32_16x16x32_bf16 v[56:59], v[166:169], v[190:193], v[56:59]
	v_mfma_f32_16x16x32_bf16 v[44:47], v[150:153], v[200:203], v[44:47]
	v_mfma_f32_16x16x32_bf16 v[40:43], v[166:169], v[200:203], v[40:43]
	v_mfma_f32_16x16x32_bf16 v[28:31], v[150:153], v[208:211], v[28:31]
	v_mfma_f32_16x16x32_bf16 v[24:27], v[166:169], v[208:211], v[24:27]
	v_mfma_f32_16x16x32_bf16 v[12:15], v[150:153], v[216:219], v[12:15]
	v_mfma_f32_16x16x32_bf16 v[8:11], v[166:169], v[216:219], v[8:11]
	v_mfma_f32_16x16x32_bf16 v[60:63], v[162:165], v[196:199], v[60:63]
	v_mfma_f32_16x16x32_bf16 v[56:59], v[170:173], v[196:199], v[56:59]
	v_mfma_f32_16x16x32_bf16 v[44:47], v[162:165], v[204:207], v[44:47]
	v_mfma_f32_16x16x32_bf16 v[40:43], v[170:173], v[204:207], v[40:43]
	v_mfma_f32_16x16x32_bf16 v[28:31], v[162:165], v[212:215], v[28:31]
	v_mfma_f32_16x16x32_bf16 v[24:27], v[170:173], v[212:215], v[24:27]
	v_mfma_f32_16x16x32_bf16 v[12:15], v[162:165], v[220:223], v[12:15]
	v_mfma_f32_16x16x32_bf16 v[8:11], v[170:173], v[220:223], v[8:11]
	v_mfma_f32_16x16x32_bf16 v[52:55], v[174:177], v[190:193], v[52:55]
	v_mfma_f32_16x16x32_bf16 v[48:51], v[182:185], v[190:193], v[48:51]
	v_mfma_f32_16x16x32_bf16 v[36:39], v[174:177], v[200:203], v[36:39]
	v_mfma_f32_16x16x32_bf16 v[32:35], v[182:185], v[200:203], v[32:35]
	v_mfma_f32_16x16x32_bf16 v[20:23], v[174:177], v[208:211], v[20:23]
	v_mfma_f32_16x16x32_bf16 v[16:19], v[182:185], v[208:211], v[16:19]
	v_mfma_f32_16x16x32_bf16 v[4:7], v[174:177], v[216:219], v[4:7]
	v_mfma_f32_16x16x32_bf16 v[0:3], v[182:185], v[216:219], v[0:3]
	v_mfma_f32_16x16x32_bf16 v[52:55], v[178:181], v[196:199], v[52:55]
	v_mfma_f32_16x16x32_bf16 v[48:51], v[186:189], v[196:199], v[48:51]
	v_mfma_f32_16x16x32_bf16 v[36:39], v[178:181], v[204:207], v[36:39]
	v_mfma_f32_16x16x32_bf16 v[32:35], v[186:189], v[204:207], v[32:35]
	v_mfma_f32_16x16x32_bf16 v[20:23], v[178:181], v[212:215], v[20:23]
	v_mfma_f32_16x16x32_bf16 v[16:19], v[186:189], v[212:215], v[16:19]
	v_mfma_f32_16x16x32_bf16 v[4:7], v[178:181], v[220:223], v[4:7]
	v_mfma_f32_16x16x32_bf16 v[0:3], v[186:189], v[220:223], v[0:3]
	s_setprio 0
	s_barrier
	s_add_i32 s81, 0, 0x18000
	v_add_u32_e32 v161, s81, v156
	s_add_i32 s82, 0, 0x1c000
	ds_read_b128 v[150:153], v161
	ds_read_b128 v[162:165], v161 offset:1024
	ds_read_b128 v[166:169], v161 offset:2048
	ds_read_b128 v[170:173], v161 offset:3072
	v_add_u32_e32 v161, s82, v156
	ds_read_b128 v[174:177], v161
	ds_read_b128 v[178:181], v161 offset:1024
	ds_read_b128 v[182:185], v161 offset:2048
	ds_read_b128 v[186:189], v161 offset:3072
	s_add_u32 s52, s52, 0x2b0000
	s_addc_u32 s53, s53, 0
	s_mov_b32 m0, s57
	v_lshl_add_u64 v[230:231], s[52:53], 0, v[128:129]
	ds_read_b128 v[190:193], v160 offset:32768
	ds_read_b128 v[196:199], v160 offset:33792
	ds_read_b128 v[200:203], v160 offset:34816
	ds_read_b128 v[204:207], v160 offset:35840
	ds_read_b128 v[208:211], v160 offset:36864
	ds_read_b128 v[212:215], v160 offset:37888
	ds_read_b128 v[216:219], v160 offset:38912
	ds_read_b128 v[220:223], v160 offset:39936
	global_load_lds_dwordx4 v[230:231], off
	v_lshl_add_u64 v[230:231], s[52:53], 0, v[134:135]
	s_mov_b32 m0, s58
	s_nop 0
	global_load_lds_dwordx4 v[230:231], off
	s_waitcnt vmcnt(8)
	s_waitcnt lgkmcnt(0)
	s_barrier
	s_setprio 1
	v_mfma_f32_16x16x32_bf16 v[124:127], v[150:153], v[190:193], v[124:127]
	v_mfma_f32_16x16x32_bf16 v[120:123], v[166:169], v[190:193], v[120:123]
	v_mfma_f32_16x16x32_bf16 v[108:111], v[150:153], v[200:203], v[108:111]
	v_mfma_f32_16x16x32_bf16 v[104:107], v[166:169], v[200:203], v[104:107]
	v_mfma_f32_16x16x32_bf16 v[92:95], v[150:153], v[208:211], v[92:95]
	v_mfma_f32_16x16x32_bf16 v[88:91], v[166:169], v[208:211], v[88:91]
	v_mfma_f32_16x16x32_bf16 v[76:79], v[150:153], v[216:219], v[76:79]
	v_mfma_f32_16x16x32_bf16 v[72:75], v[166:169], v[216:219], v[72:75]
	v_mfma_f32_16x16x32_bf16 v[124:127], v[162:165], v[196:199], v[124:127]
	v_mfma_f32_16x16x32_bf16 v[120:123], v[170:173], v[196:199], v[120:123]
	v_mfma_f32_16x16x32_bf16 v[108:111], v[162:165], v[204:207], v[108:111]
	v_mfma_f32_16x16x32_bf16 v[104:107], v[170:173], v[204:207], v[104:107]
	v_mfma_f32_16x16x32_bf16 v[92:95], v[162:165], v[212:215], v[92:95]
	v_mfma_f32_16x16x32_bf16 v[88:91], v[170:173], v[212:215], v[88:91]
	v_mfma_f32_16x16x32_bf16 v[76:79], v[162:165], v[220:223], v[76:79]
	v_mfma_f32_16x16x32_bf16 v[72:75], v[170:173], v[220:223], v[72:75]
	v_mfma_f32_16x16x32_bf16 v[116:119], v[174:177], v[190:193], v[116:119]
	v_mfma_f32_16x16x32_bf16 v[112:115], v[182:185], v[190:193], v[112:115]
	v_mfma_f32_16x16x32_bf16 v[100:103], v[174:177], v[200:203], v[100:103]
	v_mfma_f32_16x16x32_bf16 v[96:99], v[182:185], v[200:203], v[96:99]
	v_mfma_f32_16x16x32_bf16 v[84:87], v[174:177], v[208:211], v[84:87]
	v_mfma_f32_16x16x32_bf16 v[80:83], v[182:185], v[208:211], v[80:83]
	v_mfma_f32_16x16x32_bf16 v[68:71], v[174:177], v[216:219], v[68:71]
	v_mfma_f32_16x16x32_bf16 v[64:67], v[182:185], v[216:219], v[64:67]
	v_mfma_f32_16x16x32_bf16 v[116:119], v[178:181], v[196:199], v[116:119]
	v_mfma_f32_16x16x32_bf16 v[112:115], v[186:189], v[196:199], v[112:115]
	v_mfma_f32_16x16x32_bf16 v[100:103], v[178:181], v[204:207], v[100:103]
	v_mfma_f32_16x16x32_bf16 v[96:99], v[186:189], v[204:207], v[96:99]
	v_mfma_f32_16x16x32_bf16 v[84:87], v[178:181], v[212:215], v[84:87]
	v_mfma_f32_16x16x32_bf16 v[80:83], v[186:189], v[212:215], v[80:83]
	v_mfma_f32_16x16x32_bf16 v[68:71], v[178:181], v[220:223], v[68:71]
	v_mfma_f32_16x16x32_bf16 v[64:67], v[186:189], v[220:223], v[64:67]
	s_setprio 0
	s_barrier
	s_add_i32 s52, s81, s54
	v_lshl_add_u64 v[154:155], v[154:155], 0, s[14:15]
	s_mov_b32 m0, s52
	ds_read_b128 v[190:193], v160 offset:49152
	ds_read_b128 v[196:199], v160 offset:50176
	ds_read_b128 v[200:203], v160 offset:51200
	ds_read_b128 v[204:207], v160 offset:52224
	ds_read_b128 v[208:211], v160 offset:53248
	ds_read_b128 v[212:215], v160 offset:54272
	ds_read_b128 v[216:219], v160 offset:55296
	ds_read_b128 v[220:223], v160 offset:56320
	global_load_lds_dwordx4 v[154:155], off
	s_add_i32 m0, s52, 0x2000
	s_add_u32 s48, s48, 0x2b0080
	v_lshl_add_u64 v[154:155], v[224:225], 0, s[14:15]
	s_addc_u32 s49, s49, 0
	s_add_i32 s52, s82, s54
	global_load_lds_dwordx4 v[154:155], off
	v_lshl_add_u64 v[154:155], s[48:49], 0, v[132:133]
	s_mov_b32 m0, s52
	s_nop 0
	global_load_lds_dwordx4 v[154:155], off
	v_lshl_add_u64 v[154:155], s[48:49], 0, v[136:137]
	s_add_i32 m0, s52, 0x2000
	s_nop 0
	global_load_lds_dwordx4 v[154:155], off
	v_lshl_add_u64 v[154:155], v[226:227], 0, s[14:15]
	s_mov_b32 m0, s62
	s_nop 0
	global_load_lds_dwordx4 v[154:155], off
	v_lshl_add_u64 v[154:155], v[228:229], 0, s[14:15]
	s_mov_b32 m0, s63
	s_nop 0
	global_load_lds_dwordx4 v[154:155], off
	s_waitcnt vmcnt(8)
	s_waitcnt lgkmcnt(0)
	s_barrier
	s_setprio 1
	v_mfma_f32_16x16x32_bf16 v[60:63], v[150:153], v[190:193], v[60:63]
	v_mfma_f32_16x16x32_bf16 v[56:59], v[166:169], v[190:193], v[56:59]
	v_mfma_f32_16x16x32_bf16 v[44:47], v[150:153], v[200:203], v[44:47]
	v_mfma_f32_16x16x32_bf16 v[40:43], v[166:169], v[200:203], v[40:43]
	v_mfma_f32_16x16x32_bf16 v[28:31], v[150:153], v[208:211], v[28:31]
	v_mfma_f32_16x16x32_bf16 v[24:27], v[166:169], v[208:211], v[24:27]
	v_mfma_f32_16x16x32_bf16 v[12:15], v[150:153], v[216:219], v[12:15]
	v_mfma_f32_16x16x32_bf16 v[8:11], v[166:169], v[216:219], v[8:11]
	v_mfma_f32_16x16x32_bf16 v[60:63], v[162:165], v[196:199], v[60:63]
	v_mfma_f32_16x16x32_bf16 v[56:59], v[170:173], v[196:199], v[56:59]
	v_mfma_f32_16x16x32_bf16 v[44:47], v[162:165], v[204:207], v[44:47]
	v_mfma_f32_16x16x32_bf16 v[40:43], v[170:173], v[204:207], v[40:43]
	v_mfma_f32_16x16x32_bf16 v[28:31], v[162:165], v[212:215], v[28:31]
	v_mfma_f32_16x16x32_bf16 v[24:27], v[170:173], v[212:215], v[24:27]
	v_mfma_f32_16x16x32_bf16 v[12:15], v[162:165], v[220:223], v[12:15]
	v_mfma_f32_16x16x32_bf16 v[8:11], v[170:173], v[220:223], v[8:11]
	v_mfma_f32_16x16x32_bf16 v[52:55], v[174:177], v[190:193], v[52:55]
	v_mfma_f32_16x16x32_bf16 v[48:51], v[182:185], v[190:193], v[48:51]
	v_mfma_f32_16x16x32_bf16 v[36:39], v[174:177], v[200:203], v[36:39]
	v_mfma_f32_16x16x32_bf16 v[32:35], v[182:185], v[200:203], v[32:35]
	v_mfma_f32_16x16x32_bf16 v[20:23], v[174:177], v[208:211], v[20:23]
	v_mfma_f32_16x16x32_bf16 v[16:19], v[182:185], v[208:211], v[16:19]
	v_mfma_f32_16x16x32_bf16 v[4:7], v[174:177], v[216:219], v[4:7]
	v_mfma_f32_16x16x32_bf16 v[0:3], v[182:185], v[216:219], v[0:3]
	v_mfma_f32_16x16x32_bf16 v[52:55], v[178:181], v[196:199], v[52:55]
	v_mfma_f32_16x16x32_bf16 v[48:51], v[186:189], v[196:199], v[48:51]
	v_mfma_f32_16x16x32_bf16 v[36:39], v[178:181], v[204:207], v[36:39]
	v_mfma_f32_16x16x32_bf16 v[32:35], v[186:189], v[204:207], v[32:35]
	v_mfma_f32_16x16x32_bf16 v[20:23], v[178:181], v[212:215], v[20:23]
	v_mfma_f32_16x16x32_bf16 v[16:19], v[186:189], v[212:215], v[16:19]
	v_mfma_f32_16x16x32_bf16 v[4:7], v[178:181], v[220:223], v[4:7]
	v_mfma_f32_16x16x32_bf16 v[0:3], v[186:189], v[220:223], v[0:3]
	s_setprio 0
	s_barrier
	s_add_u32 s50, s50, 0x100
	s_addc_u32 s51, s51, 0
	s_add_u32 s78, s78, 0x100
	s_addc_u32 s79, s79, 0
	s_cmp_ge_i32 s80, s76
	s_mov_b32 s48, s80
	s_cbranch_scc0 .LBB0_4304
	s_and_b64 vcc, exec, s[16:17]
	s_cbranch_vccz .LBB0_4307
	s_barrier
